# stack: early-DMA gemm k-loop + attention waves 4-7 deferred PV (3-slot V ring) + DPP sum-of-squares butterflies in residual epilogues
# speedup vs baseline: 1.0110x; 1.0110x over previous
; #define MFMA16(a, b, c) __builtin_amdgcn_mfma_f32_16x16x32_bf16((a), (b), (c), 0, 0, 0)
; template <class Epi>
; DI void gemm8_tile(const bf16_t* __restrict__ Ab, int lda, const bf16_t* __restrict__ Bb, int ldb, int K, int brow, int bcol, const Epi epi,
;                    bool staged, bool has_next, const bf16_t* __restrict__ Abn, const bf16_t* __restrict__ Bbn) {
;     ...
;       for (int m = 0; m < 8; ++m)
; #pragma unroll
;         for (int n = 0; n < 4; ++n) acc[m][n] = MFMA16(At[m], Bf[n], acc[m][n]);
;       __builtin_amdgcn_sched_barrier(0);
;     }
;     asm volatile("s_waitcnt vmcnt(0)" ::: "memory");
;     __syncthreads();
;   DI void run8(f32x4 (&acc)[8][4], int rb, int cb, int fr, int fq) const {
;     const int lane = fq * 16 + fr, wid = (int)(threadIdx.x >> 6);
;     const float sc = scale; bf16_t* const xbp = xb; float* const ssqp = ssq;
;     float* scr = (float*)(smem + G8_STAGE_B + wid * 4352);
;     const int prow = lane >> 4, c4 = lane & 15;
;     const float* xp = xin + (size_t)(rb + prow) * D + cb + c4 * 4;
;     float* op = xout + (size_t)(rb + prow) * D + cb + c4 * 4;
.LBB0_488:
	v_lshrrev_b32_e32 v194, 4, v206
	s_waitcnt lgkmcnt(0)
	v_mfma_f32_16x16x32_bf16 v[200:203], v[58:61], v[2:5], v[126:129]
	v_mfma_f32_16x16x32_bf16 v[206:209], v[58:61], v[138:141], v[122:125]
	v_mfma_f32_16x16x32_bf16 v[212:215], v[58:61], v[182:185], v[118:121]
	v_mfma_f32_16x16x32_bf16 v[222:225], v[58:61], v[186:189], v[114:117]
	v_mfma_f32_16x16x32_bf16 v[150:153], v[50:53], v[2:5], v[110:113]
	v_mfma_f32_16x16x32_bf16 v[154:157], v[50:53], v[138:141], v[106:109]
	v_mfma_f32_16x16x32_bf16 v[142:145], v[50:53], v[182:185], v[102:105]
	v_mfma_f32_16x16x32_bf16 v[146:149], v[50:53], v[186:189], v[98:101]
	v_mfma_f32_16x16x32_bf16 v[114:117], v[42:45], v[2:5], v[94:97]
	v_mfma_f32_16x16x32_bf16 v[118:121], v[42:45], v[138:141], v[90:93]
	v_mfma_f32_16x16x32_bf16 v[106:109], v[42:45], v[182:185], v[86:89]
	v_mfma_f32_16x16x32_bf16 v[110:113], v[42:45], v[186:189], v[82:85]
	v_mfma_f32_16x16x32_bf16 v[82:85], v[34:37], v[2:5], v[78:81]
	v_mfma_f32_16x16x32_bf16 v[86:89], v[34:37], v[138:141], v[74:77]
	v_mfma_f32_16x16x32_bf16 v[74:77], v[34:37], v[182:185], v[70:73]
	v_mfma_f32_16x16x32_bf16 v[78:81], v[34:37], v[186:189], v[66:69]
	v_mfma_f32_16x16x32_bf16 v[58:61], v[26:29], v[2:5], v[62:65]
	v_mfma_f32_16x16x32_bf16 v[62:65], v[26:29], v[138:141], v[158:161]
	v_mfma_f32_16x16x32_bf16 v[50:53], v[26:29], v[182:185], v[54:57]
	v_mfma_f32_16x16x32_bf16 v[54:57], v[26:29], v[186:189], v[162:165]
	v_mfma_f32_16x16x32_bf16 v[42:45], v[18:21], v[2:5], v[46:49]
	v_mfma_f32_16x16x32_bf16 v[46:49], v[18:21], v[138:141], v[166:169]
	v_mfma_f32_16x16x32_bf16 v[34:37], v[18:21], v[182:185], v[38:41]
	v_mfma_f32_16x16x32_bf16 v[38:41], v[18:21], v[186:189], v[170:173]
	v_mfma_f32_16x16x32_bf16 v[26:29], v[10:13], v[2:5], v[30:33]
	v_mfma_f32_16x16x32_bf16 v[30:33], v[10:13], v[138:141], v[174:177]
	v_mfma_f32_16x16x32_bf16 v[18:21], v[10:13], v[182:185], v[22:25]
	v_mfma_f32_16x16x32_bf16 v[22:25], v[10:13], v[186:189], v[178:181]
	v_mfma_f32_16x16x32_bf16 v[10:13], v[190:193], v[2:5], v[14:17]
	v_mfma_f32_16x16x32_bf16 v[14:17], v[190:193], v[138:141], v[130:133]
	v_mfma_f32_16x16x32_bf16 v[2:5], v[190:193], v[182:185], v[6:9]
	v_mfma_f32_16x16x32_bf16 v[6:9], v[190:193], v[186:189], v[134:137]
	v_add_u32_e32 v0, s3, v205
	v_or_b32_e32 v178, v0, v194
	v_lshl_or_b32 v180, v204, 6, s31
	v_ashrrev_i32_e32 v179, 31, v178
	v_lshlrev_b64 v[182:183], 12, v[178:179]
	v_ashrrev_i32_e32 v181, 31, v180
	v_lshl_add_u64 v[66:67], s[38:39], 0, v[182:183]
	v_lshlrev_b64 v[186:187], 2, v[180:181]
	v_lshl_add_u64 v[66:67], v[66:67], 0, v[186:187]
	v_lshlrev_b32_e32 v0, 2, v199
	v_lshl_add_u64 v[184:185], v[66:67], 0, v[0:1]
	s_movk_i32 s0, 0x4000
	v_add_co_u32_e32 v66, vcc, s0, v184
	s_mov_b32 s0, 0x8000
	s_nop 0
	v_addc_co_u32_e32 v67, vcc, 0, v185, vcc
	s_waitcnt vmcnt(0)
	s_waitcnt vmcnt(0)
	s_barrier
; DI unsigned pack_bf16(float lo, float hi) { f32x2 v = {lo, hi}; bf16v2 b = __builtin_convertvector(v, bf16v2); return __builtin_bit_cast(unsigned, b); }
; DI float red16(float v) { v += __shfl_xor(v, 1); v += __shfl_xor(v, 2); v += __shfl_xor(v, 4); v += __shfl_xor(v, 8); return v; }
;   DI void run8(f32x4 (&acc)[8][4], int rb, int cb, int fr, int fq) const {
;     ...
;     for (int mh = 0; mh < 2; ++mh) {
;       f32x4 xv[4][4];
; #pragma unroll
;       for (int mm = 0; mm < 4; ++mm)
; #pragma unroll
;         for (int ps = 0; ps < 4; ++ps) xv[mm][ps] = __builtin_nontemporal_load((const f32x4*)(xp + (size_t)((mh * 4 + mm) * 16 + ps * 4) * D));
;       __builtin_amdgcn_sched_barrier(0);
; #pragma unroll
;       for (int mm = 0; mm < 4; ++mm) {
;         const int m = mh * 4 + mm;
; #pragma unroll
;         for (int n = 0; n < 4; ++n)
; #pragma unroll
;           for (int j = 0; j < 4; ++j) scr[(fq * 4 + j) * 68 + n * 16 + fr] = acc[m][n][j];
;         __builtin_amdgcn_sched_barrier(0);
; #pragma unroll
;         for (int ps = 0; ps < 4; ++ps) {
;           const f32x4 a = *(const f32x4*)(scr + (ps * 4 + prow) * 68 + c4 * 4);
;           f32x4 v;
;           v.x = xv[mm][ps].x + a.x * sc; v.y = xv[mm][ps].y + a.y * sc; v.z = xv[mm][ps].z + a.z * sc; v.w = xv[mm][ps].w + a.w * sc;
;           const int grow = rb + m * 16 + ps * 4 + prow;
;           __builtin_nontemporal_store(v, (f32x4*)(op + (size_t)(m * 16 + ps * 4) * D));
;           if (xbp) {
;             u32x2 o; o.x = pack_bf16(v.x, v.y); o.y = pack_bf16(v.z, v.w);
;             *(u32x2*)(xbp + (size_t)grow * LDH + cb + c4 * 4) = o;
;             const float t = red16(v.x * v.x + v.y * v.y + v.z * v.z + v.w * v.w);
;             if (c4 == 0) atomicAdd(ssqp + grow, t);
;           }
	global_load_dwordx4 v[174:177], v[184:185], off nt
	global_load_dwordx4 v[170:173], v[66:67], off nt
	v_add_co_u32_e32 v66, vcc, s0, v184
	s_mov_b32 s0, 0xc000
	s_nop 0
	v_addc_co_u32_e32 v67, vcc, 0, v185, vcc
	v_add_co_u32_e32 v68, vcc, s0, v184
	s_mov_b32 s0, 0x14000
	s_nop 0
	v_addc_co_u32_e32 v69, vcc, 0, v185, vcc
	global_load_dwordx4 v[166:169], v[66:67], off nt
	global_load_dwordx4 v[162:165], v[68:69], off nt
	v_add_co_u32_e32 v66, vcc, s92, v184
	v_readlane_b32 s8, v254, 0
	s_nop 0
	v_addc_co_u32_e32 v67, vcc, 0, v185, vcc
	v_add_co_u32_e32 v68, vcc, s0, v184
	s_mov_b32 s0, 0x18000
	s_nop 0
	v_addc_co_u32_e32 v69, vcc, 0, v185, vcc
	global_load_dwordx4 v[158:161], v[66:67], off nt
	global_load_dwordx4 v[138:141], v[68:69], off nt
	v_add_co_u32_e32 v66, vcc, s0, v184
	s_mov_b32 s0, 0x1c000
	s_nop 0
	v_addc_co_u32_e32 v67, vcc, 0, v185, vcc
	v_add_co_u32_e32 v68, vcc, s0, v184
	s_mov_b32 s0, 0x20000
	s_nop 0
	v_addc_co_u32_e32 v69, vcc, 0, v185, vcc
	global_load_dwordx4 v[134:137], v[66:67], off nt
	global_load_dwordx4 v[130:133], v[68:69], off nt
	v_add_co_u32_e32 v66, vcc, s0, v184
	s_mov_b32 s0, 0x24000
	s_nop 0
	v_addc_co_u32_e32 v67, vcc, 0, v185, vcc
	v_add_co_u32_e32 v68, vcc, s0, v184
	s_mov_b32 s0, 0x28000
	s_nop 0
	v_addc_co_u32_e32 v69, vcc, 0, v185, vcc
	global_load_dwordx4 v[126:129], v[66:67], off nt
	global_load_dwordx4 v[122:125], v[68:69], off nt
	v_add_co_u32_e32 v66, vcc, s0, v184
	s_mov_b32 s0, 0x2c000
	s_nop 0
	v_addc_co_u32_e32 v67, vcc, 0, v185, vcc
	v_add_co_u32_e32 v68, vcc, s0, v184
	s_mov_b32 s0, 0x30000
	s_nop 0
	v_addc_co_u32_e32 v69, vcc, 0, v185, vcc
	global_load_dwordx4 v[102:105], v[66:67], off nt
	global_load_dwordx4 v[98:101], v[68:69], off nt
	v_add_co_u32_e32 v66, vcc, s0, v184
	s_mov_b32 s0, 0x34000
	s_nop 0
	v_addc_co_u32_e32 v67, vcc, 0, v185, vcc
	v_add_co_u32_e32 v68, vcc, s0, v184
	s_mov_b32 s0, 0x38000
	s_nop 0
	v_addc_co_u32_e32 v69, vcc, 0, v185, vcc
	global_load_dwordx4 v[94:97], v[66:67], off nt
	global_load_dwordx4 v[90:93], v[68:69], off nt
	v_add_co_u32_e32 v66, vcc, s0, v184
	s_mov_b32 s0, 0x3c000
	s_nop 0
	v_addc_co_u32_e32 v67, vcc, 0, v185, vcc
	v_add_co_u32_e32 v68, vcc, s0, v184
	v_readlane_b32 s10, v254, 2
	s_nop 0
	v_addc_co_u32_e32 v69, vcc, 0, v185, vcc
	global_load_dwordx4 v[70:73], v[66:67], off nt
	s_nop 0
	global_load_dwordx4 v[66:69], v[68:69], off nt
	v_readlane_b32 s11, v254, 3
	v_readlane_b32 s9, v254, 1
	v_lshl_add_u64 v[180:181], v[180:181], 1, s[50:51]
	v_lshl_add_u64 v[182:183], s[10:11], 0, v[182:183]
	v_lshl_add_u64 v[182:183], v[182:183], 0, v[186:187]
	v_lshl_add_u64 v[182:183], v[182:183], 0, v[0:1]
	v_lshl_add_u32 v186, v198, 2, v218
	v_lshlrev_b32_e32 v0, 1, v199
	v_mad_u32_u24 v187, v198, 12, v186
	v_lshl_add_u64 v[180:181], v[180:181], 0, v[0:1]
	v_cmp_eq_u32_e64 s[8:9], 0, v198
	v_mad_u32_u24 v186, v194, s88, v186
	ds_write2_b32 v186, v200, v206 offset1:16
	ds_write2_b32 v186, v201, v207 offset0:68 offset1:84
	ds_write2_b32 v186, v202, v208 offset0:136 offset1:152
	ds_write2_b32 v186, v203, v209 offset0:204 offset1:220
	ds_write2_b32 v186, v212, v222 offset0:32 offset1:48
	ds_write2_b32 v186, v213, v223 offset0:100 offset1:116
	ds_write2_b32 v186, v214, v224 offset0:168 offset1:184
	ds_write2_b32 v186, v215, v225 offset0:236 offset1:252
	s_movk_i32 s0, 0x110
	v_mad_u32_u24 v0, v194, s0, v187
	ds_read_b128 v[188:191], v0
	v_cndmask_b32_e64 v0, 0, 1, s[76:77]
	v_cmp_ne_u32_e64 s[10:11], 1, v0
	s_andn2_b64 vcc, exec, s[76:77]
	s_waitcnt vmcnt(15) lgkmcnt(0)
	v_pk_fma_f32 v[174:175], v[188:189], 0.5, v[174:175] op_sel_hi:[1,0,1]
	v_pk_fma_f32 v[176:177], v[190:191], 0.5, v[176:177] op_sel_hi:[1,0,1]
	global_store_dwordx4 v[182:183], v[174:177], off nt
	s_cbranch_vccnz .LBB0_492
	v_cvt_pk_bf16_f32 v188, v174, v175
	v_pk_mul_f32 v[174:175], v[174:175], v[174:175]
	v_cvt_pk_bf16_f32 v189, v176, v177
	v_add_f32_e32 v0, v174, v175
	v_and_b32_e32 v175, 64, v219
	s_nop 0
	v_add_u32_e32 v175, 64, v175
	v_pk_mul_f32 v[176:177], v[176:177], v[176:177]
	s_nop 0
	v_add_f32_e32 v0, v176, v0
	v_add_f32_e32 v0, v177, v0
	s_nop 0
	s_nop 0
	v_mov_b32_dpp v174, v0 quad_perm:[1,0,3,2] row_mask:0xf bank_mask:0xf
	v_mad_i64_i32 v[190:191], s[0:1], v178, s66, v[180:181]
	global_store_dwordx2 v[190:191], v[188:189], off
	s_waitcnt lgkmcnt(0)
	v_add_f32_e32 v0, v0, v174
	s_nop 0
	s_nop 0
	s_nop 1
	s_nop 0
	s_nop 0
	v_mov_b32_dpp v174, v0 quad_perm:[2,3,0,1] row_mask:0xf bank_mask:0xf
	s_waitcnt lgkmcnt(0)
	v_add_f32_e32 v0, v0, v174
	s_nop 0
	s_nop 0
	s_nop 1
	s_nop 0
	s_nop 0
	v_mov_b32_dpp v174, v0 row_half_mirror row_mask:0xf bank_mask:0xf
	s_waitcnt lgkmcnt(0)
	v_add_f32_e32 v0, v0, v174
	v_xor_b32_e32 v174, 8, v219
	v_cmp_lt_i32_e32 vcc, v174, v175
	s_nop 1
	s_nop 0
	s_nop 0
	v_mov_b32_dpp v174, v0 row_mirror row_mask:0xf bank_mask:0xf
	s_and_saveexec_b64 s[0:1], s[8:9]
	s_cbranch_execz .LBB0_491
	s_waitcnt lgkmcnt(0)
	v_add_f32_e32 v0, v0, v174
	v_lshl_add_u64 v[174:175], v[178:179], 2, s[62:63]
	global_atomic_add_f32 v[174:175], v0, off

; DI unsigned pack_bf16(float lo, float hi) { f32x2 v = {lo, hi}; bf16v2 b = __builtin_convertvector(v, bf16v2); return __builtin_bit_cast(unsigned, b); }
; DI float red16(float v) { v += __shfl_xor(v, 1); v += __shfl_xor(v, 2); v += __shfl_xor(v, 4); v += __shfl_xor(v, 8); return v; }
;   DI void run8(f32x4 (&acc)[8][4], int rb, int cb, int fr, int fq) const {
;     ...
;         for (int ps = 0; ps < 4; ++ps) {
;           const f32x4 a = *(const f32x4*)(scr + (ps * 4 + prow) * 68 + c4 * 4);
;           f32x4 v;
;           v.x = xv[mm][ps].x + a.x * sc; v.y = xv[mm][ps].y + a.y * sc; v.z = xv[mm][ps].z + a.z * sc; v.w = xv[mm][ps].w + a.w * sc;
;           const int grow = rb + m * 16 + ps * 4 + prow;
;           __builtin_nontemporal_store(v, (f32x4*)(op + (size_t)(m * 16 + ps * 4) * D));
;           if (xbp) {
;             u32x2 o; o.x = pack_bf16(v.x, v.y); o.y = pack_bf16(v.z, v.w);
;             *(u32x2*)(xbp + (size_t)grow * LDH + cb + c4 * 4) = o;
;             const float t = red16(v.x * v.x + v.y * v.y + v.z * v.z + v.w * v.w);
;             if (c4 == 0) atomicAdd(ssqp + grow, t);
;           }
.LBB0_492:
	v_mul_u32_u24_e32 v0, 0x110, v194
	v_add_u32_e32 v0, v187, v0
	s_waitcnt lgkmcnt(0)
	ds_read_b128 v[174:177], v0 offset:1088
	s_waitcnt vmcnt(15) lgkmcnt(0)
	v_pk_fma_f32 v[170:171], v[174:175], 0.5, v[170:171] op_sel_hi:[1,0,1]
	v_add_co_u32_e32 v174, vcc, 0x4000, v182
	v_pk_fma_f32 v[172:173], v[176:177], 0.5, v[172:173] op_sel_hi:[1,0,1]
	s_nop 0
	v_addc_co_u32_e32 v175, vcc, 0, v183, vcc
	s_and_b64 vcc, exec, s[10:11]
	global_store_dwordx4 v[174:175], v[170:173], off nt
	s_cbranch_vccnz .LBB0_496
	v_pk_mul_f32 v[174:175], v[170:171], v[170:171]
	v_pk_mul_f32 v[176:177], v[172:173], v[172:173]
	v_add_f32_e32 v174, v174, v175
	v_add_f32_e32 v174, v176, v174
	v_and_b32_e32 v176, 64, v219
	v_add_f32_e32 v174, v177, v174
	s_nop 0
	v_add_u32_e32 v177, 64, v176
	s_nop 0
	v_cvt_pk_bf16_f32 v176, v170, v171
	v_xor_b32_e32 v171, 8, v219
	s_nop 0
	s_nop 0
	v_mov_b32_dpp v175, v174 quad_perm:[1,0,3,2] row_mask:0xf bank_mask:0xf
	s_waitcnt lgkmcnt(0)
	v_add_f32_e32 v174, v174, v175
	s_nop 0
	s_nop 0
	s_nop 1
	s_nop 0
	s_nop 0
	v_mov_b32_dpp v175, v174 quad_perm:[2,3,0,1] row_mask:0xf bank_mask:0xf
	s_waitcnt lgkmcnt(0)
	v_add_f32_e32 v175, v174, v175
	s_nop 0
	s_nop 0
	s_nop 1
	s_nop 0
	s_nop 0
	v_mov_b32_dpp v179, v175 row_half_mirror row_mask:0xf bank_mask:0xf
	v_cmp_lt_i32_e32 vcc, v171, v177
	v_or_b32_e32 v174, 4, v178
	v_cvt_pk_bf16_f32 v177, v172, v173
	s_nop 0
	s_waitcnt lgkmcnt(0)
	v_add_f32_e32 v170, v175, v179
	s_nop 0
	s_nop 0
	v_mov_b32_dpp v171, v170 row_mirror row_mask:0xf bank_mask:0xf
	v_mad_i64_i32 v[172:173], s[0:1], v174, s66, v[180:181]
	global_store_dwordx2 v[172:173], v[176:177], off
	s_and_saveexec_b64 s[0:1], s[8:9]
	s_cbranch_execz .LBB0_495
	v_ashrrev_i32_e32 v175, 31, v174
	s_waitcnt lgkmcnt(0)
	v_add_f32_e32 v172, v170, v171
	v_lshl_add_u64 v[170:171], v[174:175], 2, s[62:63]
	global_atomic_add_f32 v[170:171], v172, off

; DI unsigned pack_bf16(float lo, float hi) { f32x2 v = {lo, hi}; bf16v2 b = __builtin_convertvector(v, bf16v2); return __builtin_bit_cast(unsigned, b); }
; DI float red16(float v) { v += __shfl_xor(v, 1); v += __shfl_xor(v, 2); v += __shfl_xor(v, 4); v += __shfl_xor(v, 8); return v; }
;   DI void run8(f32x4 (&acc)[8][4], int rb, int cb, int fr, int fq) const {
;     ...
;         for (int ps = 0; ps < 4; ++ps) {
;           const f32x4 a = *(const f32x4*)(scr + (ps * 4 + prow) * 68 + c4 * 4);
;           f32x4 v;
;           v.x = xv[mm][ps].x + a.x * sc; v.y = xv[mm][ps].y + a.y * sc; v.z = xv[mm][ps].z + a.z * sc; v.w = xv[mm][ps].w + a.w * sc;
;           const int grow = rb + m * 16 + ps * 4 + prow;
;           __builtin_nontemporal_store(v, (f32x4*)(op + (size_t)(m * 16 + ps * 4) * D));
;           if (xbp) {
;             u32x2 o; o.x = pack_bf16(v.x, v.y); o.y = pack_bf16(v.z, v.w);
;             *(u32x2*)(xbp + (size_t)grow * LDH + cb + c4 * 4) = o;
;             const float t = red16(v.x * v.x + v.y * v.y + v.z * v.z + v.w * v.w);
;             if (c4 == 0) atomicAdd(ssqp + grow, t);
;           }
.LBB0_496:
	s_waitcnt lgkmcnt(0)
	ds_read_b128 v[170:173], v0 offset:2176
	s_waitcnt vmcnt(15) lgkmcnt(0)
	v_pk_fma_f32 v[166:167], v[170:171], 0.5, v[166:167] op_sel_hi:[1,0,1]
	v_add_co_u32_e32 v170, vcc, 0x8000, v182
	v_pk_fma_f32 v[168:169], v[172:173], 0.5, v[168:169] op_sel_hi:[1,0,1]
	s_nop 0
	v_addc_co_u32_e32 v171, vcc, 0, v183, vcc
	s_and_b64 vcc, exec, s[10:11]
	global_store_dwordx4 v[170:171], v[166:169], off nt
	s_cbranch_vccnz .LBB0_500
	v_pk_mul_f32 v[170:171], v[166:167], v[166:167]
	v_pk_mul_f32 v[172:173], v[168:169], v[168:169]
	v_add_f32_e32 v170, v170, v171
	v_add_f32_e32 v170, v172, v170
	v_and_b32_e32 v172, 64, v219
	v_add_f32_e32 v170, v173, v170
	s_nop 0
	v_add_u32_e32 v173, 64, v172
	s_nop 0
	v_cvt_pk_bf16_f32 v172, v166, v167
	v_xor_b32_e32 v167, 8, v219
	s_nop 0
	s_nop 0
	v_mov_b32_dpp v171, v170 quad_perm:[1,0,3,2] row_mask:0xf bank_mask:0xf
	s_waitcnt lgkmcnt(0)
	v_add_f32_e32 v170, v170, v171
	s_nop 0
	s_nop 0
	s_nop 1
	s_nop 0
	s_nop 0
	v_mov_b32_dpp v171, v170 quad_perm:[2,3,0,1] row_mask:0xf bank_mask:0xf
	s_waitcnt lgkmcnt(0)
	v_add_f32_e32 v171, v170, v171
	s_nop 0
	s_nop 0
	s_nop 1
	s_nop 0
	s_nop 0
	v_mov_b32_dpp v174, v171 row_half_mirror row_mask:0xf bank_mask:0xf
	v_cmp_lt_i32_e32 vcc, v167, v173
	v_or_b32_e32 v170, 8, v178
	v_cvt_pk_bf16_f32 v173, v168, v169
	s_nop 0
	s_waitcnt lgkmcnt(0)
	v_add_f32_e32 v166, v171, v174
	s_nop 0
	s_nop 0
	v_mov_b32_dpp v167, v166 row_mirror row_mask:0xf bank_mask:0xf
	v_mad_i64_i32 v[168:169], s[0:1], v170, s66, v[180:181]
	global_store_dwordx2 v[168:169], v[172:173], off
	s_and_saveexec_b64 s[0:1], s[8:9]
	s_cbranch_execz .LBB0_499
	v_ashrrev_i32_e32 v171, 31, v170
	s_waitcnt lgkmcnt(0)
	v_add_f32_e32 v168, v166, v167
	v_lshl_add_u64 v[166:167], v[170:171], 2, s[62:63]
	global_atomic_add_f32 v[166:167], v168, off

; DI unsigned pack_bf16(float lo, float hi) { f32x2 v = {lo, hi}; bf16v2 b = __builtin_convertvector(v, bf16v2); return __builtin_bit_cast(unsigned, b); }
; DI float red16(float v) { v += __shfl_xor(v, 1); v += __shfl_xor(v, 2); v += __shfl_xor(v, 4); v += __shfl_xor(v, 8); return v; }
;   DI void run8(f32x4 (&acc)[8][4], int rb, int cb, int fr, int fq) const {
;     ...
;         for (int ps = 0; ps < 4; ++ps) {
;           const f32x4 a = *(const f32x4*)(scr + (ps * 4 + prow) * 68 + c4 * 4);
;           f32x4 v;
;           v.x = xv[mm][ps].x + a.x * sc; v.y = xv[mm][ps].y + a.y * sc; v.z = xv[mm][ps].z + a.z * sc; v.w = xv[mm][ps].w + a.w * sc;
;           const int grow = rb + m * 16 + ps * 4 + prow;
;           __builtin_nontemporal_store(v, (f32x4*)(op + (size_t)(m * 16 + ps * 4) * D));
;           if (xbp) {
;             u32x2 o; o.x = pack_bf16(v.x, v.y); o.y = pack_bf16(v.z, v.w);
;             *(u32x2*)(xbp + (size_t)grow * LDH + cb + c4 * 4) = o;
;             const float t = red16(v.x * v.x + v.y * v.y + v.z * v.z + v.w * v.w);
;             if (c4 == 0) atomicAdd(ssqp + grow, t);
;           }
.LBB0_500:
	s_waitcnt lgkmcnt(0)
	ds_read_b128 v[166:169], v0 offset:3264
	s_waitcnt vmcnt(15) lgkmcnt(0)
	v_pk_fma_f32 v[162:163], v[166:167], 0.5, v[162:163] op_sel_hi:[1,0,1]
	v_add_co_u32_e32 v166, vcc, 0xc000, v182
	v_pk_fma_f32 v[164:165], v[168:169], 0.5, v[164:165] op_sel_hi:[1,0,1]
	s_nop 0
	v_addc_co_u32_e32 v167, vcc, 0, v183, vcc
	s_and_b64 vcc, exec, s[10:11]
	global_store_dwordx4 v[166:167], v[162:165], off nt
	s_cbranch_vccnz .LBB0_504
	v_pk_mul_f32 v[166:167], v[162:163], v[162:163]
	v_pk_mul_f32 v[168:169], v[164:165], v[164:165]
	v_add_f32_e32 v166, v166, v167
	v_add_f32_e32 v166, v168, v166
	v_and_b32_e32 v168, 64, v219
	v_add_f32_e32 v166, v169, v166
	s_nop 0
	v_add_u32_e32 v169, 64, v168
	s_nop 0
	v_cvt_pk_bf16_f32 v168, v162, v163
	v_xor_b32_e32 v163, 8, v219
	s_nop 0
	s_nop 0
	v_mov_b32_dpp v167, v166 quad_perm:[1,0,3,2] row_mask:0xf bank_mask:0xf
	s_waitcnt lgkmcnt(0)
	v_add_f32_e32 v166, v166, v167
	s_nop 0
	s_nop 0
	s_nop 1
	s_nop 0
	s_nop 0
	v_mov_b32_dpp v167, v166 quad_perm:[2,3,0,1] row_mask:0xf bank_mask:0xf
	s_waitcnt lgkmcnt(0)
	v_add_f32_e32 v167, v166, v167
	s_nop 0
	s_nop 0
	s_nop 1
	s_nop 0
	s_nop 0
	v_mov_b32_dpp v170, v167 row_half_mirror row_mask:0xf bank_mask:0xf
	v_cmp_lt_i32_e32 vcc, v163, v169
	v_or_b32_e32 v166, 12, v178
	v_cvt_pk_bf16_f32 v169, v164, v165
	s_nop 0
	s_waitcnt lgkmcnt(0)
	v_add_f32_e32 v162, v167, v170
	s_nop 0
	s_nop 0
	v_mov_b32_dpp v163, v162 row_mirror row_mask:0xf bank_mask:0xf
	v_mad_i64_i32 v[164:165], s[0:1], v166, s66, v[180:181]
	global_store_dwordx2 v[164:165], v[168:169], off
	s_and_saveexec_b64 s[0:1], s[8:9]
	s_cbranch_execz .LBB0_503
	v_ashrrev_i32_e32 v167, 31, v166
	s_waitcnt lgkmcnt(0)
	v_add_f32_e32 v164, v162, v163
	v_lshl_add_u64 v[162:163], v[166:167], 2, s[62:63]
	global_atomic_add_f32 v[162:163], v164, off

; DI unsigned pack_bf16(float lo, float hi) { f32x2 v = {lo, hi}; bf16v2 b = __builtin_convertvector(v, bf16v2); return __builtin_bit_cast(unsigned, b); }
; DI float red16(float v) { v += __shfl_xor(v, 1); v += __shfl_xor(v, 2); v += __shfl_xor(v, 4); v += __shfl_xor(v, 8); return v; }
;   DI void run8(f32x4 (&acc)[8][4], int rb, int cb, int fr, int fq) const {
;     ...
;       for (int mm = 0; mm < 4; ++mm) {
;         const int m = mh * 4 + mm;
; #pragma unroll
;         for (int n = 0; n < 4; ++n)
; #pragma unroll
;           for (int j = 0; j < 4; ++j) scr[(fq * 4 + j) * 68 + n * 16 + fr] = acc[m][n][j];
;         __builtin_amdgcn_sched_barrier(0);
; #pragma unroll
;         for (int ps = 0; ps < 4; ++ps) {
;           const f32x4 a = *(const f32x4*)(scr + (ps * 4 + prow) * 68 + c4 * 4);
;           f32x4 v;
;           v.x = xv[mm][ps].x + a.x * sc; v.y = xv[mm][ps].y + a.y * sc; v.z = xv[mm][ps].z + a.z * sc; v.w = xv[mm][ps].w + a.w * sc;
;           const int grow = rb + m * 16 + ps * 4 + prow;
;           __builtin_nontemporal_store(v, (f32x4*)(op + (size_t)(m * 16 + ps * 4) * D));
;           if (xbp) {
;             u32x2 o; o.x = pack_bf16(v.x, v.y); o.y = pack_bf16(v.z, v.w);
;             *(u32x2*)(xbp + (size_t)grow * LDH + cb + c4 * 4) = o;
;             const float t = red16(v.x * v.x + v.y * v.y + v.z * v.z + v.w * v.w);
;             if (c4 == 0) atomicAdd(ssqp + grow, t);
;           }
.LBB0_504:
	ds_write2_b32 v186, v150, v154 offset1:16
	ds_write2_b32 v186, v151, v155 offset0:68 offset1:84
	ds_write2_b32 v186, v152, v156 offset0:136 offset1:152
	ds_write2_b32 v186, v153, v157 offset0:204 offset1:220
	ds_write2_b32 v186, v142, v146 offset0:32 offset1:48
	ds_write2_b32 v186, v143, v147 offset0:100 offset1:116
	ds_write2_b32 v186, v144, v148 offset0:168 offset1:184
	ds_write2_b32 v186, v145, v149 offset0:236 offset1:252
	ds_read_b128 v[142:145], v0
	v_add_co_u32_e32 v146, vcc, 0x10000, v182
	s_waitcnt vmcnt(15) lgkmcnt(0)
	v_pk_fma_f32 v[142:143], v[142:143], 0.5, v[158:159] op_sel_hi:[1,0,1]
	v_addc_co_u32_e32 v147, vcc, 0, v183, vcc
	v_pk_fma_f32 v[144:145], v[144:145], 0.5, v[160:161] op_sel_hi:[1,0,1]
	s_and_b64 vcc, exec, s[10:11]
	global_store_dwordx4 v[146:147], v[142:145], off nt
	s_cbranch_vccnz .LBB0_508
	v_pk_mul_f32 v[146:147], v[142:143], v[142:143]
	v_pk_mul_f32 v[148:149], v[144:145], v[144:145]
	v_add_f32_e32 v146, v146, v147
	v_add_f32_e32 v146, v148, v146
	v_and_b32_e32 v148, 64, v219
	v_add_f32_e32 v146, v149, v146
	s_nop 0
	v_add_u32_e32 v149, 64, v148
	s_nop 0
	v_cvt_pk_bf16_f32 v148, v142, v143
	v_xor_b32_e32 v143, 8, v219
	s_nop 0
	s_nop 0
	v_mov_b32_dpp v147, v146 quad_perm:[1,0,3,2] row_mask:0xf bank_mask:0xf
	s_waitcnt lgkmcnt(0)
	v_add_f32_e32 v146, v146, v147
	s_nop 0
	s_nop 0
	s_nop 1
	s_nop 0
	s_nop 0
	v_mov_b32_dpp v147, v146 quad_perm:[2,3,0,1] row_mask:0xf bank_mask:0xf
	s_waitcnt lgkmcnt(0)
	v_add_f32_e32 v147, v146, v147
	s_nop 0
	s_nop 0
	s_nop 1
	s_nop 0
	s_nop 0
	v_mov_b32_dpp v150, v147 row_half_mirror row_mask:0xf bank_mask:0xf
	v_cmp_lt_i32_e32 vcc, v143, v149
	v_or_b32_e32 v146, 16, v178
	v_cvt_pk_bf16_f32 v149, v144, v145
	s_nop 0
	s_waitcnt lgkmcnt(0)
	v_add_f32_e32 v142, v147, v150
	s_nop 0
	s_nop 0
	v_mov_b32_dpp v143, v142 row_mirror row_mask:0xf bank_mask:0xf
	v_mad_i64_i32 v[144:145], s[0:1], v146, s66, v[180:181]
	global_store_dwordx2 v[144:145], v[148:149], off
	s_and_saveexec_b64 s[0:1], s[8:9]
	s_cbranch_execz .LBB0_507
	v_ashrrev_i32_e32 v147, 31, v146
	s_waitcnt lgkmcnt(0)
	v_add_f32_e32 v144, v142, v143
	v_lshl_add_u64 v[142:143], v[146:147], 2, s[62:63]
	global_atomic_add_f32 v[142:143], v144, off

; DI unsigned pack_bf16(float lo, float hi) { f32x2 v = {lo, hi}; bf16v2 b = __builtin_convertvector(v, bf16v2); return __builtin_bit_cast(unsigned, b); }
; DI float red16(float v) { v += __shfl_xor(v, 1); v += __shfl_xor(v, 2); v += __shfl_xor(v, 4); v += __shfl_xor(v, 8); return v; }
;   DI void run8(f32x4 (&acc)[8][4], int rb, int cb, int fr, int fq) const {
;     ...
;         for (int ps = 0; ps < 4; ++ps) {
;           const f32x4 a = *(const f32x4*)(scr + (ps * 4 + prow) * 68 + c4 * 4);
;           f32x4 v;
;           v.x = xv[mm][ps].x + a.x * sc; v.y = xv[mm][ps].y + a.y * sc; v.z = xv[mm][ps].z + a.z * sc; v.w = xv[mm][ps].w + a.w * sc;
;           const int grow = rb + m * 16 + ps * 4 + prow;
;           __builtin_nontemporal_store(v, (f32x4*)(op + (size_t)(m * 16 + ps * 4) * D));
;           if (xbp) {
;             u32x2 o; o.x = pack_bf16(v.x, v.y); o.y = pack_bf16(v.z, v.w);
;             *(u32x2*)(xbp + (size_t)grow * LDH + cb + c4 * 4) = o;
;             const float t = red16(v.x * v.x + v.y * v.y + v.z * v.z + v.w * v.w);
;             if (c4 == 0) atomicAdd(ssqp + grow, t);
;           }
.LBB0_508:
	s_waitcnt lgkmcnt(0)
	ds_read_b128 v[142:145], v0 offset:1088
	s_waitcnt vmcnt(15) lgkmcnt(0)
	v_pk_fma_f32 v[138:139], v[142:143], 0.5, v[138:139] op_sel_hi:[1,0,1]
	v_add_co_u32_e32 v142, vcc, 0x14000, v182
	v_pk_fma_f32 v[140:141], v[144:145], 0.5, v[140:141] op_sel_hi:[1,0,1]
	s_nop 0
	v_addc_co_u32_e32 v143, vcc, 0, v183, vcc
	s_and_b64 vcc, exec, s[10:11]
	global_store_dwordx4 v[142:143], v[138:141], off nt
	s_cbranch_vccnz .LBB0_512
	v_pk_mul_f32 v[142:143], v[138:139], v[138:139]
	v_pk_mul_f32 v[144:145], v[140:141], v[140:141]
	v_add_f32_e32 v142, v142, v143
	v_add_f32_e32 v142, v144, v142
	v_and_b32_e32 v144, 64, v219
	v_add_f32_e32 v142, v145, v142
	s_nop 0
	v_add_u32_e32 v145, 64, v144
	s_nop 0
	v_cvt_pk_bf16_f32 v144, v138, v139
	v_xor_b32_e32 v139, 8, v219
	s_nop 0
	s_nop 0
	v_mov_b32_dpp v143, v142 quad_perm:[1,0,3,2] row_mask:0xf bank_mask:0xf
	s_waitcnt lgkmcnt(0)
	v_add_f32_e32 v142, v142, v143
	s_nop 0
	s_nop 0
	s_nop 1
	s_nop 0
	s_nop 0
	v_mov_b32_dpp v143, v142 quad_perm:[2,3,0,1] row_mask:0xf bank_mask:0xf
	s_waitcnt lgkmcnt(0)
	v_add_f32_e32 v143, v142, v143
	s_nop 0
	s_nop 0
	s_nop 1
	s_nop 0
	s_nop 0
	v_mov_b32_dpp v146, v143 row_half_mirror row_mask:0xf bank_mask:0xf
	v_cmp_lt_i32_e32 vcc, v139, v145
	v_or_b32_e32 v142, 20, v178
	v_cvt_pk_bf16_f32 v145, v140, v141
	s_nop 0
	s_waitcnt lgkmcnt(0)
	v_add_f32_e32 v138, v143, v146
	s_nop 0
	s_nop 0
	v_mov_b32_dpp v139, v138 row_mirror row_mask:0xf bank_mask:0xf
	v_mad_i64_i32 v[140:141], s[0:1], v142, s66, v[180:181]
	global_store_dwordx2 v[140:141], v[144:145], off
	s_and_saveexec_b64 s[0:1], s[8:9]
	s_cbranch_execz .LBB0_511
	v_ashrrev_i32_e32 v143, 31, v142
	s_waitcnt lgkmcnt(0)
	v_add_f32_e32 v140, v138, v139
	v_lshl_add_u64 v[138:139], v[142:143], 2, s[62:63]
	global_atomic_add_f32 v[138:139], v140, off

; DI unsigned pack_bf16(float lo, float hi) { f32x2 v = {lo, hi}; bf16v2 b = __builtin_convertvector(v, bf16v2); return __builtin_bit_cast(unsigned, b); }
; DI float red16(float v) { v += __shfl_xor(v, 1); v += __shfl_xor(v, 2); v += __shfl_xor(v, 4); v += __shfl_xor(v, 8); return v; }
;   DI void run8(f32x4 (&acc)[8][4], int rb, int cb, int fr, int fq) const {
;     ...
;         for (int ps = 0; ps < 4; ++ps) {
;           const f32x4 a = *(const f32x4*)(scr + (ps * 4 + prow) * 68 + c4 * 4);
;           f32x4 v;
;           v.x = xv[mm][ps].x + a.x * sc; v.y = xv[mm][ps].y + a.y * sc; v.z = xv[mm][ps].z + a.z * sc; v.w = xv[mm][ps].w + a.w * sc;
;           const int grow = rb + m * 16 + ps * 4 + prow;
;           __builtin_nontemporal_store(v, (f32x4*)(op + (size_t)(m * 16 + ps * 4) * D));
;           if (xbp) {
;             u32x2 o; o.x = pack_bf16(v.x, v.y); o.y = pack_bf16(v.z, v.w);
;             *(u32x2*)(xbp + (size_t)grow * LDH + cb + c4 * 4) = o;
;             const float t = red16(v.x * v.x + v.y * v.y + v.z * v.z + v.w * v.w);
;             if (c4 == 0) atomicAdd(ssqp + grow, t);
;           }
.LBB0_512:
	s_waitcnt lgkmcnt(0)
	ds_read_b128 v[138:141], v0 offset:2176
	s_waitcnt vmcnt(15) lgkmcnt(0)
	v_pk_fma_f32 v[134:135], v[138:139], 0.5, v[134:135] op_sel_hi:[1,0,1]
	v_add_co_u32_e32 v138, vcc, 0x18000, v182
	v_pk_fma_f32 v[136:137], v[140:141], 0.5, v[136:137] op_sel_hi:[1,0,1]
	s_nop 0
	v_addc_co_u32_e32 v139, vcc, 0, v183, vcc
	s_and_b64 vcc, exec, s[10:11]
	global_store_dwordx4 v[138:139], v[134:137], off nt
	s_cbranch_vccnz .LBB0_516
	v_pk_mul_f32 v[138:139], v[134:135], v[134:135]
	v_pk_mul_f32 v[140:141], v[136:137], v[136:137]
	v_add_f32_e32 v138, v138, v139
	v_add_f32_e32 v138, v140, v138
	v_and_b32_e32 v140, 64, v219
	v_add_f32_e32 v138, v141, v138
	s_nop 0
	v_add_u32_e32 v141, 64, v140
	s_nop 0
	v_cvt_pk_bf16_f32 v140, v134, v135
	v_xor_b32_e32 v135, 8, v219
	s_nop 0
	s_nop 0
	v_mov_b32_dpp v139, v138 quad_perm:[1,0,3,2] row_mask:0xf bank_mask:0xf
	s_waitcnt lgkmcnt(0)
	v_add_f32_e32 v138, v138, v139
	s_nop 0
	s_nop 0
	s_nop 1
	s_nop 0
	s_nop 0
	v_mov_b32_dpp v139, v138 quad_perm:[2,3,0,1] row_mask:0xf bank_mask:0xf
	s_waitcnt lgkmcnt(0)
	v_add_f32_e32 v139, v138, v139
	s_nop 0
	s_nop 0
	s_nop 1
	s_nop 0
	s_nop 0
	v_mov_b32_dpp v142, v139 row_half_mirror row_mask:0xf bank_mask:0xf
	v_cmp_lt_i32_e32 vcc, v135, v141
	v_or_b32_e32 v138, 24, v178
	v_cvt_pk_bf16_f32 v141, v136, v137
	s_nop 0
	s_waitcnt lgkmcnt(0)
	v_add_f32_e32 v134, v139, v142
	s_nop 0
	s_nop 0
	v_mov_b32_dpp v135, v134 row_mirror row_mask:0xf bank_mask:0xf
	v_mad_i64_i32 v[136:137], s[0:1], v138, s66, v[180:181]
	global_store_dwordx2 v[136:137], v[140:141], off
	s_and_saveexec_b64 s[0:1], s[8:9]
	s_cbranch_execz .LBB0_515
	v_ashrrev_i32_e32 v139, 31, v138
	s_waitcnt lgkmcnt(0)
	v_add_f32_e32 v136, v134, v135
	v_lshl_add_u64 v[134:135], v[138:139], 2, s[62:63]
	global_atomic_add_f32 v[134:135], v136, off

; DI unsigned pack_bf16(float lo, float hi) { f32x2 v = {lo, hi}; bf16v2 b = __builtin_convertvector(v, bf16v2); return __builtin_bit_cast(unsigned, b); }
; DI float red16(float v) { v += __shfl_xor(v, 1); v += __shfl_xor(v, 2); v += __shfl_xor(v, 4); v += __shfl_xor(v, 8); return v; }
;   DI void run8(f32x4 (&acc)[8][4], int rb, int cb, int fr, int fq) const {
;     ...
;         for (int ps = 0; ps < 4; ++ps) {
;           const f32x4 a = *(const f32x4*)(scr + (ps * 4 + prow) * 68 + c4 * 4);
;           f32x4 v;
;           v.x = xv[mm][ps].x + a.x * sc; v.y = xv[mm][ps].y + a.y * sc; v.z = xv[mm][ps].z + a.z * sc; v.w = xv[mm][ps].w + a.w * sc;
;           const int grow = rb + m * 16 + ps * 4 + prow;
;           __builtin_nontemporal_store(v, (f32x4*)(op + (size_t)(m * 16 + ps * 4) * D));
;           if (xbp) {
;             u32x2 o; o.x = pack_bf16(v.x, v.y); o.y = pack_bf16(v.z, v.w);
;             *(u32x2*)(xbp + (size_t)grow * LDH + cb + c4 * 4) = o;
;             const float t = red16(v.x * v.x + v.y * v.y + v.z * v.z + v.w * v.w);
;             if (c4 == 0) atomicAdd(ssqp + grow, t);
;           }
.LBB0_516:
	s_waitcnt lgkmcnt(0)
	ds_read_b128 v[134:137], v0 offset:3264
	s_waitcnt vmcnt(15) lgkmcnt(0)
	v_pk_fma_f32 v[130:131], v[134:135], 0.5, v[130:131] op_sel_hi:[1,0,1]
	v_add_co_u32_e32 v134, vcc, 0x1c000, v182
	v_pk_fma_f32 v[132:133], v[136:137], 0.5, v[132:133] op_sel_hi:[1,0,1]
	s_nop 0
	v_addc_co_u32_e32 v135, vcc, 0, v183, vcc
	s_and_b64 vcc, exec, s[10:11]
	global_store_dwordx4 v[134:135], v[130:133], off nt
	s_cbranch_vccnz .LBB0_520
	v_pk_mul_f32 v[134:135], v[130:131], v[130:131]
	v_pk_mul_f32 v[136:137], v[132:133], v[132:133]
	v_add_f32_e32 v134, v134, v135
	v_add_f32_e32 v134, v136, v134
	v_and_b32_e32 v136, 64, v219
	v_add_f32_e32 v134, v137, v134
	s_nop 0
	v_add_u32_e32 v137, 64, v136
	s_nop 0
	v_cvt_pk_bf16_f32 v136, v130, v131
	v_xor_b32_e32 v131, 8, v219
	s_nop 0
	s_nop 0
	v_mov_b32_dpp v135, v134 quad_perm:[1,0,3,2] row_mask:0xf bank_mask:0xf
	s_waitcnt lgkmcnt(0)
	v_add_f32_e32 v134, v134, v135
	s_nop 0
	s_nop 0
	s_nop 1
	s_nop 0
	s_nop 0
	v_mov_b32_dpp v135, v134 quad_perm:[2,3,0,1] row_mask:0xf bank_mask:0xf
	s_waitcnt lgkmcnt(0)
	v_add_f32_e32 v135, v134, v135
	s_nop 0
	s_nop 0
	s_nop 1
	s_nop 0
	s_nop 0
	v_mov_b32_dpp v138, v135 row_half_mirror row_mask:0xf bank_mask:0xf
	v_cmp_lt_i32_e32 vcc, v131, v137
	v_or_b32_e32 v134, 28, v178
	v_cvt_pk_bf16_f32 v137, v132, v133
	s_nop 0
	s_waitcnt lgkmcnt(0)
	v_add_f32_e32 v130, v135, v138
	s_nop 0
	s_nop 0
	v_mov_b32_dpp v131, v130 row_mirror row_mask:0xf bank_mask:0xf
	v_mad_i64_i32 v[132:133], s[0:1], v134, s66, v[180:181]
	global_store_dwordx2 v[132:133], v[136:137], off
	s_and_saveexec_b64 s[0:1], s[8:9]
	s_cbranch_execz .LBB0_519
	v_ashrrev_i32_e32 v135, 31, v134
	s_waitcnt lgkmcnt(0)
	v_add_f32_e32 v132, v130, v131
	v_lshl_add_u64 v[130:131], v[134:135], 2, s[62:63]
	global_atomic_add_f32 v[130:131], v132, off

; DI unsigned pack_bf16(float lo, float hi) { f32x2 v = {lo, hi}; bf16v2 b = __builtin_convertvector(v, bf16v2); return __builtin_bit_cast(unsigned, b); }
; DI float red16(float v) { v += __shfl_xor(v, 1); v += __shfl_xor(v, 2); v += __shfl_xor(v, 4); v += __shfl_xor(v, 8); return v; }
;   DI void run8(f32x4 (&acc)[8][4], int rb, int cb, int fr, int fq) const {
;     ...
;       for (int mm = 0; mm < 4; ++mm) {
;         const int m = mh * 4 + mm;
; #pragma unroll
;         for (int n = 0; n < 4; ++n)
; #pragma unroll
;           for (int j = 0; j < 4; ++j) scr[(fq * 4 + j) * 68 + n * 16 + fr] = acc[m][n][j];
;         __builtin_amdgcn_sched_barrier(0);
; #pragma unroll
;         for (int ps = 0; ps < 4; ++ps) {
;           const f32x4 a = *(const f32x4*)(scr + (ps * 4 + prow) * 68 + c4 * 4);
;           f32x4 v;
;           v.x = xv[mm][ps].x + a.x * sc; v.y = xv[mm][ps].y + a.y * sc; v.z = xv[mm][ps].z + a.z * sc; v.w = xv[mm][ps].w + a.w * sc;
;           const int grow = rb + m * 16 + ps * 4 + prow;
;           __builtin_nontemporal_store(v, (f32x4*)(op + (size_t)(m * 16 + ps * 4) * D));
;           if (xbp) {
;             u32x2 o; o.x = pack_bf16(v.x, v.y); o.y = pack_bf16(v.z, v.w);
;             *(u32x2*)(xbp + (size_t)grow * LDH + cb + c4 * 4) = o;
;             const float t = red16(v.x * v.x + v.y * v.y + v.z * v.z + v.w * v.w);
;             if (c4 == 0) atomicAdd(ssqp + grow, t);
;           }
.LBB0_520:
	ds_write2_b32 v186, v114, v118 offset1:16
	ds_write2_b32 v186, v115, v119 offset0:68 offset1:84
	ds_write2_b32 v186, v116, v120 offset0:136 offset1:152
	ds_write2_b32 v186, v117, v121 offset0:204 offset1:220
	ds_write2_b32 v186, v106, v110 offset0:32 offset1:48
	ds_write2_b32 v186, v107, v111 offset0:100 offset1:116
	ds_write2_b32 v186, v108, v112 offset0:168 offset1:184
	ds_write2_b32 v186, v109, v113 offset0:236 offset1:252
	ds_read_b128 v[106:109], v0
	v_add_co_u32_e32 v110, vcc, 0x20000, v182
	s_waitcnt vmcnt(15) lgkmcnt(0)
	v_pk_fma_f32 v[106:107], v[106:107], 0.5, v[126:127] op_sel_hi:[1,0,1]
	v_addc_co_u32_e32 v111, vcc, 0, v183, vcc
	v_pk_fma_f32 v[108:109], v[108:109], 0.5, v[128:129] op_sel_hi:[1,0,1]
	s_and_b64 vcc, exec, s[10:11]
	global_store_dwordx4 v[110:111], v[106:109], off nt
	s_cbranch_vccnz .LBB0_524
	v_pk_mul_f32 v[110:111], v[106:107], v[106:107]
	v_pk_mul_f32 v[112:113], v[108:109], v[108:109]
	v_add_f32_e32 v110, v110, v111
	v_add_f32_e32 v110, v112, v110
	v_and_b32_e32 v112, 64, v219
	v_add_f32_e32 v110, v113, v110
	s_nop 0
	v_add_u32_e32 v113, 64, v112
	s_nop 0
	v_cvt_pk_bf16_f32 v112, v106, v107
	v_xor_b32_e32 v107, 8, v219
	s_nop 0
	s_nop 0
	v_mov_b32_dpp v111, v110 quad_perm:[1,0,3,2] row_mask:0xf bank_mask:0xf
	s_waitcnt lgkmcnt(0)
	v_add_f32_e32 v110, v110, v111
	s_nop 0
	s_nop 0
	s_nop 1
	s_nop 0
	s_nop 0
	v_mov_b32_dpp v111, v110 quad_perm:[2,3,0,1] row_mask:0xf bank_mask:0xf
	s_waitcnt lgkmcnt(0)
	v_add_f32_e32 v111, v110, v111
	s_nop 0
	s_nop 0
	s_nop 1
	s_nop 0
	s_nop 0
	v_mov_b32_dpp v114, v111 row_half_mirror row_mask:0xf bank_mask:0xf
	v_cmp_lt_i32_e32 vcc, v107, v113
	v_or_b32_e32 v110, 32, v178
	v_cvt_pk_bf16_f32 v113, v108, v109
	s_nop 0
	s_waitcnt lgkmcnt(0)
	v_add_f32_e32 v106, v111, v114
	s_nop 0
	s_nop 0
	v_mov_b32_dpp v107, v106 row_mirror row_mask:0xf bank_mask:0xf
	v_mad_i64_i32 v[108:109], s[0:1], v110, s66, v[180:181]
	global_store_dwordx2 v[108:109], v[112:113], off
	s_and_saveexec_b64 s[0:1], s[8:9]
	s_cbranch_execz .LBB0_523
	v_ashrrev_i32_e32 v111, 31, v110
	s_waitcnt lgkmcnt(0)
	v_add_f32_e32 v108, v106, v107
	v_lshl_add_u64 v[106:107], v[110:111], 2, s[62:63]
	global_atomic_add_f32 v[106:107], v108, off

; DI unsigned pack_bf16(float lo, float hi) { f32x2 v = {lo, hi}; bf16v2 b = __builtin_convertvector(v, bf16v2); return __builtin_bit_cast(unsigned, b); }
; DI float red16(float v) { v += __shfl_xor(v, 1); v += __shfl_xor(v, 2); v += __shfl_xor(v, 4); v += __shfl_xor(v, 8); return v; }
;   DI void run8(f32x4 (&acc)[8][4], int rb, int cb, int fr, int fq) const {
;     ...
;         for (int ps = 0; ps < 4; ++ps) {
;           const f32x4 a = *(const f32x4*)(scr + (ps * 4 + prow) * 68 + c4 * 4);
;           f32x4 v;
;           v.x = xv[mm][ps].x + a.x * sc; v.y = xv[mm][ps].y + a.y * sc; v.z = xv[mm][ps].z + a.z * sc; v.w = xv[mm][ps].w + a.w * sc;
;           const int grow = rb + m * 16 + ps * 4 + prow;
;           __builtin_nontemporal_store(v, (f32x4*)(op + (size_t)(m * 16 + ps * 4) * D));
;           if (xbp) {
;             u32x2 o; o.x = pack_bf16(v.x, v.y); o.y = pack_bf16(v.z, v.w);
;             *(u32x2*)(xbp + (size_t)grow * LDH + cb + c4 * 4) = o;
;             const float t = red16(v.x * v.x + v.y * v.y + v.z * v.z + v.w * v.w);
;             if (c4 == 0) atomicAdd(ssqp + grow, t);
;           }
.LBB0_524:
	s_waitcnt lgkmcnt(0)
	ds_read_b128 v[106:109], v0 offset:1088
	v_add_co_u32_e32 v110, vcc, 0x24000, v182
	s_waitcnt vmcnt(15) lgkmcnt(0)
	v_pk_fma_f32 v[106:107], v[106:107], 0.5, v[122:123] op_sel_hi:[1,0,1]
	v_addc_co_u32_e32 v111, vcc, 0, v183, vcc
	v_pk_fma_f32 v[108:109], v[108:109], 0.5, v[124:125] op_sel_hi:[1,0,1]
	s_and_b64 vcc, exec, s[10:11]
	global_store_dwordx4 v[110:111], v[106:109], off nt
	s_cbranch_vccnz .LBB0_528
	v_pk_mul_f32 v[110:111], v[106:107], v[106:107]
	v_pk_mul_f32 v[112:113], v[108:109], v[108:109]
	v_add_f32_e32 v110, v110, v111
	v_add_f32_e32 v110, v112, v110
	v_and_b32_e32 v112, 64, v219
	v_add_f32_e32 v110, v113, v110
	s_nop 0
	v_add_u32_e32 v113, 64, v112
	s_nop 0
	v_cvt_pk_bf16_f32 v112, v106, v107
	v_xor_b32_e32 v107, 8, v219
	s_nop 0
	s_nop 0
	v_mov_b32_dpp v111, v110 quad_perm:[1,0,3,2] row_mask:0xf bank_mask:0xf
	s_waitcnt lgkmcnt(0)
	v_add_f32_e32 v110, v110, v111
	s_nop 0
	s_nop 0
	s_nop 1
	s_nop 0
	s_nop 0
	v_mov_b32_dpp v111, v110 quad_perm:[2,3,0,1] row_mask:0xf bank_mask:0xf
	s_waitcnt lgkmcnt(0)
	v_add_f32_e32 v111, v110, v111
	s_nop 0
	s_nop 0
	s_nop 1
	s_nop 0
	s_nop 0
	v_mov_b32_dpp v114, v111 row_half_mirror row_mask:0xf bank_mask:0xf
	v_cmp_lt_i32_e32 vcc, v107, v113
	v_or_b32_e32 v110, 36, v178
	v_cvt_pk_bf16_f32 v113, v108, v109
	s_nop 0
	s_waitcnt lgkmcnt(0)
	v_add_f32_e32 v106, v111, v114
	s_nop 0
	s_nop 0
	v_mov_b32_dpp v107, v106 row_mirror row_mask:0xf bank_mask:0xf
	v_mad_i64_i32 v[108:109], s[0:1], v110, s66, v[180:181]
	global_store_dwordx2 v[108:109], v[112:113], off
	s_and_saveexec_b64 s[0:1], s[8:9]
	s_cbranch_execz .LBB0_527
	v_ashrrev_i32_e32 v111, 31, v110
	s_waitcnt lgkmcnt(0)
	v_add_f32_e32 v108, v106, v107
	v_lshl_add_u64 v[106:107], v[110:111], 2, s[62:63]
	global_atomic_add_f32 v[106:107], v108, off

; DI unsigned pack_bf16(float lo, float hi) { f32x2 v = {lo, hi}; bf16v2 b = __builtin_convertvector(v, bf16v2); return __builtin_bit_cast(unsigned, b); }
; DI float red16(float v) { v += __shfl_xor(v, 1); v += __shfl_xor(v, 2); v += __shfl_xor(v, 4); v += __shfl_xor(v, 8); return v; }
;   DI void run8(f32x4 (&acc)[8][4], int rb, int cb, int fr, int fq) const {
;     ...
;         for (int ps = 0; ps < 4; ++ps) {
;           const f32x4 a = *(const f32x4*)(scr + (ps * 4 + prow) * 68 + c4 * 4);
;           f32x4 v;
;           v.x = xv[mm][ps].x + a.x * sc; v.y = xv[mm][ps].y + a.y * sc; v.z = xv[mm][ps].z + a.z * sc; v.w = xv[mm][ps].w + a.w * sc;
;           const int grow = rb + m * 16 + ps * 4 + prow;
;           __builtin_nontemporal_store(v, (f32x4*)(op + (size_t)(m * 16 + ps * 4) * D));
;           if (xbp) {
;             u32x2 o; o.x = pack_bf16(v.x, v.y); o.y = pack_bf16(v.z, v.w);
;             *(u32x2*)(xbp + (size_t)grow * LDH + cb + c4 * 4) = o;
;             const float t = red16(v.x * v.x + v.y * v.y + v.z * v.z + v.w * v.w);
;             if (c4 == 0) atomicAdd(ssqp + grow, t);
;           }
.LBB0_528:
	s_waitcnt lgkmcnt(0)
	ds_read_b128 v[106:109], v0 offset:2176
	s_waitcnt vmcnt(15) lgkmcnt(0)
	v_pk_fma_f32 v[102:103], v[106:107], 0.5, v[102:103] op_sel_hi:[1,0,1]
	v_add_co_u32_e32 v106, vcc, 0x28000, v182
	v_pk_fma_f32 v[104:105], v[108:109], 0.5, v[104:105] op_sel_hi:[1,0,1]
	s_nop 0
	v_addc_co_u32_e32 v107, vcc, 0, v183, vcc
	s_and_b64 vcc, exec, s[10:11]
	global_store_dwordx4 v[106:107], v[102:105], off nt
	s_cbranch_vccnz .LBB0_532
	v_pk_mul_f32 v[106:107], v[102:103], v[102:103]
	v_pk_mul_f32 v[108:109], v[104:105], v[104:105]
	v_add_f32_e32 v106, v106, v107
	v_add_f32_e32 v106, v108, v106
	v_and_b32_e32 v108, 64, v219
	v_add_f32_e32 v106, v109, v106
	s_nop 0
	v_add_u32_e32 v109, 64, v108
	s_nop 0
	v_cvt_pk_bf16_f32 v108, v102, v103
	v_xor_b32_e32 v103, 8, v219
	s_nop 0
	s_nop 0
	v_mov_b32_dpp v107, v106 quad_perm:[1,0,3,2] row_mask:0xf bank_mask:0xf
	s_waitcnt lgkmcnt(0)
	v_add_f32_e32 v106, v106, v107
	s_nop 0
	s_nop 0
	s_nop 1
	s_nop 0
	s_nop 0
	v_mov_b32_dpp v107, v106 quad_perm:[2,3,0,1] row_mask:0xf bank_mask:0xf
	s_waitcnt lgkmcnt(0)
	v_add_f32_e32 v107, v106, v107
	s_nop 0
	s_nop 0
	s_nop 1
	s_nop 0
	s_nop 0
	v_mov_b32_dpp v110, v107 row_half_mirror row_mask:0xf bank_mask:0xf
	v_cmp_lt_i32_e32 vcc, v103, v109
	v_or_b32_e32 v106, 40, v178
	v_cvt_pk_bf16_f32 v109, v104, v105
	s_nop 0
	s_waitcnt lgkmcnt(0)
	v_add_f32_e32 v102, v107, v110
	s_nop 0
	s_nop 0
	v_mov_b32_dpp v103, v102 row_mirror row_mask:0xf bank_mask:0xf
	v_mad_i64_i32 v[104:105], s[0:1], v106, s66, v[180:181]
	global_store_dwordx2 v[104:105], v[108:109], off
	s_and_saveexec_b64 s[0:1], s[8:9]
	s_cbranch_execz .LBB0_531
	v_ashrrev_i32_e32 v107, 31, v106
	s_waitcnt lgkmcnt(0)
	v_add_f32_e32 v104, v102, v103
	v_lshl_add_u64 v[102:103], v[106:107], 2, s[62:63]
	global_atomic_add_f32 v[102:103], v104, off

; DI unsigned pack_bf16(float lo, float hi) { f32x2 v = {lo, hi}; bf16v2 b = __builtin_convertvector(v, bf16v2); return __builtin_bit_cast(unsigned, b); }
; DI float red16(float v) { v += __shfl_xor(v, 1); v += __shfl_xor(v, 2); v += __shfl_xor(v, 4); v += __shfl_xor(v, 8); return v; }
;   DI void run8(f32x4 (&acc)[8][4], int rb, int cb, int fr, int fq) const {
;     ...
;         for (int ps = 0; ps < 4; ++ps) {
;           const f32x4 a = *(const f32x4*)(scr + (ps * 4 + prow) * 68 + c4 * 4);
;           f32x4 v;
;           v.x = xv[mm][ps].x + a.x * sc; v.y = xv[mm][ps].y + a.y * sc; v.z = xv[mm][ps].z + a.z * sc; v.w = xv[mm][ps].w + a.w * sc;
;           const int grow = rb + m * 16 + ps * 4 + prow;
;           __builtin_nontemporal_store(v, (f32x4*)(op + (size_t)(m * 16 + ps * 4) * D));
;           if (xbp) {
;             u32x2 o; o.x = pack_bf16(v.x, v.y); o.y = pack_bf16(v.z, v.w);
;             *(u32x2*)(xbp + (size_t)grow * LDH + cb + c4 * 4) = o;
;             const float t = red16(v.x * v.x + v.y * v.y + v.z * v.z + v.w * v.w);
;             if (c4 == 0) atomicAdd(ssqp + grow, t);
;           }
.LBB0_532:
	s_waitcnt lgkmcnt(0)
	ds_read_b128 v[102:105], v0 offset:3264
	s_waitcnt vmcnt(15) lgkmcnt(0)
	v_pk_fma_f32 v[98:99], v[102:103], 0.5, v[98:99] op_sel_hi:[1,0,1]
	v_add_co_u32_e32 v102, vcc, 0x2c000, v182
	v_pk_fma_f32 v[100:101], v[104:105], 0.5, v[100:101] op_sel_hi:[1,0,1]
	s_nop 0
	v_addc_co_u32_e32 v103, vcc, 0, v183, vcc
	s_and_b64 vcc, exec, s[10:11]
	global_store_dwordx4 v[102:103], v[98:101], off nt
	s_cbranch_vccnz .LBB0_536
	v_pk_mul_f32 v[102:103], v[98:99], v[98:99]
	v_pk_mul_f32 v[104:105], v[100:101], v[100:101]
	v_add_f32_e32 v102, v102, v103
	v_add_f32_e32 v102, v104, v102
	v_and_b32_e32 v104, 64, v219
	v_add_f32_e32 v102, v105, v102
	s_nop 0
	v_add_u32_e32 v105, 64, v104
	s_nop 0
	v_cvt_pk_bf16_f32 v104, v98, v99
	v_xor_b32_e32 v99, 8, v219
	s_nop 0
	s_nop 0
	v_mov_b32_dpp v103, v102 quad_perm:[1,0,3,2] row_mask:0xf bank_mask:0xf
	s_waitcnt lgkmcnt(0)
	v_add_f32_e32 v102, v102, v103
	s_nop 0
	s_nop 0
	s_nop 1
	s_nop 0
	s_nop 0
	v_mov_b32_dpp v103, v102 quad_perm:[2,3,0,1] row_mask:0xf bank_mask:0xf
	s_waitcnt lgkmcnt(0)
	v_add_f32_e32 v103, v102, v103
	s_nop 0
	s_nop 0
	s_nop 1
	s_nop 0
	s_nop 0
	v_mov_b32_dpp v106, v103 row_half_mirror row_mask:0xf bank_mask:0xf
	v_cmp_lt_i32_e32 vcc, v99, v105
	v_or_b32_e32 v102, 44, v178
	v_cvt_pk_bf16_f32 v105, v100, v101
	s_nop 0
	s_waitcnt lgkmcnt(0)
	v_add_f32_e32 v98, v103, v106
	s_nop 0
	s_nop 0
	v_mov_b32_dpp v99, v98 row_mirror row_mask:0xf bank_mask:0xf
	v_mad_i64_i32 v[100:101], s[0:1], v102, s66, v[180:181]
	global_store_dwordx2 v[100:101], v[104:105], off
	s_and_saveexec_b64 s[0:1], s[8:9]
	s_cbranch_execz .LBB0_535
	v_ashrrev_i32_e32 v103, 31, v102
	s_waitcnt lgkmcnt(0)
	v_add_f32_e32 v100, v98, v99
	v_lshl_add_u64 v[98:99], v[102:103], 2, s[62:63]
	global_atomic_add_f32 v[98:99], v100, off

; DI unsigned pack_bf16(float lo, float hi) { f32x2 v = {lo, hi}; bf16v2 b = __builtin_convertvector(v, bf16v2); return __builtin_bit_cast(unsigned, b); }
; DI float red16(float v) { v += __shfl_xor(v, 1); v += __shfl_xor(v, 2); v += __shfl_xor(v, 4); v += __shfl_xor(v, 8); return v; }
;   DI void run8(f32x4 (&acc)[8][4], int rb, int cb, int fr, int fq) const {
;     ...
;       for (int mm = 0; mm < 4; ++mm) {
;         const int m = mh * 4 + mm;
; #pragma unroll
;         for (int n = 0; n < 4; ++n)
; #pragma unroll
;           for (int j = 0; j < 4; ++j) scr[(fq * 4 + j) * 68 + n * 16 + fr] = acc[m][n][j];
;         __builtin_amdgcn_sched_barrier(0);
; #pragma unroll
;         for (int ps = 0; ps < 4; ++ps) {
;           const f32x4 a = *(const f32x4*)(scr + (ps * 4 + prow) * 68 + c4 * 4);
;           f32x4 v;
;           v.x = xv[mm][ps].x + a.x * sc; v.y = xv[mm][ps].y + a.y * sc; v.z = xv[mm][ps].z + a.z * sc; v.w = xv[mm][ps].w + a.w * sc;
;           const int grow = rb + m * 16 + ps * 4 + prow;
;           __builtin_nontemporal_store(v, (f32x4*)(op + (size_t)(m * 16 + ps * 4) * D));
;           if (xbp) {
;             u32x2 o; o.x = pack_bf16(v.x, v.y); o.y = pack_bf16(v.z, v.w);
;             *(u32x2*)(xbp + (size_t)grow * LDH + cb + c4 * 4) = o;
;             const float t = red16(v.x * v.x + v.y * v.y + v.z * v.z + v.w * v.w);
;             if (c4 == 0) atomicAdd(ssqp + grow, t);
;           }
.LBB0_536:
	ds_write2_b32 v186, v82, v86 offset1:16
	ds_write2_b32 v186, v83, v87 offset0:68 offset1:84
	ds_write2_b32 v186, v84, v88 offset0:136 offset1:152
	ds_write2_b32 v186, v85, v89 offset0:204 offset1:220
	ds_write2_b32 v186, v74, v78 offset0:32 offset1:48
	ds_write2_b32 v186, v75, v79 offset0:100 offset1:116
	ds_write2_b32 v186, v76, v80 offset0:168 offset1:184
	ds_write2_b32 v186, v77, v81 offset0:236 offset1:252
	ds_read_b128 v[74:77], v0
	v_add_co_u32_e32 v78, vcc, 0x30000, v182
	s_waitcnt vmcnt(15) lgkmcnt(0)
	v_pk_fma_f32 v[74:75], v[74:75], 0.5, v[94:95] op_sel_hi:[1,0,1]
	v_addc_co_u32_e32 v79, vcc, 0, v183, vcc
	v_pk_fma_f32 v[76:77], v[76:77], 0.5, v[96:97] op_sel_hi:[1,0,1]
	s_and_b64 vcc, exec, s[10:11]
	global_store_dwordx4 v[78:79], v[74:77], off nt
	s_cbranch_vccnz .LBB0_540
	v_pk_mul_f32 v[78:79], v[74:75], v[74:75]
	v_pk_mul_f32 v[80:81], v[76:77], v[76:77]
	v_add_f32_e32 v78, v78, v79
	v_add_f32_e32 v78, v80, v78
	v_and_b32_e32 v80, 64, v219
	v_add_f32_e32 v78, v81, v78
	s_nop 0
	v_add_u32_e32 v81, 64, v80
	s_nop 0
	v_cvt_pk_bf16_f32 v80, v74, v75
	v_xor_b32_e32 v75, 8, v219
	s_nop 0
	s_nop 0
	v_mov_b32_dpp v79, v78 quad_perm:[1,0,3,2] row_mask:0xf bank_mask:0xf
	s_waitcnt lgkmcnt(0)
	v_add_f32_e32 v78, v78, v79
	s_nop 0
	s_nop 0
	s_nop 1
	s_nop 0
	s_nop 0
	v_mov_b32_dpp v79, v78 quad_perm:[2,3,0,1] row_mask:0xf bank_mask:0xf
	s_waitcnt lgkmcnt(0)
	v_add_f32_e32 v79, v78, v79
	s_nop 0
	s_nop 0
	s_nop 1
	s_nop 0
	s_nop 0
	v_mov_b32_dpp v82, v79 row_half_mirror row_mask:0xf bank_mask:0xf
	v_cmp_lt_i32_e32 vcc, v75, v81
	v_or_b32_e32 v78, 48, v178
	v_cvt_pk_bf16_f32 v81, v76, v77
	s_nop 0
	s_waitcnt lgkmcnt(0)
	v_add_f32_e32 v74, v79, v82
	s_nop 0
	s_nop 0
	v_mov_b32_dpp v75, v74 row_mirror row_mask:0xf bank_mask:0xf
	v_mad_i64_i32 v[76:77], s[0:1], v78, s66, v[180:181]
	global_store_dwordx2 v[76:77], v[80:81], off
	s_and_saveexec_b64 s[0:1], s[8:9]
	s_cbranch_execz .LBB0_539
	v_ashrrev_i32_e32 v79, 31, v78
	s_waitcnt lgkmcnt(0)
	v_add_f32_e32 v76, v74, v75
	v_lshl_add_u64 v[74:75], v[78:79], 2, s[62:63]
	global_atomic_add_f32 v[74:75], v76, off

; DI unsigned pack_bf16(float lo, float hi) { f32x2 v = {lo, hi}; bf16v2 b = __builtin_convertvector(v, bf16v2); return __builtin_bit_cast(unsigned, b); }
; DI float red16(float v) { v += __shfl_xor(v, 1); v += __shfl_xor(v, 2); v += __shfl_xor(v, 4); v += __shfl_xor(v, 8); return v; }
;   DI void run8(f32x4 (&acc)[8][4], int rb, int cb, int fr, int fq) const {
;     ...
;         for (int ps = 0; ps < 4; ++ps) {
;           const f32x4 a = *(const f32x4*)(scr + (ps * 4 + prow) * 68 + c4 * 4);
;           f32x4 v;
;           v.x = xv[mm][ps].x + a.x * sc; v.y = xv[mm][ps].y + a.y * sc; v.z = xv[mm][ps].z + a.z * sc; v.w = xv[mm][ps].w + a.w * sc;
;           const int grow = rb + m * 16 + ps * 4 + prow;
;           __builtin_nontemporal_store(v, (f32x4*)(op + (size_t)(m * 16 + ps * 4) * D));
;           if (xbp) {
;             u32x2 o; o.x = pack_bf16(v.x, v.y); o.y = pack_bf16(v.z, v.w);
;             *(u32x2*)(xbp + (size_t)grow * LDH + cb + c4 * 4) = o;
;             const float t = red16(v.x * v.x + v.y * v.y + v.z * v.z + v.w * v.w);
;             if (c4 == 0) atomicAdd(ssqp + grow, t);
;           }
.LBB0_540:
	s_waitcnt lgkmcnt(0)
	ds_read_b128 v[74:77], v0 offset:1088
	v_add_co_u32_e32 v78, vcc, 0x34000, v182
	s_waitcnt vmcnt(15) lgkmcnt(0)
	v_pk_fma_f32 v[74:75], v[74:75], 0.5, v[90:91] op_sel_hi:[1,0,1]
	v_addc_co_u32_e32 v79, vcc, 0, v183, vcc
	v_pk_fma_f32 v[76:77], v[76:77], 0.5, v[92:93] op_sel_hi:[1,0,1]
	s_and_b64 vcc, exec, s[10:11]
	global_store_dwordx4 v[78:79], v[74:77], off nt
	s_cbranch_vccnz .LBB0_544
	v_pk_mul_f32 v[78:79], v[74:75], v[74:75]
	v_pk_mul_f32 v[80:81], v[76:77], v[76:77]
	v_add_f32_e32 v78, v78, v79
	v_add_f32_e32 v78, v80, v78
	v_and_b32_e32 v80, 64, v219
	v_add_f32_e32 v78, v81, v78
	s_nop 0
	v_add_u32_e32 v81, 64, v80
	s_nop 0
	v_cvt_pk_bf16_f32 v80, v74, v75
	v_xor_b32_e32 v75, 8, v219
	s_nop 0
	s_nop 0
	v_mov_b32_dpp v79, v78 quad_perm:[1,0,3,2] row_mask:0xf bank_mask:0xf
	s_waitcnt lgkmcnt(0)
	v_add_f32_e32 v78, v78, v79
	s_nop 0
	s_nop 0
	s_nop 1
	s_nop 0
	s_nop 0
	v_mov_b32_dpp v79, v78 quad_perm:[2,3,0,1] row_mask:0xf bank_mask:0xf
	s_waitcnt lgkmcnt(0)
	v_add_f32_e32 v79, v78, v79
	s_nop 0
	s_nop 0
	s_nop 1
	s_nop 0
	s_nop 0
	v_mov_b32_dpp v82, v79 row_half_mirror row_mask:0xf bank_mask:0xf
	v_cmp_lt_i32_e32 vcc, v75, v81
	v_or_b32_e32 v78, 52, v178
	v_cvt_pk_bf16_f32 v81, v76, v77
	s_nop 0
	s_waitcnt lgkmcnt(0)
	v_add_f32_e32 v74, v79, v82
	s_nop 0
	s_nop 0
	v_mov_b32_dpp v75, v74 row_mirror row_mask:0xf bank_mask:0xf
	v_mad_i64_i32 v[76:77], s[0:1], v78, s66, v[180:181]
	global_store_dwordx2 v[76:77], v[80:81], off
	s_and_saveexec_b64 s[0:1], s[8:9]
	s_cbranch_execz .LBB0_543
	v_ashrrev_i32_e32 v79, 31, v78
	s_waitcnt lgkmcnt(0)
	v_add_f32_e32 v76, v74, v75
	v_lshl_add_u64 v[74:75], v[78:79], 2, s[62:63]
	global_atomic_add_f32 v[74:75], v76, off

; DI unsigned pack_bf16(float lo, float hi) { f32x2 v = {lo, hi}; bf16v2 b = __builtin_convertvector(v, bf16v2); return __builtin_bit_cast(unsigned, b); }
; DI float red16(float v) { v += __shfl_xor(v, 1); v += __shfl_xor(v, 2); v += __shfl_xor(v, 4); v += __shfl_xor(v, 8); return v; }
;   DI void run8(f32x4 (&acc)[8][4], int rb, int cb, int fr, int fq) const {
;     ...
;         for (int ps = 0; ps < 4; ++ps) {
;           const f32x4 a = *(const f32x4*)(scr + (ps * 4 + prow) * 68 + c4 * 4);
;           f32x4 v;
;           v.x = xv[mm][ps].x + a.x * sc; v.y = xv[mm][ps].y + a.y * sc; v.z = xv[mm][ps].z + a.z * sc; v.w = xv[mm][ps].w + a.w * sc;
;           const int grow = rb + m * 16 + ps * 4 + prow;
;           __builtin_nontemporal_store(v, (f32x4*)(op + (size_t)(m * 16 + ps * 4) * D));
;           if (xbp) {
;             u32x2 o; o.x = pack_bf16(v.x, v.y); o.y = pack_bf16(v.z, v.w);
;             *(u32x2*)(xbp + (size_t)grow * LDH + cb + c4 * 4) = o;
;             const float t = red16(v.x * v.x + v.y * v.y + v.z * v.z + v.w * v.w);
;             if (c4 == 0) atomicAdd(ssqp + grow, t);
;           }
.LBB0_544:
	s_waitcnt lgkmcnt(0)
	ds_read_b128 v[74:77], v0 offset:2176
	s_waitcnt vmcnt(15) lgkmcnt(0)
	v_pk_fma_f32 v[70:71], v[74:75], 0.5, v[70:71] op_sel_hi:[1,0,1]
	v_add_co_u32_e32 v74, vcc, 0x38000, v182
	v_pk_fma_f32 v[72:73], v[76:77], 0.5, v[72:73] op_sel_hi:[1,0,1]
	s_nop 0
	v_addc_co_u32_e32 v75, vcc, 0, v183, vcc
	s_and_b64 vcc, exec, s[10:11]
	global_store_dwordx4 v[74:75], v[70:73], off nt
	s_cbranch_vccnz .LBB0_548
	v_pk_mul_f32 v[74:75], v[70:71], v[70:71]
	v_pk_mul_f32 v[76:77], v[72:73], v[72:73]
	v_add_f32_e32 v74, v74, v75
	v_add_f32_e32 v74, v76, v74
	v_and_b32_e32 v76, 64, v219
	v_add_f32_e32 v74, v77, v74
	s_nop 0
	v_add_u32_e32 v77, 64, v76
	s_nop 0
	v_cvt_pk_bf16_f32 v76, v70, v71
	v_xor_b32_e32 v71, 8, v219
	s_nop 0
	s_nop 0
	v_mov_b32_dpp v75, v74 quad_perm:[1,0,3,2] row_mask:0xf bank_mask:0xf
	s_waitcnt lgkmcnt(0)
	v_add_f32_e32 v74, v74, v75
	s_nop 0
	s_nop 0
	s_nop 1
	s_nop 0
	s_nop 0
	v_mov_b32_dpp v75, v74 quad_perm:[2,3,0,1] row_mask:0xf bank_mask:0xf
	s_waitcnt lgkmcnt(0)
	v_add_f32_e32 v75, v74, v75
	s_nop 0
	s_nop 0
	s_nop 1
	s_nop 0
	s_nop 0
	v_mov_b32_dpp v78, v75 row_half_mirror row_mask:0xf bank_mask:0xf
	v_cmp_lt_i32_e32 vcc, v71, v77
	v_or_b32_e32 v74, 56, v178
	v_cvt_pk_bf16_f32 v77, v72, v73
	s_nop 0
	s_waitcnt lgkmcnt(0)
	v_add_f32_e32 v70, v75, v78
	s_nop 0
	s_nop 0
	v_mov_b32_dpp v71, v70 row_mirror row_mask:0xf bank_mask:0xf
	v_mad_i64_i32 v[72:73], s[0:1], v74, s66, v[180:181]
	global_store_dwordx2 v[72:73], v[76:77], off
	s_and_saveexec_b64 s[0:1], s[8:9]
	s_cbranch_execz .LBB0_547
	v_ashrrev_i32_e32 v75, 31, v74
	s_waitcnt lgkmcnt(0)
	v_add_f32_e32 v72, v70, v71
	v_lshl_add_u64 v[70:71], v[74:75], 2, s[62:63]
	global_atomic_add_f32 v[70:71], v72, off

; DI unsigned pack_bf16(float lo, float hi) { f32x2 v = {lo, hi}; bf16v2 b = __builtin_convertvector(v, bf16v2); return __builtin_bit_cast(unsigned, b); }
; DI float red16(float v) { v += __shfl_xor(v, 1); v += __shfl_xor(v, 2); v += __shfl_xor(v, 4); v += __shfl_xor(v, 8); return v; }
;   DI void run8(f32x4 (&acc)[8][4], int rb, int cb, int fr, int fq) const {
;     ...
;         for (int ps = 0; ps < 4; ++ps) {
;           const f32x4 a = *(const f32x4*)(scr + (ps * 4 + prow) * 68 + c4 * 4);
;           f32x4 v;
;           v.x = xv[mm][ps].x + a.x * sc; v.y = xv[mm][ps].y + a.y * sc; v.z = xv[mm][ps].z + a.z * sc; v.w = xv[mm][ps].w + a.w * sc;
;           const int grow = rb + m * 16 + ps * 4 + prow;
;           __builtin_nontemporal_store(v, (f32x4*)(op + (size_t)(m * 16 + ps * 4) * D));
;           if (xbp) {
;             u32x2 o; o.x = pack_bf16(v.x, v.y); o.y = pack_bf16(v.z, v.w);
;             *(u32x2*)(xbp + (size_t)grow * LDH + cb + c4 * 4) = o;
;             const float t = red16(v.x * v.x + v.y * v.y + v.z * v.z + v.w * v.w);
;             if (c4 == 0) atomicAdd(ssqp + grow, t);
;           }
.LBB0_548:
	s_waitcnt lgkmcnt(0)
	ds_read_b128 v[70:73], v0 offset:3264
	s_waitcnt vmcnt(15) lgkmcnt(0)
	v_pk_fma_f32 v[66:67], v[70:71], 0.5, v[66:67] op_sel_hi:[1,0,1]
	v_add_co_u32_e32 v70, vcc, 0x3c000, v182
	v_pk_fma_f32 v[68:69], v[72:73], 0.5, v[68:69] op_sel_hi:[1,0,1]
	s_nop 0
	v_addc_co_u32_e32 v71, vcc, 0, v183, vcc
	s_and_b64 vcc, exec, s[10:11]
	global_store_dwordx4 v[70:71], v[66:69], off nt
	s_cbranch_vccnz .LBB0_552
	v_pk_mul_f32 v[70:71], v[66:67], v[66:67]
	v_pk_mul_f32 v[72:73], v[68:69], v[68:69]
	v_add_f32_e32 v70, v70, v71
	v_add_f32_e32 v70, v72, v70
	v_and_b32_e32 v72, 64, v219
	v_add_f32_e32 v70, v73, v70
	s_nop 0
	v_add_u32_e32 v73, 64, v72
	s_nop 0
	v_cvt_pk_bf16_f32 v72, v66, v67
	v_xor_b32_e32 v67, 8, v219
	s_nop 0
	s_nop 0
	v_mov_b32_dpp v71, v70 quad_perm:[1,0,3,2] row_mask:0xf bank_mask:0xf
	s_waitcnt lgkmcnt(0)
	v_add_f32_e32 v70, v70, v71
	s_nop 0
	s_nop 0
	s_nop 1
	s_nop 0
	s_nop 0
	v_mov_b32_dpp v71, v70 quad_perm:[2,3,0,1] row_mask:0xf bank_mask:0xf
	s_waitcnt lgkmcnt(0)
	v_add_f32_e32 v71, v70, v71
	s_nop 0
	s_nop 0
	s_nop 1
	s_nop 0
	s_nop 0
	v_mov_b32_dpp v74, v71 row_half_mirror row_mask:0xf bank_mask:0xf
	v_cmp_lt_i32_e32 vcc, v67, v73
	v_or_b32_e32 v70, 60, v178
	v_cvt_pk_bf16_f32 v73, v68, v69
	s_nop 0
	s_waitcnt lgkmcnt(0)
	v_add_f32_e32 v66, v71, v74
	s_nop 0
	s_nop 0
	v_mov_b32_dpp v67, v66 row_mirror row_mask:0xf bank_mask:0xf
	v_mad_i64_i32 v[68:69], s[0:1], v70, s66, v[180:181]
	global_store_dwordx2 v[68:69], v[72:73], off
	s_and_saveexec_b64 s[0:1], s[8:9]
	s_cbranch_execz .LBB0_551
	v_ashrrev_i32_e32 v71, 31, v70
	s_waitcnt lgkmcnt(0)
	v_add_f32_e32 v68, v66, v67
	v_lshl_add_u64 v[66:67], v[70:71], 2, s[62:63]
	global_atomic_add_f32 v[66:67], v68, off

; DI unsigned pack_bf16(float lo, float hi) { f32x2 v = {lo, hi}; bf16v2 b = __builtin_convertvector(v, bf16v2); return __builtin_bit_cast(unsigned, b); }
; DI float red16(float v) { v += __shfl_xor(v, 1); v += __shfl_xor(v, 2); v += __shfl_xor(v, 4); v += __shfl_xor(v, 8); return v; }
;   DI void run8(f32x4 (&acc)[8][4], int rb, int cb, int fr, int fq) const {
;     ...
;         for (int ps = 0; ps < 4; ++ps) xv[mm][ps] = __builtin_nontemporal_load((const f32x4*)(xp + (size_t)((mh * 4 + mm) * 16 + ps * 4) * D));
;       __builtin_amdgcn_sched_barrier(0);
; #pragma unroll
;       for (int mm = 0; mm < 4; ++mm) {
;         const int m = mh * 4 + mm;
; #pragma unroll
;         for (int n = 0; n < 4; ++n)
; #pragma unroll
;           for (int j = 0; j < 4; ++j) scr[(fq * 4 + j) * 68 + n * 16 + fr] = acc[m][n][j];
;         __builtin_amdgcn_sched_barrier(0);
; #pragma unroll
;         for (int ps = 0; ps < 4; ++ps) {
;           const f32x4 a = *(const f32x4*)(scr + (ps * 4 + prow) * 68 + c4 * 4);
;           f32x4 v;
;           v.x = xv[mm][ps].x + a.x * sc; v.y = xv[mm][ps].y + a.y * sc; v.z = xv[mm][ps].z + a.z * sc; v.w = xv[mm][ps].w + a.w * sc;
;           const int grow = rb + m * 16 + ps * 4 + prow;
;           __builtin_nontemporal_store(v, (f32x4*)(op + (size_t)(m * 16 + ps * 4) * D));
;           if (xbp) {
;             u32x2 o; o.x = pack_bf16(v.x, v.y); o.y = pack_bf16(v.z, v.w);
;             *(u32x2*)(xbp + (size_t)grow * LDH + cb + c4 * 4) = o;
;             const float t = red16(v.x * v.x + v.y * v.y + v.z * v.z + v.w * v.w);
;             if (c4 == 0) atomicAdd(ssqp + grow, t);
;           }
.LBB0_552:
	s_nop 0
	v_add_co_u32_e32 v66, vcc, 0x40000, v184
	s_waitcnt lgkmcnt(0)
	s_nop 0
	v_addc_co_u32_e32 v67, vcc, 0, v185, vcc
	v_add_co_u32_e32 v68, vcc, 0x44000, v184
	s_nop 1
	v_addc_co_u32_e32 v69, vcc, 0, v185, vcc
	global_load_dwordx4 v[126:129], v[66:67], off nt
	global_load_dwordx4 v[122:125], v[68:69], off nt
	v_add_co_u32_e32 v66, vcc, 0x48000, v184
	s_nop 1
	v_addc_co_u32_e32 v67, vcc, 0, v185, vcc
	v_add_co_u32_e32 v68, vcc, 0x4c000, v184
	s_nop 1
	v_addc_co_u32_e32 v69, vcc, 0, v185, vcc
	global_load_dwordx4 v[118:121], v[66:67], off nt
	global_load_dwordx4 v[114:117], v[68:69], off nt
	v_add_co_u32_e32 v66, vcc, 0x50000, v184
	s_nop 1
	v_addc_co_u32_e32 v67, vcc, 0, v185, vcc
	v_add_co_u32_e32 v68, vcc, 0x54000, v184
	s_nop 1
	v_addc_co_u32_e32 v69, vcc, 0, v185, vcc
	global_load_dwordx4 v[110:113], v[66:67], off nt
	global_load_dwordx4 v[106:109], v[68:69], off nt
	v_add_co_u32_e32 v66, vcc, 0x58000, v184
	s_nop 1
	v_addc_co_u32_e32 v67, vcc, 0, v185, vcc
	v_add_co_u32_e32 v68, vcc, 0x5c000, v184
	s_nop 1
	v_addc_co_u32_e32 v69, vcc, 0, v185, vcc
	global_load_dwordx4 v[102:105], v[66:67], off nt
	global_load_dwordx4 v[98:101], v[68:69], off nt
	v_add_co_u32_e32 v66, vcc, 0x60000, v184
	s_nop 1
	v_addc_co_u32_e32 v67, vcc, 0, v185, vcc
	v_add_co_u32_e32 v68, vcc, 0x64000, v184
	s_nop 1
	v_addc_co_u32_e32 v69, vcc, 0, v185, vcc
	global_load_dwordx4 v[94:97], v[66:67], off nt
	global_load_dwordx4 v[90:93], v[68:69], off nt
	v_add_co_u32_e32 v66, vcc, 0x68000, v184
	s_nop 1
	v_addc_co_u32_e32 v67, vcc, 0, v185, vcc
	v_add_co_u32_e32 v68, vcc, 0x6c000, v184
	s_nop 1
	v_addc_co_u32_e32 v69, vcc, 0, v185, vcc
	global_load_dwordx4 v[86:89], v[66:67], off nt
	global_load_dwordx4 v[82:85], v[68:69], off nt
	v_add_co_u32_e32 v66, vcc, s68, v184
	s_nop 1
	v_addc_co_u32_e32 v67, vcc, 0, v185, vcc
	v_add_co_u32_e32 v68, vcc, 0x74000, v184
	s_nop 1
	v_addc_co_u32_e32 v69, vcc, 0, v185, vcc
	global_load_dwordx4 v[78:81], v[66:67], off nt
	global_load_dwordx4 v[74:77], v[68:69], off nt
	v_add_co_u32_e32 v66, vcc, 0x78000, v184
	s_nop 1
	v_addc_co_u32_e32 v67, vcc, 0, v185, vcc
	v_add_co_u32_e32 v68, vcc, 0x7c000, v184
	s_nop 1
	v_addc_co_u32_e32 v69, vcc, 0, v185, vcc
	global_load_dwordx4 v[70:73], v[66:67], off nt
	s_nop 0
	global_load_dwordx4 v[66:69], v[68:69], off nt
	ds_write2_b32 v186, v58, v62 offset1:16
	ds_write2_b32 v186, v59, v63 offset0:68 offset1:84
	ds_write2_b32 v186, v60, v64 offset0:136 offset1:152
	ds_write2_b32 v186, v61, v65 offset0:204 offset1:220
	ds_write2_b32 v186, v50, v54 offset0:32 offset1:48
	ds_write2_b32 v186, v51, v55 offset0:100 offset1:116
	ds_write2_b32 v186, v52, v56 offset0:168 offset1:184
	ds_write2_b32 v186, v53, v57 offset0:236 offset1:252
	ds_read_b128 v[50:53], v0
	v_add_co_u32_e32 v54, vcc, 0x40000, v182
	s_waitcnt vmcnt(15) lgkmcnt(0)
	v_pk_fma_f32 v[50:51], v[50:51], 0.5, v[126:127] op_sel_hi:[1,0,1]
	v_addc_co_u32_e32 v55, vcc, 0, v183, vcc
	v_pk_fma_f32 v[52:53], v[52:53], 0.5, v[128:129] op_sel_hi:[1,0,1]
	s_and_b64 vcc, exec, s[10:11]
	global_store_dwordx4 v[54:55], v[50:53], off nt
	s_cbranch_vccnz .LBB0_556
	v_pk_mul_f32 v[54:55], v[50:51], v[50:51]
	v_pk_mul_f32 v[56:57], v[52:53], v[52:53]
	v_add_f32_e32 v54, v54, v55
	v_add_f32_e32 v54, v56, v54
	v_and_b32_e32 v56, 64, v219
	v_add_f32_e32 v54, v57, v54
	s_nop 0
	v_add_u32_e32 v57, 64, v56
	s_nop 0
	v_cvt_pk_bf16_f32 v56, v50, v51
	v_xor_b32_e32 v51, 8, v219
	s_nop 0
	s_nop 0
	v_mov_b32_dpp v55, v54 quad_perm:[1,0,3,2] row_mask:0xf bank_mask:0xf
	s_waitcnt lgkmcnt(0)
	v_add_f32_e32 v54, v54, v55
	s_nop 0
	s_nop 0
	s_nop 1
	s_nop 0
	s_nop 0
	v_mov_b32_dpp v55, v54 quad_perm:[2,3,0,1] row_mask:0xf bank_mask:0xf
	s_waitcnt lgkmcnt(0)
	v_add_f32_e32 v55, v54, v55
	s_nop 0
	s_nop 0
	s_nop 1
	s_nop 0
	s_nop 0
	v_mov_b32_dpp v58, v55 row_half_mirror row_mask:0xf bank_mask:0xf
	v_cmp_lt_i32_e32 vcc, v51, v57
	v_or_b32_e32 v54, 64, v178
	v_cvt_pk_bf16_f32 v57, v52, v53
	s_nop 0
	s_waitcnt lgkmcnt(0)
	v_add_f32_e32 v50, v55, v58
	s_nop 0
	s_nop 0
	v_mov_b32_dpp v51, v50 row_mirror row_mask:0xf bank_mask:0xf
	v_mad_i64_i32 v[52:53], s[0:1], v54, s66, v[180:181]
	global_store_dwordx2 v[52:53], v[56:57], off
	s_and_saveexec_b64 s[0:1], s[8:9]
	s_cbranch_execz .LBB0_555
	v_ashrrev_i32_e32 v55, 31, v54
	s_waitcnt lgkmcnt(0)
	v_add_f32_e32 v52, v50, v51
	v_lshl_add_u64 v[50:51], v[54:55], 2, s[62:63]
	global_atomic_add_f32 v[50:51], v52, off

; DI unsigned pack_bf16(float lo, float hi) { f32x2 v = {lo, hi}; bf16v2 b = __builtin_convertvector(v, bf16v2); return __builtin_bit_cast(unsigned, b); }
; DI float red16(float v) { v += __shfl_xor(v, 1); v += __shfl_xor(v, 2); v += __shfl_xor(v, 4); v += __shfl_xor(v, 8); return v; }
;   DI void run8(f32x4 (&acc)[8][4], int rb, int cb, int fr, int fq) const {
;     ...
;         for (int ps = 0; ps < 4; ++ps) {
;           const f32x4 a = *(const f32x4*)(scr + (ps * 4 + prow) * 68 + c4 * 4);
;           f32x4 v;
;           v.x = xv[mm][ps].x + a.x * sc; v.y = xv[mm][ps].y + a.y * sc; v.z = xv[mm][ps].z + a.z * sc; v.w = xv[mm][ps].w + a.w * sc;
;           const int grow = rb + m * 16 + ps * 4 + prow;
;           __builtin_nontemporal_store(v, (f32x4*)(op + (size_t)(m * 16 + ps * 4) * D));
;           if (xbp) {
;             u32x2 o; o.x = pack_bf16(v.x, v.y); o.y = pack_bf16(v.z, v.w);
;             *(u32x2*)(xbp + (size_t)grow * LDH + cb + c4 * 4) = o;
;             const float t = red16(v.x * v.x + v.y * v.y + v.z * v.z + v.w * v.w);
;             if (c4 == 0) atomicAdd(ssqp + grow, t);
;           }
.LBB0_556:
	s_waitcnt lgkmcnt(0)
	ds_read_b128 v[50:53], v0 offset:1088
	v_add_co_u32_e32 v54, vcc, 0x44000, v182
	s_waitcnt vmcnt(15) lgkmcnt(0)
	v_pk_fma_f32 v[50:51], v[50:51], 0.5, v[122:123] op_sel_hi:[1,0,1]
	v_addc_co_u32_e32 v55, vcc, 0, v183, vcc
	v_pk_fma_f32 v[52:53], v[52:53], 0.5, v[124:125] op_sel_hi:[1,0,1]
	s_and_b64 vcc, exec, s[10:11]
	global_store_dwordx4 v[54:55], v[50:53], off nt
	s_cbranch_vccnz .LBB0_560
	v_pk_mul_f32 v[54:55], v[50:51], v[50:51]
	v_pk_mul_f32 v[56:57], v[52:53], v[52:53]
	v_add_f32_e32 v54, v54, v55
	v_add_f32_e32 v54, v56, v54
	v_and_b32_e32 v56, 64, v219
	v_add_f32_e32 v54, v57, v54
	s_nop 0
	v_add_u32_e32 v57, 64, v56
	s_nop 0
	v_cvt_pk_bf16_f32 v56, v50, v51
	v_xor_b32_e32 v51, 8, v219
	s_nop 0
	s_nop 0
	v_mov_b32_dpp v55, v54 quad_perm:[1,0,3,2] row_mask:0xf bank_mask:0xf
	s_waitcnt lgkmcnt(0)
	v_add_f32_e32 v54, v54, v55
	s_nop 0
	s_nop 0
	s_nop 1
	s_nop 0
	s_nop 0
	v_mov_b32_dpp v55, v54 quad_perm:[2,3,0,1] row_mask:0xf bank_mask:0xf
	s_waitcnt lgkmcnt(0)
	v_add_f32_e32 v55, v54, v55
	s_nop 0
	s_nop 0
	s_nop 1
	s_nop 0
	s_nop 0
	v_mov_b32_dpp v58, v55 row_half_mirror row_mask:0xf bank_mask:0xf
	v_cmp_lt_i32_e32 vcc, v51, v57
	v_or_b32_e32 v54, 0x44, v178
	v_cvt_pk_bf16_f32 v57, v52, v53
	s_nop 0
	s_waitcnt lgkmcnt(0)
	v_add_f32_e32 v50, v55, v58
	s_nop 0
	s_nop 0
	v_mov_b32_dpp v51, v50 row_mirror row_mask:0xf bank_mask:0xf
	v_mad_i64_i32 v[52:53], s[0:1], v54, s66, v[180:181]
	global_store_dwordx2 v[52:53], v[56:57], off
	s_and_saveexec_b64 s[0:1], s[8:9]
	s_cbranch_execz .LBB0_559
	v_ashrrev_i32_e32 v55, 31, v54
	s_waitcnt lgkmcnt(0)
	v_add_f32_e32 v52, v50, v51
	v_lshl_add_u64 v[50:51], v[54:55], 2, s[62:63]
	global_atomic_add_f32 v[50:51], v52, off

; DI unsigned pack_bf16(float lo, float hi) { f32x2 v = {lo, hi}; bf16v2 b = __builtin_convertvector(v, bf16v2); return __builtin_bit_cast(unsigned, b); }
; DI float red16(float v) { v += __shfl_xor(v, 1); v += __shfl_xor(v, 2); v += __shfl_xor(v, 4); v += __shfl_xor(v, 8); return v; }
;   DI void run8(f32x4 (&acc)[8][4], int rb, int cb, int fr, int fq) const {
;     ...
;         for (int ps = 0; ps < 4; ++ps) {
;           const f32x4 a = *(const f32x4*)(scr + (ps * 4 + prow) * 68 + c4 * 4);
;           f32x4 v;
;           v.x = xv[mm][ps].x + a.x * sc; v.y = xv[mm][ps].y + a.y * sc; v.z = xv[mm][ps].z + a.z * sc; v.w = xv[mm][ps].w + a.w * sc;
;           const int grow = rb + m * 16 + ps * 4 + prow;
;           __builtin_nontemporal_store(v, (f32x4*)(op + (size_t)(m * 16 + ps * 4) * D));
;           if (xbp) {
;             u32x2 o; o.x = pack_bf16(v.x, v.y); o.y = pack_bf16(v.z, v.w);
;             *(u32x2*)(xbp + (size_t)grow * LDH + cb + c4 * 4) = o;
;             const float t = red16(v.x * v.x + v.y * v.y + v.z * v.z + v.w * v.w);
;             if (c4 == 0) atomicAdd(ssqp + grow, t);
;           }
.LBB0_560:
	s_waitcnt lgkmcnt(0)
	ds_read_b128 v[50:53], v0 offset:2176
	v_add_co_u32_e32 v54, vcc, 0x48000, v182
	s_waitcnt vmcnt(15) lgkmcnt(0)
	v_pk_fma_f32 v[50:51], v[50:51], 0.5, v[118:119] op_sel_hi:[1,0,1]
	v_addc_co_u32_e32 v55, vcc, 0, v183, vcc
	v_pk_fma_f32 v[52:53], v[52:53], 0.5, v[120:121] op_sel_hi:[1,0,1]
	s_and_b64 vcc, exec, s[10:11]
	global_store_dwordx4 v[54:55], v[50:53], off nt
	s_cbranch_vccnz .LBB0_564
	v_pk_mul_f32 v[54:55], v[50:51], v[50:51]
	v_pk_mul_f32 v[56:57], v[52:53], v[52:53]
	v_add_f32_e32 v54, v54, v55
	v_add_f32_e32 v54, v56, v54
	v_and_b32_e32 v56, 64, v219
	v_add_f32_e32 v54, v57, v54
	s_nop 0
	v_add_u32_e32 v57, 64, v56
	s_nop 0
	v_cvt_pk_bf16_f32 v56, v50, v51
	v_xor_b32_e32 v51, 8, v219
	s_nop 0
	s_nop 0
	v_mov_b32_dpp v55, v54 quad_perm:[1,0,3,2] row_mask:0xf bank_mask:0xf
	s_waitcnt lgkmcnt(0)
	v_add_f32_e32 v54, v54, v55
	s_nop 0
	s_nop 0
	s_nop 1
	s_nop 0
	s_nop 0
	v_mov_b32_dpp v55, v54 quad_perm:[2,3,0,1] row_mask:0xf bank_mask:0xf
	s_waitcnt lgkmcnt(0)
	v_add_f32_e32 v55, v54, v55
	s_nop 0
	s_nop 0
	s_nop 1
	s_nop 0
	s_nop 0
	v_mov_b32_dpp v58, v55 row_half_mirror row_mask:0xf bank_mask:0xf
	v_cmp_lt_i32_e32 vcc, v51, v57
	v_or_b32_e32 v54, 0x48, v178
	v_cvt_pk_bf16_f32 v57, v52, v53
	s_nop 0
	s_waitcnt lgkmcnt(0)
	v_add_f32_e32 v50, v55, v58
	s_nop 0
	s_nop 0
	v_mov_b32_dpp v51, v50 row_mirror row_mask:0xf bank_mask:0xf
	v_mad_i64_i32 v[52:53], s[0:1], v54, s66, v[180:181]
	global_store_dwordx2 v[52:53], v[56:57], off
	s_and_saveexec_b64 s[0:1], s[8:9]
	s_cbranch_execz .LBB0_563
	v_ashrrev_i32_e32 v55, 31, v54
	s_waitcnt lgkmcnt(0)
	v_add_f32_e32 v52, v50, v51
	v_lshl_add_u64 v[50:51], v[54:55], 2, s[62:63]
	global_atomic_add_f32 v[50:51], v52, off

; DI unsigned pack_bf16(float lo, float hi) { f32x2 v = {lo, hi}; bf16v2 b = __builtin_convertvector(v, bf16v2); return __builtin_bit_cast(unsigned, b); }
; DI float red16(float v) { v += __shfl_xor(v, 1); v += __shfl_xor(v, 2); v += __shfl_xor(v, 4); v += __shfl_xor(v, 8); return v; }
;   DI void run8(f32x4 (&acc)[8][4], int rb, int cb, int fr, int fq) const {
;     ...
;         for (int ps = 0; ps < 4; ++ps) {
;           const f32x4 a = *(const f32x4*)(scr + (ps * 4 + prow) * 68 + c4 * 4);
;           f32x4 v;
;           v.x = xv[mm][ps].x + a.x * sc; v.y = xv[mm][ps].y + a.y * sc; v.z = xv[mm][ps].z + a.z * sc; v.w = xv[mm][ps].w + a.w * sc;
;           const int grow = rb + m * 16 + ps * 4 + prow;
;           __builtin_nontemporal_store(v, (f32x4*)(op + (size_t)(m * 16 + ps * 4) * D));
;           if (xbp) {
;             u32x2 o; o.x = pack_bf16(v.x, v.y); o.y = pack_bf16(v.z, v.w);
;             *(u32x2*)(xbp + (size_t)grow * LDH + cb + c4 * 4) = o;
;             const float t = red16(v.x * v.x + v.y * v.y + v.z * v.z + v.w * v.w);
;             if (c4 == 0) atomicAdd(ssqp + grow, t);
;           }
.LBB0_564:
	s_waitcnt lgkmcnt(0)
	ds_read_b128 v[50:53], v0 offset:3264
	v_add_co_u32_e32 v54, vcc, 0x4c000, v182
	s_waitcnt vmcnt(15) lgkmcnt(0)
	v_pk_fma_f32 v[50:51], v[50:51], 0.5, v[114:115] op_sel_hi:[1,0,1]
	v_addc_co_u32_e32 v55, vcc, 0, v183, vcc
	v_pk_fma_f32 v[52:53], v[52:53], 0.5, v[116:117] op_sel_hi:[1,0,1]
	s_and_b64 vcc, exec, s[10:11]
	global_store_dwordx4 v[54:55], v[50:53], off nt
	s_cbranch_vccnz .LBB0_568
	v_pk_mul_f32 v[54:55], v[50:51], v[50:51]
	v_pk_mul_f32 v[56:57], v[52:53], v[52:53]
	v_add_f32_e32 v54, v54, v55
	v_add_f32_e32 v54, v56, v54
	v_and_b32_e32 v56, 64, v219
	v_add_f32_e32 v54, v57, v54
	s_nop 0
	v_add_u32_e32 v57, 64, v56
	s_nop 0
	v_cvt_pk_bf16_f32 v56, v50, v51
	v_xor_b32_e32 v51, 8, v219
	s_nop 0
	s_nop 0
	v_mov_b32_dpp v55, v54 quad_perm:[1,0,3,2] row_mask:0xf bank_mask:0xf
	s_waitcnt lgkmcnt(0)
	v_add_f32_e32 v54, v54, v55
	s_nop 0
	s_nop 0
	s_nop 1
	s_nop 0
	s_nop 0
	v_mov_b32_dpp v55, v54 quad_perm:[2,3,0,1] row_mask:0xf bank_mask:0xf
	s_waitcnt lgkmcnt(0)
	v_add_f32_e32 v55, v54, v55
	s_nop 0
	s_nop 0
	s_nop 1
	s_nop 0
	s_nop 0
	v_mov_b32_dpp v58, v55 row_half_mirror row_mask:0xf bank_mask:0xf
	v_cmp_lt_i32_e32 vcc, v51, v57
	v_or_b32_e32 v54, 0x4c, v178
	v_cvt_pk_bf16_f32 v57, v52, v53
	s_nop 0
	s_waitcnt lgkmcnt(0)
	v_add_f32_e32 v50, v55, v58
	s_nop 0
	s_nop 0
	v_mov_b32_dpp v51, v50 row_mirror row_mask:0xf bank_mask:0xf
	v_mad_i64_i32 v[52:53], s[0:1], v54, s66, v[180:181]
	global_store_dwordx2 v[52:53], v[56:57], off
	s_and_saveexec_b64 s[0:1], s[8:9]
	s_cbranch_execz .LBB0_567
	v_ashrrev_i32_e32 v55, 31, v54
	s_waitcnt lgkmcnt(0)
	v_add_f32_e32 v52, v50, v51
	v_lshl_add_u64 v[50:51], v[54:55], 2, s[62:63]
	global_atomic_add_f32 v[50:51], v52, off

; DI unsigned pack_bf16(float lo, float hi) { f32x2 v = {lo, hi}; bf16v2 b = __builtin_convertvector(v, bf16v2); return __builtin_bit_cast(unsigned, b); }
; DI float red16(float v) { v += __shfl_xor(v, 1); v += __shfl_xor(v, 2); v += __shfl_xor(v, 4); v += __shfl_xor(v, 8); return v; }
;   DI void run8(f32x4 (&acc)[8][4], int rb, int cb, int fr, int fq) const {
;     ...
;         for (int n = 0; n < 4; ++n)
; #pragma unroll
;           for (int j = 0; j < 4; ++j) scr[(fq * 4 + j) * 68 + n * 16 + fr] = acc[m][n][j];
;         __builtin_amdgcn_sched_barrier(0);
; #pragma unroll
;         for (int ps = 0; ps < 4; ++ps) {
;           const f32x4 a = *(const f32x4*)(scr + (ps * 4 + prow) * 68 + c4 * 4);
;           f32x4 v;
;           v.x = xv[mm][ps].x + a.x * sc; v.y = xv[mm][ps].y + a.y * sc; v.z = xv[mm][ps].z + a.z * sc; v.w = xv[mm][ps].w + a.w * sc;
;           const int grow = rb + m * 16 + ps * 4 + prow;
;           __builtin_nontemporal_store(v, (f32x4*)(op + (size_t)(m * 16 + ps * 4) * D));
;           if (xbp) {
;             u32x2 o; o.x = pack_bf16(v.x, v.y); o.y = pack_bf16(v.z, v.w);
;             *(u32x2*)(xbp + (size_t)grow * LDH + cb + c4 * 4) = o;
;             const float t = red16(v.x * v.x + v.y * v.y + v.z * v.z + v.w * v.w);
;             if (c4 == 0) atomicAdd(ssqp + grow, t);
;           }
.LBB0_568:
	ds_write2_b32 v186, v42, v46 offset1:16
	ds_write2_b32 v186, v43, v47 offset0:68 offset1:84
	ds_write2_b32 v186, v44, v48 offset0:136 offset1:152
	ds_write2_b32 v186, v45, v49 offset0:204 offset1:220
	ds_write2_b32 v186, v34, v38 offset0:32 offset1:48
	ds_write2_b32 v186, v35, v39 offset0:100 offset1:116
	ds_write2_b32 v186, v36, v40 offset0:168 offset1:184
	ds_write2_b32 v186, v37, v41 offset0:236 offset1:252
	ds_read_b128 v[34:37], v0
	v_add_co_u32_e32 v38, vcc, 0x50000, v182
	s_waitcnt vmcnt(15) lgkmcnt(0)
	v_pk_fma_f32 v[34:35], v[34:35], 0.5, v[110:111] op_sel_hi:[1,0,1]
	v_addc_co_u32_e32 v39, vcc, 0, v183, vcc
	v_pk_fma_f32 v[36:37], v[36:37], 0.5, v[112:113] op_sel_hi:[1,0,1]
	s_and_b64 vcc, exec, s[10:11]
	global_store_dwordx4 v[38:39], v[34:37], off nt
	s_cbranch_vccnz .LBB0_572
	v_pk_mul_f32 v[38:39], v[34:35], v[34:35]
	v_pk_mul_f32 v[40:41], v[36:37], v[36:37]
	v_add_f32_e32 v38, v38, v39
	v_add_f32_e32 v38, v40, v38
	v_and_b32_e32 v40, 64, v219
	v_add_f32_e32 v38, v41, v38
	s_nop 0
	v_add_u32_e32 v41, 64, v40
	s_nop 0
	v_cvt_pk_bf16_f32 v40, v34, v35
	v_xor_b32_e32 v35, 8, v219
	s_nop 0
	s_nop 0
	v_mov_b32_dpp v39, v38 quad_perm:[1,0,3,2] row_mask:0xf bank_mask:0xf
	s_waitcnt lgkmcnt(0)
	v_add_f32_e32 v38, v38, v39
	s_nop 0
	s_nop 0
	s_nop 1
	s_nop 0
	s_nop 0
	v_mov_b32_dpp v39, v38 quad_perm:[2,3,0,1] row_mask:0xf bank_mask:0xf
	s_waitcnt lgkmcnt(0)
	v_add_f32_e32 v39, v38, v39
	s_nop 0
	s_nop 0
	s_nop 1
	s_nop 0
	s_nop 0
	v_mov_b32_dpp v42, v39 row_half_mirror row_mask:0xf bank_mask:0xf
	v_cmp_lt_i32_e32 vcc, v35, v41
	v_or_b32_e32 v38, 0x50, v178
	v_cvt_pk_bf16_f32 v41, v36, v37
	s_nop 0
	s_waitcnt lgkmcnt(0)
	v_add_f32_e32 v34, v39, v42
	s_nop 0
	s_nop 0
	v_mov_b32_dpp v35, v34 row_mirror row_mask:0xf bank_mask:0xf
	v_mad_i64_i32 v[36:37], s[0:1], v38, s66, v[180:181]
	global_store_dwordx2 v[36:37], v[40:41], off
	s_and_saveexec_b64 s[0:1], s[8:9]
	s_cbranch_execz .LBB0_571
	v_ashrrev_i32_e32 v39, 31, v38
	s_waitcnt lgkmcnt(0)
	v_add_f32_e32 v36, v34, v35
	v_lshl_add_u64 v[34:35], v[38:39], 2, s[62:63]
	global_atomic_add_f32 v[34:35], v36, off

; DI unsigned pack_bf16(float lo, float hi) { f32x2 v = {lo, hi}; bf16v2 b = __builtin_convertvector(v, bf16v2); return __builtin_bit_cast(unsigned, b); }
; DI float red16(float v) { v += __shfl_xor(v, 1); v += __shfl_xor(v, 2); v += __shfl_xor(v, 4); v += __shfl_xor(v, 8); return v; }
;   DI void run8(f32x4 (&acc)[8][4], int rb, int cb, int fr, int fq) const {
;     ...
;         for (int ps = 0; ps < 4; ++ps) {
;           const f32x4 a = *(const f32x4*)(scr + (ps * 4 + prow) * 68 + c4 * 4);
;           f32x4 v;
;           v.x = xv[mm][ps].x + a.x * sc; v.y = xv[mm][ps].y + a.y * sc; v.z = xv[mm][ps].z + a.z * sc; v.w = xv[mm][ps].w + a.w * sc;
;           const int grow = rb + m * 16 + ps * 4 + prow;
;           __builtin_nontemporal_store(v, (f32x4*)(op + (size_t)(m * 16 + ps * 4) * D));
;           if (xbp) {
;             u32x2 o; o.x = pack_bf16(v.x, v.y); o.y = pack_bf16(v.z, v.w);
;             *(u32x2*)(xbp + (size_t)grow * LDH + cb + c4 * 4) = o;
;             const float t = red16(v.x * v.x + v.y * v.y + v.z * v.z + v.w * v.w);
;             if (c4 == 0) atomicAdd(ssqp + grow, t);
;           }
.LBB0_572:
	s_waitcnt lgkmcnt(0)
	ds_read_b128 v[34:37], v0 offset:1088
	v_add_co_u32_e32 v38, vcc, 0x54000, v182
	s_waitcnt vmcnt(15) lgkmcnt(0)
	v_pk_fma_f32 v[34:35], v[34:35], 0.5, v[106:107] op_sel_hi:[1,0,1]
	v_addc_co_u32_e32 v39, vcc, 0, v183, vcc
	v_pk_fma_f32 v[36:37], v[36:37], 0.5, v[108:109] op_sel_hi:[1,0,1]
	s_and_b64 vcc, exec, s[10:11]
	global_store_dwordx4 v[38:39], v[34:37], off nt
	s_cbranch_vccnz .LBB0_576
	v_pk_mul_f32 v[38:39], v[34:35], v[34:35]
	v_pk_mul_f32 v[40:41], v[36:37], v[36:37]
	v_add_f32_e32 v38, v38, v39
	v_add_f32_e32 v38, v40, v38
	v_and_b32_e32 v40, 64, v219
	v_add_f32_e32 v38, v41, v38
	s_nop 0
	v_add_u32_e32 v41, 64, v40
	s_nop 0
	v_cvt_pk_bf16_f32 v40, v34, v35
	v_xor_b32_e32 v35, 8, v219
	s_nop 0
	s_nop 0
	v_mov_b32_dpp v39, v38 quad_perm:[1,0,3,2] row_mask:0xf bank_mask:0xf
	s_waitcnt lgkmcnt(0)
	v_add_f32_e32 v38, v38, v39
	s_nop 0
	s_nop 0
	s_nop 1
	s_nop 0
	s_nop 0
	v_mov_b32_dpp v39, v38 quad_perm:[2,3,0,1] row_mask:0xf bank_mask:0xf
	s_waitcnt lgkmcnt(0)
	v_add_f32_e32 v39, v38, v39
	s_nop 0
	s_nop 0
	s_nop 1
	s_nop 0
	s_nop 0
	v_mov_b32_dpp v42, v39 row_half_mirror row_mask:0xf bank_mask:0xf
	v_cmp_lt_i32_e32 vcc, v35, v41
	v_or_b32_e32 v38, 0x54, v178
	v_cvt_pk_bf16_f32 v41, v36, v37
	s_nop 0
	s_waitcnt lgkmcnt(0)
	v_add_f32_e32 v34, v39, v42
	s_nop 0
	s_nop 0
	v_mov_b32_dpp v35, v34 row_mirror row_mask:0xf bank_mask:0xf
	v_mad_i64_i32 v[36:37], s[0:1], v38, s66, v[180:181]
	global_store_dwordx2 v[36:37], v[40:41], off
	s_and_saveexec_b64 s[0:1], s[8:9]
	s_cbranch_execz .LBB0_575
	v_ashrrev_i32_e32 v39, 31, v38
	s_waitcnt lgkmcnt(0)
	v_add_f32_e32 v36, v34, v35
	v_lshl_add_u64 v[34:35], v[38:39], 2, s[62:63]
	global_atomic_add_f32 v[34:35], v36, off

; DI unsigned pack_bf16(float lo, float hi) { f32x2 v = {lo, hi}; bf16v2 b = __builtin_convertvector(v, bf16v2); return __builtin_bit_cast(unsigned, b); }
; DI float red16(float v) { v += __shfl_xor(v, 1); v += __shfl_xor(v, 2); v += __shfl_xor(v, 4); v += __shfl_xor(v, 8); return v; }
;   DI void run8(f32x4 (&acc)[8][4], int rb, int cb, int fr, int fq) const {
;     ...
;         for (int ps = 0; ps < 4; ++ps) {
;           const f32x4 a = *(const f32x4*)(scr + (ps * 4 + prow) * 68 + c4 * 4);
;           f32x4 v;
;           v.x = xv[mm][ps].x + a.x * sc; v.y = xv[mm][ps].y + a.y * sc; v.z = xv[mm][ps].z + a.z * sc; v.w = xv[mm][ps].w + a.w * sc;
;           const int grow = rb + m * 16 + ps * 4 + prow;
;           __builtin_nontemporal_store(v, (f32x4*)(op + (size_t)(m * 16 + ps * 4) * D));
;           if (xbp) {
;             u32x2 o; o.x = pack_bf16(v.x, v.y); o.y = pack_bf16(v.z, v.w);
;             *(u32x2*)(xbp + (size_t)grow * LDH + cb + c4 * 4) = o;
;             const float t = red16(v.x * v.x + v.y * v.y + v.z * v.z + v.w * v.w);
;             if (c4 == 0) atomicAdd(ssqp + grow, t);
;           }
.LBB0_576:
	s_waitcnt lgkmcnt(0)
	ds_read_b128 v[34:37], v0 offset:2176
	v_add_co_u32_e32 v38, vcc, 0x58000, v182
	s_waitcnt vmcnt(15) lgkmcnt(0)
	v_pk_fma_f32 v[34:35], v[34:35], 0.5, v[102:103] op_sel_hi:[1,0,1]
	v_addc_co_u32_e32 v39, vcc, 0, v183, vcc
	v_pk_fma_f32 v[36:37], v[36:37], 0.5, v[104:105] op_sel_hi:[1,0,1]
	s_and_b64 vcc, exec, s[10:11]
	global_store_dwordx4 v[38:39], v[34:37], off nt
	s_cbranch_vccnz .LBB0_580
	v_pk_mul_f32 v[38:39], v[34:35], v[34:35]
	v_pk_mul_f32 v[40:41], v[36:37], v[36:37]
	v_add_f32_e32 v38, v38, v39
	v_add_f32_e32 v38, v40, v38
	v_and_b32_e32 v40, 64, v219
	v_add_f32_e32 v38, v41, v38
	s_nop 0
	v_add_u32_e32 v41, 64, v40
	s_nop 0
	v_cvt_pk_bf16_f32 v40, v34, v35
	v_xor_b32_e32 v35, 8, v219
	s_nop 0
	s_nop 0
	v_mov_b32_dpp v39, v38 quad_perm:[1,0,3,2] row_mask:0xf bank_mask:0xf
	s_waitcnt lgkmcnt(0)
	v_add_f32_e32 v38, v38, v39
	s_nop 0
	s_nop 0
	s_nop 1
	s_nop 0
	s_nop 0
	v_mov_b32_dpp v39, v38 quad_perm:[2,3,0,1] row_mask:0xf bank_mask:0xf
	s_waitcnt lgkmcnt(0)
	v_add_f32_e32 v39, v38, v39
	s_nop 0
	s_nop 0
	s_nop 1
	s_nop 0
	s_nop 0
	v_mov_b32_dpp v42, v39 row_half_mirror row_mask:0xf bank_mask:0xf
	v_cmp_lt_i32_e32 vcc, v35, v41
	v_or_b32_e32 v38, 0x58, v178
	v_cvt_pk_bf16_f32 v41, v36, v37
	s_nop 0
	s_waitcnt lgkmcnt(0)
	v_add_f32_e32 v34, v39, v42
	s_nop 0
	s_nop 0
	v_mov_b32_dpp v35, v34 row_mirror row_mask:0xf bank_mask:0xf
	v_mad_i64_i32 v[36:37], s[0:1], v38, s66, v[180:181]
	global_store_dwordx2 v[36:37], v[40:41], off
	s_and_saveexec_b64 s[0:1], s[8:9]
	s_cbranch_execz .LBB0_579
	v_ashrrev_i32_e32 v39, 31, v38
	s_waitcnt lgkmcnt(0)
	v_add_f32_e32 v36, v34, v35
	v_lshl_add_u64 v[34:35], v[38:39], 2, s[62:63]
	global_atomic_add_f32 v[34:35], v36, off

; DI unsigned pack_bf16(float lo, float hi) { f32x2 v = {lo, hi}; bf16v2 b = __builtin_convertvector(v, bf16v2); return __builtin_bit_cast(unsigned, b); }
; DI float red16(float v) { v += __shfl_xor(v, 1); v += __shfl_xor(v, 2); v += __shfl_xor(v, 4); v += __shfl_xor(v, 8); return v; }
;   DI void run8(f32x4 (&acc)[8][4], int rb, int cb, int fr, int fq) const {
;     ...
;         for (int ps = 0; ps < 4; ++ps) {
;           const f32x4 a = *(const f32x4*)(scr + (ps * 4 + prow) * 68 + c4 * 4);
;           f32x4 v;
;           v.x = xv[mm][ps].x + a.x * sc; v.y = xv[mm][ps].y + a.y * sc; v.z = xv[mm][ps].z + a.z * sc; v.w = xv[mm][ps].w + a.w * sc;
;           const int grow = rb + m * 16 + ps * 4 + prow;
;           __builtin_nontemporal_store(v, (f32x4*)(op + (size_t)(m * 16 + ps * 4) * D));
;           if (xbp) {
;             u32x2 o; o.x = pack_bf16(v.x, v.y); o.y = pack_bf16(v.z, v.w);
;             *(u32x2*)(xbp + (size_t)grow * LDH + cb + c4 * 4) = o;
;             const float t = red16(v.x * v.x + v.y * v.y + v.z * v.z + v.w * v.w);
;             if (c4 == 0) atomicAdd(ssqp + grow, t);
;           }
.LBB0_580:
	s_waitcnt lgkmcnt(0)
	ds_read_b128 v[34:37], v0 offset:3264
	v_add_co_u32_e32 v38, vcc, 0x5c000, v182
	s_waitcnt vmcnt(15) lgkmcnt(0)
	v_pk_fma_f32 v[34:35], v[34:35], 0.5, v[98:99] op_sel_hi:[1,0,1]
	v_addc_co_u32_e32 v39, vcc, 0, v183, vcc
	v_pk_fma_f32 v[36:37], v[36:37], 0.5, v[100:101] op_sel_hi:[1,0,1]
	s_and_b64 vcc, exec, s[10:11]
	global_store_dwordx4 v[38:39], v[34:37], off nt
	s_cbranch_vccnz .LBB0_584
	v_pk_mul_f32 v[38:39], v[34:35], v[34:35]
	v_pk_mul_f32 v[40:41], v[36:37], v[36:37]
	v_add_f32_e32 v38, v38, v39
	v_add_f32_e32 v38, v40, v38
	v_and_b32_e32 v40, 64, v219
	v_add_f32_e32 v38, v41, v38
	s_nop 0
	v_add_u32_e32 v41, 64, v40
	s_nop 0
	v_cvt_pk_bf16_f32 v40, v34, v35
	v_xor_b32_e32 v35, 8, v219
	s_nop 0
	s_nop 0
	v_mov_b32_dpp v39, v38 quad_perm:[1,0,3,2] row_mask:0xf bank_mask:0xf
	s_waitcnt lgkmcnt(0)
	v_add_f32_e32 v38, v38, v39
	s_nop 0
	s_nop 0
	s_nop 1
	s_nop 0
	s_nop 0
	v_mov_b32_dpp v39, v38 quad_perm:[2,3,0,1] row_mask:0xf bank_mask:0xf
	s_waitcnt lgkmcnt(0)
	v_add_f32_e32 v39, v38, v39
	s_nop 0
	s_nop 0
	s_nop 1
	s_nop 0
	s_nop 0
	v_mov_b32_dpp v42, v39 row_half_mirror row_mask:0xf bank_mask:0xf
	v_cmp_lt_i32_e32 vcc, v35, v41
	v_or_b32_e32 v38, 0x5c, v178
	v_cvt_pk_bf16_f32 v41, v36, v37
	s_nop 0
	s_waitcnt lgkmcnt(0)
	v_add_f32_e32 v34, v39, v42
	s_nop 0
	s_nop 0
	v_mov_b32_dpp v35, v34 row_mirror row_mask:0xf bank_mask:0xf
	v_mad_i64_i32 v[36:37], s[0:1], v38, s66, v[180:181]
	global_store_dwordx2 v[36:37], v[40:41], off
	s_and_saveexec_b64 s[0:1], s[8:9]
	s_cbranch_execz .LBB0_583
	v_ashrrev_i32_e32 v39, 31, v38
	s_waitcnt lgkmcnt(0)
	v_add_f32_e32 v36, v34, v35
	v_lshl_add_u64 v[34:35], v[38:39], 2, s[62:63]
	global_atomic_add_f32 v[34:35], v36, off

; DI unsigned pack_bf16(float lo, float hi) { f32x2 v = {lo, hi}; bf16v2 b = __builtin_convertvector(v, bf16v2); return __builtin_bit_cast(unsigned, b); }
; DI float red16(float v) { v += __shfl_xor(v, 1); v += __shfl_xor(v, 2); v += __shfl_xor(v, 4); v += __shfl_xor(v, 8); return v; }
;   DI void run8(f32x4 (&acc)[8][4], int rb, int cb, int fr, int fq) const {
;     ...
;         for (int n = 0; n < 4; ++n)
; #pragma unroll
;           for (int j = 0; j < 4; ++j) scr[(fq * 4 + j) * 68 + n * 16 + fr] = acc[m][n][j];
;         __builtin_amdgcn_sched_barrier(0);
; #pragma unroll
;         for (int ps = 0; ps < 4; ++ps) {
;           const f32x4 a = *(const f32x4*)(scr + (ps * 4 + prow) * 68 + c4 * 4);
;           f32x4 v;
;           v.x = xv[mm][ps].x + a.x * sc; v.y = xv[mm][ps].y + a.y * sc; v.z = xv[mm][ps].z + a.z * sc; v.w = xv[mm][ps].w + a.w * sc;
;           const int grow = rb + m * 16 + ps * 4 + prow;
;           __builtin_nontemporal_store(v, (f32x4*)(op + (size_t)(m * 16 + ps * 4) * D));
;           if (xbp) {
;             u32x2 o; o.x = pack_bf16(v.x, v.y); o.y = pack_bf16(v.z, v.w);
;             *(u32x2*)(xbp + (size_t)grow * LDH + cb + c4 * 4) = o;
;             const float t = red16(v.x * v.x + v.y * v.y + v.z * v.z + v.w * v.w);
;             if (c4 == 0) atomicAdd(ssqp + grow, t);
;           }
.LBB0_584:
	ds_write2_b32 v186, v26, v30 offset1:16
	ds_write2_b32 v186, v27, v31 offset0:68 offset1:84
	ds_write2_b32 v186, v28, v32 offset0:136 offset1:152
	ds_write2_b32 v186, v29, v33 offset0:204 offset1:220
	ds_write2_b32 v186, v18, v22 offset0:32 offset1:48
	ds_write2_b32 v186, v19, v23 offset0:100 offset1:116
	ds_write2_b32 v186, v20, v24 offset0:168 offset1:184
	ds_write2_b32 v186, v21, v25 offset0:236 offset1:252
	ds_read_b128 v[18:21], v0
	v_add_co_u32_e32 v22, vcc, 0x60000, v182
	s_waitcnt vmcnt(15) lgkmcnt(0)
	v_pk_fma_f32 v[18:19], v[18:19], 0.5, v[94:95] op_sel_hi:[1,0,1]
	v_addc_co_u32_e32 v23, vcc, 0, v183, vcc
	v_pk_fma_f32 v[20:21], v[20:21], 0.5, v[96:97] op_sel_hi:[1,0,1]
	s_and_b64 vcc, exec, s[10:11]
	global_store_dwordx4 v[22:23], v[18:21], off nt
	s_cbranch_vccnz .LBB0_588
	v_pk_mul_f32 v[22:23], v[18:19], v[18:19]
	v_pk_mul_f32 v[24:25], v[20:21], v[20:21]
	v_add_f32_e32 v22, v22, v23
	v_add_f32_e32 v22, v24, v22
	v_and_b32_e32 v24, 64, v219
	v_add_f32_e32 v22, v25, v22
	s_nop 0
	v_add_u32_e32 v25, 64, v24
	s_nop 0
	v_cvt_pk_bf16_f32 v24, v18, v19
	v_xor_b32_e32 v19, 8, v219
	s_nop 0
	s_nop 0
	v_mov_b32_dpp v23, v22 quad_perm:[1,0,3,2] row_mask:0xf bank_mask:0xf
	s_waitcnt lgkmcnt(0)
	v_add_f32_e32 v22, v22, v23
	s_nop 0
	s_nop 0
	s_nop 1
	s_nop 0
	s_nop 0
	v_mov_b32_dpp v23, v22 quad_perm:[2,3,0,1] row_mask:0xf bank_mask:0xf
	s_waitcnt lgkmcnt(0)
	v_add_f32_e32 v23, v22, v23
	s_nop 0
	s_nop 0
	s_nop 1
	s_nop 0
	s_nop 0
	v_mov_b32_dpp v26, v23 row_half_mirror row_mask:0xf bank_mask:0xf
	v_cmp_lt_i32_e32 vcc, v19, v25
	v_or_b32_e32 v22, 0x60, v178
	v_cvt_pk_bf16_f32 v25, v20, v21
	s_nop 0
	s_waitcnt lgkmcnt(0)
	v_add_f32_e32 v18, v23, v26
	s_nop 0
	s_nop 0
	v_mov_b32_dpp v19, v18 row_mirror row_mask:0xf bank_mask:0xf
	v_mad_i64_i32 v[20:21], s[0:1], v22, s66, v[180:181]
	global_store_dwordx2 v[20:21], v[24:25], off
	s_and_saveexec_b64 s[0:1], s[8:9]
	s_cbranch_execz .LBB0_587
	v_ashrrev_i32_e32 v23, 31, v22
	s_waitcnt lgkmcnt(0)
	v_add_f32_e32 v20, v18, v19
	v_lshl_add_u64 v[18:19], v[22:23], 2, s[62:63]
	global_atomic_add_f32 v[18:19], v20, off

; DI unsigned pack_bf16(float lo, float hi) { f32x2 v = {lo, hi}; bf16v2 b = __builtin_convertvector(v, bf16v2); return __builtin_bit_cast(unsigned, b); }
; DI float red16(float v) { v += __shfl_xor(v, 1); v += __shfl_xor(v, 2); v += __shfl_xor(v, 4); v += __shfl_xor(v, 8); return v; }
;   DI void run8(f32x4 (&acc)[8][4], int rb, int cb, int fr, int fq) const {
;     ...
;         for (int ps = 0; ps < 4; ++ps) {
;           const f32x4 a = *(const f32x4*)(scr + (ps * 4 + prow) * 68 + c4 * 4);
;           f32x4 v;
;           v.x = xv[mm][ps].x + a.x * sc; v.y = xv[mm][ps].y + a.y * sc; v.z = xv[mm][ps].z + a.z * sc; v.w = xv[mm][ps].w + a.w * sc;
;           const int grow = rb + m * 16 + ps * 4 + prow;
;           __builtin_nontemporal_store(v, (f32x4*)(op + (size_t)(m * 16 + ps * 4) * D));
;           if (xbp) {
;             u32x2 o; o.x = pack_bf16(v.x, v.y); o.y = pack_bf16(v.z, v.w);
;             *(u32x2*)(xbp + (size_t)grow * LDH + cb + c4 * 4) = o;
;             const float t = red16(v.x * v.x + v.y * v.y + v.z * v.z + v.w * v.w);
;             if (c4 == 0) atomicAdd(ssqp + grow, t);
;           }
.LBB0_588:
	s_waitcnt lgkmcnt(0)
	ds_read_b128 v[18:21], v0 offset:1088
	v_add_co_u32_e32 v22, vcc, 0x64000, v182
	s_waitcnt vmcnt(15) lgkmcnt(0)
	v_pk_fma_f32 v[18:19], v[18:19], 0.5, v[90:91] op_sel_hi:[1,0,1]
	v_addc_co_u32_e32 v23, vcc, 0, v183, vcc
	v_pk_fma_f32 v[20:21], v[20:21], 0.5, v[92:93] op_sel_hi:[1,0,1]
	s_and_b64 vcc, exec, s[10:11]
	global_store_dwordx4 v[22:23], v[18:21], off nt
	s_cbranch_vccnz .LBB0_592
	v_pk_mul_f32 v[22:23], v[18:19], v[18:19]
	v_pk_mul_f32 v[24:25], v[20:21], v[20:21]
	v_add_f32_e32 v22, v22, v23
	v_add_f32_e32 v22, v24, v22
	v_and_b32_e32 v24, 64, v219
	v_add_f32_e32 v22, v25, v22
	s_nop 0
	v_add_u32_e32 v25, 64, v24
	s_nop 0
	v_cvt_pk_bf16_f32 v24, v18, v19
	v_xor_b32_e32 v19, 8, v219
	s_nop 0
	s_nop 0
	v_mov_b32_dpp v23, v22 quad_perm:[1,0,3,2] row_mask:0xf bank_mask:0xf
	s_waitcnt lgkmcnt(0)
	v_add_f32_e32 v22, v22, v23
	s_nop 0
	s_nop 0
	s_nop 1
	s_nop 0
	s_nop 0
	v_mov_b32_dpp v23, v22 quad_perm:[2,3,0,1] row_mask:0xf bank_mask:0xf
	s_waitcnt lgkmcnt(0)
	v_add_f32_e32 v23, v22, v23
	s_nop 0
	s_nop 0
	s_nop 1
	s_nop 0
	s_nop 0
	v_mov_b32_dpp v26, v23 row_half_mirror row_mask:0xf bank_mask:0xf
	v_cmp_lt_i32_e32 vcc, v19, v25
	v_or_b32_e32 v22, 0x64, v178
	v_cvt_pk_bf16_f32 v25, v20, v21
	s_nop 0
	s_waitcnt lgkmcnt(0)
	v_add_f32_e32 v18, v23, v26
	s_nop 0
	s_nop 0
	v_mov_b32_dpp v19, v18 row_mirror row_mask:0xf bank_mask:0xf
	v_mad_i64_i32 v[20:21], s[0:1], v22, s66, v[180:181]
	global_store_dwordx2 v[20:21], v[24:25], off
	s_and_saveexec_b64 s[0:1], s[8:9]
	s_cbranch_execz .LBB0_591
	v_ashrrev_i32_e32 v23, 31, v22
	s_waitcnt lgkmcnt(0)
	v_add_f32_e32 v20, v18, v19
	v_lshl_add_u64 v[18:19], v[22:23], 2, s[62:63]
	global_atomic_add_f32 v[18:19], v20, off

; DI unsigned pack_bf16(float lo, float hi) { f32x2 v = {lo, hi}; bf16v2 b = __builtin_convertvector(v, bf16v2); return __builtin_bit_cast(unsigned, b); }
; DI float red16(float v) { v += __shfl_xor(v, 1); v += __shfl_xor(v, 2); v += __shfl_xor(v, 4); v += __shfl_xor(v, 8); return v; }
;   DI void run8(f32x4 (&acc)[8][4], int rb, int cb, int fr, int fq) const {
;     ...
;         for (int ps = 0; ps < 4; ++ps) {
;           const f32x4 a = *(const f32x4*)(scr + (ps * 4 + prow) * 68 + c4 * 4);
;           f32x4 v;
;           v.x = xv[mm][ps].x + a.x * sc; v.y = xv[mm][ps].y + a.y * sc; v.z = xv[mm][ps].z + a.z * sc; v.w = xv[mm][ps].w + a.w * sc;
;           const int grow = rb + m * 16 + ps * 4 + prow;
;           __builtin_nontemporal_store(v, (f32x4*)(op + (size_t)(m * 16 + ps * 4) * D));
;           if (xbp) {
;             u32x2 o; o.x = pack_bf16(v.x, v.y); o.y = pack_bf16(v.z, v.w);
;             *(u32x2*)(xbp + (size_t)grow * LDH + cb + c4 * 4) = o;
;             const float t = red16(v.x * v.x + v.y * v.y + v.z * v.z + v.w * v.w);
;             if (c4 == 0) atomicAdd(ssqp + grow, t);
;           }
.LBB0_592:
	s_waitcnt lgkmcnt(0)
	ds_read_b128 v[18:21], v0 offset:2176
	v_add_co_u32_e32 v22, vcc, 0x68000, v182
	s_waitcnt vmcnt(15) lgkmcnt(0)
	v_pk_fma_f32 v[18:19], v[18:19], 0.5, v[86:87] op_sel_hi:[1,0,1]
	v_addc_co_u32_e32 v23, vcc, 0, v183, vcc
	v_pk_fma_f32 v[20:21], v[20:21], 0.5, v[88:89] op_sel_hi:[1,0,1]
	s_and_b64 vcc, exec, s[10:11]
	global_store_dwordx4 v[22:23], v[18:21], off nt
	s_cbranch_vccnz .LBB0_596
	v_pk_mul_f32 v[22:23], v[18:19], v[18:19]
	v_pk_mul_f32 v[24:25], v[20:21], v[20:21]
	v_add_f32_e32 v22, v22, v23
	v_add_f32_e32 v22, v24, v22
	v_and_b32_e32 v24, 64, v219
	v_add_f32_e32 v22, v25, v22
	s_nop 0
	v_add_u32_e32 v25, 64, v24
	s_nop 0
	v_cvt_pk_bf16_f32 v24, v18, v19
	v_xor_b32_e32 v19, 8, v219
	s_nop 0
	s_nop 0
	v_mov_b32_dpp v23, v22 quad_perm:[1,0,3,2] row_mask:0xf bank_mask:0xf
	s_waitcnt lgkmcnt(0)
	v_add_f32_e32 v22, v22, v23
	s_nop 0
	s_nop 0
	s_nop 1
	s_nop 0
	s_nop 0
	v_mov_b32_dpp v23, v22 quad_perm:[2,3,0,1] row_mask:0xf bank_mask:0xf
	s_waitcnt lgkmcnt(0)
	v_add_f32_e32 v23, v22, v23
	s_nop 0
	s_nop 0
	s_nop 1
	s_nop 0
	s_nop 0
	v_mov_b32_dpp v26, v23 row_half_mirror row_mask:0xf bank_mask:0xf
	v_cmp_lt_i32_e32 vcc, v19, v25
	v_or_b32_e32 v22, 0x68, v178
	v_cvt_pk_bf16_f32 v25, v20, v21
	s_nop 0
	s_waitcnt lgkmcnt(0)
	v_add_f32_e32 v18, v23, v26
	s_nop 0
	s_nop 0
	v_mov_b32_dpp v19, v18 row_mirror row_mask:0xf bank_mask:0xf
	v_mad_i64_i32 v[20:21], s[0:1], v22, s66, v[180:181]
	global_store_dwordx2 v[20:21], v[24:25], off
	s_and_saveexec_b64 s[0:1], s[8:9]
	s_cbranch_execz .LBB0_595
	v_ashrrev_i32_e32 v23, 31, v22
	s_waitcnt lgkmcnt(0)
	v_add_f32_e32 v20, v18, v19
	v_lshl_add_u64 v[18:19], v[22:23], 2, s[62:63]
	global_atomic_add_f32 v[18:19], v20, off

; DI unsigned pack_bf16(float lo, float hi) { f32x2 v = {lo, hi}; bf16v2 b = __builtin_convertvector(v, bf16v2); return __builtin_bit_cast(unsigned, b); }
; DI float red16(float v) { v += __shfl_xor(v, 1); v += __shfl_xor(v, 2); v += __shfl_xor(v, 4); v += __shfl_xor(v, 8); return v; }
;   DI void run8(f32x4 (&acc)[8][4], int rb, int cb, int fr, int fq) const {
;     ...
;         for (int ps = 0; ps < 4; ++ps) {
;           const f32x4 a = *(const f32x4*)(scr + (ps * 4 + prow) * 68 + c4 * 4);
;           f32x4 v;
;           v.x = xv[mm][ps].x + a.x * sc; v.y = xv[mm][ps].y + a.y * sc; v.z = xv[mm][ps].z + a.z * sc; v.w = xv[mm][ps].w + a.w * sc;
;           const int grow = rb + m * 16 + ps * 4 + prow;
;           __builtin_nontemporal_store(v, (f32x4*)(op + (size_t)(m * 16 + ps * 4) * D));
;           if (xbp) {
;             u32x2 o; o.x = pack_bf16(v.x, v.y); o.y = pack_bf16(v.z, v.w);
;             *(u32x2*)(xbp + (size_t)grow * LDH + cb + c4 * 4) = o;
;             const float t = red16(v.x * v.x + v.y * v.y + v.z * v.z + v.w * v.w);
;             if (c4 == 0) atomicAdd(ssqp + grow, t);
;           }
.LBB0_596:
	s_waitcnt lgkmcnt(0)
	ds_read_b128 v[18:21], v0 offset:3264
	v_add_co_u32_e32 v22, vcc, 0x6c000, v182
	s_waitcnt vmcnt(15) lgkmcnt(0)
	v_pk_fma_f32 v[18:19], v[18:19], 0.5, v[82:83] op_sel_hi:[1,0,1]
	v_addc_co_u32_e32 v23, vcc, 0, v183, vcc
	v_pk_fma_f32 v[20:21], v[20:21], 0.5, v[84:85] op_sel_hi:[1,0,1]
	s_and_b64 vcc, exec, s[10:11]
	global_store_dwordx4 v[22:23], v[18:21], off nt
	s_cbranch_vccnz .LBB0_600
	v_pk_mul_f32 v[22:23], v[18:19], v[18:19]
	v_pk_mul_f32 v[24:25], v[20:21], v[20:21]
	v_add_f32_e32 v22, v22, v23
	v_add_f32_e32 v22, v24, v22
	v_and_b32_e32 v24, 64, v219
	v_add_f32_e32 v22, v25, v22
	s_nop 0
	v_add_u32_e32 v25, 64, v24
	s_nop 0
	v_cvt_pk_bf16_f32 v24, v18, v19
	v_xor_b32_e32 v19, 8, v219
	s_nop 0
	s_nop 0
	v_mov_b32_dpp v23, v22 quad_perm:[1,0,3,2] row_mask:0xf bank_mask:0xf
	s_waitcnt lgkmcnt(0)
	v_add_f32_e32 v22, v22, v23
	s_nop 0
	s_nop 0
	s_nop 1
	s_nop 0
	s_nop 0
	v_mov_b32_dpp v23, v22 quad_perm:[2,3,0,1] row_mask:0xf bank_mask:0xf
	s_waitcnt lgkmcnt(0)
	v_add_f32_e32 v23, v22, v23
	s_nop 0
	s_nop 0
	s_nop 1
	s_nop 0
	s_nop 0
	v_mov_b32_dpp v26, v23 row_half_mirror row_mask:0xf bank_mask:0xf
	v_cmp_lt_i32_e32 vcc, v19, v25
	v_or_b32_e32 v22, 0x6c, v178
	v_cvt_pk_bf16_f32 v25, v20, v21
	s_nop 0
	s_waitcnt lgkmcnt(0)
	v_add_f32_e32 v18, v23, v26
	s_nop 0
	s_nop 0
	v_mov_b32_dpp v19, v18 row_mirror row_mask:0xf bank_mask:0xf
	v_mad_i64_i32 v[20:21], s[0:1], v22, s66, v[180:181]
	global_store_dwordx2 v[20:21], v[24:25], off
	s_and_saveexec_b64 s[0:1], s[8:9]
	s_cbranch_execz .LBB0_599
	v_ashrrev_i32_e32 v23, 31, v22
	s_waitcnt lgkmcnt(0)
	v_add_f32_e32 v20, v18, v19
	v_lshl_add_u64 v[18:19], v[22:23], 2, s[62:63]
	global_atomic_add_f32 v[18:19], v20, off

; DI unsigned pack_bf16(float lo, float hi) { f32x2 v = {lo, hi}; bf16v2 b = __builtin_convertvector(v, bf16v2); return __builtin_bit_cast(unsigned, b); }
; DI float red16(float v) { v += __shfl_xor(v, 1); v += __shfl_xor(v, 2); v += __shfl_xor(v, 4); v += __shfl_xor(v, 8); return v; }
;   DI void run8(f32x4 (&acc)[8][4], int rb, int cb, int fr, int fq) const {
;     ...
;         for (int n = 0; n < 4; ++n)
; #pragma unroll
;           for (int j = 0; j < 4; ++j) scr[(fq * 4 + j) * 68 + n * 16 + fr] = acc[m][n][j];
;         __builtin_amdgcn_sched_barrier(0);
; #pragma unroll
;         for (int ps = 0; ps < 4; ++ps) {
;           const f32x4 a = *(const f32x4*)(scr + (ps * 4 + prow) * 68 + c4 * 4);
;           f32x4 v;
;           v.x = xv[mm][ps].x + a.x * sc; v.y = xv[mm][ps].y + a.y * sc; v.z = xv[mm][ps].z + a.z * sc; v.w = xv[mm][ps].w + a.w * sc;
;           const int grow = rb + m * 16 + ps * 4 + prow;
;           __builtin_nontemporal_store(v, (f32x4*)(op + (size_t)(m * 16 + ps * 4) * D));
;           if (xbp) {
;             u32x2 o; o.x = pack_bf16(v.x, v.y); o.y = pack_bf16(v.z, v.w);
;             *(u32x2*)(xbp + (size_t)grow * LDH + cb + c4 * 4) = o;
;             const float t = red16(v.x * v.x + v.y * v.y + v.z * v.z + v.w * v.w);
;             if (c4 == 0) atomicAdd(ssqp + grow, t);
;           }
.LBB0_600:
	ds_write2_b32 v186, v10, v14 offset1:16
	ds_write2_b32 v186, v11, v15 offset0:68 offset1:84
	ds_write2_b32 v186, v12, v16 offset0:136 offset1:152
	ds_write2_b32 v186, v13, v17 offset0:204 offset1:220
	ds_write2_b32 v186, v2, v6 offset0:32 offset1:48
	ds_write2_b32 v186, v3, v7 offset0:100 offset1:116
	ds_write2_b32 v186, v4, v8 offset0:168 offset1:184
	ds_write2_b32 v186, v5, v9 offset0:236 offset1:252
	ds_read_b128 v[2:5], v0
	v_add_co_u32_e32 v6, vcc, 0x70000, v182
	s_waitcnt vmcnt(15) lgkmcnt(0)
	v_pk_fma_f32 v[2:3], v[2:3], 0.5, v[78:79] op_sel_hi:[1,0,1]
	v_addc_co_u32_e32 v7, vcc, 0, v183, vcc
	v_pk_fma_f32 v[4:5], v[4:5], 0.5, v[80:81] op_sel_hi:[1,0,1]
	s_and_b64 vcc, exec, s[10:11]
	global_store_dwordx4 v[6:7], v[2:5], off nt
	s_cbranch_vccnz .LBB0_604
	v_pk_mul_f32 v[6:7], v[2:3], v[2:3]
	v_pk_mul_f32 v[8:9], v[4:5], v[4:5]
	v_add_f32_e32 v6, v6, v7
	v_add_f32_e32 v6, v8, v6
	v_and_b32_e32 v8, 64, v219
	v_add_f32_e32 v6, v9, v6
	s_nop 0
	v_add_u32_e32 v9, 64, v8
	s_nop 0
	v_cvt_pk_bf16_f32 v8, v2, v3
	v_xor_b32_e32 v3, 8, v219
	s_nop 0
	s_nop 0
	v_mov_b32_dpp v7, v6 quad_perm:[1,0,3,2] row_mask:0xf bank_mask:0xf
	s_waitcnt lgkmcnt(0)
	v_add_f32_e32 v6, v6, v7
	s_nop 0
	s_nop 0
	s_nop 1
	s_nop 0
	s_nop 0
	v_mov_b32_dpp v7, v6 quad_perm:[2,3,0,1] row_mask:0xf bank_mask:0xf
	s_waitcnt lgkmcnt(0)
	v_add_f32_e32 v7, v6, v7
	s_nop 0
	s_nop 0
	s_nop 1
	s_nop 0
	s_nop 0
	v_mov_b32_dpp v10, v7 row_half_mirror row_mask:0xf bank_mask:0xf
	v_cmp_lt_i32_e32 vcc, v3, v9
	v_or_b32_e32 v6, 0x70, v178
	v_cvt_pk_bf16_f32 v9, v4, v5
	s_nop 0
	s_waitcnt lgkmcnt(0)
	v_add_f32_e32 v2, v7, v10
	s_nop 0
	s_nop 0
	v_mov_b32_dpp v3, v2 row_mirror row_mask:0xf bank_mask:0xf
	v_mad_i64_i32 v[4:5], s[0:1], v6, s66, v[180:181]
	global_store_dwordx2 v[4:5], v[8:9], off
	s_and_saveexec_b64 s[0:1], s[8:9]
	s_cbranch_execz .LBB0_603
	v_ashrrev_i32_e32 v7, 31, v6
	s_waitcnt lgkmcnt(0)
	v_add_f32_e32 v4, v2, v3
	v_lshl_add_u64 v[2:3], v[6:7], 2, s[62:63]
	global_atomic_add_f32 v[2:3], v4, off

; DI unsigned pack_bf16(float lo, float hi) { f32x2 v = {lo, hi}; bf16v2 b = __builtin_convertvector(v, bf16v2); return __builtin_bit_cast(unsigned, b); }
; DI float red16(float v) { v += __shfl_xor(v, 1); v += __shfl_xor(v, 2); v += __shfl_xor(v, 4); v += __shfl_xor(v, 8); return v; }
;   DI void run8(f32x4 (&acc)[8][4], int rb, int cb, int fr, int fq) const {
;     ...
;         for (int ps = 0; ps < 4; ++ps) {
;           const f32x4 a = *(const f32x4*)(scr + (ps * 4 + prow) * 68 + c4 * 4);
;           f32x4 v;
;           v.x = xv[mm][ps].x + a.x * sc; v.y = xv[mm][ps].y + a.y * sc; v.z = xv[mm][ps].z + a.z * sc; v.w = xv[mm][ps].w + a.w * sc;
;           const int grow = rb + m * 16 + ps * 4 + prow;
;           __builtin_nontemporal_store(v, (f32x4*)(op + (size_t)(m * 16 + ps * 4) * D));
;           if (xbp) {
;             u32x2 o; o.x = pack_bf16(v.x, v.y); o.y = pack_bf16(v.z, v.w);
;             *(u32x2*)(xbp + (size_t)grow * LDH + cb + c4 * 4) = o;
;             const float t = red16(v.x * v.x + v.y * v.y + v.z * v.z + v.w * v.w);
;             if (c4 == 0) atomicAdd(ssqp + grow, t);
;           }
.LBB0_604:
	s_waitcnt lgkmcnt(0)
	ds_read_b128 v[2:5], v0 offset:1088
	v_add_co_u32_e32 v6, vcc, 0x74000, v182
	s_waitcnt vmcnt(15) lgkmcnt(0)
	v_pk_fma_f32 v[2:3], v[2:3], 0.5, v[74:75] op_sel_hi:[1,0,1]
	v_addc_co_u32_e32 v7, vcc, 0, v183, vcc
	v_pk_fma_f32 v[4:5], v[4:5], 0.5, v[76:77] op_sel_hi:[1,0,1]
	s_and_b64 vcc, exec, s[10:11]
	global_store_dwordx4 v[6:7], v[2:5], off nt
	s_cbranch_vccnz .LBB0_608
	v_pk_mul_f32 v[6:7], v[2:3], v[2:3]
	v_pk_mul_f32 v[8:9], v[4:5], v[4:5]
	v_add_f32_e32 v6, v6, v7
	v_add_f32_e32 v6, v8, v6
	v_and_b32_e32 v8, 64, v219
	v_add_f32_e32 v6, v9, v6
	s_nop 0
	v_add_u32_e32 v9, 64, v8
	s_nop 0
	v_cvt_pk_bf16_f32 v8, v2, v3
	v_xor_b32_e32 v3, 8, v219
	s_nop 0
	s_nop 0
	v_mov_b32_dpp v7, v6 quad_perm:[1,0,3,2] row_mask:0xf bank_mask:0xf
	s_waitcnt lgkmcnt(0)
	v_add_f32_e32 v6, v6, v7
	s_nop 0
	s_nop 0
	s_nop 1
	s_nop 0
	s_nop 0
	v_mov_b32_dpp v7, v6 quad_perm:[2,3,0,1] row_mask:0xf bank_mask:0xf
	s_waitcnt lgkmcnt(0)
	v_add_f32_e32 v7, v6, v7
	s_nop 0
	s_nop 0
	s_nop 1
	s_nop 0
	s_nop 0
	v_mov_b32_dpp v10, v7 row_half_mirror row_mask:0xf bank_mask:0xf
	v_cmp_lt_i32_e32 vcc, v3, v9
	v_or_b32_e32 v6, 0x74, v178
	v_cvt_pk_bf16_f32 v9, v4, v5
	s_nop 0
	s_waitcnt lgkmcnt(0)
	v_add_f32_e32 v2, v7, v10
	s_nop 0
	s_nop 0
	v_mov_b32_dpp v3, v2 row_mirror row_mask:0xf bank_mask:0xf
	v_mad_i64_i32 v[4:5], s[0:1], v6, s66, v[180:181]
	global_store_dwordx2 v[4:5], v[8:9], off
	s_and_saveexec_b64 s[0:1], s[8:9]
	s_cbranch_execz .LBB0_607
	v_ashrrev_i32_e32 v7, 31, v6
	s_waitcnt lgkmcnt(0)
	v_add_f32_e32 v4, v2, v3
	v_lshl_add_u64 v[2:3], v[6:7], 2, s[62:63]
	global_atomic_add_f32 v[2:3], v4, off

; DI unsigned pack_bf16(float lo, float hi) { f32x2 v = {lo, hi}; bf16v2 b = __builtin_convertvector(v, bf16v2); return __builtin_bit_cast(unsigned, b); }
; DI float red16(float v) { v += __shfl_xor(v, 1); v += __shfl_xor(v, 2); v += __shfl_xor(v, 4); v += __shfl_xor(v, 8); return v; }
;   DI void run8(f32x4 (&acc)[8][4], int rb, int cb, int fr, int fq) const {
;     ...
;         for (int ps = 0; ps < 4; ++ps) {
;           const f32x4 a = *(const f32x4*)(scr + (ps * 4 + prow) * 68 + c4 * 4);
;           f32x4 v;
;           v.x = xv[mm][ps].x + a.x * sc; v.y = xv[mm][ps].y + a.y * sc; v.z = xv[mm][ps].z + a.z * sc; v.w = xv[mm][ps].w + a.w * sc;
;           const int grow = rb + m * 16 + ps * 4 + prow;
;           __builtin_nontemporal_store(v, (f32x4*)(op + (size_t)(m * 16 + ps * 4) * D));
;           if (xbp) {
;             u32x2 o; o.x = pack_bf16(v.x, v.y); o.y = pack_bf16(v.z, v.w);
;             *(u32x2*)(xbp + (size_t)grow * LDH + cb + c4 * 4) = o;
;             const float t = red16(v.x * v.x + v.y * v.y + v.z * v.z + v.w * v.w);
;             if (c4 == 0) atomicAdd(ssqp + grow, t);
;           }
.LBB0_608:
	s_waitcnt lgkmcnt(0)
	ds_read_b128 v[2:5], v0 offset:2176
	v_add_co_u32_e32 v6, vcc, 0x78000, v182
	s_waitcnt vmcnt(15) lgkmcnt(0)
	v_pk_fma_f32 v[2:3], v[2:3], 0.5, v[70:71] op_sel_hi:[1,0,1]
	v_addc_co_u32_e32 v7, vcc, 0, v183, vcc
	v_pk_fma_f32 v[4:5], v[4:5], 0.5, v[72:73] op_sel_hi:[1,0,1]
	s_and_b64 vcc, exec, s[10:11]
	global_store_dwordx4 v[6:7], v[2:5], off nt
	s_cbranch_vccnz .LBB0_612
	v_pk_mul_f32 v[6:7], v[2:3], v[2:3]
	v_pk_mul_f32 v[8:9], v[4:5], v[4:5]
	v_add_f32_e32 v6, v6, v7
	v_add_f32_e32 v6, v8, v6
	v_and_b32_e32 v8, 64, v219
	v_add_f32_e32 v6, v9, v6
	s_nop 0
	v_add_u32_e32 v9, 64, v8
	s_nop 0
	v_cvt_pk_bf16_f32 v8, v2, v3
	v_xor_b32_e32 v3, 8, v219
	s_nop 0
	s_nop 0
	v_mov_b32_dpp v7, v6 quad_perm:[1,0,3,2] row_mask:0xf bank_mask:0xf
	s_waitcnt lgkmcnt(0)
	v_add_f32_e32 v6, v6, v7
	s_nop 0
	s_nop 0
	s_nop 1
	s_nop 0
	s_nop 0
	v_mov_b32_dpp v7, v6 quad_perm:[2,3,0,1] row_mask:0xf bank_mask:0xf
	s_waitcnt lgkmcnt(0)
	v_add_f32_e32 v7, v6, v7
	s_nop 0
	s_nop 0
	s_nop 1
	s_nop 0
	s_nop 0
	v_mov_b32_dpp v10, v7 row_half_mirror row_mask:0xf bank_mask:0xf
	v_cmp_lt_i32_e32 vcc, v3, v9
	v_or_b32_e32 v6, 0x78, v178
	v_cvt_pk_bf16_f32 v9, v4, v5
	s_nop 0
	s_waitcnt lgkmcnt(0)
	v_add_f32_e32 v2, v7, v10
	s_nop 0
	s_nop 0
	v_mov_b32_dpp v3, v2 row_mirror row_mask:0xf bank_mask:0xf
	v_mad_i64_i32 v[4:5], s[0:1], v6, s66, v[180:181]
	global_store_dwordx2 v[4:5], v[8:9], off
	s_and_saveexec_b64 s[0:1], s[8:9]
	s_cbranch_execz .LBB0_611
	v_ashrrev_i32_e32 v7, 31, v6
	s_waitcnt lgkmcnt(0)
	v_add_f32_e32 v4, v2, v3
	v_lshl_add_u64 v[2:3], v[6:7], 2, s[62:63]
	global_atomic_add_f32 v[2:3], v4, off

; DI unsigned pack_bf16(float lo, float hi) { f32x2 v = {lo, hi}; bf16v2 b = __builtin_convertvector(v, bf16v2); return __builtin_bit_cast(unsigned, b); }
; DI float red16(float v) { v += __shfl_xor(v, 1); v += __shfl_xor(v, 2); v += __shfl_xor(v, 4); v += __shfl_xor(v, 8); return v; }
;   DI void run8(f32x4 (&acc)[8][4], int rb, int cb, int fr, int fq) const {
;     ...
;         for (int ps = 0; ps < 4; ++ps) {
;           const f32x4 a = *(const f32x4*)(scr + (ps * 4 + prow) * 68 + c4 * 4);
;           f32x4 v;
;           v.x = xv[mm][ps].x + a.x * sc; v.y = xv[mm][ps].y + a.y * sc; v.z = xv[mm][ps].z + a.z * sc; v.w = xv[mm][ps].w + a.w * sc;
;           const int grow = rb + m * 16 + ps * 4 + prow;
;           __builtin_nontemporal_store(v, (f32x4*)(op + (size_t)(m * 16 + ps * 4) * D));
;           if (xbp) {
;             u32x2 o; o.x = pack_bf16(v.x, v.y); o.y = pack_bf16(v.z, v.w);
;             *(u32x2*)(xbp + (size_t)grow * LDH + cb + c4 * 4) = o;
;             const float t = red16(v.x * v.x + v.y * v.y + v.z * v.z + v.w * v.w);
;             if (c4 == 0) atomicAdd(ssqp + grow, t);
;           }
.LBB0_612:
	s_waitcnt lgkmcnt(0)
	ds_read_b128 v[2:5], v0 offset:3264
	v_add_co_u32_e32 v6, vcc, 0x7c000, v182
	s_waitcnt vmcnt(15) lgkmcnt(0)
	v_pk_fma_f32 v[2:3], v[2:3], 0.5, v[66:67] op_sel_hi:[1,0,1]
	v_addc_co_u32_e32 v7, vcc, 0, v183, vcc
	v_pk_fma_f32 v[4:5], v[4:5], 0.5, v[68:69] op_sel_hi:[1,0,1]
	s_and_b64 vcc, exec, s[10:11]
	global_store_dwordx4 v[6:7], v[2:5], off nt
	s_cbranch_vccnz .LBB0_477
	v_cvt_pk_bf16_f32 v8, v2, v3
	v_pk_mul_f32 v[2:3], v[2:3], v[2:3]
	v_cvt_pk_bf16_f32 v9, v4, v5
	v_add_f32_e32 v0, v2, v3
	v_and_b32_e32 v3, 64, v219
	s_nop 0
	v_add_u32_e32 v3, 64, v3
	v_pk_mul_f32 v[4:5], v[4:5], v[4:5]
	s_nop 0
	v_add_f32_e32 v0, v4, v0
	v_add_f32_e32 v0, v5, v0
	s_nop 0
	s_nop 0
	v_mov_b32_dpp v2, v0 quad_perm:[1,0,3,2] row_mask:0xf bank_mask:0xf
	v_or_b32_e32 v6, 0x7c, v178
	v_mad_i64_i32 v[10:11], s[0:1], v6, s66, v[180:181]
	global_store_dwordx2 v[10:11], v[8:9], off
	s_waitcnt lgkmcnt(0)
	v_add_f32_e32 v0, v0, v2
	s_nop 0
	s_nop 0
	s_nop 1
	s_nop 0
	s_nop 0
	v_mov_b32_dpp v2, v0 quad_perm:[2,3,0,1] row_mask:0xf bank_mask:0xf
	s_waitcnt lgkmcnt(0)
	v_add_f32_e32 v0, v0, v2
	s_nop 0
	s_nop 0
	s_nop 1
	s_nop 0
	s_nop 0
	v_mov_b32_dpp v2, v0 row_half_mirror row_mask:0xf bank_mask:0xf
	s_waitcnt lgkmcnt(0)
	v_add_f32_e32 v0, v0, v2
	v_xor_b32_e32 v2, 8, v219
	v_cmp_lt_i32_e32 vcc, v2, v3
	s_nop 1
	s_nop 0
	s_nop 0
	v_mov_b32_dpp v2, v0 row_mirror row_mask:0xf bank_mask:0xf
	s_and_saveexec_b64 s[0:1], s[8:9]
	s_cbranch_execz .LBB0_476
	v_ashrrev_i32_e32 v7, 31, v6
	s_waitcnt lgkmcnt(0)
	v_add_f32_e32 v0, v0, v2
	v_lshl_add_u64 v[2:3], v[6:7], 2, s[62:63]
	global_atomic_add_f32 v[2:3], v0, off
	s_branch .LBB0_476

; #define MFMA16(a, b, c) __builtin_amdgcn_mfma_f32_16x16x32_bf16((a), (b), (c), 0, 0, 0)
; template <class Epi>
; DI void gemm8_tile(const bf16_t* __restrict__ Ab, int lda, const bf16_t* __restrict__ Bb, int ldb, int K, int brow, int bcol, const Epi epi,
;                    bool staged, bool has_next, const bf16_t* __restrict__ Abn, const bf16_t* __restrict__ Bbn) {
;     ...
;       for (int m = 0; m < 8; ++m)
; #pragma unroll
;         for (int n = 0; n < 4; ++n) acc[m][n] = MFMA16(At[m], Bf[n], acc[m][n]);
;       __builtin_amdgcn_sched_barrier(0);
;     }
;     asm volatile("s_waitcnt vmcnt(0)" ::: "memory");
;     __syncthreads();
;   DI void run8(f32x4 (&acc)[8][4], int rb, int cb, int fr, int fq) const {
;     const int lane = fq * 16 + fr, wid = (int)(threadIdx.x >> 6);
;     const float sc = scale; bf16_t* const xbp = xb; float* const ssqp = ssq;
;     float* scr = (float*)(smem + G8_STAGE_B + wid * 4352);
;     const int prow = lane >> 4, c4 = lane & 15;
;     const float* xp = xin + (size_t)(rb + prow) * D + cb + c4 * 4;
;     float* op = xout + (size_t)(rb + prow) * D + cb + c4 * 4;
.LBB0_1317:
	v_lshrrev_b32_e32 v194, 4, v206
	s_waitcnt lgkmcnt(0)
	v_mfma_f32_16x16x32_bf16 v[200:203], v[58:61], v[2:5], v[126:129]
	v_mfma_f32_16x16x32_bf16 v[206:209], v[58:61], v[138:141], v[122:125]
	v_mfma_f32_16x16x32_bf16 v[212:215], v[58:61], v[182:185], v[118:121]
	v_mfma_f32_16x16x32_bf16 v[222:225], v[58:61], v[186:189], v[114:117]
	v_mfma_f32_16x16x32_bf16 v[150:153], v[50:53], v[2:5], v[110:113]
	v_mfma_f32_16x16x32_bf16 v[154:157], v[50:53], v[138:141], v[106:109]
	v_mfma_f32_16x16x32_bf16 v[142:145], v[50:53], v[182:185], v[102:105]
	v_mfma_f32_16x16x32_bf16 v[146:149], v[50:53], v[186:189], v[98:101]
	v_mfma_f32_16x16x32_bf16 v[118:121], v[42:45], v[2:5], v[94:97]
	v_mfma_f32_16x16x32_bf16 v[122:125], v[42:45], v[138:141], v[90:93]
	v_mfma_f32_16x16x32_bf16 v[110:113], v[42:45], v[182:185], v[86:89]
	v_mfma_f32_16x16x32_bf16 v[114:117], v[42:45], v[186:189], v[82:85]
	v_mfma_f32_16x16x32_bf16 v[86:89], v[34:37], v[2:5], v[78:81]
	v_mfma_f32_16x16x32_bf16 v[90:93], v[34:37], v[138:141], v[74:77]
	v_mfma_f32_16x16x32_bf16 v[78:81], v[34:37], v[182:185], v[70:73]
	v_mfma_f32_16x16x32_bf16 v[82:85], v[34:37], v[186:189], v[66:69]
	v_mfma_f32_16x16x32_bf16 v[58:61], v[26:29], v[2:5], v[62:65]
	v_mfma_f32_16x16x32_bf16 v[62:65], v[26:29], v[138:141], v[158:161]
	v_mfma_f32_16x16x32_bf16 v[50:53], v[26:29], v[182:185], v[54:57]
	v_mfma_f32_16x16x32_bf16 v[54:57], v[26:29], v[186:189], v[162:165]
	v_mfma_f32_16x16x32_bf16 v[42:45], v[18:21], v[2:5], v[46:49]
	v_mfma_f32_16x16x32_bf16 v[46:49], v[18:21], v[138:141], v[166:169]
	v_mfma_f32_16x16x32_bf16 v[34:37], v[18:21], v[182:185], v[38:41]
	v_mfma_f32_16x16x32_bf16 v[38:41], v[18:21], v[186:189], v[170:173]
	v_mfma_f32_16x16x32_bf16 v[26:29], v[10:13], v[2:5], v[30:33]
	v_mfma_f32_16x16x32_bf16 v[30:33], v[10:13], v[138:141], v[174:177]
	v_mfma_f32_16x16x32_bf16 v[18:21], v[10:13], v[182:185], v[22:25]
	v_mfma_f32_16x16x32_bf16 v[22:25], v[10:13], v[186:189], v[178:181]
	v_mfma_f32_16x16x32_bf16 v[10:13], v[190:193], v[2:5], v[14:17]
	v_mfma_f32_16x16x32_bf16 v[14:17], v[190:193], v[138:141], v[130:133]
	v_mfma_f32_16x16x32_bf16 v[2:5], v[190:193], v[182:185], v[6:9]
	v_mfma_f32_16x16x32_bf16 v[6:9], v[190:193], v[186:189], v[134:137]
	v_add_u32_e32 v0, s31, v205
	v_or_b32_e32 v178, v0, v194
	v_ashrrev_i32_e32 v179, 31, v178
	v_readlane_b32 s8, v254, 0
	v_lshl_or_b32 v182, v204, 6, s70
	v_lshlrev_b64 v[66:67], 12, v[178:179]
	v_readlane_b32 s10, v254, 2
	v_readlane_b32 s11, v254, 3
	v_ashrrev_i32_e32 v183, 31, v182
	v_lshlrev_b32_e32 v0, 2, v199
	v_lshl_add_u64 v[66:67], s[10:11], 0, v[66:67]
	v_lshl_add_u64 v[66:67], v[182:183], 2, v[66:67]
	v_lshl_add_u64 v[180:181], v[66:67], 0, v[0:1]
	s_movk_i32 s0, 0x4000
	v_add_co_u32_e32 v66, vcc, s0, v180
	s_mov_b32 s0, 0x8000
	s_nop 0
	v_addc_co_u32_e32 v67, vcc, 0, v181, vcc
	s_waitcnt vmcnt(0)
	s_waitcnt vmcnt(0)
	s_barrier
; DI unsigned pack_bf16(float lo, float hi) { f32x2 v = {lo, hi}; bf16v2 b = __builtin_convertvector(v, bf16v2); return __builtin_bit_cast(unsigned, b); }
; DI float red16(float v) { v += __shfl_xor(v, 1); v += __shfl_xor(v, 2); v += __shfl_xor(v, 4); v += __shfl_xor(v, 8); return v; }
;   DI void run8(f32x4 (&acc)[8][4], int rb, int cb, int fr, int fq) const {
;     ...
;         for (int ps = 0; ps < 4; ++ps) xv[mm][ps] = __builtin_nontemporal_load((const f32x4*)(xp + (size_t)((mh * 4 + mm) * 16 + ps * 4) * D));
;       __builtin_amdgcn_sched_barrier(0);
; #pragma unroll
;       for (int mm = 0; mm < 4; ++mm) {
;         const int m = mh * 4 + mm;
; #pragma unroll
;         for (int n = 0; n < 4; ++n)
; #pragma unroll
;           for (int j = 0; j < 4; ++j) scr[(fq * 4 + j) * 68 + n * 16 + fr] = acc[m][n][j];
;         __builtin_amdgcn_sched_barrier(0);
; #pragma unroll
;         for (int ps = 0; ps < 4; ++ps) {
;           const f32x4 a = *(const f32x4*)(scr + (ps * 4 + prow) * 68 + c4 * 4);
;           f32x4 v;
;           v.x = xv[mm][ps].x + a.x * sc; v.y = xv[mm][ps].y + a.y * sc; v.z = xv[mm][ps].z + a.z * sc; v.w = xv[mm][ps].w + a.w * sc;
;           const int grow = rb + m * 16 + ps * 4 + prow;
;           __builtin_nontemporal_store(v, (f32x4*)(op + (size_t)(m * 16 + ps * 4) * D));
;           if (xbp) {
;             u32x2 o; o.x = pack_bf16(v.x, v.y); o.y = pack_bf16(v.z, v.w);
;             *(u32x2*)(xbp + (size_t)grow * LDH + cb + c4 * 4) = o;
;             const float t = red16(v.x * v.x + v.y * v.y + v.z * v.z + v.w * v.w);
;             if (c4 == 0) atomicAdd(ssqp + grow, t);
;           }
	global_load_dwordx4 v[174:177], v[180:181], off nt
	global_load_dwordx4 v[170:173], v[66:67], off nt
	v_add_co_u32_e32 v66, vcc, s0, v180
	s_mov_b32 s0, 0xc000
	s_nop 0
	v_addc_co_u32_e32 v67, vcc, 0, v181, vcc
	v_add_co_u32_e32 v68, vcc, s0, v180
	s_mov_b32 s0, 0x14000
	s_nop 0
	v_addc_co_u32_e32 v69, vcc, 0, v181, vcc
	global_load_dwordx4 v[166:169], v[66:67], off nt
	global_load_dwordx4 v[162:165], v[68:69], off nt
	v_add_co_u32_e32 v66, vcc, s92, v180
	v_readlane_b32 s9, v254, 1
	s_nop 0
	v_addc_co_u32_e32 v67, vcc, 0, v181, vcc
	v_add_co_u32_e32 v68, vcc, s0, v180
	s_mov_b32 s0, 0x18000
	s_nop 0
	v_addc_co_u32_e32 v69, vcc, 0, v181, vcc
	global_load_dwordx4 v[158:161], v[66:67], off nt
	global_load_dwordx4 v[138:141], v[68:69], off nt
	v_add_co_u32_e32 v66, vcc, s0, v180
	s_mov_b32 s0, 0x1c000
	s_nop 0
	v_addc_co_u32_e32 v67, vcc, 0, v181, vcc
	v_add_co_u32_e32 v68, vcc, s0, v180
	s_mov_b32 s0, 0x20000
	s_nop 0
	v_addc_co_u32_e32 v69, vcc, 0, v181, vcc
	global_load_dwordx4 v[134:137], v[66:67], off nt
	global_load_dwordx4 v[130:133], v[68:69], off nt
	v_add_co_u32_e32 v66, vcc, s0, v180
	s_mov_b32 s0, 0x24000
	s_nop 0
	v_addc_co_u32_e32 v67, vcc, 0, v181, vcc
	v_add_co_u32_e32 v68, vcc, s0, v180
	s_mov_b32 s0, 0x28000
	s_nop 0
	v_addc_co_u32_e32 v69, vcc, 0, v181, vcc
	global_load_dwordx4 v[126:129], v[66:67], off nt
	global_load_dwordx4 v[106:109], v[68:69], off nt
	v_add_co_u32_e32 v66, vcc, s0, v180
	s_mov_b32 s0, 0x2c000
	s_nop 0
	v_addc_co_u32_e32 v67, vcc, 0, v181, vcc
	v_add_co_u32_e32 v68, vcc, s0, v180
	s_mov_b32 s0, 0x30000
	s_nop 0
	v_addc_co_u32_e32 v69, vcc, 0, v181, vcc
	global_load_dwordx4 v[102:105], v[66:67], off nt
	global_load_dwordx4 v[98:101], v[68:69], off nt
	v_add_co_u32_e32 v66, vcc, s0, v180
	s_mov_b32 s0, 0x34000
	s_nop 0
	v_addc_co_u32_e32 v67, vcc, 0, v181, vcc
	v_add_co_u32_e32 v68, vcc, s0, v180
	s_mov_b32 s0, 0x38000
	s_nop 0
	v_addc_co_u32_e32 v69, vcc, 0, v181, vcc
	global_load_dwordx4 v[94:97], v[66:67], off nt
	global_load_dwordx4 v[74:77], v[68:69], off nt
	v_add_co_u32_e32 v66, vcc, s0, v180
	s_mov_b32 s0, 0x3c000
	s_nop 0
	v_addc_co_u32_e32 v67, vcc, 0, v181, vcc
	v_add_co_u32_e32 v68, vcc, s0, v180
	v_lshl_add_u32 v184, v198, 2, v218
	s_nop 0
	v_addc_co_u32_e32 v69, vcc, 0, v181, vcc
	global_load_dwordx4 v[70:73], v[66:67], off nt
	s_nop 0
	global_load_dwordx4 v[66:69], v[68:69], off nt
	v_lshl_add_u64 v[182:183], v[182:183], 1, s[50:51]
	v_lshlrev_b32_e32 v0, 1, v199
	v_mad_u32_u24 v185, v198, 12, v184
	v_lshl_add_u64 v[182:183], v[182:183], 0, v[0:1]
	v_cmp_eq_u32_e64 s[8:9], 0, v198
	v_mad_u32_u24 v184, v194, s88, v184
	ds_write2_b32 v184, v200, v206 offset1:16
	ds_write2_b32 v184, v201, v207 offset0:68 offset1:84
	ds_write2_b32 v184, v202, v208 offset0:136 offset1:152
	ds_write2_b32 v184, v203, v209 offset0:204 offset1:220
	ds_write2_b32 v184, v212, v222 offset0:32 offset1:48
	ds_write2_b32 v184, v213, v223 offset0:100 offset1:116
	ds_write2_b32 v184, v214, v224 offset0:168 offset1:184
	ds_write2_b32 v184, v215, v225 offset0:236 offset1:252
	s_movk_i32 s0, 0x110
	v_mad_u32_u24 v0, v194, s0, v185
	ds_read_b128 v[186:189], v0
	v_cndmask_b32_e64 v0, 0, 1, s[76:77]
	v_cmp_ne_u32_e64 s[10:11], 1, v0
	s_andn2_b64 vcc, exec, s[76:77]
	s_waitcnt vmcnt(15) lgkmcnt(0)
	v_pk_add_f32 v[176:177], v[176:177], v[188:189]
	v_pk_add_f32 v[174:175], v[174:175], v[186:187]
	global_store_dwordx4 v[180:181], v[174:177], off nt
	s_cbranch_vccnz .LBB0_1321
	v_cvt_pk_bf16_f32 v186, v174, v175
	v_pk_mul_f32 v[174:175], v[174:175], v[174:175]
	v_cvt_pk_bf16_f32 v187, v176, v177
	v_add_f32_e32 v0, v174, v175
	v_and_b32_e32 v175, 64, v219
	s_nop 0
	v_add_u32_e32 v175, 64, v175
	v_pk_mul_f32 v[176:177], v[176:177], v[176:177]
	s_nop 0
	v_add_f32_e32 v0, v176, v0
	v_add_f32_e32 v0, v177, v0
	s_nop 0
	s_nop 0
	v_mov_b32_dpp v174, v0 quad_perm:[1,0,3,2] row_mask:0xf bank_mask:0xf
	v_mad_i64_i32 v[188:189], s[0:1], v178, s66, v[182:183]
	global_store_dwordx2 v[188:189], v[186:187], off
	s_waitcnt lgkmcnt(0)
	v_add_f32_e32 v0, v0, v174
	s_nop 0
	s_nop 0
	s_nop 1
	s_nop 0
	s_nop 0
	v_mov_b32_dpp v174, v0 quad_perm:[2,3,0,1] row_mask:0xf bank_mask:0xf
	s_waitcnt lgkmcnt(0)
	v_add_f32_e32 v0, v0, v174
	s_nop 0
	s_nop 0
	s_nop 1
	s_nop 0
	s_nop 0
	v_mov_b32_dpp v174, v0 row_half_mirror row_mask:0xf bank_mask:0xf
	s_waitcnt lgkmcnt(0)
	v_add_f32_e32 v0, v0, v174
	v_xor_b32_e32 v174, 8, v219
	v_cmp_lt_i32_e32 vcc, v174, v175
	s_nop 1
	s_nop 0
	s_nop 0
	v_mov_b32_dpp v174, v0 row_mirror row_mask:0xf bank_mask:0xf
	s_and_saveexec_b64 s[0:1], s[8:9]
	s_cbranch_execz .LBB0_1320
	s_waitcnt lgkmcnt(0)
	v_add_f32_e32 v0, v0, v174
	v_lshl_add_u64 v[174:175], v[178:179], 2, s[60:61]
	global_atomic_add_f32 v[174:175], v0, off

; DI unsigned pack_bf16(float lo, float hi) { f32x2 v = {lo, hi}; bf16v2 b = __builtin_convertvector(v, bf16v2); return __builtin_bit_cast(unsigned, b); }
; DI float red16(float v) { v += __shfl_xor(v, 1); v += __shfl_xor(v, 2); v += __shfl_xor(v, 4); v += __shfl_xor(v, 8); return v; }
;   DI void run8(f32x4 (&acc)[8][4], int rb, int cb, int fr, int fq) const {
;     ...
;         for (int ps = 0; ps < 4; ++ps) {
;           const f32x4 a = *(const f32x4*)(scr + (ps * 4 + prow) * 68 + c4 * 4);
;           f32x4 v;
;           v.x = xv[mm][ps].x + a.x * sc; v.y = xv[mm][ps].y + a.y * sc; v.z = xv[mm][ps].z + a.z * sc; v.w = xv[mm][ps].w + a.w * sc;
;           const int grow = rb + m * 16 + ps * 4 + prow;
;           __builtin_nontemporal_store(v, (f32x4*)(op + (size_t)(m * 16 + ps * 4) * D));
;           if (xbp) {
;             u32x2 o; o.x = pack_bf16(v.x, v.y); o.y = pack_bf16(v.z, v.w);
;             *(u32x2*)(xbp + (size_t)grow * LDH + cb + c4 * 4) = o;
;             const float t = red16(v.x * v.x + v.y * v.y + v.z * v.z + v.w * v.w);
;             if (c4 == 0) atomicAdd(ssqp + grow, t);
;           }
.LBB0_1321:
	v_mul_u32_u24_e32 v0, 0x110, v194
	v_add_u32_e32 v0, v185, v0
	s_waitcnt lgkmcnt(0)
	ds_read_b128 v[174:177], v0 offset:1088
	s_mov_b64 s[0:1], 0x4000
	v_lshl_add_u64 v[186:187], v[180:181], 0, s[0:1]
	s_and_b64 vcc, exec, s[10:11]
	s_waitcnt vmcnt(15) lgkmcnt(0)
	v_pk_add_f32 v[172:173], v[172:173], v[176:177]
	v_pk_add_f32 v[170:171], v[170:171], v[174:175]
	global_store_dwordx4 v[186:187], v[170:173], off nt
	s_cbranch_vccnz .LBB0_1325
	v_pk_mul_f32 v[176:177], v[170:171], v[170:171]
	v_pk_mul_f32 v[174:175], v[172:173], v[172:173]
	v_add_f32_e32 v176, v176, v177
	v_add_f32_e32 v174, v174, v176
	v_and_b32_e32 v176, 64, v219
	v_add_f32_e32 v174, v175, v174
	s_nop 0
	v_add_u32_e32 v177, 64, v176
	s_nop 0
	v_cvt_pk_bf16_f32 v176, v170, v171
	v_xor_b32_e32 v171, 8, v219
	s_nop 0
	s_nop 0
	v_mov_b32_dpp v175, v174 quad_perm:[1,0,3,2] row_mask:0xf bank_mask:0xf
	s_waitcnt lgkmcnt(0)
	v_add_f32_e32 v174, v174, v175
	s_nop 0
	s_nop 0
	s_nop 1
	s_nop 0
	s_nop 0
	v_mov_b32_dpp v175, v174 quad_perm:[2,3,0,1] row_mask:0xf bank_mask:0xf
	s_waitcnt lgkmcnt(0)
	v_add_f32_e32 v175, v174, v175
	s_nop 0
	s_nop 0
	s_nop 1
	s_nop 0
	s_nop 0
	v_mov_b32_dpp v179, v175 row_half_mirror row_mask:0xf bank_mask:0xf
	v_cmp_lt_i32_e32 vcc, v171, v177
	v_or_b32_e32 v174, 4, v178
	v_cvt_pk_bf16_f32 v177, v172, v173
	s_nop 0
	s_waitcnt lgkmcnt(0)
	v_add_f32_e32 v170, v175, v179
	s_nop 0
	s_nop 0
	v_mov_b32_dpp v171, v170 row_mirror row_mask:0xf bank_mask:0xf
	v_mad_i64_i32 v[172:173], s[0:1], v174, s66, v[182:183]
	global_store_dwordx2 v[172:173], v[176:177], off
	s_and_saveexec_b64 s[0:1], s[8:9]
	s_cbranch_execz .LBB0_1324
	v_ashrrev_i32_e32 v175, 31, v174
	s_waitcnt lgkmcnt(0)
	v_add_f32_e32 v172, v170, v171
	v_lshl_add_u64 v[170:171], v[174:175], 2, s[60:61]
	global_atomic_add_f32 v[170:171], v172, off

; DI unsigned pack_bf16(float lo, float hi) { f32x2 v = {lo, hi}; bf16v2 b = __builtin_convertvector(v, bf16v2); return __builtin_bit_cast(unsigned, b); }
; DI float red16(float v) { v += __shfl_xor(v, 1); v += __shfl_xor(v, 2); v += __shfl_xor(v, 4); v += __shfl_xor(v, 8); return v; }
;   DI void run8(f32x4 (&acc)[8][4], int rb, int cb, int fr, int fq) const {
;     ...
;         for (int ps = 0; ps < 4; ++ps) {
;           const f32x4 a = *(const f32x4*)(scr + (ps * 4 + prow) * 68 + c4 * 4);
;           f32x4 v;
;           v.x = xv[mm][ps].x + a.x * sc; v.y = xv[mm][ps].y + a.y * sc; v.z = xv[mm][ps].z + a.z * sc; v.w = xv[mm][ps].w + a.w * sc;
;           const int grow = rb + m * 16 + ps * 4 + prow;
;           __builtin_nontemporal_store(v, (f32x4*)(op + (size_t)(m * 16 + ps * 4) * D));
;           if (xbp) {
;             u32x2 o; o.x = pack_bf16(v.x, v.y); o.y = pack_bf16(v.z, v.w);
;             *(u32x2*)(xbp + (size_t)grow * LDH + cb + c4 * 4) = o;
;             const float t = red16(v.x * v.x + v.y * v.y + v.z * v.z + v.w * v.w);
;             if (c4 == 0) atomicAdd(ssqp + grow, t);
;           }
.LBB0_1325:
	s_waitcnt lgkmcnt(0)
	ds_read_b128 v[170:173], v0 offset:2176
	v_lshl_add_u64 v[174:175], v[180:181], 0, s[82:83]
	s_and_b64 vcc, exec, s[10:11]
	s_waitcnt vmcnt(15) lgkmcnt(0)
	v_pk_add_f32 v[168:169], v[168:169], v[172:173]
	v_pk_add_f32 v[166:167], v[166:167], v[170:171]
	global_store_dwordx4 v[174:175], v[166:169], off nt
	s_cbranch_vccnz .LBB0_1329
	v_pk_mul_f32 v[172:173], v[166:167], v[166:167]
	v_pk_mul_f32 v[170:171], v[168:169], v[168:169]
	v_add_f32_e32 v172, v172, v173
	v_add_f32_e32 v170, v170, v172
	v_and_b32_e32 v172, 64, v219
	v_add_f32_e32 v170, v171, v170
	s_nop 0
	v_add_u32_e32 v173, 64, v172
	s_nop 0
	v_cvt_pk_bf16_f32 v172, v166, v167
	v_xor_b32_e32 v167, 8, v219
	s_nop 0
	s_nop 0
	v_mov_b32_dpp v171, v170 quad_perm:[1,0,3,2] row_mask:0xf bank_mask:0xf
	s_waitcnt lgkmcnt(0)
	v_add_f32_e32 v170, v170, v171
	s_nop 0
	s_nop 0
	s_nop 1
	s_nop 0
	s_nop 0
	v_mov_b32_dpp v171, v170 quad_perm:[2,3,0,1] row_mask:0xf bank_mask:0xf
	s_waitcnt lgkmcnt(0)
	v_add_f32_e32 v171, v170, v171
	s_nop 0
	s_nop 0
	s_nop 1
	s_nop 0
	s_nop 0
	v_mov_b32_dpp v174, v171 row_half_mirror row_mask:0xf bank_mask:0xf
	v_cmp_lt_i32_e32 vcc, v167, v173
	v_or_b32_e32 v170, 8, v178
	v_cvt_pk_bf16_f32 v173, v168, v169
	s_nop 0
	s_waitcnt lgkmcnt(0)
	v_add_f32_e32 v166, v171, v174
	s_nop 0
	s_nop 0
	v_mov_b32_dpp v167, v166 row_mirror row_mask:0xf bank_mask:0xf
	v_mad_i64_i32 v[168:169], s[0:1], v170, s66, v[182:183]
	global_store_dwordx2 v[168:169], v[172:173], off
	s_and_saveexec_b64 s[0:1], s[8:9]
	s_cbranch_execz .LBB0_1328
	v_ashrrev_i32_e32 v171, 31, v170
	s_waitcnt lgkmcnt(0)
	v_add_f32_e32 v168, v166, v167
	v_lshl_add_u64 v[166:167], v[170:171], 2, s[60:61]
	global_atomic_add_f32 v[166:167], v168, off

; DI unsigned pack_bf16(float lo, float hi) { f32x2 v = {lo, hi}; bf16v2 b = __builtin_convertvector(v, bf16v2); return __builtin_bit_cast(unsigned, b); }
; DI float red16(float v) { v += __shfl_xor(v, 1); v += __shfl_xor(v, 2); v += __shfl_xor(v, 4); v += __shfl_xor(v, 8); return v; }
;   DI void run8(f32x4 (&acc)[8][4], int rb, int cb, int fr, int fq) const {
;     ...
;         for (int ps = 0; ps < 4; ++ps) {
;           const f32x4 a = *(const f32x4*)(scr + (ps * 4 + prow) * 68 + c4 * 4);
;           f32x4 v;
;           v.x = xv[mm][ps].x + a.x * sc; v.y = xv[mm][ps].y + a.y * sc; v.z = xv[mm][ps].z + a.z * sc; v.w = xv[mm][ps].w + a.w * sc;
;           const int grow = rb + m * 16 + ps * 4 + prow;
;           __builtin_nontemporal_store(v, (f32x4*)(op + (size_t)(m * 16 + ps * 4) * D));
;           if (xbp) {
;             u32x2 o; o.x = pack_bf16(v.x, v.y); o.y = pack_bf16(v.z, v.w);
;             *(u32x2*)(xbp + (size_t)grow * LDH + cb + c4 * 4) = o;
;             const float t = red16(v.x * v.x + v.y * v.y + v.z * v.z + v.w * v.w);
;             if (c4 == 0) atomicAdd(ssqp + grow, t);
;           }
.LBB0_1329:
	s_waitcnt lgkmcnt(0)
	ds_read_b128 v[166:169], v0 offset:3264
	s_mov_b64 s[0:1], 0xc000
	v_lshl_add_u64 v[170:171], v[180:181], 0, s[0:1]
	s_and_b64 vcc, exec, s[10:11]
	s_waitcnt vmcnt(15) lgkmcnt(0)
	v_pk_add_f32 v[164:165], v[164:165], v[168:169]
	v_pk_add_f32 v[162:163], v[162:163], v[166:167]
	global_store_dwordx4 v[170:171], v[162:165], off nt
	s_cbranch_vccnz .LBB0_1333
	v_pk_mul_f32 v[168:169], v[162:163], v[162:163]
	v_pk_mul_f32 v[166:167], v[164:165], v[164:165]
	v_add_f32_e32 v168, v168, v169
	v_add_f32_e32 v166, v166, v168
	v_and_b32_e32 v168, 64, v219
	v_add_f32_e32 v166, v167, v166
	s_nop 0
	v_add_u32_e32 v169, 64, v168
	s_nop 0
	v_cvt_pk_bf16_f32 v168, v162, v163
	v_xor_b32_e32 v163, 8, v219
	s_nop 0
	s_nop 0
	v_mov_b32_dpp v167, v166 quad_perm:[1,0,3,2] row_mask:0xf bank_mask:0xf
	s_waitcnt lgkmcnt(0)
	v_add_f32_e32 v166, v166, v167
	s_nop 0
	s_nop 0
	s_nop 1
	s_nop 0
	s_nop 0
	v_mov_b32_dpp v167, v166 quad_perm:[2,3,0,1] row_mask:0xf bank_mask:0xf
	s_waitcnt lgkmcnt(0)
	v_add_f32_e32 v167, v166, v167
	s_nop 0
	s_nop 0
	s_nop 1
	s_nop 0
	s_nop 0
	v_mov_b32_dpp v170, v167 row_half_mirror row_mask:0xf bank_mask:0xf
	v_cmp_lt_i32_e32 vcc, v163, v169
	v_or_b32_e32 v166, 12, v178
	v_cvt_pk_bf16_f32 v169, v164, v165
	s_nop 0
	s_waitcnt lgkmcnt(0)
	v_add_f32_e32 v162, v167, v170
	s_nop 0
	s_nop 0
	v_mov_b32_dpp v163, v162 row_mirror row_mask:0xf bank_mask:0xf
	v_mad_i64_i32 v[164:165], s[0:1], v166, s66, v[182:183]
	global_store_dwordx2 v[164:165], v[168:169], off
	s_and_saveexec_b64 s[0:1], s[8:9]
	s_cbranch_execz .LBB0_1332
	v_ashrrev_i32_e32 v167, 31, v166
	s_waitcnt lgkmcnt(0)
	v_add_f32_e32 v164, v162, v163
	v_lshl_add_u64 v[162:163], v[166:167], 2, s[60:61]
	global_atomic_add_f32 v[162:163], v164, off

; DI unsigned pack_bf16(float lo, float hi) { f32x2 v = {lo, hi}; bf16v2 b = __builtin_convertvector(v, bf16v2); return __builtin_bit_cast(unsigned, b); }
; DI float red16(float v) { v += __shfl_xor(v, 1); v += __shfl_xor(v, 2); v += __shfl_xor(v, 4); v += __shfl_xor(v, 8); return v; }
;   DI void run8(f32x4 (&acc)[8][4], int rb, int cb, int fr, int fq) const {
;     ...
;         for (int ps = 0; ps < 4; ++ps) {
;           const f32x4 a = *(const f32x4*)(scr + (ps * 4 + prow) * 68 + c4 * 4);
;           f32x4 v;
;           v.x = xv[mm][ps].x + a.x * sc; v.y = xv[mm][ps].y + a.y * sc; v.z = xv[mm][ps].z + a.z * sc; v.w = xv[mm][ps].w + a.w * sc;
;           const int grow = rb + m * 16 + ps * 4 + prow;
;           __builtin_nontemporal_store(v, (f32x4*)(op + (size_t)(m * 16 + ps * 4) * D));
;           if (xbp) {
;             u32x2 o; o.x = pack_bf16(v.x, v.y); o.y = pack_bf16(v.z, v.w);
;             *(u32x2*)(xbp + (size_t)grow * LDH + cb + c4 * 4) = o;
;             const float t = red16(v.x * v.x + v.y * v.y + v.z * v.z + v.w * v.w);
;             if (c4 == 0) atomicAdd(ssqp + grow, t);
;           }
.LBB0_1340:
	s_waitcnt vmcnt(15)
	ds_read_b128 v[140:143], v0 offset:2176
	s_mov_b64 s[0:1], 0x18000
	s_waitcnt lgkmcnt(1)
	v_lshl_add_u64 v[144:145], v[180:181], 0, s[0:1]
	s_mov_b64 s[0:1], 0x1c000
	v_lshl_add_u64 v[138:139], v[180:181], 0, s[0:1]
	s_waitcnt vmcnt(14) lgkmcnt(0)
	v_pk_add_f32 v[136:137], v[136:137], v[142:143]
	v_pk_add_f32 v[134:135], v[134:135], v[140:141]
	s_and_b64 vcc, exec, s[10:11]
	global_store_dwordx4 v[144:145], v[134:137], off nt
	s_cbranch_vccnz .LBB0_1445
	v_pk_mul_f32 v[142:143], v[134:135], v[134:135]
	v_pk_mul_f32 v[140:141], v[136:137], v[136:137]
	v_add_f32_e32 v142, v142, v143
	v_add_f32_e32 v140, v140, v142
	v_add_f32_e32 v140, v141, v140
	v_and_b32_e32 v141, 64, v219
	v_xor_b32_e32 v143, 1, v219
	v_add_u32_e32 v142, 64, v141
	s_nop 0
	v_xor_b32_e32 v145, 2, v219
	v_xor_b32_e32 v144, 4, v219
	s_nop 0
	s_nop 0
	v_mov_b32_dpp v141, v140 quad_perm:[1,0,3,2] row_mask:0xf bank_mask:0xf
	s_nop 0
	v_cvt_pk_bf16_f32 v148, v134, v135
	v_cvt_pk_bf16_f32 v149, v136, v137
	s_waitcnt lgkmcnt(0)
	v_add_f32_e32 v140, v140, v141
	s_nop 0
	s_nop 0
	v_mov_b32_dpp v141, v140 quad_perm:[2,3,0,1] row_mask:0xf bank_mask:0xf
	s_nop 0
	s_waitcnt lgkmcnt(0)
	v_add_f32_e32 v141, v140, v141
	s_nop 0
	s_nop 0
	v_mov_b32_dpp v146, v141 row_half_mirror row_mask:0xf bank_mask:0xf
	v_or_b32_e32 v140, 24, v178
	v_mad_i64_i32 v[136:137], s[0:1], v140, s66, v[182:183]
	global_store_dwordx2 v[136:137], v[148:149], off
	s_waitcnt lgkmcnt(0)
	v_add_f32_e32 v134, v141, v146
	v_xor_b32_e32 v146, 8, v219
	v_cmp_lt_i32_e32 vcc, v146, v142
	s_nop 1
	s_nop 0
	s_nop 0
	v_mov_b32_dpp v135, v134 row_mirror row_mask:0xf bank_mask:0xf
	s_and_saveexec_b64 s[0:1], s[8:9]
	s_cbranch_execz .LBB0_1343
	v_ashrrev_i32_e32 v141, 31, v140
	s_waitcnt lgkmcnt(0)
	v_add_f32_e32 v136, v134, v135
	v_lshl_add_u64 v[134:135], v[140:141], 2, s[60:61]
	global_atomic_add_f32 v[134:135], v136, off

; DI unsigned pack_bf16(float lo, float hi) { f32x2 v = {lo, hi}; bf16v2 b = __builtin_convertvector(v, bf16v2); return __builtin_bit_cast(unsigned, b); }
; DI float red16(float v) { v += __shfl_xor(v, 1); v += __shfl_xor(v, 2); v += __shfl_xor(v, 4); v += __shfl_xor(v, 8); return v; }
;   DI void run8(f32x4 (&acc)[8][4], int rb, int cb, int fr, int fq) const {
;     ...
;         for (int ps = 0; ps < 4; ++ps) {
;           const f32x4 a = *(const f32x4*)(scr + (ps * 4 + prow) * 68 + c4 * 4);
;           f32x4 v;
;           v.x = xv[mm][ps].x + a.x * sc; v.y = xv[mm][ps].y + a.y * sc; v.z = xv[mm][ps].z + a.z * sc; v.w = xv[mm][ps].w + a.w * sc;
;           const int grow = rb + m * 16 + ps * 4 + prow;
;           __builtin_nontemporal_store(v, (f32x4*)(op + (size_t)(m * 16 + ps * 4) * D));
;           if (xbp) {
;             u32x2 o; o.x = pack_bf16(v.x, v.y); o.y = pack_bf16(v.z, v.w);
;             *(u32x2*)(xbp + (size_t)grow * LDH + cb + c4 * 4) = o;
;             const float t = red16(v.x * v.x + v.y * v.y + v.z * v.z + v.w * v.w);
;             if (c4 == 0) atomicAdd(ssqp + grow, t);
;           }
.LBB0_1356:
	s_waitcnt vmcnt(13)
	ds_read_b128 v[108:111], v0 offset:2176
	s_mov_b64 s[0:1], 0x28000
	s_waitcnt lgkmcnt(1)
	v_lshl_add_u64 v[112:113], v[180:181], 0, s[0:1]
	s_mov_b64 s[0:1], 0x2c000
	v_lshl_add_u64 v[106:107], v[180:181], 0, s[0:1]
	s_waitcnt vmcnt(12) lgkmcnt(0)
	v_pk_add_f32 v[104:105], v[104:105], v[110:111]
	v_pk_add_f32 v[102:103], v[102:103], v[108:109]
	s_and_b64 vcc, exec, s[10:11]
	global_store_dwordx4 v[112:113], v[102:105], off nt
	s_cbranch_vccnz .LBB0_1447
	v_or_b32_e32 v108, 40, v178
	v_cvt_pk_bf16_f32 v110, v102, v103
	v_pk_mul_f32 v[102:103], v[102:103], v[102:103]
	v_cvt_pk_bf16_f32 v111, v104, v105
	v_mad_i64_i32 v[112:113], s[0:1], v108, s66, v[182:183]
	v_add_f32_e32 v102, v102, v103
	v_and_b32_e32 v103, 64, v219
	global_store_dwordx2 v[112:113], v[110:111], off
	v_xor_b32_e32 v111, 1, v219
	v_add_u32_e32 v110, 64, v103
	v_pk_mul_f32 v[104:105], v[104:105], v[104:105]
	s_nop 0
	v_add_f32_e32 v102, v104, v102
	v_add_f32_e32 v102, v105, v102
	s_nop 0
	s_nop 0
	v_mov_b32_dpp v103, v102 quad_perm:[1,0,3,2] row_mask:0xf bank_mask:0xf
	v_xor_b32_e32 v113, 2, v219
	s_nop 0
	v_xor_b32_e32 v112, 4, v219
	v_xor_b32_e32 v114, 8, v219
	s_waitcnt lgkmcnt(0)
	v_add_f32_e32 v102, v102, v103
	s_nop 0
	s_nop 0
	v_mov_b32_dpp v103, v102 quad_perm:[2,3,0,1] row_mask:0xf bank_mask:0xf
	s_nop 0
	s_waitcnt lgkmcnt(0)
	v_add_f32_e32 v102, v102, v103
	s_nop 0
	s_nop 0
	v_mov_b32_dpp v103, v102 row_half_mirror row_mask:0xf bank_mask:0xf
	v_cmp_lt_i32_e32 vcc, v114, v110
	s_waitcnt lgkmcnt(0)
	v_add_f32_e32 v102, v102, v103
	s_nop 0
	s_nop 0
	v_mov_b32_dpp v103, v102 row_mirror row_mask:0xf bank_mask:0xf
	s_and_saveexec_b64 s[0:1], s[8:9]
	s_cbranch_execz .LBB0_1359
	v_ashrrev_i32_e32 v109, 31, v108
	s_waitcnt lgkmcnt(0)
	v_add_f32_e32 v104, v102, v103
	v_lshl_add_u64 v[102:103], v[108:109], 2, s[60:61]
	global_atomic_add_f32 v[102:103], v104, off

; DI unsigned pack_bf16(float lo, float hi) { f32x2 v = {lo, hi}; bf16v2 b = __builtin_convertvector(v, bf16v2); return __builtin_bit_cast(unsigned, b); }
; DI float red16(float v) { v += __shfl_xor(v, 1); v += __shfl_xor(v, 2); v += __shfl_xor(v, 4); v += __shfl_xor(v, 8); return v; }
;   DI void run8(f32x4 (&acc)[8][4], int rb, int cb, int fr, int fq) const {
;     ...
;         for (int ps = 0; ps < 4; ++ps) {
;           const f32x4 a = *(const f32x4*)(scr + (ps * 4 + prow) * 68 + c4 * 4);
;           f32x4 v;
;           v.x = xv[mm][ps].x + a.x * sc; v.y = xv[mm][ps].y + a.y * sc; v.z = xv[mm][ps].z + a.z * sc; v.w = xv[mm][ps].w + a.w * sc;
;           const int grow = rb + m * 16 + ps * 4 + prow;
;           __builtin_nontemporal_store(v, (f32x4*)(op + (size_t)(m * 16 + ps * 4) * D));
;           if (xbp) {
;             u32x2 o; o.x = pack_bf16(v.x, v.y); o.y = pack_bf16(v.z, v.w);
;             *(u32x2*)(xbp + (size_t)grow * LDH + cb + c4 * 4) = o;
;             const float t = red16(v.x * v.x + v.y * v.y + v.z * v.z + v.w * v.w);
;             if (c4 == 0) atomicAdd(ssqp + grow, t);
;           }
.LBB0_1372:
	s_waitcnt vmcnt(11)
	ds_read_b128 v[76:79], v0 offset:2176
	s_mov_b64 s[0:1], 0x38000
	s_waitcnt lgkmcnt(1)
	v_lshl_add_u64 v[80:81], v[180:181], 0, s[0:1]
	s_mov_b64 s[0:1], 0x3c000
	v_lshl_add_u64 v[74:75], v[180:181], 0, s[0:1]
	s_waitcnt vmcnt(10) lgkmcnt(0)
	v_pk_add_f32 v[72:73], v[72:73], v[78:79]
	v_pk_add_f32 v[70:71], v[70:71], v[76:77]
	s_and_b64 vcc, exec, s[10:11]
	global_store_dwordx4 v[80:81], v[70:73], off nt
	s_cbranch_vccnz .LBB0_1449
	v_or_b32_e32 v76, 56, v178
	v_cvt_pk_bf16_f32 v78, v70, v71
	v_pk_mul_f32 v[70:71], v[70:71], v[70:71]
	v_cvt_pk_bf16_f32 v79, v72, v73
	v_mad_i64_i32 v[80:81], s[0:1], v76, s66, v[182:183]
	v_add_f32_e32 v70, v70, v71
	v_and_b32_e32 v71, 64, v219
	global_store_dwordx2 v[80:81], v[78:79], off
	v_xor_b32_e32 v79, 1, v219
	v_add_u32_e32 v78, 64, v71
	v_pk_mul_f32 v[72:73], v[72:73], v[72:73]
	s_nop 0
	v_add_f32_e32 v70, v72, v70
	v_add_f32_e32 v70, v73, v70
	s_nop 0
	s_nop 0
	v_mov_b32_dpp v71, v70 quad_perm:[1,0,3,2] row_mask:0xf bank_mask:0xf
	v_xor_b32_e32 v81, 2, v219
	s_nop 0
	v_xor_b32_e32 v80, 4, v219
	v_xor_b32_e32 v82, 8, v219
	s_waitcnt lgkmcnt(0)
	v_add_f32_e32 v70, v70, v71
	s_nop 0
	s_nop 0
	v_mov_b32_dpp v71, v70 quad_perm:[2,3,0,1] row_mask:0xf bank_mask:0xf
	s_nop 0
	s_waitcnt lgkmcnt(0)
	v_add_f32_e32 v70, v70, v71
	s_nop 0
	s_nop 0
	v_mov_b32_dpp v71, v70 row_half_mirror row_mask:0xf bank_mask:0xf
	v_cmp_lt_i32_e32 vcc, v82, v78
	s_waitcnt lgkmcnt(0)
	v_add_f32_e32 v70, v70, v71
	s_nop 0
	s_nop 0
	v_mov_b32_dpp v71, v70 row_mirror row_mask:0xf bank_mask:0xf
	s_and_saveexec_b64 s[0:1], s[8:9]
	s_cbranch_execz .LBB0_1375
	v_ashrrev_i32_e32 v77, 31, v76
	s_waitcnt lgkmcnt(0)
	v_add_f32_e32 v72, v70, v71
	v_lshl_add_u64 v[70:71], v[76:77], 2, s[60:61]
	global_atomic_add_f32 v[70:71], v72, off

; DI unsigned pack_bf16(float lo, float hi) { f32x2 v = {lo, hi}; bf16v2 b = __builtin_convertvector(v, bf16v2); return __builtin_bit_cast(unsigned, b); }
; DI float red16(float v) { v += __shfl_xor(v, 1); v += __shfl_xor(v, 2); v += __shfl_xor(v, 4); v += __shfl_xor(v, 8); return v; }
;   DI void run8(f32x4 (&acc)[8][4], int rb, int cb, int fr, int fq) const {
;     ...
;         for (int ps = 0; ps < 4; ++ps) {
;           const f32x4 a = *(const f32x4*)(scr + (ps * 4 + prow) * 68 + c4 * 4);
;           f32x4 v;
;           v.x = xv[mm][ps].x + a.x * sc; v.y = xv[mm][ps].y + a.y * sc; v.z = xv[mm][ps].z + a.z * sc; v.w = xv[mm][ps].w + a.w * sc;
;           const int grow = rb + m * 16 + ps * 4 + prow;
;           __builtin_nontemporal_store(v, (f32x4*)(op + (size_t)(m * 16 + ps * 4) * D));
;           if (xbp) {
;             u32x2 o; o.x = pack_bf16(v.x, v.y); o.y = pack_bf16(v.z, v.w);
;             *(u32x2*)(xbp + (size_t)grow * LDH + cb + c4 * 4) = o;
;             const float t = red16(v.x * v.x + v.y * v.y + v.z * v.z + v.w * v.w);
;             if (c4 == 0) atomicAdd(ssqp + grow, t);
;           }
.LBB0_1388:
	s_waitcnt lgkmcnt(0)
	ds_read_b128 v[50:53], v0 offset:2176
	s_mov_b64 s[0:1], 0x48000
	v_lshl_add_u64 v[56:57], v[180:181], 0, s[0:1]
	s_mov_b64 s[0:1], 0x4c000
	v_lshl_add_u64 v[54:55], v[180:181], 0, s[0:1]
	s_waitcnt vmcnt(14) lgkmcnt(0)
	v_pk_add_f32 v[52:53], v[120:121], v[52:53]
	v_pk_add_f32 v[50:51], v[118:119], v[50:51]
	s_and_b64 vcc, exec, s[10:11]
	global_store_dwordx4 v[56:57], v[50:53], off nt
	s_cbranch_vccnz .LBB0_1451
	v_or_b32_e32 v56, 0x48, v178
	v_cvt_pk_bf16_f32 v58, v50, v51
	v_pk_mul_f32 v[50:51], v[50:51], v[50:51]
	v_cvt_pk_bf16_f32 v59, v52, v53
	v_mad_i64_i32 v[60:61], s[0:1], v56, s66, v[182:183]
	v_add_f32_e32 v50, v50, v51
	v_and_b32_e32 v51, 64, v219
	global_store_dwordx2 v[60:61], v[58:59], off
	v_xor_b32_e32 v59, 1, v219
	v_add_u32_e32 v58, 64, v51
	v_pk_mul_f32 v[52:53], v[52:53], v[52:53]
	s_nop 0
	v_add_f32_e32 v50, v52, v50
	v_add_f32_e32 v50, v53, v50
	s_nop 0
	s_nop 0
	v_mov_b32_dpp v51, v50 quad_perm:[1,0,3,2] row_mask:0xf bank_mask:0xf
	v_xor_b32_e32 v61, 2, v219
	s_nop 0
	v_xor_b32_e32 v60, 4, v219
	v_xor_b32_e32 v62, 8, v219
	s_waitcnt lgkmcnt(0)
	v_add_f32_e32 v50, v50, v51
	s_nop 0
	s_nop 0
	v_mov_b32_dpp v51, v50 quad_perm:[2,3,0,1] row_mask:0xf bank_mask:0xf
	s_nop 0
	s_waitcnt lgkmcnt(0)
	v_add_f32_e32 v50, v50, v51
	s_nop 0
	s_nop 0
	v_mov_b32_dpp v51, v50 row_half_mirror row_mask:0xf bank_mask:0xf
	v_cmp_lt_i32_e32 vcc, v62, v58
	s_waitcnt lgkmcnt(0)
	v_add_f32_e32 v50, v50, v51
	s_nop 0
	s_nop 0
	v_mov_b32_dpp v51, v50 row_mirror row_mask:0xf bank_mask:0xf
	s_and_saveexec_b64 s[0:1], s[8:9]
	s_cbranch_execz .LBB0_1391
	v_ashrrev_i32_e32 v57, 31, v56
	s_waitcnt lgkmcnt(0)
	v_add_f32_e32 v52, v50, v51
	v_lshl_add_u64 v[50:51], v[56:57], 2, s[60:61]
	global_atomic_add_f32 v[50:51], v52, off

; DI unsigned pack_bf16(float lo, float hi) { f32x2 v = {lo, hi}; bf16v2 b = __builtin_convertvector(v, bf16v2); return __builtin_bit_cast(unsigned, b); }
; DI float red16(float v) { v += __shfl_xor(v, 1); v += __shfl_xor(v, 2); v += __shfl_xor(v, 4); v += __shfl_xor(v, 8); return v; }
;   DI void run8(f32x4 (&acc)[8][4], int rb, int cb, int fr, int fq) const {
;     ...
;         for (int ps = 0; ps < 4; ++ps) {
;           const f32x4 a = *(const f32x4*)(scr + (ps * 4 + prow) * 68 + c4 * 4);
;           f32x4 v;
;           v.x = xv[mm][ps].x + a.x * sc; v.y = xv[mm][ps].y + a.y * sc; v.z = xv[mm][ps].z + a.z * sc; v.w = xv[mm][ps].w + a.w * sc;
;           const int grow = rb + m * 16 + ps * 4 + prow;
;           __builtin_nontemporal_store(v, (f32x4*)(op + (size_t)(m * 16 + ps * 4) * D));
;           if (xbp) {
;             u32x2 o; o.x = pack_bf16(v.x, v.y); o.y = pack_bf16(v.z, v.w);
;             *(u32x2*)(xbp + (size_t)grow * LDH + cb + c4 * 4) = o;
;             const float t = red16(v.x * v.x + v.y * v.y + v.z * v.z + v.w * v.w);
;             if (c4 == 0) atomicAdd(ssqp + grow, t);
;           }
.LBB0_1404:
	s_waitcnt lgkmcnt(0)
	ds_read_b128 v[34:37], v0 offset:2176
	s_mov_b64 s[0:1], 0x58000
	v_lshl_add_u64 v[40:41], v[180:181], 0, s[0:1]
	s_mov_b64 s[0:1], 0x5c000
	v_lshl_add_u64 v[38:39], v[180:181], 0, s[0:1]
	s_waitcnt vmcnt(12) lgkmcnt(0)
	v_pk_add_f32 v[36:37], v[104:105], v[36:37]
	v_pk_add_f32 v[34:35], v[102:103], v[34:35]
	s_and_b64 vcc, exec, s[10:11]
	global_store_dwordx4 v[40:41], v[34:37], off nt
	s_cbranch_vccnz .LBB0_1453
	v_or_b32_e32 v40, 0x58, v178
	v_cvt_pk_bf16_f32 v42, v34, v35
	v_pk_mul_f32 v[34:35], v[34:35], v[34:35]
	v_cvt_pk_bf16_f32 v43, v36, v37
	v_mad_i64_i32 v[44:45], s[0:1], v40, s66, v[182:183]
	v_add_f32_e32 v34, v34, v35
	v_and_b32_e32 v35, 64, v219
	global_store_dwordx2 v[44:45], v[42:43], off
	v_xor_b32_e32 v43, 1, v219
	v_add_u32_e32 v42, 64, v35
	v_pk_mul_f32 v[36:37], v[36:37], v[36:37]
	s_nop 0
	v_add_f32_e32 v34, v36, v34
	v_add_f32_e32 v34, v37, v34
	s_nop 0
	s_nop 0
	v_mov_b32_dpp v35, v34 quad_perm:[1,0,3,2] row_mask:0xf bank_mask:0xf
	v_xor_b32_e32 v45, 2, v219
	s_nop 0
	v_xor_b32_e32 v44, 4, v219
	v_xor_b32_e32 v46, 8, v219
	s_waitcnt lgkmcnt(0)
	v_add_f32_e32 v34, v34, v35
	s_nop 0
	s_nop 0
	v_mov_b32_dpp v35, v34 quad_perm:[2,3,0,1] row_mask:0xf bank_mask:0xf
	s_nop 0
	s_waitcnt lgkmcnt(0)
	v_add_f32_e32 v34, v34, v35
	s_nop 0
	s_nop 0
	v_mov_b32_dpp v35, v34 row_half_mirror row_mask:0xf bank_mask:0xf
	v_cmp_lt_i32_e32 vcc, v46, v42
	s_waitcnt lgkmcnt(0)
	v_add_f32_e32 v34, v34, v35
	s_nop 0
	s_nop 0
	v_mov_b32_dpp v35, v34 row_mirror row_mask:0xf bank_mask:0xf
	s_and_saveexec_b64 s[0:1], s[8:9]
	s_cbranch_execz .LBB0_1407
	v_ashrrev_i32_e32 v41, 31, v40
	s_waitcnt lgkmcnt(0)
	v_add_f32_e32 v36, v34, v35
	v_lshl_add_u64 v[34:35], v[40:41], 2, s[60:61]
	global_atomic_add_f32 v[34:35], v36, off

; DI unsigned pack_bf16(float lo, float hi) { f32x2 v = {lo, hi}; bf16v2 b = __builtin_convertvector(v, bf16v2); return __builtin_bit_cast(unsigned, b); }
; DI float red16(float v) { v += __shfl_xor(v, 1); v += __shfl_xor(v, 2); v += __shfl_xor(v, 4); v += __shfl_xor(v, 8); return v; }
;   DI void run8(f32x4 (&acc)[8][4], int rb, int cb, int fr, int fq) const {
;     ...
;         for (int ps = 0; ps < 4; ++ps) {
;           const f32x4 a = *(const f32x4*)(scr + (ps * 4 + prow) * 68 + c4 * 4);
;           f32x4 v;
;           v.x = xv[mm][ps].x + a.x * sc; v.y = xv[mm][ps].y + a.y * sc; v.z = xv[mm][ps].z + a.z * sc; v.w = xv[mm][ps].w + a.w * sc;
;           const int grow = rb + m * 16 + ps * 4 + prow;
;           __builtin_nontemporal_store(v, (f32x4*)(op + (size_t)(m * 16 + ps * 4) * D));
;           if (xbp) {
;             u32x2 o; o.x = pack_bf16(v.x, v.y); o.y = pack_bf16(v.z, v.w);
;             *(u32x2*)(xbp + (size_t)grow * LDH + cb + c4 * 4) = o;
;             const float t = red16(v.x * v.x + v.y * v.y + v.z * v.z + v.w * v.w);
;             if (c4 == 0) atomicAdd(ssqp + grow, t);
;           }
.LBB0_1420:
	s_waitcnt lgkmcnt(0)
	ds_read_b128 v[18:21], v0 offset:2176
	s_mov_b64 s[0:1], 0x68000
	v_lshl_add_u64 v[24:25], v[180:181], 0, s[0:1]
	s_mov_b64 s[0:1], 0x6c000
	v_lshl_add_u64 v[22:23], v[180:181], 0, s[0:1]
	s_waitcnt vmcnt(10) lgkmcnt(0)
	v_pk_add_f32 v[20:21], v[88:89], v[20:21]
	v_pk_add_f32 v[18:19], v[86:87], v[18:19]
	s_and_b64 vcc, exec, s[10:11]
	global_store_dwordx4 v[24:25], v[18:21], off nt
	s_cbranch_vccnz .LBB0_1455
	v_pk_mul_f32 v[26:27], v[18:19], v[18:19]
	v_pk_mul_f32 v[24:25], v[20:21], v[20:21]
	v_add_f32_e32 v26, v26, v27
	v_add_f32_e32 v24, v24, v26
	v_add_f32_e32 v24, v25, v24
	v_and_b32_e32 v25, 64, v219
	v_xor_b32_e32 v27, 1, v219
	v_add_u32_e32 v26, 64, v25
	s_nop 0
	v_xor_b32_e32 v29, 2, v219
	v_xor_b32_e32 v28, 4, v219
	s_nop 0
	s_nop 0
	v_mov_b32_dpp v25, v24 quad_perm:[1,0,3,2] row_mask:0xf bank_mask:0xf
	s_nop 0
	v_cvt_pk_bf16_f32 v32, v18, v19
	v_cvt_pk_bf16_f32 v33, v20, v21
	s_waitcnt lgkmcnt(0)
	v_add_f32_e32 v24, v24, v25
	s_nop 0
	s_nop 0
	v_mov_b32_dpp v25, v24 quad_perm:[2,3,0,1] row_mask:0xf bank_mask:0xf
	s_nop 0
	s_waitcnt lgkmcnt(0)
	v_add_f32_e32 v25, v24, v25
	s_nop 0
	s_nop 0
	v_mov_b32_dpp v30, v25 row_half_mirror row_mask:0xf bank_mask:0xf
	v_or_b32_e32 v24, 0x68, v178
	v_mad_i64_i32 v[20:21], s[0:1], v24, s66, v[182:183]
	global_store_dwordx2 v[20:21], v[32:33], off
	s_waitcnt lgkmcnt(0)
	v_add_f32_e32 v18, v25, v30
	v_xor_b32_e32 v30, 8, v219
	v_cmp_lt_i32_e32 vcc, v30, v26
	s_nop 1
	s_nop 0
	s_nop 0
	v_mov_b32_dpp v19, v18 row_mirror row_mask:0xf bank_mask:0xf
	s_and_saveexec_b64 s[0:1], s[8:9]
	s_cbranch_execz .LBB0_1423
	v_ashrrev_i32_e32 v25, 31, v24
	s_waitcnt lgkmcnt(0)
	v_add_f32_e32 v20, v18, v19
	v_lshl_add_u64 v[18:19], v[24:25], 2, s[60:61]
	global_atomic_add_f32 v[18:19], v20, off

; DI unsigned pack_bf16(float lo, float hi) { f32x2 v = {lo, hi}; bf16v2 b = __builtin_convertvector(v, bf16v2); return __builtin_bit_cast(unsigned, b); }
; DI float red16(float v) { v += __shfl_xor(v, 1); v += __shfl_xor(v, 2); v += __shfl_xor(v, 4); v += __shfl_xor(v, 8); return v; }
;   DI void run8(f32x4 (&acc)[8][4], int rb, int cb, int fr, int fq) const {
;     ...
;         for (int ps = 0; ps < 4; ++ps) {
;           const f32x4 a = *(const f32x4*)(scr + (ps * 4 + prow) * 68 + c4 * 4);
;           f32x4 v;
;           v.x = xv[mm][ps].x + a.x * sc; v.y = xv[mm][ps].y + a.y * sc; v.z = xv[mm][ps].z + a.z * sc; v.w = xv[mm][ps].w + a.w * sc;
;           const int grow = rb + m * 16 + ps * 4 + prow;
;           __builtin_nontemporal_store(v, (f32x4*)(op + (size_t)(m * 16 + ps * 4) * D));
;           if (xbp) {
;             u32x2 o; o.x = pack_bf16(v.x, v.y); o.y = pack_bf16(v.z, v.w);
;             *(u32x2*)(xbp + (size_t)grow * LDH + cb + c4 * 4) = o;
;             const float t = red16(v.x * v.x + v.y * v.y + v.z * v.z + v.w * v.w);
;             if (c4 == 0) atomicAdd(ssqp + grow, t);
;           }
.LBB0_1436:
	s_waitcnt lgkmcnt(0)
	ds_read_b128 v[2:5], v0 offset:2176
	s_mov_b64 s[0:1], 0x78000
	v_lshl_add_u64 v[8:9], v[180:181], 0, s[0:1]
	s_mov_b64 s[0:1], 0x7c000
	v_lshl_add_u64 v[6:7], v[180:181], 0, s[0:1]
	s_waitcnt vmcnt(8) lgkmcnt(0)
	v_pk_add_f32 v[4:5], v[72:73], v[4:5]
	v_pk_add_f32 v[2:3], v[70:71], v[2:3]
	s_and_b64 vcc, exec, s[10:11]
	global_store_dwordx4 v[8:9], v[2:5], off nt
	s_cbranch_vccnz .LBB0_1457
	v_pk_mul_f32 v[10:11], v[2:3], v[2:3]
	v_pk_mul_f32 v[8:9], v[4:5], v[4:5]
	v_add_f32_e32 v10, v10, v11
	v_add_f32_e32 v8, v8, v10
	v_add_f32_e32 v8, v9, v8
	v_and_b32_e32 v9, 64, v219
	v_xor_b32_e32 v12, 1, v219
	v_add_u32_e32 v10, 64, v9
	s_nop 0
	v_xor_b32_e32 v14, 2, v219
	v_xor_b32_e32 v13, 4, v219
	s_nop 0
	s_nop 0
	v_mov_b32_dpp v9, v8 quad_perm:[1,0,3,2] row_mask:0xf bank_mask:0xf
	s_nop 0
	v_cvt_pk_bf16_f32 v16, v2, v3
	v_cvt_pk_bf16_f32 v17, v4, v5
	s_waitcnt lgkmcnt(0)
	v_add_f32_e32 v8, v8, v9
	s_nop 0
	s_nop 0
	v_mov_b32_dpp v9, v8 quad_perm:[2,3,0,1] row_mask:0xf bank_mask:0xf
	s_nop 0
	s_waitcnt lgkmcnt(0)
	v_add_f32_e32 v9, v8, v9
	s_nop 0
	s_nop 0
	v_mov_b32_dpp v11, v9 row_half_mirror row_mask:0xf bank_mask:0xf
	v_or_b32_e32 v8, 0x78, v178
	v_mad_i64_i32 v[4:5], s[0:1], v8, s66, v[182:183]
	global_store_dwordx2 v[4:5], v[16:17], off
	s_waitcnt lgkmcnt(0)
	v_add_f32_e32 v2, v9, v11
	v_xor_b32_e32 v11, 8, v219
	v_cmp_lt_i32_e32 vcc, v11, v10
	s_nop 1
	s_nop 0
	s_nop 0
	v_mov_b32_dpp v3, v2 row_mirror row_mask:0xf bank_mask:0xf
	s_and_saveexec_b64 s[0:1], s[8:9]
	s_cbranch_execz .LBB0_1439
	v_ashrrev_i32_e32 v9, 31, v8
	s_waitcnt lgkmcnt(0)
	v_add_f32_e32 v4, v2, v3
	v_lshl_add_u64 v[2:3], v[8:9], 2, s[60:61]
	global_atomic_add_f32 v[2:3], v4, off

; #define MFMA16(a, b, c) __builtin_amdgcn_mfma_f32_16x16x32_bf16((a), (b), (c), 0, 0, 0)
; template <class Epi>
; DI void gemm8_tile(const bf16_t* __restrict__ Ab, int lda, const bf16_t* __restrict__ Bb, int ldb, int K, int brow, int bcol, const Epi epi,
;                    bool staged, bool has_next, const bf16_t* __restrict__ Abn, const bf16_t* __restrict__ Bbn) {
;     ...
;       for (int m = 0; m < 8; ++m)
; #pragma unroll
;         for (int n = 0; n < 4; ++n) acc[m][n] = MFMA16(At[m], Bf[n], acc[m][n]);
;       __builtin_amdgcn_sched_barrier(0);
;     }
;     asm volatile("s_waitcnt vmcnt(0)" ::: "memory");
;     __syncthreads();
;   DI void run8(f32x4 (&acc)[8][4], int rb, int cb, int fr, int fq) const {
;     const int lane = fq * 16 + fr, wid = (int)(threadIdx.x >> 6);
;     const float sc = scale; bf16_t* const xbp = xb; float* const ssqp = ssq;
;     float* scr = (float*)(smem + G8_STAGE_B + wid * 4352);
;     const int prow = lane >> 4, c4 = lane & 15;
;     const float* xp = xin + (size_t)(rb + prow) * D + cb + c4 * 4;
;     float* op = xout + (size_t)(rb + prow) * D + cb + c4 * 4;
.LBB0_1515:
	v_lshrrev_b32_e32 v194, 4, v208
	s_waitcnt lgkmcnt(0)
	v_mfma_f32_16x16x32_bf16 v[196:199], v[58:61], v[2:5], v[126:129]
	v_mfma_f32_16x16x32_bf16 v[202:205], v[58:61], v[138:141], v[122:125]
	v_mfma_f32_16x16x32_bf16 v[212:215], v[58:61], v[182:185], v[118:121]
	v_mfma_f32_16x16x32_bf16 v[222:225], v[58:61], v[186:189], v[114:117]
	v_mfma_f32_16x16x32_bf16 v[150:153], v[50:53], v[2:5], v[110:113]
	v_mfma_f32_16x16x32_bf16 v[154:157], v[50:53], v[138:141], v[106:109]
	v_mfma_f32_16x16x32_bf16 v[142:145], v[50:53], v[182:185], v[102:105]
	v_mfma_f32_16x16x32_bf16 v[146:149], v[50:53], v[186:189], v[98:101]
	v_mfma_f32_16x16x32_bf16 v[118:121], v[42:45], v[2:5], v[94:97]
	v_mfma_f32_16x16x32_bf16 v[122:125], v[42:45], v[138:141], v[90:93]
	v_mfma_f32_16x16x32_bf16 v[110:113], v[42:45], v[182:185], v[86:89]
	v_mfma_f32_16x16x32_bf16 v[114:117], v[42:45], v[186:189], v[82:85]
	v_mfma_f32_16x16x32_bf16 v[86:89], v[34:37], v[2:5], v[78:81]
	v_mfma_f32_16x16x32_bf16 v[90:93], v[34:37], v[138:141], v[74:77]
	v_mfma_f32_16x16x32_bf16 v[78:81], v[34:37], v[182:185], v[70:73]
	v_mfma_f32_16x16x32_bf16 v[82:85], v[34:37], v[186:189], v[66:69]
	v_mfma_f32_16x16x32_bf16 v[58:61], v[26:29], v[2:5], v[62:65]
	v_mfma_f32_16x16x32_bf16 v[62:65], v[26:29], v[138:141], v[158:161]
	v_mfma_f32_16x16x32_bf16 v[50:53], v[26:29], v[182:185], v[54:57]
	v_mfma_f32_16x16x32_bf16 v[54:57], v[26:29], v[186:189], v[162:165]
	v_mfma_f32_16x16x32_bf16 v[42:45], v[18:21], v[2:5], v[46:49]
	v_mfma_f32_16x16x32_bf16 v[46:49], v[18:21], v[138:141], v[166:169]
	v_mfma_f32_16x16x32_bf16 v[34:37], v[18:21], v[182:185], v[38:41]
	v_mfma_f32_16x16x32_bf16 v[38:41], v[18:21], v[186:189], v[170:173]
	v_mfma_f32_16x16x32_bf16 v[26:29], v[10:13], v[2:5], v[30:33]
	v_mfma_f32_16x16x32_bf16 v[30:33], v[10:13], v[138:141], v[174:177]
	v_mfma_f32_16x16x32_bf16 v[18:21], v[10:13], v[182:185], v[22:25]
	v_mfma_f32_16x16x32_bf16 v[22:25], v[10:13], v[186:189], v[178:181]
	v_mfma_f32_16x16x32_bf16 v[10:13], v[190:193], v[2:5], v[14:17]
	v_mfma_f32_16x16x32_bf16 v[14:17], v[190:193], v[138:141], v[130:133]
	v_mfma_f32_16x16x32_bf16 v[2:5], v[190:193], v[182:185], v[6:9]
	v_mfma_f32_16x16x32_bf16 v[6:9], v[190:193], v[186:189], v[134:137]
	v_add_u32_e32 v0, s31, v207
	v_or_b32_e32 v178, v0, v194
	v_lshl_or_b32 v182, v206, 6, s8
	v_ashrrev_i32_e32 v179, 31, v178
	v_readlane_b32 s8, v254, 0
	v_lshlrev_b64 v[66:67], 12, v[178:179]
	v_readlane_b32 s10, v254, 2
	v_readlane_b32 s11, v254, 3
	v_ashrrev_i32_e32 v183, 31, v182
	v_lshlrev_b32_e32 v0, 2, v201
	v_lshl_add_u64 v[66:67], s[10:11], 0, v[66:67]
	v_lshl_add_u64 v[66:67], v[182:183], 2, v[66:67]
	v_lshl_add_u64 v[180:181], v[66:67], 0, v[0:1]
	s_movk_i32 s0, 0x4000
	v_add_co_u32_e32 v66, vcc, s0, v180
	s_mov_b32 s0, 0x8000
	s_nop 0
	v_addc_co_u32_e32 v67, vcc, 0, v181, vcc
	s_waitcnt vmcnt(0)
	s_waitcnt vmcnt(0)
	s_barrier
; DI unsigned pack_bf16(float lo, float hi) { f32x2 v = {lo, hi}; bf16v2 b = __builtin_convertvector(v, bf16v2); return __builtin_bit_cast(unsigned, b); }
; DI float red16(float v) { v += __shfl_xor(v, 1); v += __shfl_xor(v, 2); v += __shfl_xor(v, 4); v += __shfl_xor(v, 8); return v; }
;   DI void run8(f32x4 (&acc)[8][4], int rb, int cb, int fr, int fq) const {
;     ...
;         for (int ps = 0; ps < 4; ++ps) xv[mm][ps] = __builtin_nontemporal_load((const f32x4*)(xp + (size_t)((mh * 4 + mm) * 16 + ps * 4) * D));
;       __builtin_amdgcn_sched_barrier(0);
; #pragma unroll
;       for (int mm = 0; mm < 4; ++mm) {
;         const int m = mh * 4 + mm;
; #pragma unroll
;         for (int n = 0; n < 4; ++n)
; #pragma unroll
;           for (int j = 0; j < 4; ++j) scr[(fq * 4 + j) * 68 + n * 16 + fr] = acc[m][n][j];
;         __builtin_amdgcn_sched_barrier(0);
; #pragma unroll
;         for (int ps = 0; ps < 4; ++ps) {
;           const f32x4 a = *(const f32x4*)(scr + (ps * 4 + prow) * 68 + c4 * 4);
;           f32x4 v;
;           v.x = xv[mm][ps].x + a.x * sc; v.y = xv[mm][ps].y + a.y * sc; v.z = xv[mm][ps].z + a.z * sc; v.w = xv[mm][ps].w + a.w * sc;
;           const int grow = rb + m * 16 + ps * 4 + prow;
;           __builtin_nontemporal_store(v, (f32x4*)(op + (size_t)(m * 16 + ps * 4) * D));
;           if (xbp) {
;             u32x2 o; o.x = pack_bf16(v.x, v.y); o.y = pack_bf16(v.z, v.w);
;             *(u32x2*)(xbp + (size_t)grow * LDH + cb + c4 * 4) = o;
;             const float t = red16(v.x * v.x + v.y * v.y + v.z * v.z + v.w * v.w);
;             if (c4 == 0) atomicAdd(ssqp + grow, t);
;           }
	global_load_dwordx4 v[174:177], v[180:181], off nt
	global_load_dwordx4 v[170:173], v[66:67], off nt
	v_add_co_u32_e32 v66, vcc, s0, v180
	s_mov_b32 s0, 0xc000
	s_nop 0
	v_addc_co_u32_e32 v67, vcc, 0, v181, vcc
	v_add_co_u32_e32 v68, vcc, s0, v180
	s_mov_b32 s0, 0x14000
	s_nop 0
	v_addc_co_u32_e32 v69, vcc, 0, v181, vcc
	global_load_dwordx4 v[166:169], v[66:67], off nt
	global_load_dwordx4 v[162:165], v[68:69], off nt
	v_add_co_u32_e32 v66, vcc, s92, v180
	v_readlane_b32 s9, v254, 1
	s_nop 0
	v_addc_co_u32_e32 v67, vcc, 0, v181, vcc
	v_add_co_u32_e32 v68, vcc, s0, v180
	s_mov_b32 s0, 0x18000
	s_nop 0
	v_addc_co_u32_e32 v69, vcc, 0, v181, vcc
	global_load_dwordx4 v[158:161], v[66:67], off nt
	global_load_dwordx4 v[138:141], v[68:69], off nt
	v_add_co_u32_e32 v66, vcc, s0, v180
	s_mov_b32 s0, 0x1c000
	s_nop 0
	v_addc_co_u32_e32 v67, vcc, 0, v181, vcc
	v_add_co_u32_e32 v68, vcc, s0, v180
	s_mov_b32 s0, 0x20000
	s_nop 0
	v_addc_co_u32_e32 v69, vcc, 0, v181, vcc
	global_load_dwordx4 v[134:137], v[66:67], off nt
	global_load_dwordx4 v[130:133], v[68:69], off nt
	v_add_co_u32_e32 v66, vcc, s0, v180
	s_mov_b32 s0, 0x24000
	s_nop 0
	v_addc_co_u32_e32 v67, vcc, 0, v181, vcc
	v_add_co_u32_e32 v68, vcc, s0, v180
	s_mov_b32 s0, 0x28000
	s_nop 0
	v_addc_co_u32_e32 v69, vcc, 0, v181, vcc
	global_load_dwordx4 v[126:129], v[66:67], off nt
	global_load_dwordx4 v[106:109], v[68:69], off nt
	v_add_co_u32_e32 v66, vcc, s0, v180
	s_mov_b32 s0, 0x2c000
	s_nop 0
	v_addc_co_u32_e32 v67, vcc, 0, v181, vcc
	v_add_co_u32_e32 v68, vcc, s0, v180
	s_mov_b32 s0, 0x30000
	s_nop 0
	v_addc_co_u32_e32 v69, vcc, 0, v181, vcc
	global_load_dwordx4 v[102:105], v[66:67], off nt
	global_load_dwordx4 v[98:101], v[68:69], off nt
	v_add_co_u32_e32 v66, vcc, s0, v180
	s_mov_b32 s0, 0x34000
	s_nop 0
	v_addc_co_u32_e32 v67, vcc, 0, v181, vcc
	v_add_co_u32_e32 v68, vcc, s0, v180
	s_mov_b32 s0, 0x38000
	s_nop 0
	v_addc_co_u32_e32 v69, vcc, 0, v181, vcc
	global_load_dwordx4 v[94:97], v[66:67], off nt
	global_load_dwordx4 v[74:77], v[68:69], off nt
	v_add_co_u32_e32 v66, vcc, s0, v180
	s_mov_b32 s0, 0x3c000
	s_nop 0
	v_addc_co_u32_e32 v67, vcc, 0, v181, vcc
	v_add_co_u32_e32 v68, vcc, s0, v180
	v_lshl_add_u32 v184, v200, 2, v218
	s_nop 0
	v_addc_co_u32_e32 v69, vcc, 0, v181, vcc
	global_load_dwordx4 v[70:73], v[66:67], off nt
	s_nop 0
	global_load_dwordx4 v[66:69], v[68:69], off nt
	v_lshl_add_u64 v[182:183], v[182:183], 1, s[50:51]
	v_lshlrev_b32_e32 v0, 1, v201
	v_mad_u32_u24 v185, v200, 12, v184
	v_lshl_add_u64 v[182:183], v[182:183], 0, v[0:1]
	v_cmp_eq_u32_e64 s[8:9], 0, v200
	v_mad_u32_u24 v184, v194, s88, v184
	ds_write2_b32 v184, v196, v202 offset1:16
	ds_write2_b32 v184, v197, v203 offset0:68 offset1:84
	ds_write2_b32 v184, v198, v204 offset0:136 offset1:152
	ds_write2_b32 v184, v199, v205 offset0:204 offset1:220
	ds_write2_b32 v184, v212, v222 offset0:32 offset1:48
	ds_write2_b32 v184, v213, v223 offset0:100 offset1:116
	ds_write2_b32 v184, v214, v224 offset0:168 offset1:184
	ds_write2_b32 v184, v215, v225 offset0:236 offset1:252
	s_movk_i32 s0, 0x110
	v_mad_u32_u24 v0, v194, s0, v185
	ds_read_b128 v[186:189], v0
	v_cndmask_b32_e64 v0, 0, 1, s[76:77]
	v_cmp_ne_u32_e64 s[10:11], 1, v0
	s_andn2_b64 vcc, exec, s[76:77]
	s_waitcnt vmcnt(15) lgkmcnt(0)
	v_pk_add_f32 v[176:177], v[176:177], v[188:189]
	v_pk_add_f32 v[174:175], v[174:175], v[186:187]
	global_store_dwordx4 v[180:181], v[174:177], off nt
	s_cbranch_vccnz .LBB0_1519
	v_cvt_pk_bf16_f32 v186, v174, v175
	v_pk_mul_f32 v[174:175], v[174:175], v[174:175]
	v_cvt_pk_bf16_f32 v187, v176, v177
	v_add_f32_e32 v0, v174, v175
	v_and_b32_e32 v175, 64, v219
	s_nop 0
	v_add_u32_e32 v175, 64, v175
	v_pk_mul_f32 v[176:177], v[176:177], v[176:177]
	s_nop 0
	v_add_f32_e32 v0, v176, v0
	v_add_f32_e32 v0, v177, v0
	s_nop 0
	s_nop 0
	v_mov_b32_dpp v174, v0 quad_perm:[1,0,3,2] row_mask:0xf bank_mask:0xf
	v_mad_i64_i32 v[188:189], s[0:1], v178, s66, v[182:183]
	global_store_dwordx2 v[188:189], v[186:187], off
	s_waitcnt lgkmcnt(0)
	v_add_f32_e32 v0, v0, v174
	s_nop 0
	s_nop 0
	s_nop 1
	s_nop 0
	s_nop 0
	v_mov_b32_dpp v174, v0 quad_perm:[2,3,0,1] row_mask:0xf bank_mask:0xf
	s_waitcnt lgkmcnt(0)
	v_add_f32_e32 v0, v0, v174
	s_nop 0
	s_nop 0
	s_nop 1
	s_nop 0
	s_nop 0
	v_mov_b32_dpp v174, v0 row_half_mirror row_mask:0xf bank_mask:0xf
	s_waitcnt lgkmcnt(0)
	v_add_f32_e32 v0, v0, v174
	v_xor_b32_e32 v174, 8, v219
	v_cmp_lt_i32_e32 vcc, v174, v175
	s_nop 1
	s_nop 0
	s_nop 0
	v_mov_b32_dpp v174, v0 row_mirror row_mask:0xf bank_mask:0xf
	s_and_saveexec_b64 s[0:1], s[8:9]
	s_cbranch_execz .LBB0_1518
	s_waitcnt lgkmcnt(0)
	v_add_f32_e32 v0, v0, v174
	v_lshl_add_u64 v[174:175], v[178:179], 2, s[60:61]
	global_atomic_add_f32 v[174:175], v0, off

; #define MFMA16(a, b, c) __builtin_amdgcn_mfma_f32_16x16x32_bf16((a), (b), (c), 0, 0, 0)
; template <class Epi>
; DI void gemm8_tile(const bf16_t* __restrict__ Ab, int lda, const bf16_t* __restrict__ Bb, int ldb, int K, int brow, int bcol, const Epi epi,
;                    bool staged, bool has_next, const bf16_t* __restrict__ Abn, const bf16_t* __restrict__ Bbn) {
;     ...
;       for (int m = 0; m < 8; ++m)
; #pragma unroll
;         for (int n = 0; n < 4; ++n) acc[m][n] = MFMA16(At[m], Bf[n], acc[m][n]);
;       __builtin_amdgcn_sched_barrier(0);
;     }
;     asm volatile("s_waitcnt vmcnt(0)" ::: "memory");
;     __syncthreads();
;   DI void run8(f32x4 (&acc)[8][4], int rb, int cb, int fr, int fq) const {
;     const int lane = fq * 16 + fr, wid = (int)(threadIdx.x >> 6);
;     const float sc = scale; bf16_t* const xbp = xb; float* const ssqp = ssq;
;     float* scr = (float*)(smem + G8_STAGE_B + wid * 4352);
;     const int prow = lane >> 4, c4 = lane & 15;
;     const float* xp = xin + (size_t)(rb + prow) * D + cb + c4 * 4;
;     float* op = xout + (size_t)(rb + prow) * D + cb + c4 * 4;
.LBB0_1700:
	v_lshrrev_b32_e32 v194, 4, v206
	s_waitcnt lgkmcnt(0)
	v_mfma_f32_16x16x32_bf16 v[200:203], v[58:61], v[2:5], v[126:129]
	v_mfma_f32_16x16x32_bf16 v[206:209], v[58:61], v[178:181], v[122:125]
	v_mfma_f32_16x16x32_bf16 v[212:215], v[58:61], v[182:185], v[118:121]
	v_mfma_f32_16x16x32_bf16 v[222:225], v[58:61], v[186:189], v[114:117]
	v_mfma_f32_16x16x32_bf16 v[146:149], v[50:53], v[2:5], v[110:113]
	v_mfma_f32_16x16x32_bf16 v[150:153], v[50:53], v[178:181], v[106:109]
	v_mfma_f32_16x16x32_bf16 v[138:141], v[50:53], v[182:185], v[102:105]
	v_mfma_f32_16x16x32_bf16 v[142:145], v[50:53], v[186:189], v[98:101]
	v_mfma_f32_16x16x32_bf16 v[114:117], v[42:45], v[2:5], v[94:97]
	v_mfma_f32_16x16x32_bf16 v[118:121], v[42:45], v[178:181], v[90:93]
	v_mfma_f32_16x16x32_bf16 v[106:109], v[42:45], v[182:185], v[86:89]
	v_mfma_f32_16x16x32_bf16 v[110:113], v[42:45], v[186:189], v[82:85]
	v_mfma_f32_16x16x32_bf16 v[82:85], v[34:37], v[2:5], v[78:81]
	v_mfma_f32_16x16x32_bf16 v[86:89], v[34:37], v[178:181], v[74:77]
	v_mfma_f32_16x16x32_bf16 v[74:77], v[34:37], v[182:185], v[70:73]
	v_mfma_f32_16x16x32_bf16 v[78:81], v[34:37], v[186:189], v[66:69]
	v_mfma_f32_16x16x32_bf16 v[58:61], v[26:29], v[2:5], v[62:65]
	v_mfma_f32_16x16x32_bf16 v[62:65], v[26:29], v[178:181], v[154:157]
	v_mfma_f32_16x16x32_bf16 v[50:53], v[26:29], v[182:185], v[54:57]
	v_mfma_f32_16x16x32_bf16 v[54:57], v[26:29], v[186:189], v[158:161]
	v_mfma_f32_16x16x32_bf16 v[42:45], v[18:21], v[2:5], v[46:49]
	v_mfma_f32_16x16x32_bf16 v[46:49], v[18:21], v[178:181], v[162:165]
	v_mfma_f32_16x16x32_bf16 v[34:37], v[18:21], v[182:185], v[38:41]
	v_mfma_f32_16x16x32_bf16 v[38:41], v[18:21], v[186:189], v[166:169]
	v_mfma_f32_16x16x32_bf16 v[26:29], v[10:13], v[2:5], v[30:33]
	v_mfma_f32_16x16x32_bf16 v[30:33], v[10:13], v[178:181], v[170:173]
	v_mfma_f32_16x16x32_bf16 v[18:21], v[10:13], v[182:185], v[22:25]
	v_mfma_f32_16x16x32_bf16 v[22:25], v[10:13], v[186:189], v[174:177]
	v_mfma_f32_16x16x32_bf16 v[10:13], v[190:193], v[2:5], v[14:17]
	v_mfma_f32_16x16x32_bf16 v[14:17], v[190:193], v[178:181], v[130:133]
	v_mfma_f32_16x16x32_bf16 v[2:5], v[190:193], v[182:185], v[6:9]
	v_mfma_f32_16x16x32_bf16 v[6:9], v[190:193], v[186:189], v[134:137]
	v_add_u32_e32 v0, s3, v205
	v_or_b32_e32 v178, v0, v194
	v_ashrrev_i32_e32 v179, 31, v178
	v_readlane_b32 s4, v254, 0
	v_lshl_or_b32 v182, v204, 6, s31
	v_lshlrev_b64 v[66:67], 12, v[178:179]
	v_readlane_b32 s6, v254, 2
	v_readlane_b32 s7, v254, 3
	v_ashrrev_i32_e32 v183, 31, v182
	v_lshlrev_b32_e32 v0, 2, v199
	v_lshl_add_u64 v[66:67], s[6:7], 0, v[66:67]
	v_lshl_add_u64 v[66:67], v[182:183], 2, v[66:67]
	v_lshl_add_u64 v[180:181], v[66:67], 0, v[0:1]
	s_movk_i32 s0, 0x4000
	v_add_co_u32_e32 v66, vcc, s0, v180
	s_mov_b32 s0, 0x8000
	s_nop 0
	v_addc_co_u32_e32 v67, vcc, 0, v181, vcc
	s_waitcnt vmcnt(0)
	s_waitcnt vmcnt(0)
	s_barrier
; DI unsigned pack_bf16(float lo, float hi) { f32x2 v = {lo, hi}; bf16v2 b = __builtin_convertvector(v, bf16v2); return __builtin_bit_cast(unsigned, b); }
; DI float red16(float v) { v += __shfl_xor(v, 1); v += __shfl_xor(v, 2); v += __shfl_xor(v, 4); v += __shfl_xor(v, 8); return v; }
;   DI void run8(f32x4 (&acc)[8][4], int rb, int cb, int fr, int fq) const {
;     ...
;         for (int ps = 0; ps < 4; ++ps) xv[mm][ps] = __builtin_nontemporal_load((const f32x4*)(xp + (size_t)((mh * 4 + mm) * 16 + ps * 4) * D));
;       __builtin_amdgcn_sched_barrier(0);
; #pragma unroll
;       for (int mm = 0; mm < 4; ++mm) {
;         const int m = mh * 4 + mm;
; #pragma unroll
;         for (int n = 0; n < 4; ++n)
; #pragma unroll
;           for (int j = 0; j < 4; ++j) scr[(fq * 4 + j) * 68 + n * 16 + fr] = acc[m][n][j];
;         __builtin_amdgcn_sched_barrier(0);
; #pragma unroll
;         for (int ps = 0; ps < 4; ++ps) {
;           const f32x4 a = *(const f32x4*)(scr + (ps * 4 + prow) * 68 + c4 * 4);
;           f32x4 v;
;           v.x = xv[mm][ps].x + a.x * sc; v.y = xv[mm][ps].y + a.y * sc; v.z = xv[mm][ps].z + a.z * sc; v.w = xv[mm][ps].w + a.w * sc;
;           const int grow = rb + m * 16 + ps * 4 + prow;
;           __builtin_nontemporal_store(v, (f32x4*)(op + (size_t)(m * 16 + ps * 4) * D));
;           if (xbp) {
;             u32x2 o; o.x = pack_bf16(v.x, v.y); o.y = pack_bf16(v.z, v.w);
;             *(u32x2*)(xbp + (size_t)grow * LDH + cb + c4 * 4) = o;
;             const float t = red16(v.x * v.x + v.y * v.y + v.z * v.z + v.w * v.w);
;             if (c4 == 0) atomicAdd(ssqp + grow, t);
;           }
	global_load_dwordx4 v[174:177], v[180:181], off nt
	global_load_dwordx4 v[170:173], v[66:67], off nt
	v_add_co_u32_e32 v66, vcc, s0, v180
	s_mov_b32 s0, 0xc000
	s_nop 0
	v_addc_co_u32_e32 v67, vcc, 0, v181, vcc
	v_add_co_u32_e32 v68, vcc, s0, v180
	s_mov_b32 s0, 0x14000
	s_nop 0
	v_addc_co_u32_e32 v69, vcc, 0, v181, vcc
	global_load_dwordx4 v[166:169], v[66:67], off nt
	global_load_dwordx4 v[162:165], v[68:69], off nt
	v_add_co_u32_e32 v66, vcc, s92, v180
	v_readlane_b32 s5, v254, 1
	s_nop 0
	v_addc_co_u32_e32 v67, vcc, 0, v181, vcc
	v_add_co_u32_e32 v68, vcc, s0, v180
	s_mov_b32 s0, 0x18000
	s_nop 0
	v_addc_co_u32_e32 v69, vcc, 0, v181, vcc
	global_load_dwordx4 v[158:161], v[66:67], off nt
	global_load_dwordx4 v[154:157], v[68:69], off nt
	v_add_co_u32_e32 v66, vcc, s0, v180
	s_mov_b32 s0, 0x1c000
	s_nop 0
	v_addc_co_u32_e32 v67, vcc, 0, v181, vcc
	v_add_co_u32_e32 v68, vcc, s0, v180
	s_mov_b32 s0, 0x20000
	s_nop 0
	v_addc_co_u32_e32 v69, vcc, 0, v181, vcc
	global_load_dwordx4 v[134:137], v[66:67], off nt
	global_load_dwordx4 v[130:133], v[68:69], off nt
	v_add_co_u32_e32 v66, vcc, s0, v180
	s_mov_b32 s0, 0x24000
	s_nop 0
	v_addc_co_u32_e32 v67, vcc, 0, v181, vcc
	v_add_co_u32_e32 v68, vcc, s0, v180
	s_mov_b32 s0, 0x28000
	s_nop 0
	v_addc_co_u32_e32 v69, vcc, 0, v181, vcc
	global_load_dwordx4 v[126:129], v[66:67], off nt
	global_load_dwordx4 v[122:125], v[68:69], off nt
	v_add_co_u32_e32 v66, vcc, s0, v180
	s_mov_b32 s0, 0x2c000
	s_nop 0
	v_addc_co_u32_e32 v67, vcc, 0, v181, vcc
	v_add_co_u32_e32 v68, vcc, s0, v180
	s_mov_b32 s0, 0x30000
	s_nop 0
	v_addc_co_u32_e32 v69, vcc, 0, v181, vcc
	global_load_dwordx4 v[102:105], v[66:67], off nt
	global_load_dwordx4 v[98:101], v[68:69], off nt
	v_add_co_u32_e32 v66, vcc, s0, v180
	s_mov_b32 s0, 0x34000
	s_nop 0
	v_addc_co_u32_e32 v67, vcc, 0, v181, vcc
	v_add_co_u32_e32 v68, vcc, s0, v180
	s_mov_b32 s0, 0x38000
	s_nop 0
	v_addc_co_u32_e32 v69, vcc, 0, v181, vcc
	global_load_dwordx4 v[94:97], v[66:67], off nt
	global_load_dwordx4 v[90:93], v[68:69], off nt
	v_add_co_u32_e32 v66, vcc, s0, v180
	s_mov_b32 s0, 0x3c000
	s_nop 0
	v_addc_co_u32_e32 v67, vcc, 0, v181, vcc
	v_add_co_u32_e32 v68, vcc, s0, v180
	v_lshl_add_u32 v184, v198, 2, v218
	s_nop 0
	v_addc_co_u32_e32 v69, vcc, 0, v181, vcc
	global_load_dwordx4 v[70:73], v[66:67], off nt
	s_nop 0
	global_load_dwordx4 v[66:69], v[68:69], off nt
	v_lshl_add_u64 v[182:183], v[182:183], 1, s[12:13]
	v_lshlrev_b32_e32 v0, 1, v199
	v_mad_u32_u24 v185, v198, 12, v184
	v_lshl_add_u64 v[182:183], v[182:183], 0, v[0:1]
	v_cmp_eq_u32_e64 s[4:5], 0, v198
	v_mad_u32_u24 v184, v194, s88, v184
	ds_write2_b32 v184, v200, v206 offset1:16
	ds_write2_b32 v184, v201, v207 offset0:68 offset1:84
	ds_write2_b32 v184, v202, v208 offset0:136 offset1:152
	ds_write2_b32 v184, v203, v209 offset0:204 offset1:220
	ds_write2_b32 v184, v212, v222 offset0:32 offset1:48
	ds_write2_b32 v184, v213, v223 offset0:100 offset1:116
	ds_write2_b32 v184, v214, v224 offset0:168 offset1:184
	ds_write2_b32 v184, v215, v225 offset0:236 offset1:252
	s_movk_i32 s0, 0x110
	v_mad_u32_u24 v0, v194, s0, v185
	ds_read_b128 v[186:189], v0
	v_cndmask_b32_e64 v0, 0, 1, s[54:55]
	v_cmp_ne_u32_e64 s[6:7], 1, v0
	s_andn2_b64 vcc, exec, s[54:55]
	s_waitcnt vmcnt(15) lgkmcnt(0)
	v_pk_fma_f32 v[174:175], v[186:187], 0.5, v[174:175] op_sel_hi:[1,0,1]
	v_pk_fma_f32 v[176:177], v[188:189], 0.5, v[176:177] op_sel_hi:[1,0,1]
	global_store_dwordx4 v[180:181], v[174:177], off nt
	s_cbranch_vccnz .LBB0_1704
	v_cvt_pk_bf16_f32 v186, v174, v175
	v_pk_mul_f32 v[174:175], v[174:175], v[174:175]
	v_cvt_pk_bf16_f32 v187, v176, v177
	v_add_f32_e32 v0, v174, v175
	v_and_b32_e32 v175, 64, v219
	s_nop 0
	v_add_u32_e32 v175, 64, v175
	v_pk_mul_f32 v[176:177], v[176:177], v[176:177]
	s_nop 0
	v_add_f32_e32 v0, v176, v0
	v_add_f32_e32 v0, v177, v0
	s_nop 0
	s_nop 0
	v_mov_b32_dpp v174, v0 quad_perm:[1,0,3,2] row_mask:0xf bank_mask:0xf
	v_mad_i64_i32 v[188:189], s[0:1], v178, s66, v[182:183]
	global_store_dwordx2 v[188:189], v[186:187], off
	s_waitcnt lgkmcnt(0)
	v_add_f32_e32 v0, v0, v174
	s_nop 0
	s_nop 0
	s_nop 1
	s_nop 0
	s_nop 0
	v_mov_b32_dpp v174, v0 quad_perm:[2,3,0,1] row_mask:0xf bank_mask:0xf
	s_waitcnt lgkmcnt(0)
	v_add_f32_e32 v0, v0, v174
	s_nop 0
	s_nop 0
	s_nop 1
	s_nop 0
	s_nop 0
	v_mov_b32_dpp v174, v0 row_half_mirror row_mask:0xf bank_mask:0xf
	s_waitcnt lgkmcnt(0)
	v_add_f32_e32 v0, v0, v174
	v_xor_b32_e32 v174, 8, v219
	v_cmp_lt_i32_e32 vcc, v174, v175
	s_nop 1
	s_nop 0
	s_nop 0
	v_mov_b32_dpp v174, v0 row_mirror row_mask:0xf bank_mask:0xf
	s_and_saveexec_b64 s[0:1], s[4:5]
	s_cbranch_execz .LBB0_1703
	s_waitcnt lgkmcnt(0)
	v_add_f32_e32 v0, v0, v174
	v_lshl_add_u64 v[174:175], v[178:179], 2, s[38:39]
	global_atomic_add_f32 v[174:175], v0, off

; DI unsigned pack_bf16(float lo, float hi) { f32x2 v = {lo, hi}; bf16v2 b = __builtin_convertvector(v, bf16v2); return __builtin_bit_cast(unsigned, b); }
; DI float red16(float v) { v += __shfl_xor(v, 1); v += __shfl_xor(v, 2); v += __shfl_xor(v, 4); v += __shfl_xor(v, 8); return v; }
;   DI void run8(f32x4 (&acc)[8][4], int rb, int cb, int fr, int fq) const {
;     ...
;         for (int ps = 0; ps < 4; ++ps) {
;           const f32x4 a = *(const f32x4*)(scr + (ps * 4 + prow) * 68 + c4 * 4);
;           f32x4 v;
;           v.x = xv[mm][ps].x + a.x * sc; v.y = xv[mm][ps].y + a.y * sc; v.z = xv[mm][ps].z + a.z * sc; v.w = xv[mm][ps].w + a.w * sc;
;           const int grow = rb + m * 16 + ps * 4 + prow;
;           __builtin_nontemporal_store(v, (f32x4*)(op + (size_t)(m * 16 + ps * 4) * D));
;           if (xbp) {
;             u32x2 o; o.x = pack_bf16(v.x, v.y); o.y = pack_bf16(v.z, v.w);
;             *(u32x2*)(xbp + (size_t)grow * LDH + cb + c4 * 4) = o;
;             const float t = red16(v.x * v.x + v.y * v.y + v.z * v.z + v.w * v.w);
;             if (c4 == 0) atomicAdd(ssqp + grow, t);
;           }
.LBB0_1704:
	v_mul_u32_u24_e32 v0, 0x110, v194
	v_add_u32_e32 v0, v185, v0
	s_waitcnt lgkmcnt(0)
	ds_read_b128 v[174:177], v0 offset:1088
	s_mov_b64 s[0:1], 0x4000
	v_lshl_add_u64 v[186:187], v[180:181], 0, s[0:1]
	s_and_b64 vcc, exec, s[6:7]
	s_waitcnt vmcnt(15) lgkmcnt(0)
	v_pk_fma_f32 v[170:171], v[174:175], 0.5, v[170:171] op_sel_hi:[1,0,1]
	v_pk_fma_f32 v[172:173], v[176:177], 0.5, v[172:173] op_sel_hi:[1,0,1]
	global_store_dwordx4 v[186:187], v[170:173], off nt
	s_cbranch_vccnz .LBB0_1708
	v_pk_mul_f32 v[174:175], v[170:171], v[170:171]
	v_pk_mul_f32 v[176:177], v[172:173], v[172:173]
	v_add_f32_e32 v174, v174, v175
	v_add_f32_e32 v174, v176, v174
	v_and_b32_e32 v176, 64, v219
	s_nop 0
	v_add_u32_e32 v176, 64, v176
	s_nop 0
	v_add_f32_e32 v174, v177, v174
	v_or_b32_e32 v185, 4, v178
	s_nop 0
	s_nop 0
	v_mov_b32_dpp v175, v174 quad_perm:[1,0,3,2] row_mask:0xf bank_mask:0xf
	s_waitcnt lgkmcnt(0)
	v_add_f32_e32 v174, v174, v175
	s_nop 0
	s_nop 0
	s_nop 1
	s_nop 0
	s_nop 0
	v_mov_b32_dpp v175, v174 quad_perm:[2,3,0,1] row_mask:0xf bank_mask:0xf
	s_waitcnt lgkmcnt(0)
	v_add_f32_e32 v175, v174, v175
	s_nop 0
	s_nop 0
	s_nop 1
	s_nop 0
	s_nop 0
	v_mov_b32_dpp v177, v175 row_half_mirror row_mask:0xf bank_mask:0xf
	v_cvt_pk_bf16_f32 v174, v170, v171
	v_xor_b32_e32 v171, 8, v219
	v_cmp_lt_i32_e32 vcc, v171, v176
	s_waitcnt lgkmcnt(0)
	v_add_f32_e32 v170, v175, v177
	s_nop 0
	s_nop 0
	v_mov_b32_dpp v171, v170 row_mirror row_mask:0xf bank_mask:0xf
	v_cvt_pk_bf16_f32 v175, v172, v173
	v_mad_i64_i32 v[172:173], s[0:1], v185, s66, v[182:183]
	global_store_dwordx2 v[172:173], v[174:175], off
	s_and_saveexec_b64 s[0:1], s[4:5]
	s_cbranch_execz .LBB0_1707
	s_waitcnt lgkmcnt(0)
	v_add_f32_e32 v172, v170, v171
	v_lshl_add_u64 v[170:171], v[178:179], 2, s[38:39]
	global_atomic_add_f32 v[170:171], v172, off offset:16

; DI unsigned pack_bf16(float lo, float hi) { f32x2 v = {lo, hi}; bf16v2 b = __builtin_convertvector(v, bf16v2); return __builtin_bit_cast(unsigned, b); }
; DI float red16(float v) { v += __shfl_xor(v, 1); v += __shfl_xor(v, 2); v += __shfl_xor(v, 4); v += __shfl_xor(v, 8); return v; }
;   DI void run8(f32x4 (&acc)[8][4], int rb, int cb, int fr, int fq) const {
;     ...
;         for (int ps = 0; ps < 4; ++ps) {
;           const f32x4 a = *(const f32x4*)(scr + (ps * 4 + prow) * 68 + c4 * 4);
;           f32x4 v;
;           v.x = xv[mm][ps].x + a.x * sc; v.y = xv[mm][ps].y + a.y * sc; v.z = xv[mm][ps].z + a.z * sc; v.w = xv[mm][ps].w + a.w * sc;
;           const int grow = rb + m * 16 + ps * 4 + prow;
;           __builtin_nontemporal_store(v, (f32x4*)(op + (size_t)(m * 16 + ps * 4) * D));
;           if (xbp) {
;             u32x2 o; o.x = pack_bf16(v.x, v.y); o.y = pack_bf16(v.z, v.w);
;             *(u32x2*)(xbp + (size_t)grow * LDH + cb + c4 * 4) = o;
;             const float t = red16(v.x * v.x + v.y * v.y + v.z * v.z + v.w * v.w);
;             if (c4 == 0) atomicAdd(ssqp + grow, t);
;           }
.LBB0_1708:
	s_waitcnt lgkmcnt(0)
	ds_read_b128 v[170:173], v0 offset:2176
	v_lshl_add_u64 v[174:175], v[180:181], 0, s[82:83]
	s_and_b64 vcc, exec, s[6:7]
	s_waitcnt vmcnt(15) lgkmcnt(0)
	v_pk_fma_f32 v[166:167], v[170:171], 0.5, v[166:167] op_sel_hi:[1,0,1]
	v_pk_fma_f32 v[168:169], v[172:173], 0.5, v[168:169] op_sel_hi:[1,0,1]
	global_store_dwordx4 v[174:175], v[166:169], off nt
	s_cbranch_vccnz .LBB0_1712
	v_pk_mul_f32 v[170:171], v[166:167], v[166:167]
	v_pk_mul_f32 v[172:173], v[168:169], v[168:169]
	v_add_f32_e32 v170, v170, v171
	v_add_f32_e32 v170, v172, v170
	v_and_b32_e32 v172, 64, v219
	s_nop 0
	v_add_u32_e32 v172, 64, v172
	s_nop 0
	v_add_f32_e32 v170, v173, v170
	v_or_b32_e32 v174, 8, v178
	s_nop 0
	s_nop 0
	v_mov_b32_dpp v171, v170 quad_perm:[1,0,3,2] row_mask:0xf bank_mask:0xf
	s_waitcnt lgkmcnt(0)
	v_add_f32_e32 v170, v170, v171
	s_nop 0
	s_nop 0
	s_nop 1
	s_nop 0
	s_nop 0
	v_mov_b32_dpp v171, v170 quad_perm:[2,3,0,1] row_mask:0xf bank_mask:0xf
	s_waitcnt lgkmcnt(0)
	v_add_f32_e32 v171, v170, v171
	s_nop 0
	s_nop 0
	s_nop 1
	s_nop 0
	s_nop 0
	v_mov_b32_dpp v173, v171 row_half_mirror row_mask:0xf bank_mask:0xf
	v_cvt_pk_bf16_f32 v170, v166, v167
	v_xor_b32_e32 v167, 8, v219
	v_cmp_lt_i32_e32 vcc, v167, v172
	s_waitcnt lgkmcnt(0)
	v_add_f32_e32 v166, v171, v173
	s_nop 0
	s_nop 0
	v_mov_b32_dpp v167, v166 row_mirror row_mask:0xf bank_mask:0xf
	v_cvt_pk_bf16_f32 v171, v168, v169
	v_mad_i64_i32 v[168:169], s[0:1], v174, s66, v[182:183]
	global_store_dwordx2 v[168:169], v[170:171], off
	s_and_saveexec_b64 s[0:1], s[4:5]
	s_cbranch_execz .LBB0_1711
	s_waitcnt lgkmcnt(0)
	v_add_f32_e32 v168, v166, v167
	v_lshl_add_u64 v[166:167], v[178:179], 2, s[38:39]
	global_atomic_add_f32 v[166:167], v168, off offset:32

; DI unsigned pack_bf16(float lo, float hi) { f32x2 v = {lo, hi}; bf16v2 b = __builtin_convertvector(v, bf16v2); return __builtin_bit_cast(unsigned, b); }
; DI float red16(float v) { v += __shfl_xor(v, 1); v += __shfl_xor(v, 2); v += __shfl_xor(v, 4); v += __shfl_xor(v, 8); return v; }
;   DI void run8(f32x4 (&acc)[8][4], int rb, int cb, int fr, int fq) const {
;     ...
;         for (int ps = 0; ps < 4; ++ps) {
;           const f32x4 a = *(const f32x4*)(scr + (ps * 4 + prow) * 68 + c4 * 4);
;           f32x4 v;
;           v.x = xv[mm][ps].x + a.x * sc; v.y = xv[mm][ps].y + a.y * sc; v.z = xv[mm][ps].z + a.z * sc; v.w = xv[mm][ps].w + a.w * sc;
;           const int grow = rb + m * 16 + ps * 4 + prow;
;           __builtin_nontemporal_store(v, (f32x4*)(op + (size_t)(m * 16 + ps * 4) * D));
;           if (xbp) {
;             u32x2 o; o.x = pack_bf16(v.x, v.y); o.y = pack_bf16(v.z, v.w);
;             *(u32x2*)(xbp + (size_t)grow * LDH + cb + c4 * 4) = o;
;             const float t = red16(v.x * v.x + v.y * v.y + v.z * v.z + v.w * v.w);
;             if (c4 == 0) atomicAdd(ssqp + grow, t);
;           }
.LBB0_1712:
	s_waitcnt lgkmcnt(0)
	ds_read_b128 v[166:169], v0 offset:3264
	s_mov_b64 s[0:1], 0xc000
	v_lshl_add_u64 v[170:171], v[180:181], 0, s[0:1]
	s_and_b64 vcc, exec, s[6:7]
	s_waitcnt vmcnt(15) lgkmcnt(0)
	v_pk_fma_f32 v[162:163], v[166:167], 0.5, v[162:163] op_sel_hi:[1,0,1]
	v_pk_fma_f32 v[164:165], v[168:169], 0.5, v[164:165] op_sel_hi:[1,0,1]
	global_store_dwordx4 v[170:171], v[162:165], off nt
	s_cbranch_vccnz .LBB0_1716
	v_pk_mul_f32 v[166:167], v[162:163], v[162:163]
	v_pk_mul_f32 v[168:169], v[164:165], v[164:165]
	v_add_f32_e32 v166, v166, v167
	v_add_f32_e32 v166, v168, v166
	v_and_b32_e32 v168, 64, v219
	s_nop 0
	v_add_u32_e32 v168, 64, v168
	s_nop 0
	v_add_f32_e32 v166, v169, v166
	v_or_b32_e32 v170, 12, v178
	s_nop 0
	s_nop 0
	v_mov_b32_dpp v167, v166 quad_perm:[1,0,3,2] row_mask:0xf bank_mask:0xf
	s_waitcnt lgkmcnt(0)
	v_add_f32_e32 v166, v166, v167
	s_nop 0
	s_nop 0
	s_nop 1
	s_nop 0
	s_nop 0
	v_mov_b32_dpp v167, v166 quad_perm:[2,3,0,1] row_mask:0xf bank_mask:0xf
	s_waitcnt lgkmcnt(0)
	v_add_f32_e32 v167, v166, v167
	s_nop 0
	s_nop 0
	s_nop 1
	s_nop 0
	s_nop 0
	v_mov_b32_dpp v169, v167 row_half_mirror row_mask:0xf bank_mask:0xf
	v_cvt_pk_bf16_f32 v166, v162, v163
	v_xor_b32_e32 v163, 8, v219
	v_cmp_lt_i32_e32 vcc, v163, v168
	s_waitcnt lgkmcnt(0)
	v_add_f32_e32 v162, v167, v169
	s_nop 0
	s_nop 0
	v_mov_b32_dpp v163, v162 row_mirror row_mask:0xf bank_mask:0xf
	v_cvt_pk_bf16_f32 v167, v164, v165
	v_mad_i64_i32 v[164:165], s[0:1], v170, s66, v[182:183]
	global_store_dwordx2 v[164:165], v[166:167], off
	s_and_saveexec_b64 s[0:1], s[4:5]
	s_cbranch_execz .LBB0_1715
	s_waitcnt lgkmcnt(0)
	v_add_f32_e32 v164, v162, v163
	v_lshl_add_u64 v[162:163], v[178:179], 2, s[38:39]
	global_atomic_add_f32 v[162:163], v164, off offset:48

; DI unsigned pack_bf16(float lo, float hi) { f32x2 v = {lo, hi}; bf16v2 b = __builtin_convertvector(v, bf16v2); return __builtin_bit_cast(unsigned, b); }
; DI float red16(float v) { v += __shfl_xor(v, 1); v += __shfl_xor(v, 2); v += __shfl_xor(v, 4); v += __shfl_xor(v, 8); return v; }
;   DI void run8(f32x4 (&acc)[8][4], int rb, int cb, int fr, int fq) const {
;     ...
;         for (int n = 0; n < 4; ++n)
; #pragma unroll
;           for (int j = 0; j < 4; ++j) scr[(fq * 4 + j) * 68 + n * 16 + fr] = acc[m][n][j];
;         __builtin_amdgcn_sched_barrier(0);
; #pragma unroll
;         for (int ps = 0; ps < 4; ++ps) {
;           const f32x4 a = *(const f32x4*)(scr + (ps * 4 + prow) * 68 + c4 * 4);
;           f32x4 v;
;           v.x = xv[mm][ps].x + a.x * sc; v.y = xv[mm][ps].y + a.y * sc; v.z = xv[mm][ps].z + a.z * sc; v.w = xv[mm][ps].w + a.w * sc;
;           const int grow = rb + m * 16 + ps * 4 + prow;
;           __builtin_nontemporal_store(v, (f32x4*)(op + (size_t)(m * 16 + ps * 4) * D));
;           if (xbp) {
;             u32x2 o; o.x = pack_bf16(v.x, v.y); o.y = pack_bf16(v.z, v.w);
;             *(u32x2*)(xbp + (size_t)grow * LDH + cb + c4 * 4) = o;
;             const float t = red16(v.x * v.x + v.y * v.y + v.z * v.z + v.w * v.w);
;             if (c4 == 0) atomicAdd(ssqp + grow, t);
;           }
.LBB0_1716:
	s_mov_b64 s[0:1], 0x10000
	s_waitcnt lgkmcnt(0)
	v_lshl_add_u64 v[162:163], v[180:181], 0, s[0:1]
	ds_write2_b32 v184, v146, v150 offset1:16
	ds_write2_b32 v184, v147, v151 offset0:68 offset1:84
	ds_write2_b32 v184, v148, v152 offset0:136 offset1:152
	ds_write2_b32 v184, v149, v153 offset0:204 offset1:220
	ds_write2_b32 v184, v138, v142 offset0:32 offset1:48
	ds_write2_b32 v184, v139, v143 offset0:100 offset1:116
	ds_write2_b32 v184, v140, v144 offset0:168 offset1:184
	ds_write2_b32 v184, v141, v145 offset0:236 offset1:252
	ds_read_b128 v[138:141], v0
	s_and_b64 vcc, exec, s[6:7]
	s_waitcnt vmcnt(15) lgkmcnt(0)
	v_pk_fma_f32 v[138:139], v[138:139], 0.5, v[158:159] op_sel_hi:[1,0,1]
	v_pk_fma_f32 v[140:141], v[140:141], 0.5, v[160:161] op_sel_hi:[1,0,1]
	global_store_dwordx4 v[162:163], v[138:141], off nt
	s_cbranch_vccnz .LBB0_1720
	v_pk_mul_f32 v[142:143], v[138:139], v[138:139]
	v_pk_mul_f32 v[144:145], v[140:141], v[140:141]
	v_add_f32_e32 v142, v142, v143
	v_add_f32_e32 v142, v144, v142
	v_and_b32_e32 v144, 64, v219
	s_nop 0
	v_add_u32_e32 v144, 64, v144
	s_nop 0
	v_add_f32_e32 v142, v145, v142
	v_or_b32_e32 v146, 16, v178
	s_nop 0
	s_nop 0
	v_mov_b32_dpp v143, v142 quad_perm:[1,0,3,2] row_mask:0xf bank_mask:0xf
	s_waitcnt lgkmcnt(0)
	v_add_f32_e32 v142, v142, v143
	s_nop 0
	s_nop 0
	s_nop 1
	s_nop 0
	s_nop 0
	v_mov_b32_dpp v143, v142 quad_perm:[2,3,0,1] row_mask:0xf bank_mask:0xf
	s_waitcnt lgkmcnt(0)
	v_add_f32_e32 v143, v142, v143
	s_nop 0
	s_nop 0
	s_nop 1
	s_nop 0
	s_nop 0
	v_mov_b32_dpp v145, v143 row_half_mirror row_mask:0xf bank_mask:0xf
	v_cvt_pk_bf16_f32 v142, v138, v139
	v_xor_b32_e32 v139, 8, v219
	v_cmp_lt_i32_e32 vcc, v139, v144
	s_waitcnt lgkmcnt(0)
	v_add_f32_e32 v138, v143, v145
	s_nop 0
	s_nop 0
	v_mov_b32_dpp v139, v138 row_mirror row_mask:0xf bank_mask:0xf
	v_cvt_pk_bf16_f32 v143, v140, v141
	v_mad_i64_i32 v[140:141], s[0:1], v146, s66, v[182:183]
	global_store_dwordx2 v[140:141], v[142:143], off
	s_and_saveexec_b64 s[0:1], s[4:5]
	s_cbranch_execz .LBB0_1719
	s_waitcnt lgkmcnt(0)
	v_add_f32_e32 v140, v138, v139
	v_lshl_add_u64 v[138:139], v[178:179], 2, s[38:39]
	global_atomic_add_f32 v[138:139], v140, off offset:64

; DI unsigned pack_bf16(float lo, float hi) { f32x2 v = {lo, hi}; bf16v2 b = __builtin_convertvector(v, bf16v2); return __builtin_bit_cast(unsigned, b); }
; DI float red16(float v) { v += __shfl_xor(v, 1); v += __shfl_xor(v, 2); v += __shfl_xor(v, 4); v += __shfl_xor(v, 8); return v; }
;   DI void run8(f32x4 (&acc)[8][4], int rb, int cb, int fr, int fq) const {
;     ...
;         for (int ps = 0; ps < 4; ++ps) {
;           const f32x4 a = *(const f32x4*)(scr + (ps * 4 + prow) * 68 + c4 * 4);
;           f32x4 v;
;           v.x = xv[mm][ps].x + a.x * sc; v.y = xv[mm][ps].y + a.y * sc; v.z = xv[mm][ps].z + a.z * sc; v.w = xv[mm][ps].w + a.w * sc;
;           const int grow = rb + m * 16 + ps * 4 + prow;
;           __builtin_nontemporal_store(v, (f32x4*)(op + (size_t)(m * 16 + ps * 4) * D));
;           if (xbp) {
;             u32x2 o; o.x = pack_bf16(v.x, v.y); o.y = pack_bf16(v.z, v.w);
;             *(u32x2*)(xbp + (size_t)grow * LDH + cb + c4 * 4) = o;
;             const float t = red16(v.x * v.x + v.y * v.y + v.z * v.z + v.w * v.w);
;             if (c4 == 0) atomicAdd(ssqp + grow, t);
;           }
.LBB0_1720:
	s_waitcnt lgkmcnt(0)
	ds_read_b128 v[138:141], v0 offset:1088
	s_mov_b64 s[0:1], 0x14000
	v_lshl_add_u64 v[142:143], v[180:181], 0, s[0:1]
	s_and_b64 vcc, exec, s[6:7]
	s_waitcnt vmcnt(15) lgkmcnt(0)
	v_pk_fma_f32 v[138:139], v[138:139], 0.5, v[154:155] op_sel_hi:[1,0,1]
	v_pk_fma_f32 v[140:141], v[140:141], 0.5, v[156:157] op_sel_hi:[1,0,1]
	global_store_dwordx4 v[142:143], v[138:141], off nt
	s_cbranch_vccnz .LBB0_1724
	v_pk_mul_f32 v[142:143], v[138:139], v[138:139]
	v_pk_mul_f32 v[144:145], v[140:141], v[140:141]
	v_add_f32_e32 v142, v142, v143
	v_add_f32_e32 v142, v144, v142
	v_and_b32_e32 v144, 64, v219
	s_nop 0
	v_add_u32_e32 v144, 64, v144
	s_nop 0
	v_add_f32_e32 v142, v145, v142
	v_or_b32_e32 v146, 20, v178
	s_nop 0
	s_nop 0
	v_mov_b32_dpp v143, v142 quad_perm:[1,0,3,2] row_mask:0xf bank_mask:0xf
	s_waitcnt lgkmcnt(0)
	v_add_f32_e32 v142, v142, v143
	s_nop 0
	s_nop 0
	s_nop 1
	s_nop 0
	s_nop 0
	v_mov_b32_dpp v143, v142 quad_perm:[2,3,0,1] row_mask:0xf bank_mask:0xf
	s_waitcnt lgkmcnt(0)
	v_add_f32_e32 v143, v142, v143
	s_nop 0
	s_nop 0
	s_nop 1
	s_nop 0
	s_nop 0
	v_mov_b32_dpp v145, v143 row_half_mirror row_mask:0xf bank_mask:0xf
	v_cvt_pk_bf16_f32 v142, v138, v139
	v_xor_b32_e32 v139, 8, v219
	v_cmp_lt_i32_e32 vcc, v139, v144
	s_waitcnt lgkmcnt(0)
	v_add_f32_e32 v138, v143, v145
	s_nop 0
	s_nop 0
	v_mov_b32_dpp v139, v138 row_mirror row_mask:0xf bank_mask:0xf
	v_cvt_pk_bf16_f32 v143, v140, v141
	v_mad_i64_i32 v[140:141], s[0:1], v146, s66, v[182:183]
	global_store_dwordx2 v[140:141], v[142:143], off
	s_and_saveexec_b64 s[0:1], s[4:5]
	s_cbranch_execz .LBB0_1723
	s_waitcnt lgkmcnt(0)
	v_add_f32_e32 v140, v138, v139
	v_lshl_add_u64 v[138:139], v[178:179], 2, s[38:39]
	global_atomic_add_f32 v[138:139], v140, off offset:80

; DI unsigned pack_bf16(float lo, float hi) { f32x2 v = {lo, hi}; bf16v2 b = __builtin_convertvector(v, bf16v2); return __builtin_bit_cast(unsigned, b); }
; DI float red16(float v) { v += __shfl_xor(v, 1); v += __shfl_xor(v, 2); v += __shfl_xor(v, 4); v += __shfl_xor(v, 8); return v; }
;   DI void run8(f32x4 (&acc)[8][4], int rb, int cb, int fr, int fq) const {
;     ...
;         for (int ps = 0; ps < 4; ++ps) {
;           const f32x4 a = *(const f32x4*)(scr + (ps * 4 + prow) * 68 + c4 * 4);
;           f32x4 v;
;           v.x = xv[mm][ps].x + a.x * sc; v.y = xv[mm][ps].y + a.y * sc; v.z = xv[mm][ps].z + a.z * sc; v.w = xv[mm][ps].w + a.w * sc;
;           const int grow = rb + m * 16 + ps * 4 + prow;
;           __builtin_nontemporal_store(v, (f32x4*)(op + (size_t)(m * 16 + ps * 4) * D));
;           if (xbp) {
;             u32x2 o; o.x = pack_bf16(v.x, v.y); o.y = pack_bf16(v.z, v.w);
;             *(u32x2*)(xbp + (size_t)grow * LDH + cb + c4 * 4) = o;
;             const float t = red16(v.x * v.x + v.y * v.y + v.z * v.z + v.w * v.w);
;             if (c4 == 0) atomicAdd(ssqp + grow, t);
;           }
.LBB0_1724:
	s_waitcnt lgkmcnt(0)
	ds_read_b128 v[138:141], v0 offset:2176
	s_mov_b64 s[0:1], 0x18000
	v_lshl_add_u64 v[142:143], v[180:181], 0, s[0:1]
	s_and_b64 vcc, exec, s[6:7]
	s_waitcnt vmcnt(15) lgkmcnt(0)
	v_pk_fma_f32 v[134:135], v[138:139], 0.5, v[134:135] op_sel_hi:[1,0,1]
	v_pk_fma_f32 v[136:137], v[140:141], 0.5, v[136:137] op_sel_hi:[1,0,1]
	global_store_dwordx4 v[142:143], v[134:137], off nt
	s_cbranch_vccnz .LBB0_1728
	v_pk_mul_f32 v[138:139], v[134:135], v[134:135]
	v_pk_mul_f32 v[140:141], v[136:137], v[136:137]
	v_add_f32_e32 v138, v138, v139
	v_add_f32_e32 v138, v140, v138
	v_and_b32_e32 v140, 64, v219
	s_nop 0
	v_add_u32_e32 v140, 64, v140
	s_nop 0
	v_add_f32_e32 v138, v141, v138
	v_or_b32_e32 v142, 24, v178
	s_nop 0
	s_nop 0
	v_mov_b32_dpp v139, v138 quad_perm:[1,0,3,2] row_mask:0xf bank_mask:0xf
	s_waitcnt lgkmcnt(0)
	v_add_f32_e32 v138, v138, v139
	s_nop 0
	s_nop 0
	s_nop 1
	s_nop 0
	s_nop 0
	v_mov_b32_dpp v139, v138 quad_perm:[2,3,0,1] row_mask:0xf bank_mask:0xf
	s_waitcnt lgkmcnt(0)
	v_add_f32_e32 v139, v138, v139
	s_nop 0
	s_nop 0
	s_nop 1
	s_nop 0
	s_nop 0
	v_mov_b32_dpp v141, v139 row_half_mirror row_mask:0xf bank_mask:0xf
	v_cvt_pk_bf16_f32 v138, v134, v135
	v_xor_b32_e32 v135, 8, v219
	v_cmp_lt_i32_e32 vcc, v135, v140
	s_waitcnt lgkmcnt(0)
	v_add_f32_e32 v134, v139, v141
	s_nop 0
	s_nop 0
	v_mov_b32_dpp v135, v134 row_mirror row_mask:0xf bank_mask:0xf
	v_cvt_pk_bf16_f32 v139, v136, v137
	v_mad_i64_i32 v[136:137], s[0:1], v142, s66, v[182:183]
	global_store_dwordx2 v[136:137], v[138:139], off
	s_and_saveexec_b64 s[0:1], s[4:5]
	s_cbranch_execz .LBB0_1727
	s_waitcnt lgkmcnt(0)
	v_add_f32_e32 v136, v134, v135
	v_lshl_add_u64 v[134:135], v[178:179], 2, s[38:39]
	global_atomic_add_f32 v[134:135], v136, off offset:96

; DI unsigned pack_bf16(float lo, float hi) { f32x2 v = {lo, hi}; bf16v2 b = __builtin_convertvector(v, bf16v2); return __builtin_bit_cast(unsigned, b); }
; DI float red16(float v) { v += __shfl_xor(v, 1); v += __shfl_xor(v, 2); v += __shfl_xor(v, 4); v += __shfl_xor(v, 8); return v; }
;   DI void run8(f32x4 (&acc)[8][4], int rb, int cb, int fr, int fq) const {
;     ...
;         for (int ps = 0; ps < 4; ++ps) {
;           const f32x4 a = *(const f32x4*)(scr + (ps * 4 + prow) * 68 + c4 * 4);
;           f32x4 v;
;           v.x = xv[mm][ps].x + a.x * sc; v.y = xv[mm][ps].y + a.y * sc; v.z = xv[mm][ps].z + a.z * sc; v.w = xv[mm][ps].w + a.w * sc;
;           const int grow = rb + m * 16 + ps * 4 + prow;
;           __builtin_nontemporal_store(v, (f32x4*)(op + (size_t)(m * 16 + ps * 4) * D));
;           if (xbp) {
;             u32x2 o; o.x = pack_bf16(v.x, v.y); o.y = pack_bf16(v.z, v.w);
;             *(u32x2*)(xbp + (size_t)grow * LDH + cb + c4 * 4) = o;
;             const float t = red16(v.x * v.x + v.y * v.y + v.z * v.z + v.w * v.w);
;             if (c4 == 0) atomicAdd(ssqp + grow, t);
;           }
.LBB0_1728:
	s_waitcnt lgkmcnt(0)
	ds_read_b128 v[134:137], v0 offset:3264
	s_mov_b64 s[0:1], 0x1c000
	v_lshl_add_u64 v[138:139], v[180:181], 0, s[0:1]
	s_and_b64 vcc, exec, s[6:7]
	s_waitcnt vmcnt(15) lgkmcnt(0)
	v_pk_fma_f32 v[130:131], v[134:135], 0.5, v[130:131] op_sel_hi:[1,0,1]
	v_pk_fma_f32 v[132:133], v[136:137], 0.5, v[132:133] op_sel_hi:[1,0,1]
	global_store_dwordx4 v[138:139], v[130:133], off nt
	s_cbranch_vccnz .LBB0_1732
	v_pk_mul_f32 v[134:135], v[130:131], v[130:131]
	v_pk_mul_f32 v[136:137], v[132:133], v[132:133]
	v_add_f32_e32 v134, v134, v135
	v_add_f32_e32 v134, v136, v134
	v_and_b32_e32 v136, 64, v219
	s_nop 0
	v_add_u32_e32 v136, 64, v136
	s_nop 0
	v_add_f32_e32 v134, v137, v134
	v_or_b32_e32 v138, 28, v178
	s_nop 0
	s_nop 0
	v_mov_b32_dpp v135, v134 quad_perm:[1,0,3,2] row_mask:0xf bank_mask:0xf
	s_waitcnt lgkmcnt(0)
	v_add_f32_e32 v134, v134, v135
	s_nop 0
	s_nop 0
	s_nop 1
	s_nop 0
	s_nop 0
	v_mov_b32_dpp v135, v134 quad_perm:[2,3,0,1] row_mask:0xf bank_mask:0xf
	s_waitcnt lgkmcnt(0)
	v_add_f32_e32 v135, v134, v135
	s_nop 0
	s_nop 0
	s_nop 1
	s_nop 0
	s_nop 0
	v_mov_b32_dpp v137, v135 row_half_mirror row_mask:0xf bank_mask:0xf
	v_cvt_pk_bf16_f32 v134, v130, v131
	v_xor_b32_e32 v131, 8, v219
	v_cmp_lt_i32_e32 vcc, v131, v136
	s_waitcnt lgkmcnt(0)
	v_add_f32_e32 v130, v135, v137
	s_nop 0
	s_nop 0
	v_mov_b32_dpp v131, v130 row_mirror row_mask:0xf bank_mask:0xf
	v_cvt_pk_bf16_f32 v135, v132, v133
	v_mad_i64_i32 v[132:133], s[0:1], v138, s66, v[182:183]
	global_store_dwordx2 v[132:133], v[134:135], off
	s_and_saveexec_b64 s[0:1], s[4:5]
	s_cbranch_execz .LBB0_1731
	s_waitcnt lgkmcnt(0)
	v_add_f32_e32 v132, v130, v131
	v_lshl_add_u64 v[130:131], v[178:179], 2, s[38:39]
	global_atomic_add_f32 v[130:131], v132, off offset:112

; DI unsigned pack_bf16(float lo, float hi) { f32x2 v = {lo, hi}; bf16v2 b = __builtin_convertvector(v, bf16v2); return __builtin_bit_cast(unsigned, b); }
; DI float red16(float v) { v += __shfl_xor(v, 1); v += __shfl_xor(v, 2); v += __shfl_xor(v, 4); v += __shfl_xor(v, 8); return v; }
;   DI void run8(f32x4 (&acc)[8][4], int rb, int cb, int fr, int fq) const {
;     ...
;         for (int n = 0; n < 4; ++n)
; #pragma unroll
;           for (int j = 0; j < 4; ++j) scr[(fq * 4 + j) * 68 + n * 16 + fr] = acc[m][n][j];
;         __builtin_amdgcn_sched_barrier(0);
; #pragma unroll
;         for (int ps = 0; ps < 4; ++ps) {
;           const f32x4 a = *(const f32x4*)(scr + (ps * 4 + prow) * 68 + c4 * 4);
;           f32x4 v;
;           v.x = xv[mm][ps].x + a.x * sc; v.y = xv[mm][ps].y + a.y * sc; v.z = xv[mm][ps].z + a.z * sc; v.w = xv[mm][ps].w + a.w * sc;
;           const int grow = rb + m * 16 + ps * 4 + prow;
;           __builtin_nontemporal_store(v, (f32x4*)(op + (size_t)(m * 16 + ps * 4) * D));
;           if (xbp) {
;             u32x2 o; o.x = pack_bf16(v.x, v.y); o.y = pack_bf16(v.z, v.w);
;             *(u32x2*)(xbp + (size_t)grow * LDH + cb + c4 * 4) = o;
;             const float t = red16(v.x * v.x + v.y * v.y + v.z * v.z + v.w * v.w);
;             if (c4 == 0) atomicAdd(ssqp + grow, t);
;           }
.LBB0_1732:
	s_mov_b64 s[0:1], 0x20000
	s_waitcnt lgkmcnt(0)
	v_lshl_add_u64 v[130:131], v[180:181], 0, s[0:1]
	ds_write2_b32 v184, v114, v118 offset1:16
	ds_write2_b32 v184, v115, v119 offset0:68 offset1:84
	ds_write2_b32 v184, v116, v120 offset0:136 offset1:152
	ds_write2_b32 v184, v117, v121 offset0:204 offset1:220
	ds_write2_b32 v184, v106, v110 offset0:32 offset1:48
	ds_write2_b32 v184, v107, v111 offset0:100 offset1:116
	ds_write2_b32 v184, v108, v112 offset0:168 offset1:184
	ds_write2_b32 v184, v109, v113 offset0:236 offset1:252
	ds_read_b128 v[106:109], v0
	s_and_b64 vcc, exec, s[6:7]
	s_waitcnt vmcnt(15) lgkmcnt(0)
	v_pk_fma_f32 v[106:107], v[106:107], 0.5, v[126:127] op_sel_hi:[1,0,1]
	v_pk_fma_f32 v[108:109], v[108:109], 0.5, v[128:129] op_sel_hi:[1,0,1]
	global_store_dwordx4 v[130:131], v[106:109], off nt
	s_cbranch_vccnz .LBB0_1736
	v_pk_mul_f32 v[110:111], v[106:107], v[106:107]
	v_pk_mul_f32 v[112:113], v[108:109], v[108:109]
	v_add_f32_e32 v110, v110, v111
	v_add_f32_e32 v110, v112, v110
	v_and_b32_e32 v112, 64, v219
	s_nop 0
	v_add_u32_e32 v112, 64, v112
	s_nop 0
	v_add_f32_e32 v110, v113, v110
	v_or_b32_e32 v114, 32, v178
	s_nop 0
	s_nop 0
	v_mov_b32_dpp v111, v110 quad_perm:[1,0,3,2] row_mask:0xf bank_mask:0xf
	s_waitcnt lgkmcnt(0)
	v_add_f32_e32 v110, v110, v111
	s_nop 0
	s_nop 0
	s_nop 1
	s_nop 0
	s_nop 0
	v_mov_b32_dpp v111, v110 quad_perm:[2,3,0,1] row_mask:0xf bank_mask:0xf
	s_waitcnt lgkmcnt(0)
	v_add_f32_e32 v111, v110, v111
	s_nop 0
	s_nop 0
	s_nop 1
	s_nop 0
	s_nop 0
	v_mov_b32_dpp v113, v111 row_half_mirror row_mask:0xf bank_mask:0xf
	v_cvt_pk_bf16_f32 v110, v106, v107
	v_xor_b32_e32 v107, 8, v219
	v_cmp_lt_i32_e32 vcc, v107, v112
	s_waitcnt lgkmcnt(0)
	v_add_f32_e32 v106, v111, v113
	s_nop 0
	s_nop 0
	v_mov_b32_dpp v107, v106 row_mirror row_mask:0xf bank_mask:0xf
	v_cvt_pk_bf16_f32 v111, v108, v109
	v_mad_i64_i32 v[108:109], s[0:1], v114, s66, v[182:183]
	global_store_dwordx2 v[108:109], v[110:111], off
	s_and_saveexec_b64 s[0:1], s[4:5]
	s_cbranch_execz .LBB0_1735
	s_waitcnt lgkmcnt(0)
	v_add_f32_e32 v108, v106, v107
	v_lshl_add_u64 v[106:107], v[178:179], 2, s[38:39]
	global_atomic_add_f32 v[106:107], v108, off offset:128

; DI unsigned pack_bf16(float lo, float hi) { f32x2 v = {lo, hi}; bf16v2 b = __builtin_convertvector(v, bf16v2); return __builtin_bit_cast(unsigned, b); }
; DI float red16(float v) { v += __shfl_xor(v, 1); v += __shfl_xor(v, 2); v += __shfl_xor(v, 4); v += __shfl_xor(v, 8); return v; }
;   DI void run8(f32x4 (&acc)[8][4], int rb, int cb, int fr, int fq) const {
;     ...
;         for (int ps = 0; ps < 4; ++ps) {
;           const f32x4 a = *(const f32x4*)(scr + (ps * 4 + prow) * 68 + c4 * 4);
;           f32x4 v;
;           v.x = xv[mm][ps].x + a.x * sc; v.y = xv[mm][ps].y + a.y * sc; v.z = xv[mm][ps].z + a.z * sc; v.w = xv[mm][ps].w + a.w * sc;
;           const int grow = rb + m * 16 + ps * 4 + prow;
;           __builtin_nontemporal_store(v, (f32x4*)(op + (size_t)(m * 16 + ps * 4) * D));
;           if (xbp) {
;             u32x2 o; o.x = pack_bf16(v.x, v.y); o.y = pack_bf16(v.z, v.w);
;             *(u32x2*)(xbp + (size_t)grow * LDH + cb + c4 * 4) = o;
;             const float t = red16(v.x * v.x + v.y * v.y + v.z * v.z + v.w * v.w);
;             if (c4 == 0) atomicAdd(ssqp + grow, t);
;           }
.LBB0_1736:
	s_waitcnt lgkmcnt(0)
	ds_read_b128 v[106:109], v0 offset:1088
	s_mov_b64 s[0:1], 0x24000
	v_lshl_add_u64 v[110:111], v[180:181], 0, s[0:1]
	s_and_b64 vcc, exec, s[6:7]
	s_waitcnt vmcnt(15) lgkmcnt(0)
	v_pk_fma_f32 v[106:107], v[106:107], 0.5, v[122:123] op_sel_hi:[1,0,1]
	v_pk_fma_f32 v[108:109], v[108:109], 0.5, v[124:125] op_sel_hi:[1,0,1]
	global_store_dwordx4 v[110:111], v[106:109], off nt
	s_cbranch_vccnz .LBB0_1740
	v_pk_mul_f32 v[110:111], v[106:107], v[106:107]
	v_pk_mul_f32 v[112:113], v[108:109], v[108:109]
	v_add_f32_e32 v110, v110, v111
	v_add_f32_e32 v110, v112, v110
	v_and_b32_e32 v112, 64, v219
	s_nop 0
	v_add_u32_e32 v112, 64, v112
	s_nop 0
	v_add_f32_e32 v110, v113, v110
	v_or_b32_e32 v114, 36, v178
	s_nop 0
	s_nop 0
	v_mov_b32_dpp v111, v110 quad_perm:[1,0,3,2] row_mask:0xf bank_mask:0xf
	s_waitcnt lgkmcnt(0)
	v_add_f32_e32 v110, v110, v111
	s_nop 0
	s_nop 0
	s_nop 1
	s_nop 0
	s_nop 0
	v_mov_b32_dpp v111, v110 quad_perm:[2,3,0,1] row_mask:0xf bank_mask:0xf
	s_waitcnt lgkmcnt(0)
	v_add_f32_e32 v111, v110, v111
	s_nop 0
	s_nop 0
	s_nop 1
	s_nop 0
	s_nop 0
	v_mov_b32_dpp v113, v111 row_half_mirror row_mask:0xf bank_mask:0xf
	v_cvt_pk_bf16_f32 v110, v106, v107
	v_xor_b32_e32 v107, 8, v219
	v_cmp_lt_i32_e32 vcc, v107, v112
	s_waitcnt lgkmcnt(0)
	v_add_f32_e32 v106, v111, v113
	s_nop 0
	s_nop 0
	v_mov_b32_dpp v107, v106 row_mirror row_mask:0xf bank_mask:0xf
	v_cvt_pk_bf16_f32 v111, v108, v109
	v_mad_i64_i32 v[108:109], s[0:1], v114, s66, v[182:183]
	global_store_dwordx2 v[108:109], v[110:111], off
	s_and_saveexec_b64 s[0:1], s[4:5]
	s_cbranch_execz .LBB0_1739
	s_waitcnt lgkmcnt(0)
	v_add_f32_e32 v108, v106, v107
	v_lshl_add_u64 v[106:107], v[178:179], 2, s[38:39]
	global_atomic_add_f32 v[106:107], v108, off offset:144

; DI unsigned pack_bf16(float lo, float hi) { f32x2 v = {lo, hi}; bf16v2 b = __builtin_convertvector(v, bf16v2); return __builtin_bit_cast(unsigned, b); }
; DI float red16(float v) { v += __shfl_xor(v, 1); v += __shfl_xor(v, 2); v += __shfl_xor(v, 4); v += __shfl_xor(v, 8); return v; }
;   DI void run8(f32x4 (&acc)[8][4], int rb, int cb, int fr, int fq) const {
;     ...
;         for (int ps = 0; ps < 4; ++ps) {
;           const f32x4 a = *(const f32x4*)(scr + (ps * 4 + prow) * 68 + c4 * 4);
;           f32x4 v;
;           v.x = xv[mm][ps].x + a.x * sc; v.y = xv[mm][ps].y + a.y * sc; v.z = xv[mm][ps].z + a.z * sc; v.w = xv[mm][ps].w + a.w * sc;
;           const int grow = rb + m * 16 + ps * 4 + prow;
;           __builtin_nontemporal_store(v, (f32x4*)(op + (size_t)(m * 16 + ps * 4) * D));
;           if (xbp) {
;             u32x2 o; o.x = pack_bf16(v.x, v.y); o.y = pack_bf16(v.z, v.w);
;             *(u32x2*)(xbp + (size_t)grow * LDH + cb + c4 * 4) = o;
;             const float t = red16(v.x * v.x + v.y * v.y + v.z * v.z + v.w * v.w);
;             if (c4 == 0) atomicAdd(ssqp + grow, t);
;           }
.LBB0_1740:
	s_waitcnt lgkmcnt(0)
	ds_read_b128 v[106:109], v0 offset:2176
	s_mov_b64 s[0:1], 0x28000
	v_lshl_add_u64 v[110:111], v[180:181], 0, s[0:1]
	s_and_b64 vcc, exec, s[6:7]
	s_waitcnt vmcnt(15) lgkmcnt(0)
	v_pk_fma_f32 v[102:103], v[106:107], 0.5, v[102:103] op_sel_hi:[1,0,1]
	v_pk_fma_f32 v[104:105], v[108:109], 0.5, v[104:105] op_sel_hi:[1,0,1]
	global_store_dwordx4 v[110:111], v[102:105], off nt
	s_cbranch_vccnz .LBB0_1744
	v_pk_mul_f32 v[106:107], v[102:103], v[102:103]
	v_pk_mul_f32 v[108:109], v[104:105], v[104:105]
	v_add_f32_e32 v106, v106, v107
	v_add_f32_e32 v106, v108, v106
	v_and_b32_e32 v108, 64, v219
	s_nop 0
	v_add_u32_e32 v108, 64, v108
	s_nop 0
	v_add_f32_e32 v106, v109, v106
	v_or_b32_e32 v110, 40, v178
	s_nop 0
	s_nop 0
	v_mov_b32_dpp v107, v106 quad_perm:[1,0,3,2] row_mask:0xf bank_mask:0xf
	s_waitcnt lgkmcnt(0)
	v_add_f32_e32 v106, v106, v107
	s_nop 0
	s_nop 0
	s_nop 1
	s_nop 0
	s_nop 0
	v_mov_b32_dpp v107, v106 quad_perm:[2,3,0,1] row_mask:0xf bank_mask:0xf
	s_waitcnt lgkmcnt(0)
	v_add_f32_e32 v107, v106, v107
	s_nop 0
	s_nop 0
	s_nop 1
	s_nop 0
	s_nop 0
	v_mov_b32_dpp v109, v107 row_half_mirror row_mask:0xf bank_mask:0xf
	v_cvt_pk_bf16_f32 v106, v102, v103
	v_xor_b32_e32 v103, 8, v219
	v_cmp_lt_i32_e32 vcc, v103, v108
	s_waitcnt lgkmcnt(0)
	v_add_f32_e32 v102, v107, v109
	s_nop 0
	s_nop 0
	v_mov_b32_dpp v103, v102 row_mirror row_mask:0xf bank_mask:0xf
	v_cvt_pk_bf16_f32 v107, v104, v105
	v_mad_i64_i32 v[104:105], s[0:1], v110, s66, v[182:183]
	global_store_dwordx2 v[104:105], v[106:107], off
	s_and_saveexec_b64 s[0:1], s[4:5]
	s_cbranch_execz .LBB0_1743
	s_waitcnt lgkmcnt(0)
	v_add_f32_e32 v104, v102, v103
	v_lshl_add_u64 v[102:103], v[178:179], 2, s[38:39]
	global_atomic_add_f32 v[102:103], v104, off offset:160

; DI unsigned pack_bf16(float lo, float hi) { f32x2 v = {lo, hi}; bf16v2 b = __builtin_convertvector(v, bf16v2); return __builtin_bit_cast(unsigned, b); }
; DI float red16(float v) { v += __shfl_xor(v, 1); v += __shfl_xor(v, 2); v += __shfl_xor(v, 4); v += __shfl_xor(v, 8); return v; }
;   DI void run8(f32x4 (&acc)[8][4], int rb, int cb, int fr, int fq) const {
;     ...
;         for (int ps = 0; ps < 4; ++ps) {
;           const f32x4 a = *(const f32x4*)(scr + (ps * 4 + prow) * 68 + c4 * 4);
;           f32x4 v;
;           v.x = xv[mm][ps].x + a.x * sc; v.y = xv[mm][ps].y + a.y * sc; v.z = xv[mm][ps].z + a.z * sc; v.w = xv[mm][ps].w + a.w * sc;
;           const int grow = rb + m * 16 + ps * 4 + prow;
;           __builtin_nontemporal_store(v, (f32x4*)(op + (size_t)(m * 16 + ps * 4) * D));
;           if (xbp) {
;             u32x2 o; o.x = pack_bf16(v.x, v.y); o.y = pack_bf16(v.z, v.w);
;             *(u32x2*)(xbp + (size_t)grow * LDH + cb + c4 * 4) = o;
;             const float t = red16(v.x * v.x + v.y * v.y + v.z * v.z + v.w * v.w);
;             if (c4 == 0) atomicAdd(ssqp + grow, t);
;           }
.LBB0_1744:
	s_waitcnt lgkmcnt(0)
	ds_read_b128 v[102:105], v0 offset:3264
	s_mov_b64 s[0:1], 0x2c000
	v_lshl_add_u64 v[106:107], v[180:181], 0, s[0:1]
	s_and_b64 vcc, exec, s[6:7]
	s_waitcnt vmcnt(15) lgkmcnt(0)
	v_pk_fma_f32 v[98:99], v[102:103], 0.5, v[98:99] op_sel_hi:[1,0,1]
	v_pk_fma_f32 v[100:101], v[104:105], 0.5, v[100:101] op_sel_hi:[1,0,1]
	global_store_dwordx4 v[106:107], v[98:101], off nt
	s_cbranch_vccnz .LBB0_1748
	v_pk_mul_f32 v[102:103], v[98:99], v[98:99]
	v_pk_mul_f32 v[104:105], v[100:101], v[100:101]
	v_add_f32_e32 v102, v102, v103
	v_add_f32_e32 v102, v104, v102
	v_and_b32_e32 v104, 64, v219
	s_nop 0
	v_add_u32_e32 v104, 64, v104
	s_nop 0
	v_add_f32_e32 v102, v105, v102
	v_or_b32_e32 v106, 44, v178
	s_nop 0
	s_nop 0
	v_mov_b32_dpp v103, v102 quad_perm:[1,0,3,2] row_mask:0xf bank_mask:0xf
	s_waitcnt lgkmcnt(0)
	v_add_f32_e32 v102, v102, v103
	s_nop 0
	s_nop 0
	s_nop 1
	s_nop 0
	s_nop 0
	v_mov_b32_dpp v103, v102 quad_perm:[2,3,0,1] row_mask:0xf bank_mask:0xf
	s_waitcnt lgkmcnt(0)
	v_add_f32_e32 v103, v102, v103
	s_nop 0
	s_nop 0
	s_nop 1
	s_nop 0
	s_nop 0
	v_mov_b32_dpp v105, v103 row_half_mirror row_mask:0xf bank_mask:0xf
	v_cvt_pk_bf16_f32 v102, v98, v99
	v_xor_b32_e32 v99, 8, v219
	v_cmp_lt_i32_e32 vcc, v99, v104
	s_waitcnt lgkmcnt(0)
	v_add_f32_e32 v98, v103, v105
	s_nop 0
	s_nop 0
	v_mov_b32_dpp v99, v98 row_mirror row_mask:0xf bank_mask:0xf
	v_cvt_pk_bf16_f32 v103, v100, v101
	v_mad_i64_i32 v[100:101], s[0:1], v106, s66, v[182:183]
	global_store_dwordx2 v[100:101], v[102:103], off
	s_and_saveexec_b64 s[0:1], s[4:5]
	s_cbranch_execz .LBB0_1747
	s_waitcnt lgkmcnt(0)
	v_add_f32_e32 v100, v98, v99
	v_lshl_add_u64 v[98:99], v[178:179], 2, s[38:39]
	global_atomic_add_f32 v[98:99], v100, off offset:176

; DI unsigned pack_bf16(float lo, float hi) { f32x2 v = {lo, hi}; bf16v2 b = __builtin_convertvector(v, bf16v2); return __builtin_bit_cast(unsigned, b); }
; DI float red16(float v) { v += __shfl_xor(v, 1); v += __shfl_xor(v, 2); v += __shfl_xor(v, 4); v += __shfl_xor(v, 8); return v; }
;   DI void run8(f32x4 (&acc)[8][4], int rb, int cb, int fr, int fq) const {
;     ...
;           for (int j = 0; j < 4; ++j) scr[(fq * 4 + j) * 68 + n * 16 + fr] = acc[m][n][j];
;         __builtin_amdgcn_sched_barrier(0);
; #pragma unroll
;         for (int ps = 0; ps < 4; ++ps) {
;           const f32x4 a = *(const f32x4*)(scr + (ps * 4 + prow) * 68 + c4 * 4);
;           f32x4 v;
;           v.x = xv[mm][ps].x + a.x * sc; v.y = xv[mm][ps].y + a.y * sc; v.z = xv[mm][ps].z + a.z * sc; v.w = xv[mm][ps].w + a.w * sc;
;           const int grow = rb + m * 16 + ps * 4 + prow;
;           __builtin_nontemporal_store(v, (f32x4*)(op + (size_t)(m * 16 + ps * 4) * D));
;           if (xbp) {
;             u32x2 o; o.x = pack_bf16(v.x, v.y); o.y = pack_bf16(v.z, v.w);
;             *(u32x2*)(xbp + (size_t)grow * LDH + cb + c4 * 4) = o;
;             const float t = red16(v.x * v.x + v.y * v.y + v.z * v.z + v.w * v.w);
;             if (c4 == 0) atomicAdd(ssqp + grow, t);
;           }
.LBB0_1748:
	s_mov_b64 s[0:1], 0x30000
	s_waitcnt lgkmcnt(0)
	v_lshl_add_u64 v[98:99], v[180:181], 0, s[0:1]
	ds_write2_b32 v184, v82, v86 offset1:16
	ds_write2_b32 v184, v83, v87 offset0:68 offset1:84
	ds_write2_b32 v184, v84, v88 offset0:136 offset1:152
	ds_write2_b32 v184, v85, v89 offset0:204 offset1:220
	ds_write2_b32 v184, v74, v78 offset0:32 offset1:48
	ds_write2_b32 v184, v75, v79 offset0:100 offset1:116
	ds_write2_b32 v184, v76, v80 offset0:168 offset1:184
	ds_write2_b32 v184, v77, v81 offset0:236 offset1:252
	ds_read_b128 v[74:77], v0
	s_and_b64 vcc, exec, s[6:7]
	s_waitcnt vmcnt(15) lgkmcnt(0)
	v_pk_fma_f32 v[74:75], v[74:75], 0.5, v[94:95] op_sel_hi:[1,0,1]
	v_pk_fma_f32 v[76:77], v[76:77], 0.5, v[96:97] op_sel_hi:[1,0,1]
	global_store_dwordx4 v[98:99], v[74:77], off nt
	s_cbranch_vccnz .LBB0_1752
	v_pk_mul_f32 v[78:79], v[74:75], v[74:75]
	v_pk_mul_f32 v[80:81], v[76:77], v[76:77]
	v_add_f32_e32 v78, v78, v79
	v_add_f32_e32 v78, v80, v78
	v_and_b32_e32 v80, 64, v219
	s_nop 0
	v_add_u32_e32 v80, 64, v80
	s_nop 0
	v_add_f32_e32 v78, v81, v78
	v_or_b32_e32 v82, 48, v178
	s_nop 0
	s_nop 0
	v_mov_b32_dpp v79, v78 quad_perm:[1,0,3,2] row_mask:0xf bank_mask:0xf
	s_waitcnt lgkmcnt(0)
	v_add_f32_e32 v78, v78, v79
	s_nop 0
	s_nop 0
	s_nop 1
	s_nop 0
	s_nop 0
	v_mov_b32_dpp v79, v78 quad_perm:[2,3,0,1] row_mask:0xf bank_mask:0xf
	s_waitcnt lgkmcnt(0)
	v_add_f32_e32 v79, v78, v79
	s_nop 0
	s_nop 0
	s_nop 1
	s_nop 0
	s_nop 0
	v_mov_b32_dpp v81, v79 row_half_mirror row_mask:0xf bank_mask:0xf
	v_cvt_pk_bf16_f32 v78, v74, v75
	v_xor_b32_e32 v75, 8, v219
	v_cmp_lt_i32_e32 vcc, v75, v80
	s_waitcnt lgkmcnt(0)
	v_add_f32_e32 v74, v79, v81
	s_nop 0
	s_nop 0
	v_mov_b32_dpp v75, v74 row_mirror row_mask:0xf bank_mask:0xf
	v_cvt_pk_bf16_f32 v79, v76, v77
	v_mad_i64_i32 v[76:77], s[0:1], v82, s66, v[182:183]
	global_store_dwordx2 v[76:77], v[78:79], off
	s_and_saveexec_b64 s[0:1], s[4:5]
	s_cbranch_execz .LBB0_1751
	s_waitcnt lgkmcnt(0)
	v_add_f32_e32 v76, v74, v75
	v_lshl_add_u64 v[74:75], v[178:179], 2, s[38:39]
	global_atomic_add_f32 v[74:75], v76, off offset:192

; DI unsigned pack_bf16(float lo, float hi) { f32x2 v = {lo, hi}; bf16v2 b = __builtin_convertvector(v, bf16v2); return __builtin_bit_cast(unsigned, b); }
; DI float red16(float v) { v += __shfl_xor(v, 1); v += __shfl_xor(v, 2); v += __shfl_xor(v, 4); v += __shfl_xor(v, 8); return v; }
;   DI void run8(f32x4 (&acc)[8][4], int rb, int cb, int fr, int fq) const {
;     ...
;         for (int ps = 0; ps < 4; ++ps) {
;           const f32x4 a = *(const f32x4*)(scr + (ps * 4 + prow) * 68 + c4 * 4);
;           f32x4 v;
;           v.x = xv[mm][ps].x + a.x * sc; v.y = xv[mm][ps].y + a.y * sc; v.z = xv[mm][ps].z + a.z * sc; v.w = xv[mm][ps].w + a.w * sc;
;           const int grow = rb + m * 16 + ps * 4 + prow;
;           __builtin_nontemporal_store(v, (f32x4*)(op + (size_t)(m * 16 + ps * 4) * D));
;           if (xbp) {
;             u32x2 o; o.x = pack_bf16(v.x, v.y); o.y = pack_bf16(v.z, v.w);
;             *(u32x2*)(xbp + (size_t)grow * LDH + cb + c4 * 4) = o;
;             const float t = red16(v.x * v.x + v.y * v.y + v.z * v.z + v.w * v.w);
;             if (c4 == 0) atomicAdd(ssqp + grow, t);
;           }
.LBB0_1752:
	s_waitcnt lgkmcnt(0)
	ds_read_b128 v[74:77], v0 offset:1088
	s_mov_b64 s[0:1], 0x34000
	v_lshl_add_u64 v[78:79], v[180:181], 0, s[0:1]
	s_and_b64 vcc, exec, s[6:7]
	s_waitcnt vmcnt(15) lgkmcnt(0)
	v_pk_fma_f32 v[74:75], v[74:75], 0.5, v[90:91] op_sel_hi:[1,0,1]
	v_pk_fma_f32 v[76:77], v[76:77], 0.5, v[92:93] op_sel_hi:[1,0,1]
	global_store_dwordx4 v[78:79], v[74:77], off nt
	s_cbranch_vccnz .LBB0_1756
	v_pk_mul_f32 v[78:79], v[74:75], v[74:75]
	v_pk_mul_f32 v[80:81], v[76:77], v[76:77]
	v_add_f32_e32 v78, v78, v79
	v_add_f32_e32 v78, v80, v78
	v_and_b32_e32 v80, 64, v219
	s_nop 0
	v_add_u32_e32 v80, 64, v80
	s_nop 0
	v_add_f32_e32 v78, v81, v78
	v_or_b32_e32 v82, 52, v178
	s_nop 0
	s_nop 0
	v_mov_b32_dpp v79, v78 quad_perm:[1,0,3,2] row_mask:0xf bank_mask:0xf
	s_waitcnt lgkmcnt(0)
	v_add_f32_e32 v78, v78, v79
	s_nop 0
	s_nop 0
	s_nop 1
	s_nop 0
	s_nop 0
	v_mov_b32_dpp v79, v78 quad_perm:[2,3,0,1] row_mask:0xf bank_mask:0xf
	s_waitcnt lgkmcnt(0)
	v_add_f32_e32 v79, v78, v79
	s_nop 0
	s_nop 0
	s_nop 1
	s_nop 0
	s_nop 0
	v_mov_b32_dpp v81, v79 row_half_mirror row_mask:0xf bank_mask:0xf
	v_cvt_pk_bf16_f32 v78, v74, v75
	v_xor_b32_e32 v75, 8, v219
	v_cmp_lt_i32_e32 vcc, v75, v80
	s_waitcnt lgkmcnt(0)
	v_add_f32_e32 v74, v79, v81
	s_nop 0
	s_nop 0
	v_mov_b32_dpp v75, v74 row_mirror row_mask:0xf bank_mask:0xf
	v_cvt_pk_bf16_f32 v79, v76, v77
	v_mad_i64_i32 v[76:77], s[0:1], v82, s66, v[182:183]
	global_store_dwordx2 v[76:77], v[78:79], off
	s_and_saveexec_b64 s[0:1], s[4:5]
	s_cbranch_execz .LBB0_1755
	s_waitcnt lgkmcnt(0)
	v_add_f32_e32 v76, v74, v75
	v_lshl_add_u64 v[74:75], v[178:179], 2, s[38:39]
	global_atomic_add_f32 v[74:75], v76, off offset:208

; DI unsigned pack_bf16(float lo, float hi) { f32x2 v = {lo, hi}; bf16v2 b = __builtin_convertvector(v, bf16v2); return __builtin_bit_cast(unsigned, b); }
; DI float red16(float v) { v += __shfl_xor(v, 1); v += __shfl_xor(v, 2); v += __shfl_xor(v, 4); v += __shfl_xor(v, 8); return v; }
;   DI void run8(f32x4 (&acc)[8][4], int rb, int cb, int fr, int fq) const {
;     ...
;         for (int ps = 0; ps < 4; ++ps) {
;           const f32x4 a = *(const f32x4*)(scr + (ps * 4 + prow) * 68 + c4 * 4);
;           f32x4 v;
;           v.x = xv[mm][ps].x + a.x * sc; v.y = xv[mm][ps].y + a.y * sc; v.z = xv[mm][ps].z + a.z * sc; v.w = xv[mm][ps].w + a.w * sc;
;           const int grow = rb + m * 16 + ps * 4 + prow;
;           __builtin_nontemporal_store(v, (f32x4*)(op + (size_t)(m * 16 + ps * 4) * D));
;           if (xbp) {
;             u32x2 o; o.x = pack_bf16(v.x, v.y); o.y = pack_bf16(v.z, v.w);
;             *(u32x2*)(xbp + (size_t)grow * LDH + cb + c4 * 4) = o;
;             const float t = red16(v.x * v.x + v.y * v.y + v.z * v.z + v.w * v.w);
;             if (c4 == 0) atomicAdd(ssqp + grow, t);
;           }
.LBB0_1756:
	s_waitcnt lgkmcnt(0)
	ds_read_b128 v[74:77], v0 offset:2176
	s_mov_b64 s[0:1], 0x38000
	v_lshl_add_u64 v[78:79], v[180:181], 0, s[0:1]
	s_and_b64 vcc, exec, s[6:7]
	s_waitcnt vmcnt(15) lgkmcnt(0)
	v_pk_fma_f32 v[70:71], v[74:75], 0.5, v[70:71] op_sel_hi:[1,0,1]
	v_pk_fma_f32 v[72:73], v[76:77], 0.5, v[72:73] op_sel_hi:[1,0,1]
	global_store_dwordx4 v[78:79], v[70:73], off nt
	s_cbranch_vccnz .LBB0_1760
	v_pk_mul_f32 v[74:75], v[70:71], v[70:71]
	v_pk_mul_f32 v[76:77], v[72:73], v[72:73]
	v_add_f32_e32 v74, v74, v75
	v_add_f32_e32 v74, v76, v74
	v_and_b32_e32 v76, 64, v219
	s_nop 0
	v_add_u32_e32 v76, 64, v76
	s_nop 0
	v_add_f32_e32 v74, v77, v74
	v_or_b32_e32 v78, 56, v178
	s_nop 0
	s_nop 0
	v_mov_b32_dpp v75, v74 quad_perm:[1,0,3,2] row_mask:0xf bank_mask:0xf
	s_waitcnt lgkmcnt(0)
	v_add_f32_e32 v74, v74, v75
	s_nop 0
	s_nop 0
	s_nop 1
	s_nop 0
	s_nop 0
	v_mov_b32_dpp v75, v74 quad_perm:[2,3,0,1] row_mask:0xf bank_mask:0xf
	s_waitcnt lgkmcnt(0)
	v_add_f32_e32 v75, v74, v75
	s_nop 0
	s_nop 0
	s_nop 1
	s_nop 0
	s_nop 0
	v_mov_b32_dpp v77, v75 row_half_mirror row_mask:0xf bank_mask:0xf
	v_cvt_pk_bf16_f32 v74, v70, v71
	v_xor_b32_e32 v71, 8, v219
	v_cmp_lt_i32_e32 vcc, v71, v76
	s_waitcnt lgkmcnt(0)
	v_add_f32_e32 v70, v75, v77
	s_nop 0
	s_nop 0
	v_mov_b32_dpp v71, v70 row_mirror row_mask:0xf bank_mask:0xf
	v_cvt_pk_bf16_f32 v75, v72, v73
	v_mad_i64_i32 v[72:73], s[0:1], v78, s66, v[182:183]
	global_store_dwordx2 v[72:73], v[74:75], off
	s_and_saveexec_b64 s[0:1], s[4:5]
	s_cbranch_execz .LBB0_1759
	s_waitcnt lgkmcnt(0)
	v_add_f32_e32 v72, v70, v71
	v_lshl_add_u64 v[70:71], v[178:179], 2, s[38:39]
	global_atomic_add_f32 v[70:71], v72, off offset:224

; DI unsigned pack_bf16(float lo, float hi) { f32x2 v = {lo, hi}; bf16v2 b = __builtin_convertvector(v, bf16v2); return __builtin_bit_cast(unsigned, b); }
; DI float red16(float v) { v += __shfl_xor(v, 1); v += __shfl_xor(v, 2); v += __shfl_xor(v, 4); v += __shfl_xor(v, 8); return v; }
;   DI void run8(f32x4 (&acc)[8][4], int rb, int cb, int fr, int fq) const {
;     ...
;         for (int ps = 0; ps < 4; ++ps) {
;           const f32x4 a = *(const f32x4*)(scr + (ps * 4 + prow) * 68 + c4 * 4);
;           f32x4 v;
;           v.x = xv[mm][ps].x + a.x * sc; v.y = xv[mm][ps].y + a.y * sc; v.z = xv[mm][ps].z + a.z * sc; v.w = xv[mm][ps].w + a.w * sc;
;           const int grow = rb + m * 16 + ps * 4 + prow;
;           __builtin_nontemporal_store(v, (f32x4*)(op + (size_t)(m * 16 + ps * 4) * D));
;           if (xbp) {
;             u32x2 o; o.x = pack_bf16(v.x, v.y); o.y = pack_bf16(v.z, v.w);
;             *(u32x2*)(xbp + (size_t)grow * LDH + cb + c4 * 4) = o;
;             const float t = red16(v.x * v.x + v.y * v.y + v.z * v.z + v.w * v.w);
;             if (c4 == 0) atomicAdd(ssqp + grow, t);
;           }
.LBB0_1760:
	s_waitcnt lgkmcnt(0)
	ds_read_b128 v[70:73], v0 offset:3264
	s_mov_b64 s[0:1], 0x3c000
	v_lshl_add_u64 v[74:75], v[180:181], 0, s[0:1]
	s_and_b64 vcc, exec, s[6:7]
	s_waitcnt vmcnt(15) lgkmcnt(0)
	v_pk_fma_f32 v[66:67], v[70:71], 0.5, v[66:67] op_sel_hi:[1,0,1]
	v_pk_fma_f32 v[68:69], v[72:73], 0.5, v[68:69] op_sel_hi:[1,0,1]
	global_store_dwordx4 v[74:75], v[66:69], off nt
	s_cbranch_vccnz .LBB0_1764
	v_pk_mul_f32 v[70:71], v[66:67], v[66:67]
	v_pk_mul_f32 v[72:73], v[68:69], v[68:69]
	v_add_f32_e32 v70, v70, v71
	v_add_f32_e32 v70, v72, v70
	v_and_b32_e32 v72, 64, v219
	s_nop 0
	v_add_u32_e32 v72, 64, v72
	s_nop 0
	v_add_f32_e32 v70, v73, v70
	v_or_b32_e32 v74, 60, v178
	s_nop 0
	s_nop 0
	v_mov_b32_dpp v71, v70 quad_perm:[1,0,3,2] row_mask:0xf bank_mask:0xf
	s_waitcnt lgkmcnt(0)
	v_add_f32_e32 v70, v70, v71
	s_nop 0
	s_nop 0
	s_nop 1
	s_nop 0
	s_nop 0
	v_mov_b32_dpp v71, v70 quad_perm:[2,3,0,1] row_mask:0xf bank_mask:0xf
	s_waitcnt lgkmcnt(0)
	v_add_f32_e32 v71, v70, v71
	s_nop 0
	s_nop 0
	s_nop 1
	s_nop 0
	s_nop 0
	v_mov_b32_dpp v73, v71 row_half_mirror row_mask:0xf bank_mask:0xf
	v_cvt_pk_bf16_f32 v70, v66, v67
	v_xor_b32_e32 v67, 8, v219
	v_cmp_lt_i32_e32 vcc, v67, v72
	s_waitcnt lgkmcnt(0)
	v_add_f32_e32 v66, v71, v73
	s_nop 0
	s_nop 0
	v_mov_b32_dpp v67, v66 row_mirror row_mask:0xf bank_mask:0xf
	v_cvt_pk_bf16_f32 v71, v68, v69
	v_mad_i64_i32 v[68:69], s[0:1], v74, s66, v[182:183]
	global_store_dwordx2 v[68:69], v[70:71], off
	s_and_saveexec_b64 s[0:1], s[4:5]
	s_cbranch_execz .LBB0_1763
	s_waitcnt lgkmcnt(0)
	v_add_f32_e32 v68, v66, v67
	v_lshl_add_u64 v[66:67], v[178:179], 2, s[38:39]
	global_atomic_add_f32 v[66:67], v68, off offset:240

; DI unsigned pack_bf16(float lo, float hi) { f32x2 v = {lo, hi}; bf16v2 b = __builtin_convertvector(v, bf16v2); return __builtin_bit_cast(unsigned, b); }
; DI float red16(float v) { v += __shfl_xor(v, 1); v += __shfl_xor(v, 2); v += __shfl_xor(v, 4); v += __shfl_xor(v, 8); return v; }
;   DI void run8(f32x4 (&acc)[8][4], int rb, int cb, int fr, int fq) const {
;     ...
;     for (int mh = 0; mh < 2; ++mh) {
;       f32x4 xv[4][4];
; #pragma unroll
;       for (int mm = 0; mm < 4; ++mm)
; #pragma unroll
;         for (int ps = 0; ps < 4; ++ps) xv[mm][ps] = __builtin_nontemporal_load((const f32x4*)(xp + (size_t)((mh * 4 + mm) * 16 + ps * 4) * D));
;       __builtin_amdgcn_sched_barrier(0);
; #pragma unroll
;       for (int mm = 0; mm < 4; ++mm) {
;         const int m = mh * 4 + mm;
; #pragma unroll
;         for (int n = 0; n < 4; ++n)
; #pragma unroll
;           for (int j = 0; j < 4; ++j) scr[(fq * 4 + j) * 68 + n * 16 + fr] = acc[m][n][j];
;         __builtin_amdgcn_sched_barrier(0);
; #pragma unroll
;         for (int ps = 0; ps < 4; ++ps) {
;           const f32x4 a = *(const f32x4*)(scr + (ps * 4 + prow) * 68 + c4 * 4);
;           f32x4 v;
;           v.x = xv[mm][ps].x + a.x * sc; v.y = xv[mm][ps].y + a.y * sc; v.z = xv[mm][ps].z + a.z * sc; v.w = xv[mm][ps].w + a.w * sc;
;           const int grow = rb + m * 16 + ps * 4 + prow;
;           __builtin_nontemporal_store(v, (f32x4*)(op + (size_t)(m * 16 + ps * 4) * D));
;           if (xbp) {
;             u32x2 o; o.x = pack_bf16(v.x, v.y); o.y = pack_bf16(v.z, v.w);
;             *(u32x2*)(xbp + (size_t)grow * LDH + cb + c4 * 4) = o;
;             const float t = red16(v.x * v.x + v.y * v.y + v.z * v.z + v.w * v.w);
;             if (c4 == 0) atomicAdd(ssqp + grow, t);
;           }
.LBB0_1764:
	v_add_co_u32_e32 v130, vcc, 0x40000, v180
	s_nop 1
	v_addc_co_u32_e32 v131, vcc, 0, v181, vcc
	v_add_co_u32_e32 v66, vcc, 0x44000, v180
	s_waitcnt lgkmcnt(0)
	s_nop 0
	v_addc_co_u32_e32 v67, vcc, 0, v181, vcc
	global_load_dwordx4 v[126:129], v[130:131], off nt
	global_load_dwordx4 v[122:125], v[66:67], off nt
	v_add_co_u32_e32 v66, vcc, 0x48000, v180
	s_nop 1
	v_addc_co_u32_e32 v67, vcc, 0, v181, vcc
	v_add_co_u32_e32 v68, vcc, 0x4c000, v180
	s_nop 1
	v_addc_co_u32_e32 v69, vcc, 0, v181, vcc
	global_load_dwordx4 v[118:121], v[66:67], off nt
	global_load_dwordx4 v[114:117], v[68:69], off nt
	v_add_co_u32_e32 v66, vcc, 0x50000, v180
	s_nop 1
	v_addc_co_u32_e32 v67, vcc, 0, v181, vcc
	v_add_co_u32_e32 v68, vcc, 0x54000, v180
	s_nop 1
	v_addc_co_u32_e32 v69, vcc, 0, v181, vcc
	global_load_dwordx4 v[110:113], v[66:67], off nt
	global_load_dwordx4 v[106:109], v[68:69], off nt
	v_add_co_u32_e32 v66, vcc, 0x58000, v180
	s_nop 1
	v_addc_co_u32_e32 v67, vcc, 0, v181, vcc
	v_add_co_u32_e32 v68, vcc, 0x5c000, v180
	s_nop 1
	v_addc_co_u32_e32 v69, vcc, 0, v181, vcc
	global_load_dwordx4 v[102:105], v[66:67], off nt
	global_load_dwordx4 v[98:101], v[68:69], off nt
	v_add_co_u32_e32 v66, vcc, 0x60000, v180
	s_nop 1
	v_addc_co_u32_e32 v67, vcc, 0, v181, vcc
	v_add_co_u32_e32 v68, vcc, 0x64000, v180
	s_nop 1
	v_addc_co_u32_e32 v69, vcc, 0, v181, vcc
	global_load_dwordx4 v[94:97], v[66:67], off nt
	global_load_dwordx4 v[90:93], v[68:69], off nt
	v_add_co_u32_e32 v66, vcc, 0x68000, v180
	s_nop 1
	v_addc_co_u32_e32 v67, vcc, 0, v181, vcc
	v_add_co_u32_e32 v68, vcc, 0x6c000, v180
	s_nop 1
	v_addc_co_u32_e32 v69, vcc, 0, v181, vcc
	global_load_dwordx4 v[86:89], v[66:67], off nt
	global_load_dwordx4 v[82:85], v[68:69], off nt
	v_add_co_u32_e32 v66, vcc, s68, v180
	s_nop 1
	v_addc_co_u32_e32 v67, vcc, 0, v181, vcc
	v_add_co_u32_e32 v68, vcc, 0x74000, v180
	s_nop 1
	v_addc_co_u32_e32 v69, vcc, 0, v181, vcc
	global_load_dwordx4 v[78:81], v[66:67], off nt
	global_load_dwordx4 v[74:77], v[68:69], off nt
	v_add_co_u32_e32 v66, vcc, 0x78000, v180
	s_nop 1
	v_addc_co_u32_e32 v67, vcc, 0, v181, vcc
	v_add_co_u32_e32 v68, vcc, 0x7c000, v180
	s_nop 1
	v_addc_co_u32_e32 v69, vcc, 0, v181, vcc
	global_load_dwordx4 v[70:73], v[66:67], off nt
	s_nop 0
	global_load_dwordx4 v[66:69], v[68:69], off nt
	ds_write2_b32 v184, v58, v62 offset1:16
	ds_write2_b32 v184, v59, v63 offset0:68 offset1:84
	ds_write2_b32 v184, v60, v64 offset0:136 offset1:152
	ds_write2_b32 v184, v61, v65 offset0:204 offset1:220
	ds_write2_b32 v184, v50, v54 offset0:32 offset1:48
	ds_write2_b32 v184, v51, v55 offset0:100 offset1:116
	ds_write2_b32 v184, v52, v56 offset0:168 offset1:184
	ds_write2_b32 v184, v53, v57 offset0:236 offset1:252
	ds_read_b128 v[50:53], v0
	s_and_b64 vcc, exec, s[6:7]
	s_waitcnt vmcnt(15) lgkmcnt(0)
	v_pk_fma_f32 v[50:51], v[50:51], 0.5, v[126:127] op_sel_hi:[1,0,1]
	v_pk_fma_f32 v[52:53], v[52:53], 0.5, v[128:129] op_sel_hi:[1,0,1]
	global_store_dwordx4 v[130:131], v[50:53], off nt
	s_cbranch_vccnz .LBB0_1768
	v_pk_mul_f32 v[54:55], v[50:51], v[50:51]
	v_pk_mul_f32 v[56:57], v[52:53], v[52:53]
	v_add_f32_e32 v54, v54, v55
	v_add_f32_e32 v54, v56, v54
	v_and_b32_e32 v56, 64, v219
	s_nop 0
	v_add_u32_e32 v56, 64, v56
	s_nop 0
	v_add_f32_e32 v54, v57, v54
	v_or_b32_e32 v58, 64, v178
	s_nop 0
	s_nop 0
	v_mov_b32_dpp v55, v54 quad_perm:[1,0,3,2] row_mask:0xf bank_mask:0xf
	s_waitcnt lgkmcnt(0)
	v_add_f32_e32 v54, v54, v55
	s_nop 0
	s_nop 0
	s_nop 1
	s_nop 0
	s_nop 0
	v_mov_b32_dpp v55, v54 quad_perm:[2,3,0,1] row_mask:0xf bank_mask:0xf
	s_waitcnt lgkmcnt(0)
	v_add_f32_e32 v55, v54, v55
	s_nop 0
	s_nop 0
	s_nop 1
	s_nop 0
	s_nop 0
	v_mov_b32_dpp v57, v55 row_half_mirror row_mask:0xf bank_mask:0xf
	v_cvt_pk_bf16_f32 v54, v50, v51
	v_xor_b32_e32 v51, 8, v219
	v_cmp_lt_i32_e32 vcc, v51, v56
	s_waitcnt lgkmcnt(0)
	v_add_f32_e32 v50, v55, v57
	s_nop 0
	s_nop 0
	v_mov_b32_dpp v51, v50 row_mirror row_mask:0xf bank_mask:0xf
	v_cvt_pk_bf16_f32 v55, v52, v53
	v_mad_i64_i32 v[52:53], s[0:1], v58, s66, v[182:183]
	global_store_dwordx2 v[52:53], v[54:55], off
	s_and_saveexec_b64 s[0:1], s[4:5]
	s_cbranch_execz .LBB0_1767
	s_waitcnt lgkmcnt(0)
	v_add_f32_e32 v52, v50, v51
	v_lshl_add_u64 v[50:51], v[178:179], 2, s[38:39]
	global_atomic_add_f32 v[50:51], v52, off offset:256

; DI unsigned pack_bf16(float lo, float hi) { f32x2 v = {lo, hi}; bf16v2 b = __builtin_convertvector(v, bf16v2); return __builtin_bit_cast(unsigned, b); }
; DI float red16(float v) { v += __shfl_xor(v, 1); v += __shfl_xor(v, 2); v += __shfl_xor(v, 4); v += __shfl_xor(v, 8); return v; }
;   DI void run8(f32x4 (&acc)[8][4], int rb, int cb, int fr, int fq) const {
;     ...
;         for (int ps = 0; ps < 4; ++ps) {
;           const f32x4 a = *(const f32x4*)(scr + (ps * 4 + prow) * 68 + c4 * 4);
;           f32x4 v;
;           v.x = xv[mm][ps].x + a.x * sc; v.y = xv[mm][ps].y + a.y * sc; v.z = xv[mm][ps].z + a.z * sc; v.w = xv[mm][ps].w + a.w * sc;
;           const int grow = rb + m * 16 + ps * 4 + prow;
;           __builtin_nontemporal_store(v, (f32x4*)(op + (size_t)(m * 16 + ps * 4) * D));
;           if (xbp) {
;             u32x2 o; o.x = pack_bf16(v.x, v.y); o.y = pack_bf16(v.z, v.w);
;             *(u32x2*)(xbp + (size_t)grow * LDH + cb + c4 * 4) = o;
;             const float t = red16(v.x * v.x + v.y * v.y + v.z * v.z + v.w * v.w);
;             if (c4 == 0) atomicAdd(ssqp + grow, t);
;           }
.LBB0_1768:
	s_waitcnt lgkmcnt(0)
	ds_read_b128 v[50:53], v0 offset:1088
	s_mov_b64 s[0:1], 0x44000
	v_lshl_add_u64 v[54:55], v[180:181], 0, s[0:1]
	s_and_b64 vcc, exec, s[6:7]
	s_waitcnt vmcnt(15) lgkmcnt(0)
	v_pk_fma_f32 v[50:51], v[50:51], 0.5, v[122:123] op_sel_hi:[1,0,1]
	v_pk_fma_f32 v[52:53], v[52:53], 0.5, v[124:125] op_sel_hi:[1,0,1]
	global_store_dwordx4 v[54:55], v[50:53], off nt
	s_cbranch_vccnz .LBB0_1772
	v_pk_mul_f32 v[54:55], v[50:51], v[50:51]
	v_pk_mul_f32 v[56:57], v[52:53], v[52:53]
	v_add_f32_e32 v54, v54, v55
	v_add_f32_e32 v54, v56, v54
	v_and_b32_e32 v56, 64, v219
	s_nop 0
	v_add_u32_e32 v56, 64, v56
	s_nop 0
	v_add_f32_e32 v54, v57, v54
	v_or_b32_e32 v58, 0x44, v178
	s_nop 0
	s_nop 0
	v_mov_b32_dpp v55, v54 quad_perm:[1,0,3,2] row_mask:0xf bank_mask:0xf
	s_waitcnt lgkmcnt(0)
	v_add_f32_e32 v54, v54, v55
	s_nop 0
	s_nop 0
	s_nop 1
	s_nop 0
	s_nop 0
	v_mov_b32_dpp v55, v54 quad_perm:[2,3,0,1] row_mask:0xf bank_mask:0xf
	s_waitcnt lgkmcnt(0)
	v_add_f32_e32 v55, v54, v55
	s_nop 0
	s_nop 0
	s_nop 1
	s_nop 0
	s_nop 0
	v_mov_b32_dpp v57, v55 row_half_mirror row_mask:0xf bank_mask:0xf
	v_cvt_pk_bf16_f32 v54, v50, v51
	v_xor_b32_e32 v51, 8, v219
	v_cmp_lt_i32_e32 vcc, v51, v56
	s_waitcnt lgkmcnt(0)
	v_add_f32_e32 v50, v55, v57
	s_nop 0
	s_nop 0
	v_mov_b32_dpp v51, v50 row_mirror row_mask:0xf bank_mask:0xf
	v_cvt_pk_bf16_f32 v55, v52, v53
	v_mad_i64_i32 v[52:53], s[0:1], v58, s66, v[182:183]
	global_store_dwordx2 v[52:53], v[54:55], off
	s_and_saveexec_b64 s[0:1], s[4:5]
	s_cbranch_execz .LBB0_1771
	s_waitcnt lgkmcnt(0)
	v_add_f32_e32 v52, v50, v51
	v_lshl_add_u64 v[50:51], v[178:179], 2, s[38:39]
	global_atomic_add_f32 v[50:51], v52, off offset:272

; DI unsigned pack_bf16(float lo, float hi) { f32x2 v = {lo, hi}; bf16v2 b = __builtin_convertvector(v, bf16v2); return __builtin_bit_cast(unsigned, b); }
; DI float red16(float v) { v += __shfl_xor(v, 1); v += __shfl_xor(v, 2); v += __shfl_xor(v, 4); v += __shfl_xor(v, 8); return v; }
;   DI void run8(f32x4 (&acc)[8][4], int rb, int cb, int fr, int fq) const {
;     ...
;         for (int ps = 0; ps < 4; ++ps) {
;           const f32x4 a = *(const f32x4*)(scr + (ps * 4 + prow) * 68 + c4 * 4);
;           f32x4 v;
;           v.x = xv[mm][ps].x + a.x * sc; v.y = xv[mm][ps].y + a.y * sc; v.z = xv[mm][ps].z + a.z * sc; v.w = xv[mm][ps].w + a.w * sc;
;           const int grow = rb + m * 16 + ps * 4 + prow;
;           __builtin_nontemporal_store(v, (f32x4*)(op + (size_t)(m * 16 + ps * 4) * D));
;           if (xbp) {
;             u32x2 o; o.x = pack_bf16(v.x, v.y); o.y = pack_bf16(v.z, v.w);
;             *(u32x2*)(xbp + (size_t)grow * LDH + cb + c4 * 4) = o;
;             const float t = red16(v.x * v.x + v.y * v.y + v.z * v.z + v.w * v.w);
;             if (c4 == 0) atomicAdd(ssqp + grow, t);
;           }
.LBB0_1772:
	s_waitcnt lgkmcnt(0)
	ds_read_b128 v[50:53], v0 offset:2176
	s_mov_b64 s[0:1], 0x48000
	v_lshl_add_u64 v[54:55], v[180:181], 0, s[0:1]
	s_and_b64 vcc, exec, s[6:7]
	s_waitcnt vmcnt(15) lgkmcnt(0)
	v_pk_fma_f32 v[50:51], v[50:51], 0.5, v[118:119] op_sel_hi:[1,0,1]
	v_pk_fma_f32 v[52:53], v[52:53], 0.5, v[120:121] op_sel_hi:[1,0,1]
	global_store_dwordx4 v[54:55], v[50:53], off nt
	s_cbranch_vccnz .LBB0_1776
	v_pk_mul_f32 v[54:55], v[50:51], v[50:51]
	v_pk_mul_f32 v[56:57], v[52:53], v[52:53]
	v_add_f32_e32 v54, v54, v55
	v_add_f32_e32 v54, v56, v54
	v_and_b32_e32 v56, 64, v219
	s_nop 0
	v_add_u32_e32 v56, 64, v56
	s_nop 0
	v_add_f32_e32 v54, v57, v54
	v_or_b32_e32 v58, 0x48, v178
	s_nop 0
	s_nop 0
	v_mov_b32_dpp v55, v54 quad_perm:[1,0,3,2] row_mask:0xf bank_mask:0xf
	s_waitcnt lgkmcnt(0)
	v_add_f32_e32 v54, v54, v55
	s_nop 0
	s_nop 0
	s_nop 1
	s_nop 0
	s_nop 0
	v_mov_b32_dpp v55, v54 quad_perm:[2,3,0,1] row_mask:0xf bank_mask:0xf
	s_waitcnt lgkmcnt(0)
	v_add_f32_e32 v55, v54, v55
	s_nop 0
	s_nop 0
	s_nop 1
	s_nop 0
	s_nop 0
	v_mov_b32_dpp v57, v55 row_half_mirror row_mask:0xf bank_mask:0xf
	v_cvt_pk_bf16_f32 v54, v50, v51
	v_xor_b32_e32 v51, 8, v219
	v_cmp_lt_i32_e32 vcc, v51, v56
	s_waitcnt lgkmcnt(0)
	v_add_f32_e32 v50, v55, v57
	s_nop 0
	s_nop 0
	v_mov_b32_dpp v51, v50 row_mirror row_mask:0xf bank_mask:0xf
	v_cvt_pk_bf16_f32 v55, v52, v53
	v_mad_i64_i32 v[52:53], s[0:1], v58, s66, v[182:183]
	global_store_dwordx2 v[52:53], v[54:55], off
	s_and_saveexec_b64 s[0:1], s[4:5]
	s_cbranch_execz .LBB0_1775
	s_waitcnt lgkmcnt(0)
	v_add_f32_e32 v52, v50, v51
	v_lshl_add_u64 v[50:51], v[178:179], 2, s[38:39]
	global_atomic_add_f32 v[50:51], v52, off offset:288

; DI unsigned pack_bf16(float lo, float hi) { f32x2 v = {lo, hi}; bf16v2 b = __builtin_convertvector(v, bf16v2); return __builtin_bit_cast(unsigned, b); }
; DI float red16(float v) { v += __shfl_xor(v, 1); v += __shfl_xor(v, 2); v += __shfl_xor(v, 4); v += __shfl_xor(v, 8); return v; }
;   DI void run8(f32x4 (&acc)[8][4], int rb, int cb, int fr, int fq) const {
;     ...
;         for (int ps = 0; ps < 4; ++ps) {
;           const f32x4 a = *(const f32x4*)(scr + (ps * 4 + prow) * 68 + c4 * 4);
;           f32x4 v;
;           v.x = xv[mm][ps].x + a.x * sc; v.y = xv[mm][ps].y + a.y * sc; v.z = xv[mm][ps].z + a.z * sc; v.w = xv[mm][ps].w + a.w * sc;
;           const int grow = rb + m * 16 + ps * 4 + prow;
;           __builtin_nontemporal_store(v, (f32x4*)(op + (size_t)(m * 16 + ps * 4) * D));
;           if (xbp) {
;             u32x2 o; o.x = pack_bf16(v.x, v.y); o.y = pack_bf16(v.z, v.w);
;             *(u32x2*)(xbp + (size_t)grow * LDH + cb + c4 * 4) = o;
;             const float t = red16(v.x * v.x + v.y * v.y + v.z * v.z + v.w * v.w);
;             if (c4 == 0) atomicAdd(ssqp + grow, t);
;           }
.LBB0_1776:
	s_waitcnt lgkmcnt(0)
	ds_read_b128 v[50:53], v0 offset:3264
	s_mov_b64 s[0:1], 0x4c000
	v_lshl_add_u64 v[54:55], v[180:181], 0, s[0:1]
	s_and_b64 vcc, exec, s[6:7]
	s_waitcnt vmcnt(15) lgkmcnt(0)
	v_pk_fma_f32 v[50:51], v[50:51], 0.5, v[114:115] op_sel_hi:[1,0,1]
	v_pk_fma_f32 v[52:53], v[52:53], 0.5, v[116:117] op_sel_hi:[1,0,1]
	global_store_dwordx4 v[54:55], v[50:53], off nt
	s_cbranch_vccnz .LBB0_1780
	v_pk_mul_f32 v[54:55], v[50:51], v[50:51]
	v_pk_mul_f32 v[56:57], v[52:53], v[52:53]
	v_add_f32_e32 v54, v54, v55
	v_add_f32_e32 v54, v56, v54
	v_and_b32_e32 v56, 64, v219
	s_nop 0
	v_add_u32_e32 v56, 64, v56
	s_nop 0
	v_add_f32_e32 v54, v57, v54
	v_or_b32_e32 v58, 0x4c, v178
	s_nop 0
	s_nop 0
	v_mov_b32_dpp v55, v54 quad_perm:[1,0,3,2] row_mask:0xf bank_mask:0xf
	s_waitcnt lgkmcnt(0)
	v_add_f32_e32 v54, v54, v55
	s_nop 0
	s_nop 0
	s_nop 1
	s_nop 0
	s_nop 0
	v_mov_b32_dpp v55, v54 quad_perm:[2,3,0,1] row_mask:0xf bank_mask:0xf
	s_waitcnt lgkmcnt(0)
	v_add_f32_e32 v55, v54, v55
	s_nop 0
	s_nop 0
	s_nop 1
	s_nop 0
	s_nop 0
	v_mov_b32_dpp v57, v55 row_half_mirror row_mask:0xf bank_mask:0xf
	v_cvt_pk_bf16_f32 v54, v50, v51
	v_xor_b32_e32 v51, 8, v219
	v_cmp_lt_i32_e32 vcc, v51, v56
	s_waitcnt lgkmcnt(0)
	v_add_f32_e32 v50, v55, v57
	s_nop 0
	s_nop 0
	v_mov_b32_dpp v51, v50 row_mirror row_mask:0xf bank_mask:0xf
	v_cvt_pk_bf16_f32 v55, v52, v53
	v_mad_i64_i32 v[52:53], s[0:1], v58, s66, v[182:183]
	global_store_dwordx2 v[52:53], v[54:55], off
	s_and_saveexec_b64 s[0:1], s[4:5]
	s_cbranch_execz .LBB0_1779
	s_waitcnt lgkmcnt(0)
	v_add_f32_e32 v52, v50, v51
	v_lshl_add_u64 v[50:51], v[178:179], 2, s[38:39]
	global_atomic_add_f32 v[50:51], v52, off offset:304

; DI unsigned pack_bf16(float lo, float hi) { f32x2 v = {lo, hi}; bf16v2 b = __builtin_convertvector(v, bf16v2); return __builtin_bit_cast(unsigned, b); }
; DI float red16(float v) { v += __shfl_xor(v, 1); v += __shfl_xor(v, 2); v += __shfl_xor(v, 4); v += __shfl_xor(v, 8); return v; }
;   DI void run8(f32x4 (&acc)[8][4], int rb, int cb, int fr, int fq) const {
;     ...
;           for (int j = 0; j < 4; ++j) scr[(fq * 4 + j) * 68 + n * 16 + fr] = acc[m][n][j];
;         __builtin_amdgcn_sched_barrier(0);
; #pragma unroll
;         for (int ps = 0; ps < 4; ++ps) {
;           const f32x4 a = *(const f32x4*)(scr + (ps * 4 + prow) * 68 + c4 * 4);
;           f32x4 v;
;           v.x = xv[mm][ps].x + a.x * sc; v.y = xv[mm][ps].y + a.y * sc; v.z = xv[mm][ps].z + a.z * sc; v.w = xv[mm][ps].w + a.w * sc;
;           const int grow = rb + m * 16 + ps * 4 + prow;
;           __builtin_nontemporal_store(v, (f32x4*)(op + (size_t)(m * 16 + ps * 4) * D));
;           if (xbp) {
;             u32x2 o; o.x = pack_bf16(v.x, v.y); o.y = pack_bf16(v.z, v.w);
;             *(u32x2*)(xbp + (size_t)grow * LDH + cb + c4 * 4) = o;
;             const float t = red16(v.x * v.x + v.y * v.y + v.z * v.z + v.w * v.w);
;             if (c4 == 0) atomicAdd(ssqp + grow, t);
;           }
.LBB0_1780:
	s_mov_b64 s[0:1], 0x50000
	s_waitcnt lgkmcnt(0)
	v_lshl_add_u64 v[50:51], v[180:181], 0, s[0:1]
	ds_write2_b32 v184, v42, v46 offset1:16
	ds_write2_b32 v184, v43, v47 offset0:68 offset1:84
	ds_write2_b32 v184, v44, v48 offset0:136 offset1:152
	ds_write2_b32 v184, v45, v49 offset0:204 offset1:220
	ds_write2_b32 v184, v34, v38 offset0:32 offset1:48
	ds_write2_b32 v184, v35, v39 offset0:100 offset1:116
	ds_write2_b32 v184, v36, v40 offset0:168 offset1:184
	ds_write2_b32 v184, v37, v41 offset0:236 offset1:252
	ds_read_b128 v[34:37], v0
	s_and_b64 vcc, exec, s[6:7]
	s_waitcnt vmcnt(15) lgkmcnt(0)
	v_pk_fma_f32 v[34:35], v[34:35], 0.5, v[110:111] op_sel_hi:[1,0,1]
	v_pk_fma_f32 v[36:37], v[36:37], 0.5, v[112:113] op_sel_hi:[1,0,1]
	global_store_dwordx4 v[50:51], v[34:37], off nt
	s_cbranch_vccnz .LBB0_1784
	v_pk_mul_f32 v[38:39], v[34:35], v[34:35]
	v_pk_mul_f32 v[40:41], v[36:37], v[36:37]
	v_add_f32_e32 v38, v38, v39
	v_add_f32_e32 v38, v40, v38
	v_and_b32_e32 v40, 64, v219
	s_nop 0
	v_add_u32_e32 v40, 64, v40
	s_nop 0
	v_add_f32_e32 v38, v41, v38
	v_or_b32_e32 v42, 0x50, v178
	s_nop 0
	s_nop 0
	v_mov_b32_dpp v39, v38 quad_perm:[1,0,3,2] row_mask:0xf bank_mask:0xf
	s_waitcnt lgkmcnt(0)
	v_add_f32_e32 v38, v38, v39
	s_nop 0
	s_nop 0
	s_nop 1
	s_nop 0
	s_nop 0
	v_mov_b32_dpp v39, v38 quad_perm:[2,3,0,1] row_mask:0xf bank_mask:0xf
	s_waitcnt lgkmcnt(0)
	v_add_f32_e32 v39, v38, v39
	s_nop 0
	s_nop 0
	s_nop 1
	s_nop 0
	s_nop 0
	v_mov_b32_dpp v41, v39 row_half_mirror row_mask:0xf bank_mask:0xf
	v_cvt_pk_bf16_f32 v38, v34, v35
	v_xor_b32_e32 v35, 8, v219
	v_cmp_lt_i32_e32 vcc, v35, v40
	s_waitcnt lgkmcnt(0)
	v_add_f32_e32 v34, v39, v41
	s_nop 0
	s_nop 0
	v_mov_b32_dpp v35, v34 row_mirror row_mask:0xf bank_mask:0xf
	v_cvt_pk_bf16_f32 v39, v36, v37
	v_mad_i64_i32 v[36:37], s[0:1], v42, s66, v[182:183]
	global_store_dwordx2 v[36:37], v[38:39], off
	s_and_saveexec_b64 s[0:1], s[4:5]
	s_cbranch_execz .LBB0_1783
	s_waitcnt lgkmcnt(0)
	v_add_f32_e32 v36, v34, v35
	v_lshl_add_u64 v[34:35], v[178:179], 2, s[38:39]
	global_atomic_add_f32 v[34:35], v36, off offset:320

; DI unsigned pack_bf16(float lo, float hi) { f32x2 v = {lo, hi}; bf16v2 b = __builtin_convertvector(v, bf16v2); return __builtin_bit_cast(unsigned, b); }
; DI float red16(float v) { v += __shfl_xor(v, 1); v += __shfl_xor(v, 2); v += __shfl_xor(v, 4); v += __shfl_xor(v, 8); return v; }
;   DI void run8(f32x4 (&acc)[8][4], int rb, int cb, int fr, int fq) const {
;     ...
;         for (int ps = 0; ps < 4; ++ps) {
;           const f32x4 a = *(const f32x4*)(scr + (ps * 4 + prow) * 68 + c4 * 4);
;           f32x4 v;
;           v.x = xv[mm][ps].x + a.x * sc; v.y = xv[mm][ps].y + a.y * sc; v.z = xv[mm][ps].z + a.z * sc; v.w = xv[mm][ps].w + a.w * sc;
;           const int grow = rb + m * 16 + ps * 4 + prow;
;           __builtin_nontemporal_store(v, (f32x4*)(op + (size_t)(m * 16 + ps * 4) * D));
;           if (xbp) {
;             u32x2 o; o.x = pack_bf16(v.x, v.y); o.y = pack_bf16(v.z, v.w);
;             *(u32x2*)(xbp + (size_t)grow * LDH + cb + c4 * 4) = o;
;             const float t = red16(v.x * v.x + v.y * v.y + v.z * v.z + v.w * v.w);
;             if (c4 == 0) atomicAdd(ssqp + grow, t);
;           }
.LBB0_1784:
	s_waitcnt lgkmcnt(0)
	ds_read_b128 v[34:37], v0 offset:1088
	s_mov_b64 s[0:1], 0x54000
	v_lshl_add_u64 v[38:39], v[180:181], 0, s[0:1]
	s_and_b64 vcc, exec, s[6:7]
	s_waitcnt vmcnt(15) lgkmcnt(0)
	v_pk_fma_f32 v[34:35], v[34:35], 0.5, v[106:107] op_sel_hi:[1,0,1]
	v_pk_fma_f32 v[36:37], v[36:37], 0.5, v[108:109] op_sel_hi:[1,0,1]
	global_store_dwordx4 v[38:39], v[34:37], off nt
	s_cbranch_vccnz .LBB0_1788
	v_pk_mul_f32 v[38:39], v[34:35], v[34:35]
	v_pk_mul_f32 v[40:41], v[36:37], v[36:37]
	v_add_f32_e32 v38, v38, v39
	v_add_f32_e32 v38, v40, v38
	v_and_b32_e32 v40, 64, v219
	s_nop 0
	v_add_u32_e32 v40, 64, v40
	s_nop 0
	v_add_f32_e32 v38, v41, v38
	v_or_b32_e32 v42, 0x54, v178
	s_nop 0
	s_nop 0
	v_mov_b32_dpp v39, v38 quad_perm:[1,0,3,2] row_mask:0xf bank_mask:0xf
	s_waitcnt lgkmcnt(0)
	v_add_f32_e32 v38, v38, v39
	s_nop 0
	s_nop 0
	s_nop 1
	s_nop 0
	s_nop 0
	v_mov_b32_dpp v39, v38 quad_perm:[2,3,0,1] row_mask:0xf bank_mask:0xf
	s_waitcnt lgkmcnt(0)
	v_add_f32_e32 v39, v38, v39
	s_nop 0
	s_nop 0
	s_nop 1
	s_nop 0
	s_nop 0
	v_mov_b32_dpp v41, v39 row_half_mirror row_mask:0xf bank_mask:0xf
	v_cvt_pk_bf16_f32 v38, v34, v35
	v_xor_b32_e32 v35, 8, v219
	v_cmp_lt_i32_e32 vcc, v35, v40
	s_waitcnt lgkmcnt(0)
	v_add_f32_e32 v34, v39, v41
	s_nop 0
	s_nop 0
	v_mov_b32_dpp v35, v34 row_mirror row_mask:0xf bank_mask:0xf
	v_cvt_pk_bf16_f32 v39, v36, v37
	v_mad_i64_i32 v[36:37], s[0:1], v42, s66, v[182:183]
	global_store_dwordx2 v[36:37], v[38:39], off
	s_and_saveexec_b64 s[0:1], s[4:5]
	s_cbranch_execz .LBB0_1787
	s_waitcnt lgkmcnt(0)
	v_add_f32_e32 v36, v34, v35
	v_lshl_add_u64 v[34:35], v[178:179], 2, s[38:39]
	global_atomic_add_f32 v[34:35], v36, off offset:336

; DI unsigned pack_bf16(float lo, float hi) { f32x2 v = {lo, hi}; bf16v2 b = __builtin_convertvector(v, bf16v2); return __builtin_bit_cast(unsigned, b); }
; DI float red16(float v) { v += __shfl_xor(v, 1); v += __shfl_xor(v, 2); v += __shfl_xor(v, 4); v += __shfl_xor(v, 8); return v; }
;   DI void run8(f32x4 (&acc)[8][4], int rb, int cb, int fr, int fq) const {
;     ...
;         for (int ps = 0; ps < 4; ++ps) {
;           const f32x4 a = *(const f32x4*)(scr + (ps * 4 + prow) * 68 + c4 * 4);
;           f32x4 v;
;           v.x = xv[mm][ps].x + a.x * sc; v.y = xv[mm][ps].y + a.y * sc; v.z = xv[mm][ps].z + a.z * sc; v.w = xv[mm][ps].w + a.w * sc;
;           const int grow = rb + m * 16 + ps * 4 + prow;
;           __builtin_nontemporal_store(v, (f32x4*)(op + (size_t)(m * 16 + ps * 4) * D));
;           if (xbp) {
;             u32x2 o; o.x = pack_bf16(v.x, v.y); o.y = pack_bf16(v.z, v.w);
;             *(u32x2*)(xbp + (size_t)grow * LDH + cb + c4 * 4) = o;
;             const float t = red16(v.x * v.x + v.y * v.y + v.z * v.z + v.w * v.w);
;             if (c4 == 0) atomicAdd(ssqp + grow, t);
;           }
.LBB0_1788:
	s_waitcnt lgkmcnt(0)
	ds_read_b128 v[34:37], v0 offset:2176
	s_mov_b64 s[0:1], 0x58000
	v_lshl_add_u64 v[38:39], v[180:181], 0, s[0:1]
	s_and_b64 vcc, exec, s[6:7]
	s_waitcnt vmcnt(15) lgkmcnt(0)
	v_pk_fma_f32 v[34:35], v[34:35], 0.5, v[102:103] op_sel_hi:[1,0,1]
	v_pk_fma_f32 v[36:37], v[36:37], 0.5, v[104:105] op_sel_hi:[1,0,1]
	global_store_dwordx4 v[38:39], v[34:37], off nt
	s_cbranch_vccnz .LBB0_1792
	v_pk_mul_f32 v[38:39], v[34:35], v[34:35]
	v_pk_mul_f32 v[40:41], v[36:37], v[36:37]
	v_add_f32_e32 v38, v38, v39
	v_add_f32_e32 v38, v40, v38
	v_and_b32_e32 v40, 64, v219
	s_nop 0
	v_add_u32_e32 v40, 64, v40
	s_nop 0
	v_add_f32_e32 v38, v41, v38
	v_or_b32_e32 v42, 0x58, v178
	s_nop 0
	s_nop 0
	v_mov_b32_dpp v39, v38 quad_perm:[1,0,3,2] row_mask:0xf bank_mask:0xf
	s_waitcnt lgkmcnt(0)
	v_add_f32_e32 v38, v38, v39
	s_nop 0
	s_nop 0
	s_nop 1
	s_nop 0
	s_nop 0
	v_mov_b32_dpp v39, v38 quad_perm:[2,3,0,1] row_mask:0xf bank_mask:0xf
	s_waitcnt lgkmcnt(0)
	v_add_f32_e32 v39, v38, v39
	s_nop 0
	s_nop 0
	s_nop 1
	s_nop 0
	s_nop 0
	v_mov_b32_dpp v41, v39 row_half_mirror row_mask:0xf bank_mask:0xf
	v_cvt_pk_bf16_f32 v38, v34, v35
	v_xor_b32_e32 v35, 8, v219
	v_cmp_lt_i32_e32 vcc, v35, v40
	s_waitcnt lgkmcnt(0)
	v_add_f32_e32 v34, v39, v41
	s_nop 0
	s_nop 0
	v_mov_b32_dpp v35, v34 row_mirror row_mask:0xf bank_mask:0xf
	v_cvt_pk_bf16_f32 v39, v36, v37
	v_mad_i64_i32 v[36:37], s[0:1], v42, s66, v[182:183]
	global_store_dwordx2 v[36:37], v[38:39], off
	s_and_saveexec_b64 s[0:1], s[4:5]
	s_cbranch_execz .LBB0_1791
	s_waitcnt lgkmcnt(0)
	v_add_f32_e32 v36, v34, v35
	v_lshl_add_u64 v[34:35], v[178:179], 2, s[38:39]
	global_atomic_add_f32 v[34:35], v36, off offset:352

; DI unsigned pack_bf16(float lo, float hi) { f32x2 v = {lo, hi}; bf16v2 b = __builtin_convertvector(v, bf16v2); return __builtin_bit_cast(unsigned, b); }
; DI float red16(float v) { v += __shfl_xor(v, 1); v += __shfl_xor(v, 2); v += __shfl_xor(v, 4); v += __shfl_xor(v, 8); return v; }
;   DI void run8(f32x4 (&acc)[8][4], int rb, int cb, int fr, int fq) const {
;     ...
;         for (int ps = 0; ps < 4; ++ps) {
;           const f32x4 a = *(const f32x4*)(scr + (ps * 4 + prow) * 68 + c4 * 4);
;           f32x4 v;
;           v.x = xv[mm][ps].x + a.x * sc; v.y = xv[mm][ps].y + a.y * sc; v.z = xv[mm][ps].z + a.z * sc; v.w = xv[mm][ps].w + a.w * sc;
;           const int grow = rb + m * 16 + ps * 4 + prow;
;           __builtin_nontemporal_store(v, (f32x4*)(op + (size_t)(m * 16 + ps * 4) * D));
;           if (xbp) {
;             u32x2 o; o.x = pack_bf16(v.x, v.y); o.y = pack_bf16(v.z, v.w);
;             *(u32x2*)(xbp + (size_t)grow * LDH + cb + c4 * 4) = o;
;             const float t = red16(v.x * v.x + v.y * v.y + v.z * v.z + v.w * v.w);
;             if (c4 == 0) atomicAdd(ssqp + grow, t);
;           }
.LBB0_1792:
	s_waitcnt lgkmcnt(0)
	ds_read_b128 v[34:37], v0 offset:3264
	s_mov_b64 s[0:1], 0x5c000
	v_lshl_add_u64 v[38:39], v[180:181], 0, s[0:1]
	s_and_b64 vcc, exec, s[6:7]
	s_waitcnt vmcnt(15) lgkmcnt(0)
	v_pk_fma_f32 v[34:35], v[34:35], 0.5, v[98:99] op_sel_hi:[1,0,1]
	v_pk_fma_f32 v[36:37], v[36:37], 0.5, v[100:101] op_sel_hi:[1,0,1]
	global_store_dwordx4 v[38:39], v[34:37], off nt
	s_cbranch_vccnz .LBB0_1796
	v_pk_mul_f32 v[38:39], v[34:35], v[34:35]
	v_pk_mul_f32 v[40:41], v[36:37], v[36:37]
	v_add_f32_e32 v38, v38, v39
	v_add_f32_e32 v38, v40, v38
	v_and_b32_e32 v40, 64, v219
	s_nop 0
	v_add_u32_e32 v40, 64, v40
	s_nop 0
	v_add_f32_e32 v38, v41, v38
	v_or_b32_e32 v42, 0x5c, v178
	s_nop 0
	s_nop 0
	v_mov_b32_dpp v39, v38 quad_perm:[1,0,3,2] row_mask:0xf bank_mask:0xf
	s_waitcnt lgkmcnt(0)
	v_add_f32_e32 v38, v38, v39
	s_nop 0
	s_nop 0
	s_nop 1
	s_nop 0
	s_nop 0
	v_mov_b32_dpp v39, v38 quad_perm:[2,3,0,1] row_mask:0xf bank_mask:0xf
	s_waitcnt lgkmcnt(0)
	v_add_f32_e32 v39, v38, v39
	s_nop 0
	s_nop 0
	s_nop 1
	s_nop 0
	s_nop 0
	v_mov_b32_dpp v41, v39 row_half_mirror row_mask:0xf bank_mask:0xf
	v_cvt_pk_bf16_f32 v38, v34, v35
	v_xor_b32_e32 v35, 8, v219
	v_cmp_lt_i32_e32 vcc, v35, v40
	s_waitcnt lgkmcnt(0)
	v_add_f32_e32 v34, v39, v41
	s_nop 0
	s_nop 0
	v_mov_b32_dpp v35, v34 row_mirror row_mask:0xf bank_mask:0xf
	v_cvt_pk_bf16_f32 v39, v36, v37
	v_mad_i64_i32 v[36:37], s[0:1], v42, s66, v[182:183]
	global_store_dwordx2 v[36:37], v[38:39], off
	s_and_saveexec_b64 s[0:1], s[4:5]
	s_cbranch_execz .LBB0_1795
	s_waitcnt lgkmcnt(0)
	v_add_f32_e32 v36, v34, v35
	v_lshl_add_u64 v[34:35], v[178:179], 2, s[38:39]
	global_atomic_add_f32 v[34:35], v36, off offset:368

; DI unsigned pack_bf16(float lo, float hi) { f32x2 v = {lo, hi}; bf16v2 b = __builtin_convertvector(v, bf16v2); return __builtin_bit_cast(unsigned, b); }
; DI float red16(float v) { v += __shfl_xor(v, 1); v += __shfl_xor(v, 2); v += __shfl_xor(v, 4); v += __shfl_xor(v, 8); return v; }
;   DI void run8(f32x4 (&acc)[8][4], int rb, int cb, int fr, int fq) const {
;     ...
;           for (int j = 0; j < 4; ++j) scr[(fq * 4 + j) * 68 + n * 16 + fr] = acc[m][n][j];
;         __builtin_amdgcn_sched_barrier(0);
; #pragma unroll
;         for (int ps = 0; ps < 4; ++ps) {
;           const f32x4 a = *(const f32x4*)(scr + (ps * 4 + prow) * 68 + c4 * 4);
;           f32x4 v;
;           v.x = xv[mm][ps].x + a.x * sc; v.y = xv[mm][ps].y + a.y * sc; v.z = xv[mm][ps].z + a.z * sc; v.w = xv[mm][ps].w + a.w * sc;
;           const int grow = rb + m * 16 + ps * 4 + prow;
;           __builtin_nontemporal_store(v, (f32x4*)(op + (size_t)(m * 16 + ps * 4) * D));
;           if (xbp) {
;             u32x2 o; o.x = pack_bf16(v.x, v.y); o.y = pack_bf16(v.z, v.w);
;             *(u32x2*)(xbp + (size_t)grow * LDH + cb + c4 * 4) = o;
;             const float t = red16(v.x * v.x + v.y * v.y + v.z * v.z + v.w * v.w);
;             if (c4 == 0) atomicAdd(ssqp + grow, t);
;           }
.LBB0_1796:
	s_mov_b64 s[0:1], 0x60000
	s_waitcnt lgkmcnt(0)
	v_lshl_add_u64 v[34:35], v[180:181], 0, s[0:1]
	ds_write2_b32 v184, v26, v30 offset1:16
	ds_write2_b32 v184, v27, v31 offset0:68 offset1:84
	ds_write2_b32 v184, v28, v32 offset0:136 offset1:152
	ds_write2_b32 v184, v29, v33 offset0:204 offset1:220
	ds_write2_b32 v184, v18, v22 offset0:32 offset1:48
	ds_write2_b32 v184, v19, v23 offset0:100 offset1:116
	ds_write2_b32 v184, v20, v24 offset0:168 offset1:184
	ds_write2_b32 v184, v21, v25 offset0:236 offset1:252
	ds_read_b128 v[18:21], v0
	s_and_b64 vcc, exec, s[6:7]
	s_waitcnt vmcnt(15) lgkmcnt(0)
	v_pk_fma_f32 v[18:19], v[18:19], 0.5, v[94:95] op_sel_hi:[1,0,1]
	v_pk_fma_f32 v[20:21], v[20:21], 0.5, v[96:97] op_sel_hi:[1,0,1]
	global_store_dwordx4 v[34:35], v[18:21], off nt
	s_cbranch_vccnz .LBB0_1800
	v_pk_mul_f32 v[22:23], v[18:19], v[18:19]
	v_pk_mul_f32 v[24:25], v[20:21], v[20:21]
	v_add_f32_e32 v22, v22, v23
	v_add_f32_e32 v22, v24, v22
	v_and_b32_e32 v24, 64, v219
	s_nop 0
	v_add_u32_e32 v24, 64, v24
	s_nop 0
	v_add_f32_e32 v22, v25, v22
	v_or_b32_e32 v26, 0x60, v178
	s_nop 0
	s_nop 0
	v_mov_b32_dpp v23, v22 quad_perm:[1,0,3,2] row_mask:0xf bank_mask:0xf
	s_waitcnt lgkmcnt(0)
	v_add_f32_e32 v22, v22, v23
	s_nop 0
	s_nop 0
	s_nop 1
	s_nop 0
	s_nop 0
	v_mov_b32_dpp v23, v22 quad_perm:[2,3,0,1] row_mask:0xf bank_mask:0xf
	s_waitcnt lgkmcnt(0)
	v_add_f32_e32 v23, v22, v23
	s_nop 0
	s_nop 0
	s_nop 1
	s_nop 0
	s_nop 0
	v_mov_b32_dpp v25, v23 row_half_mirror row_mask:0xf bank_mask:0xf
	v_cvt_pk_bf16_f32 v22, v18, v19
	v_xor_b32_e32 v19, 8, v219
	v_cmp_lt_i32_e32 vcc, v19, v24
	s_waitcnt lgkmcnt(0)
	v_add_f32_e32 v18, v23, v25
	s_nop 0
	s_nop 0
	v_mov_b32_dpp v19, v18 row_mirror row_mask:0xf bank_mask:0xf
	v_cvt_pk_bf16_f32 v23, v20, v21
	v_mad_i64_i32 v[20:21], s[0:1], v26, s66, v[182:183]
	global_store_dwordx2 v[20:21], v[22:23], off
	s_and_saveexec_b64 s[0:1], s[4:5]
	s_cbranch_execz .LBB0_1799
	s_waitcnt lgkmcnt(0)
	v_add_f32_e32 v20, v18, v19
	v_lshl_add_u64 v[18:19], v[178:179], 2, s[38:39]
	global_atomic_add_f32 v[18:19], v20, off offset:384

; DI unsigned pack_bf16(float lo, float hi) { f32x2 v = {lo, hi}; bf16v2 b = __builtin_convertvector(v, bf16v2); return __builtin_bit_cast(unsigned, b); }
; DI float red16(float v) { v += __shfl_xor(v, 1); v += __shfl_xor(v, 2); v += __shfl_xor(v, 4); v += __shfl_xor(v, 8); return v; }
;   DI void run8(f32x4 (&acc)[8][4], int rb, int cb, int fr, int fq) const {
;     ...
;         for (int ps = 0; ps < 4; ++ps) {
;           const f32x4 a = *(const f32x4*)(scr + (ps * 4 + prow) * 68 + c4 * 4);
;           f32x4 v;
;           v.x = xv[mm][ps].x + a.x * sc; v.y = xv[mm][ps].y + a.y * sc; v.z = xv[mm][ps].z + a.z * sc; v.w = xv[mm][ps].w + a.w * sc;
;           const int grow = rb + m * 16 + ps * 4 + prow;
;           __builtin_nontemporal_store(v, (f32x4*)(op + (size_t)(m * 16 + ps * 4) * D));
;           if (xbp) {
;             u32x2 o; o.x = pack_bf16(v.x, v.y); o.y = pack_bf16(v.z, v.w);
;             *(u32x2*)(xbp + (size_t)grow * LDH + cb + c4 * 4) = o;
;             const float t = red16(v.x * v.x + v.y * v.y + v.z * v.z + v.w * v.w);
;             if (c4 == 0) atomicAdd(ssqp + grow, t);
;           }
.LBB0_1800:
	s_waitcnt lgkmcnt(0)
	ds_read_b128 v[18:21], v0 offset:1088
	s_mov_b64 s[0:1], 0x64000
	v_lshl_add_u64 v[22:23], v[180:181], 0, s[0:1]
	s_and_b64 vcc, exec, s[6:7]
	s_waitcnt vmcnt(15) lgkmcnt(0)
	v_pk_fma_f32 v[18:19], v[18:19], 0.5, v[90:91] op_sel_hi:[1,0,1]
	v_pk_fma_f32 v[20:21], v[20:21], 0.5, v[92:93] op_sel_hi:[1,0,1]
	global_store_dwordx4 v[22:23], v[18:21], off nt
	s_cbranch_vccnz .LBB0_1804
	v_pk_mul_f32 v[22:23], v[18:19], v[18:19]
	v_pk_mul_f32 v[24:25], v[20:21], v[20:21]
	v_add_f32_e32 v22, v22, v23
	v_add_f32_e32 v22, v24, v22
	v_and_b32_e32 v24, 64, v219
	s_nop 0
	v_add_u32_e32 v24, 64, v24
	s_nop 0
	v_add_f32_e32 v22, v25, v22
	v_or_b32_e32 v26, 0x64, v178
	s_nop 0
	s_nop 0
	v_mov_b32_dpp v23, v22 quad_perm:[1,0,3,2] row_mask:0xf bank_mask:0xf
	s_waitcnt lgkmcnt(0)
	v_add_f32_e32 v22, v22, v23
	s_nop 0
	s_nop 0
	s_nop 1
	s_nop 0
	s_nop 0
	v_mov_b32_dpp v23, v22 quad_perm:[2,3,0,1] row_mask:0xf bank_mask:0xf
	s_waitcnt lgkmcnt(0)
	v_add_f32_e32 v23, v22, v23
	s_nop 0
	s_nop 0
	s_nop 1
	s_nop 0
	s_nop 0
	v_mov_b32_dpp v25, v23 row_half_mirror row_mask:0xf bank_mask:0xf
	v_cvt_pk_bf16_f32 v22, v18, v19
	v_xor_b32_e32 v19, 8, v219
	v_cmp_lt_i32_e32 vcc, v19, v24
	s_waitcnt lgkmcnt(0)
	v_add_f32_e32 v18, v23, v25
	s_nop 0
	s_nop 0
	v_mov_b32_dpp v19, v18 row_mirror row_mask:0xf bank_mask:0xf
	v_cvt_pk_bf16_f32 v23, v20, v21
	v_mad_i64_i32 v[20:21], s[0:1], v26, s66, v[182:183]
	global_store_dwordx2 v[20:21], v[22:23], off
	s_and_saveexec_b64 s[0:1], s[4:5]
	s_cbranch_execz .LBB0_1803
	s_waitcnt lgkmcnt(0)
	v_add_f32_e32 v20, v18, v19
	v_lshl_add_u64 v[18:19], v[178:179], 2, s[38:39]
	global_atomic_add_f32 v[18:19], v20, off offset:400

; DI unsigned pack_bf16(float lo, float hi) { f32x2 v = {lo, hi}; bf16v2 b = __builtin_convertvector(v, bf16v2); return __builtin_bit_cast(unsigned, b); }
; DI float red16(float v) { v += __shfl_xor(v, 1); v += __shfl_xor(v, 2); v += __shfl_xor(v, 4); v += __shfl_xor(v, 8); return v; }
;   DI void run8(f32x4 (&acc)[8][4], int rb, int cb, int fr, int fq) const {
;     ...
;         for (int ps = 0; ps < 4; ++ps) {
;           const f32x4 a = *(const f32x4*)(scr + (ps * 4 + prow) * 68 + c4 * 4);
;           f32x4 v;
;           v.x = xv[mm][ps].x + a.x * sc; v.y = xv[mm][ps].y + a.y * sc; v.z = xv[mm][ps].z + a.z * sc; v.w = xv[mm][ps].w + a.w * sc;
;           const int grow = rb + m * 16 + ps * 4 + prow;
;           __builtin_nontemporal_store(v, (f32x4*)(op + (size_t)(m * 16 + ps * 4) * D));
;           if (xbp) {
;             u32x2 o; o.x = pack_bf16(v.x, v.y); o.y = pack_bf16(v.z, v.w);
;             *(u32x2*)(xbp + (size_t)grow * LDH + cb + c4 * 4) = o;
;             const float t = red16(v.x * v.x + v.y * v.y + v.z * v.z + v.w * v.w);
;             if (c4 == 0) atomicAdd(ssqp + grow, t);
;           }
.LBB0_1804:
	s_waitcnt lgkmcnt(0)
	ds_read_b128 v[18:21], v0 offset:2176
	s_mov_b64 s[0:1], 0x68000
	v_lshl_add_u64 v[22:23], v[180:181], 0, s[0:1]
	s_and_b64 vcc, exec, s[6:7]
	s_waitcnt vmcnt(15) lgkmcnt(0)
	v_pk_fma_f32 v[18:19], v[18:19], 0.5, v[86:87] op_sel_hi:[1,0,1]
	v_pk_fma_f32 v[20:21], v[20:21], 0.5, v[88:89] op_sel_hi:[1,0,1]
	global_store_dwordx4 v[22:23], v[18:21], off nt
	s_cbranch_vccnz .LBB0_1808
	v_pk_mul_f32 v[22:23], v[18:19], v[18:19]
	v_pk_mul_f32 v[24:25], v[20:21], v[20:21]
	v_add_f32_e32 v22, v22, v23
	v_add_f32_e32 v22, v24, v22
	v_and_b32_e32 v24, 64, v219
	s_nop 0
	v_add_u32_e32 v24, 64, v24
	s_nop 0
	v_add_f32_e32 v22, v25, v22
	v_or_b32_e32 v26, 0x68, v178
	s_nop 0
	s_nop 0
	v_mov_b32_dpp v23, v22 quad_perm:[1,0,3,2] row_mask:0xf bank_mask:0xf
	s_waitcnt lgkmcnt(0)
	v_add_f32_e32 v22, v22, v23
	s_nop 0
	s_nop 0
	s_nop 1
	s_nop 0
	s_nop 0
	v_mov_b32_dpp v23, v22 quad_perm:[2,3,0,1] row_mask:0xf bank_mask:0xf
	s_waitcnt lgkmcnt(0)
	v_add_f32_e32 v23, v22, v23
	s_nop 0
	s_nop 0
	s_nop 1
	s_nop 0
	s_nop 0
	v_mov_b32_dpp v25, v23 row_half_mirror row_mask:0xf bank_mask:0xf
	v_cvt_pk_bf16_f32 v22, v18, v19
	v_xor_b32_e32 v19, 8, v219
	v_cmp_lt_i32_e32 vcc, v19, v24
	s_waitcnt lgkmcnt(0)
	v_add_f32_e32 v18, v23, v25
	s_nop 0
	s_nop 0
	v_mov_b32_dpp v19, v18 row_mirror row_mask:0xf bank_mask:0xf
	v_cvt_pk_bf16_f32 v23, v20, v21
	v_mad_i64_i32 v[20:21], s[0:1], v26, s66, v[182:183]
	global_store_dwordx2 v[20:21], v[22:23], off
	s_and_saveexec_b64 s[0:1], s[4:5]
	s_cbranch_execz .LBB0_1807
	s_waitcnt lgkmcnt(0)
	v_add_f32_e32 v20, v18, v19
	v_lshl_add_u64 v[18:19], v[178:179], 2, s[38:39]
	global_atomic_add_f32 v[18:19], v20, off offset:416

; DI unsigned pack_bf16(float lo, float hi) { f32x2 v = {lo, hi}; bf16v2 b = __builtin_convertvector(v, bf16v2); return __builtin_bit_cast(unsigned, b); }
; DI float red16(float v) { v += __shfl_xor(v, 1); v += __shfl_xor(v, 2); v += __shfl_xor(v, 4); v += __shfl_xor(v, 8); return v; }
;   DI void run8(f32x4 (&acc)[8][4], int rb, int cb, int fr, int fq) const {
;     ...
;         for (int ps = 0; ps < 4; ++ps) {
;           const f32x4 a = *(const f32x4*)(scr + (ps * 4 + prow) * 68 + c4 * 4);
;           f32x4 v;
;           v.x = xv[mm][ps].x + a.x * sc; v.y = xv[mm][ps].y + a.y * sc; v.z = xv[mm][ps].z + a.z * sc; v.w = xv[mm][ps].w + a.w * sc;
;           const int grow = rb + m * 16 + ps * 4 + prow;
;           __builtin_nontemporal_store(v, (f32x4*)(op + (size_t)(m * 16 + ps * 4) * D));
;           if (xbp) {
;             u32x2 o; o.x = pack_bf16(v.x, v.y); o.y = pack_bf16(v.z, v.w);
;             *(u32x2*)(xbp + (size_t)grow * LDH + cb + c4 * 4) = o;
;             const float t = red16(v.x * v.x + v.y * v.y + v.z * v.z + v.w * v.w);
;             if (c4 == 0) atomicAdd(ssqp + grow, t);
;           }
.LBB0_1808:
	s_waitcnt lgkmcnt(0)
	ds_read_b128 v[18:21], v0 offset:3264
	s_mov_b64 s[0:1], 0x6c000
	v_lshl_add_u64 v[22:23], v[180:181], 0, s[0:1]
	s_and_b64 vcc, exec, s[6:7]
	s_waitcnt vmcnt(15) lgkmcnt(0)
	v_pk_fma_f32 v[18:19], v[18:19], 0.5, v[82:83] op_sel_hi:[1,0,1]
	v_pk_fma_f32 v[20:21], v[20:21], 0.5, v[84:85] op_sel_hi:[1,0,1]
	global_store_dwordx4 v[22:23], v[18:21], off nt
	s_cbranch_vccnz .LBB0_1812
	v_pk_mul_f32 v[22:23], v[18:19], v[18:19]
	v_pk_mul_f32 v[24:25], v[20:21], v[20:21]
	v_add_f32_e32 v22, v22, v23
	v_add_f32_e32 v22, v24, v22
	v_and_b32_e32 v24, 64, v219
	s_nop 0
	v_add_u32_e32 v24, 64, v24
	s_nop 0
	v_add_f32_e32 v22, v25, v22
	v_or_b32_e32 v26, 0x6c, v178
	s_nop 0
	s_nop 0
	v_mov_b32_dpp v23, v22 quad_perm:[1,0,3,2] row_mask:0xf bank_mask:0xf
	s_waitcnt lgkmcnt(0)
	v_add_f32_e32 v22, v22, v23
	s_nop 0
	s_nop 0
	s_nop 1
	s_nop 0
	s_nop 0
	v_mov_b32_dpp v23, v22 quad_perm:[2,3,0,1] row_mask:0xf bank_mask:0xf
	s_waitcnt lgkmcnt(0)
	v_add_f32_e32 v23, v22, v23
	s_nop 0
	s_nop 0
	s_nop 1
	s_nop 0
	s_nop 0
	v_mov_b32_dpp v25, v23 row_half_mirror row_mask:0xf bank_mask:0xf
	v_cvt_pk_bf16_f32 v22, v18, v19
	v_xor_b32_e32 v19, 8, v219
	v_cmp_lt_i32_e32 vcc, v19, v24
	s_waitcnt lgkmcnt(0)
	v_add_f32_e32 v18, v23, v25
	s_nop 0
	s_nop 0
	v_mov_b32_dpp v19, v18 row_mirror row_mask:0xf bank_mask:0xf
	v_cvt_pk_bf16_f32 v23, v20, v21
	v_mad_i64_i32 v[20:21], s[0:1], v26, s66, v[182:183]
	global_store_dwordx2 v[20:21], v[22:23], off
	s_and_saveexec_b64 s[0:1], s[4:5]
	s_cbranch_execz .LBB0_1811
	s_waitcnt lgkmcnt(0)
	v_add_f32_e32 v20, v18, v19
	v_lshl_add_u64 v[18:19], v[178:179], 2, s[38:39]
	global_atomic_add_f32 v[18:19], v20, off offset:432

; DI unsigned pack_bf16(float lo, float hi) { f32x2 v = {lo, hi}; bf16v2 b = __builtin_convertvector(v, bf16v2); return __builtin_bit_cast(unsigned, b); }
; DI float red16(float v) { v += __shfl_xor(v, 1); v += __shfl_xor(v, 2); v += __shfl_xor(v, 4); v += __shfl_xor(v, 8); return v; }
;   DI void run8(f32x4 (&acc)[8][4], int rb, int cb, int fr, int fq) const {
;     ...
;           for (int j = 0; j < 4; ++j) scr[(fq * 4 + j) * 68 + n * 16 + fr] = acc[m][n][j];
;         __builtin_amdgcn_sched_barrier(0);
; #pragma unroll
;         for (int ps = 0; ps < 4; ++ps) {
;           const f32x4 a = *(const f32x4*)(scr + (ps * 4 + prow) * 68 + c4 * 4);
;           f32x4 v;
;           v.x = xv[mm][ps].x + a.x * sc; v.y = xv[mm][ps].y + a.y * sc; v.z = xv[mm][ps].z + a.z * sc; v.w = xv[mm][ps].w + a.w * sc;
;           const int grow = rb + m * 16 + ps * 4 + prow;
;           __builtin_nontemporal_store(v, (f32x4*)(op + (size_t)(m * 16 + ps * 4) * D));
;           if (xbp) {
;             u32x2 o; o.x = pack_bf16(v.x, v.y); o.y = pack_bf16(v.z, v.w);
;             *(u32x2*)(xbp + (size_t)grow * LDH + cb + c4 * 4) = o;
;             const float t = red16(v.x * v.x + v.y * v.y + v.z * v.z + v.w * v.w);
;             if (c4 == 0) atomicAdd(ssqp + grow, t);
;           }
.LBB0_1812:
	s_mov_b64 s[0:1], 0x70000
	s_waitcnt lgkmcnt(0)
	v_lshl_add_u64 v[18:19], v[180:181], 0, s[0:1]
	ds_write2_b32 v184, v10, v14 offset1:16
	ds_write2_b32 v184, v11, v15 offset0:68 offset1:84
	ds_write2_b32 v184, v12, v16 offset0:136 offset1:152
	ds_write2_b32 v184, v13, v17 offset0:204 offset1:220
	ds_write2_b32 v184, v2, v6 offset0:32 offset1:48
	ds_write2_b32 v184, v3, v7 offset0:100 offset1:116
	ds_write2_b32 v184, v4, v8 offset0:168 offset1:184
	ds_write2_b32 v184, v5, v9 offset0:236 offset1:252
	ds_read_b128 v[2:5], v0
	s_and_b64 vcc, exec, s[6:7]
	s_waitcnt vmcnt(15) lgkmcnt(0)
	v_pk_fma_f32 v[2:3], v[2:3], 0.5, v[78:79] op_sel_hi:[1,0,1]
	v_pk_fma_f32 v[4:5], v[4:5], 0.5, v[80:81] op_sel_hi:[1,0,1]
	global_store_dwordx4 v[18:19], v[2:5], off nt
	s_cbranch_vccnz .LBB0_1816
	v_pk_mul_f32 v[6:7], v[2:3], v[2:3]
	v_pk_mul_f32 v[8:9], v[4:5], v[4:5]
	v_add_f32_e32 v6, v6, v7
	v_add_f32_e32 v6, v8, v6
	v_and_b32_e32 v8, 64, v219
	s_nop 0
	v_add_u32_e32 v8, 64, v8
	s_nop 0
	v_add_f32_e32 v6, v9, v6
	v_or_b32_e32 v10, 0x70, v178
	s_nop 0
	s_nop 0
	v_mov_b32_dpp v7, v6 quad_perm:[1,0,3,2] row_mask:0xf bank_mask:0xf
	s_waitcnt lgkmcnt(0)
	v_add_f32_e32 v6, v6, v7
	s_nop 0
	s_nop 0
	s_nop 1
	s_nop 0
	s_nop 0
	v_mov_b32_dpp v7, v6 quad_perm:[2,3,0,1] row_mask:0xf bank_mask:0xf
	s_waitcnt lgkmcnt(0)
	v_add_f32_e32 v7, v6, v7
	s_nop 0
	s_nop 0
	s_nop 1
	s_nop 0
	s_nop 0
	v_mov_b32_dpp v9, v7 row_half_mirror row_mask:0xf bank_mask:0xf
	v_cvt_pk_bf16_f32 v6, v2, v3
	v_xor_b32_e32 v3, 8, v219
	v_cmp_lt_i32_e32 vcc, v3, v8
	s_waitcnt lgkmcnt(0)
	v_add_f32_e32 v2, v7, v9
	s_nop 0
	s_nop 0
	v_mov_b32_dpp v3, v2 row_mirror row_mask:0xf bank_mask:0xf
	v_cvt_pk_bf16_f32 v7, v4, v5
	v_mad_i64_i32 v[4:5], s[0:1], v10, s66, v[182:183]
	global_store_dwordx2 v[4:5], v[6:7], off
	s_and_saveexec_b64 s[0:1], s[4:5]
	s_cbranch_execz .LBB0_1815
	s_waitcnt lgkmcnt(0)
	v_add_f32_e32 v4, v2, v3
	v_lshl_add_u64 v[2:3], v[178:179], 2, s[38:39]
	global_atomic_add_f32 v[2:3], v4, off offset:448

; DI unsigned pack_bf16(float lo, float hi) { f32x2 v = {lo, hi}; bf16v2 b = __builtin_convertvector(v, bf16v2); return __builtin_bit_cast(unsigned, b); }
; DI float red16(float v) { v += __shfl_xor(v, 1); v += __shfl_xor(v, 2); v += __shfl_xor(v, 4); v += __shfl_xor(v, 8); return v; }
;   DI void run8(f32x4 (&acc)[8][4], int rb, int cb, int fr, int fq) const {
;     ...
;         for (int ps = 0; ps < 4; ++ps) {
;           const f32x4 a = *(const f32x4*)(scr + (ps * 4 + prow) * 68 + c4 * 4);
;           f32x4 v;
;           v.x = xv[mm][ps].x + a.x * sc; v.y = xv[mm][ps].y + a.y * sc; v.z = xv[mm][ps].z + a.z * sc; v.w = xv[mm][ps].w + a.w * sc;
;           const int grow = rb + m * 16 + ps * 4 + prow;
;           __builtin_nontemporal_store(v, (f32x4*)(op + (size_t)(m * 16 + ps * 4) * D));
;           if (xbp) {
;             u32x2 o; o.x = pack_bf16(v.x, v.y); o.y = pack_bf16(v.z, v.w);
;             *(u32x2*)(xbp + (size_t)grow * LDH + cb + c4 * 4) = o;
;             const float t = red16(v.x * v.x + v.y * v.y + v.z * v.z + v.w * v.w);
;             if (c4 == 0) atomicAdd(ssqp + grow, t);
;           }
.LBB0_1816:
	s_waitcnt lgkmcnt(0)
	ds_read_b128 v[2:5], v0 offset:1088
	s_mov_b64 s[0:1], 0x74000
	v_lshl_add_u64 v[6:7], v[180:181], 0, s[0:1]
	s_and_b64 vcc, exec, s[6:7]
	s_waitcnt vmcnt(15) lgkmcnt(0)
	v_pk_fma_f32 v[2:3], v[2:3], 0.5, v[74:75] op_sel_hi:[1,0,1]
	v_pk_fma_f32 v[4:5], v[4:5], 0.5, v[76:77] op_sel_hi:[1,0,1]
	global_store_dwordx4 v[6:7], v[2:5], off nt
	s_cbranch_vccnz .LBB0_1820
	v_pk_mul_f32 v[6:7], v[2:3], v[2:3]
	v_pk_mul_f32 v[8:9], v[4:5], v[4:5]
	v_add_f32_e32 v6, v6, v7
	v_add_f32_e32 v6, v8, v6
	v_and_b32_e32 v8, 64, v219
	s_nop 0
	v_add_u32_e32 v8, 64, v8
	s_nop 0
	v_add_f32_e32 v6, v9, v6
	v_or_b32_e32 v10, 0x74, v178
	s_nop 0
	s_nop 0
	v_mov_b32_dpp v7, v6 quad_perm:[1,0,3,2] row_mask:0xf bank_mask:0xf
	s_waitcnt lgkmcnt(0)
	v_add_f32_e32 v6, v6, v7
	s_nop 0
	s_nop 0
	s_nop 1
	s_nop 0
	s_nop 0
	v_mov_b32_dpp v7, v6 quad_perm:[2,3,0,1] row_mask:0xf bank_mask:0xf
	s_waitcnt lgkmcnt(0)
	v_add_f32_e32 v7, v6, v7
	s_nop 0
	s_nop 0
	s_nop 1
	s_nop 0
	s_nop 0
	v_mov_b32_dpp v9, v7 row_half_mirror row_mask:0xf bank_mask:0xf
	v_cvt_pk_bf16_f32 v6, v2, v3
	v_xor_b32_e32 v3, 8, v219
	v_cmp_lt_i32_e32 vcc, v3, v8
	s_waitcnt lgkmcnt(0)
	v_add_f32_e32 v2, v7, v9
	s_nop 0
	s_nop 0
	v_mov_b32_dpp v3, v2 row_mirror row_mask:0xf bank_mask:0xf
	v_cvt_pk_bf16_f32 v7, v4, v5
	v_mad_i64_i32 v[4:5], s[0:1], v10, s66, v[182:183]
	global_store_dwordx2 v[4:5], v[6:7], off
	s_and_saveexec_b64 s[0:1], s[4:5]
	s_cbranch_execz .LBB0_1819
	s_waitcnt lgkmcnt(0)
	v_add_f32_e32 v4, v2, v3
	v_lshl_add_u64 v[2:3], v[178:179], 2, s[38:39]
	global_atomic_add_f32 v[2:3], v4, off offset:464

; DI unsigned pack_bf16(float lo, float hi) { f32x2 v = {lo, hi}; bf16v2 b = __builtin_convertvector(v, bf16v2); return __builtin_bit_cast(unsigned, b); }
; DI float red16(float v) { v += __shfl_xor(v, 1); v += __shfl_xor(v, 2); v += __shfl_xor(v, 4); v += __shfl_xor(v, 8); return v; }
;   DI void run8(f32x4 (&acc)[8][4], int rb, int cb, int fr, int fq) const {
;     ...
;         for (int ps = 0; ps < 4; ++ps) {
;           const f32x4 a = *(const f32x4*)(scr + (ps * 4 + prow) * 68 + c4 * 4);
;           f32x4 v;
;           v.x = xv[mm][ps].x + a.x * sc; v.y = xv[mm][ps].y + a.y * sc; v.z = xv[mm][ps].z + a.z * sc; v.w = xv[mm][ps].w + a.w * sc;
;           const int grow = rb + m * 16 + ps * 4 + prow;
;           __builtin_nontemporal_store(v, (f32x4*)(op + (size_t)(m * 16 + ps * 4) * D));
;           if (xbp) {
;             u32x2 o; o.x = pack_bf16(v.x, v.y); o.y = pack_bf16(v.z, v.w);
;             *(u32x2*)(xbp + (size_t)grow * LDH + cb + c4 * 4) = o;
;             const float t = red16(v.x * v.x + v.y * v.y + v.z * v.z + v.w * v.w);
;             if (c4 == 0) atomicAdd(ssqp + grow, t);
;           }
.LBB0_1820:
	s_waitcnt lgkmcnt(0)
	ds_read_b128 v[2:5], v0 offset:2176
	s_mov_b64 s[0:1], 0x78000
	v_lshl_add_u64 v[6:7], v[180:181], 0, s[0:1]
	s_and_b64 vcc, exec, s[6:7]
	s_waitcnt vmcnt(15) lgkmcnt(0)
	v_pk_fma_f32 v[2:3], v[2:3], 0.5, v[70:71] op_sel_hi:[1,0,1]
	v_pk_fma_f32 v[4:5], v[4:5], 0.5, v[72:73] op_sel_hi:[1,0,1]
	global_store_dwordx4 v[6:7], v[2:5], off nt
	s_cbranch_vccnz .LBB0_1824
	v_pk_mul_f32 v[6:7], v[2:3], v[2:3]
	v_pk_mul_f32 v[8:9], v[4:5], v[4:5]
	v_add_f32_e32 v6, v6, v7
	v_add_f32_e32 v6, v8, v6
	v_and_b32_e32 v8, 64, v219
	s_nop 0
	v_add_u32_e32 v8, 64, v8
	s_nop 0
	v_add_f32_e32 v6, v9, v6
	v_or_b32_e32 v10, 0x78, v178
	s_nop 0
	s_nop 0
	v_mov_b32_dpp v7, v6 quad_perm:[1,0,3,2] row_mask:0xf bank_mask:0xf
	s_waitcnt lgkmcnt(0)
	v_add_f32_e32 v6, v6, v7
	s_nop 0
	s_nop 0
	s_nop 1
	s_nop 0
	s_nop 0
	v_mov_b32_dpp v7, v6 quad_perm:[2,3,0,1] row_mask:0xf bank_mask:0xf
	s_waitcnt lgkmcnt(0)
	v_add_f32_e32 v7, v6, v7
	s_nop 0
	s_nop 0
	s_nop 1
	s_nop 0
	s_nop 0
	v_mov_b32_dpp v9, v7 row_half_mirror row_mask:0xf bank_mask:0xf
	v_cvt_pk_bf16_f32 v6, v2, v3
	v_xor_b32_e32 v3, 8, v219
	v_cmp_lt_i32_e32 vcc, v3, v8
	s_waitcnt lgkmcnt(0)
	v_add_f32_e32 v2, v7, v9
	s_nop 0
	s_nop 0
	v_mov_b32_dpp v3, v2 row_mirror row_mask:0xf bank_mask:0xf
	v_cvt_pk_bf16_f32 v7, v4, v5
	v_mad_i64_i32 v[4:5], s[0:1], v10, s66, v[182:183]
	global_store_dwordx2 v[4:5], v[6:7], off
	s_and_saveexec_b64 s[0:1], s[4:5]
	s_cbranch_execz .LBB0_1823
	s_waitcnt lgkmcnt(0)
	v_add_f32_e32 v4, v2, v3
	v_lshl_add_u64 v[2:3], v[178:179], 2, s[38:39]
	global_atomic_add_f32 v[2:3], v4, off offset:480

; DI unsigned pack_bf16(float lo, float hi) { f32x2 v = {lo, hi}; bf16v2 b = __builtin_convertvector(v, bf16v2); return __builtin_bit_cast(unsigned, b); }
; template <class Epi>
; DI void gemm8_tile(const bf16_t* __restrict__ Ab, int lda, const bf16_t* __restrict__ Bb, int ldb, int K, int brow, int bcol, const Epi epi,
;                    bool staged, bool has_next, const bf16_t* __restrict__ Abn, const bf16_t* __restrict__ Bbn) {
;     ...
;   epi.run8(acc, brow + wr * 128, bcol + wc * 64, fr, fq);
;   if (Epi::LDS_SCRATCH) __syncthreads();
; DI float red16(float v) { v += __shfl_xor(v, 1); v += __shfl_xor(v, 2); v += __shfl_xor(v, 4); v += __shfl_xor(v, 8); return v; }
;   DI void run8(f32x4 (&acc)[8][4], int rb, int cb, int fr, int fq) const {
;     ...
;         for (int ps = 0; ps < 4; ++ps) {
;           const f32x4 a = *(const f32x4*)(scr + (ps * 4 + prow) * 68 + c4 * 4);
;           f32x4 v;
;           v.x = xv[mm][ps].x + a.x * sc; v.y = xv[mm][ps].y + a.y * sc; v.z = xv[mm][ps].z + a.z * sc; v.w = xv[mm][ps].w + a.w * sc;
;           const int grow = rb + m * 16 + ps * 4 + prow;
;           __builtin_nontemporal_store(v, (f32x4*)(op + (size_t)(m * 16 + ps * 4) * D));
;           if (xbp) {
;             u32x2 o; o.x = pack_bf16(v.x, v.y); o.y = pack_bf16(v.z, v.w);
;             *(u32x2*)(xbp + (size_t)grow * LDH + cb + c4 * 4) = o;
;             const float t = red16(v.x * v.x + v.y * v.y + v.z * v.z + v.w * v.w);
;             if (c4 == 0) atomicAdd(ssqp + grow, t);
;           }
.LBB0_1824:
	s_waitcnt lgkmcnt(0)
	ds_read_b128 v[2:5], v0 offset:3264
	s_mov_b64 s[0:1], 0x7c000
	v_lshl_add_u64 v[6:7], v[180:181], 0, s[0:1]
	s_and_b64 vcc, exec, s[6:7]
	s_waitcnt vmcnt(15) lgkmcnt(0)
	v_pk_fma_f32 v[2:3], v[2:3], 0.5, v[66:67] op_sel_hi:[1,0,1]
	v_pk_fma_f32 v[4:5], v[4:5], 0.5, v[68:69] op_sel_hi:[1,0,1]
	global_store_dwordx4 v[6:7], v[2:5], off nt
	s_cbranch_vccnz .LBB0_1689
	v_pk_mul_f32 v[6:7], v[2:3], v[2:3]
	v_pk_mul_f32 v[8:9], v[4:5], v[4:5]
	v_add_f32_e32 v0, v6, v7
	v_and_b32_e32 v7, 64, v219
	s_nop 0
	v_add_u32_e32 v7, 64, v7
	s_nop 0
	v_add_f32_e32 v0, v8, v0
	v_add_f32_e32 v0, v9, v0
	s_nop 0
	s_nop 0
	v_mov_b32_dpp v6, v0 quad_perm:[1,0,3,2] row_mask:0xf bank_mask:0xf
	v_or_b32_e32 v9, 0x7c, v178
	s_waitcnt lgkmcnt(0)
	v_add_f32_e32 v0, v0, v6
	s_nop 0
	s_nop 0
	s_nop 1
	s_nop 0
	s_nop 0
	v_mov_b32_dpp v6, v0 quad_perm:[2,3,0,1] row_mask:0xf bank_mask:0xf
	s_waitcnt lgkmcnt(0)
	v_add_f32_e32 v0, v0, v6
	s_nop 0
	s_nop 0
	s_nop 1
	s_nop 0
	s_nop 0
	v_mov_b32_dpp v8, v0 row_half_mirror row_mask:0xf bank_mask:0xf
	v_cvt_pk_bf16_f32 v6, v2, v3
	v_xor_b32_e32 v2, 8, v219
	v_cmp_lt_i32_e32 vcc, v2, v7
	v_cvt_pk_bf16_f32 v7, v4, v5
	s_waitcnt lgkmcnt(0)
	v_add_f32_e32 v0, v0, v8
	s_nop 0
	s_nop 0
	v_mov_b32_dpp v2, v0 row_mirror row_mask:0xf bank_mask:0xf
	v_mad_i64_i32 v[4:5], s[0:1], v9, s66, v[182:183]
	global_store_dwordx2 v[4:5], v[6:7], off
	s_and_saveexec_b64 s[0:1], s[4:5]
	s_cbranch_execz .LBB0_1688
	s_waitcnt lgkmcnt(0)
	v_add_f32_e32 v0, v0, v2
	v_lshl_add_u64 v[2:3], v[178:179], 2, s[38:39]
	global_atomic_add_f32 v[2:3], v0, off offset:496
	s_branch .LBB0_1688
